# loop-edge: every backward-branch target (64 loop heads) aligned to 64 bytes
# baseline (speedup 1.0000x reference)
; __device__ __forceinline__ unsigned xb_ld(unsigned* p)              { return __hip_atomic_load(p, __ATOMIC_RELAXED, __HIP_MEMORY_SCOPE_AGENT); }
; __device__ __forceinline__ void xcd_barrier_complete(unsigned* bar, unsigned x, unsigned& nloc, unsigned& nx) {
;     const unsigned G = gridDim.x * gridDim.y * gridDim.z;
;     unsigned sum, cnt, mine, sp = 0u;
;     for (;;) {
;         sum = 0u; cnt = 0u; mine = 0u;
; #pragma unroll
;         for (unsigned j = 0; j < 16; ++j) { const unsigned c = xb_ld(&bar[XB_XCNT(j)]); sum += c; cnt += (c > 0u) ? 1u : 0u; mine = (j == x) ? c : mine; }
;         if (sum == G) break;
;         __builtin_amdgcn_s_sleep(1);
;         if ((++sp & 255u) == 0u) { if (xb_ld(&bar[XB_TMO])) break; if (sp > XB_SPIN_CAP) { atomicAdd(&bar[XB_TMO], 1u); break; } }
;     }
;     nloc = mine > 0u ? mine : 1u; nx = cnt > 0u ? cnt : 1u;
; }
; __device__ __forceinline__ void xcd_barrier(const XcdBarrier& b) {
;     asm volatile("s_waitcnt vmcnt(0)" ::: "memory");
;     __syncthreads();
;     if (threadIdx.x == 0) {
;         unsigned* bar = b.bar;
;         __builtin_amdgcn_s_waitcnt(0);
;         unsigned nloc = b.st[0], nx = b.st[1];
;         if (nloc == 0u) { xcd_barrier_complete(bar, b.x, nloc, nx); b.st[0] = nloc; b.st[1] = nx; }
.LBB0_9:
	s_cmp_gt_i32 s29, s8
	v_readlane_b32 s6, v253, 9
	s_cselect_b64 s[0:1], -1, 0
	v_readlane_b32 s7, v253, 10
	s_and_b64 s[0:1], s[0:1], s[6:7]
	s_andn2_b64 vcc, exec, s[0:1]
	s_cbranch_vccnz .LBB0_77
	v_readlane_b32 s0, v253, 11
	s_cmp_lg_u32 s29, s0
	s_mov_b64 s[0:1], -1
	s_cbranch_scc0 .LBB0_64
	v_readlane_b32 s6, v253, 2
	v_readlane_b32 s7, v253, 3
	s_getreg_b32 s8, hwreg(HW_REG_XCC_ID, 0, 4)
	s_waitcnt vmcnt(0)
	s_barrier
	s_mov_b64 s[0:1], exec
	v_readlane_b32 s10, v253, 6
	v_readlane_b32 s11, v253, 7
	s_and_b64 s[10:11], s[0:1], s[10:11]
	s_mov_b64 exec, s[10:11]
	s_cbranch_execz .LBB0_63
	v_readlane_b32 s9, v253, 21
	s_load_dwordx2 s[6:7], s[6:7], 0xa0
	s_waitcnt vmcnt(0) expcnt(0) lgkmcnt(0)
	v_mov_b32_e32 v0, s9
	ds_read_b32 v2, v0
	v_readlane_b32 s9, v253, 22
	s_and_b32 s33, s8, 15
	s_waitcnt lgkmcnt(0)
	v_cmp_ne_u32_e32 vcc, 0, v2
	v_mov_b32_e32 v0, s9
	ds_read_b32 v0, v0
	s_cbranch_vccnz .LBB0_27
	s_add_u32 s8, s6, 0x380200
	s_addc_u32 s9, s7, 0
	s_add_u32 s10, s6, 0x380400
	s_addc_u32 s11, s7, 0
	s_add_u32 s12, s6, 0x380500
	s_addc_u32 s13, s7, 0
	s_add_u32 s14, s6, 0x380600
	s_addc_u32 s15, s7, 0
	s_add_u32 s16, s6, 0x380700
	s_addc_u32 s17, s7, 0
	s_add_u32 s18, s6, 0x380800
	s_addc_u32 s19, s7, 0
	s_add_u32 s20, s6, 0x380900
	s_addc_u32 s21, s7, 0
	s_add_u32 s22, s6, 0x380a00
	s_addc_u32 s23, s7, 0
	s_add_u32 s24, s6, 0x380b00
	s_addc_u32 s25, s7, 0
	s_add_u32 s26, s6, 0x380c00
	s_addc_u32 s27, s7, 0
	s_add_u32 s28, s6, 0x380d00
	s_mov_b32 s51, s29
	s_addc_u32 s29, s7, 0
	s_add_u32 s30, s6, 0x380e00
	s_addc_u32 s31, s7, 0
	s_add_u32 s34, s6, 0x380f00
	s_addc_u32 s35, s7, 0
	s_add_u32 s36, s6, 0x381000
	s_addc_u32 s37, s7, 0
	s_add_u32 s38, s6, 0x381100
	s_addc_u32 s39, s7, 0
	s_add_u32 s40, s6, 0x381200
	s_addc_u32 s41, s7, 0
	s_add_u32 s42, s6, 0x381300
	s_addc_u32 s43, s7, 0
	s_mov_b32 s50, 1
	s_branch .LBB0_15
	.p2align	6

; __device__ __forceinline__ unsigned xb_ld(unsigned* p)              { return __hip_atomic_load(p, __ATOMIC_RELAXED, __HIP_MEMORY_SCOPE_AGENT); }
; __device__ __forceinline__ void xcd_barrier_complete(unsigned* bar, unsigned x, unsigned& nloc, unsigned& nx) {
;     const unsigned G = gridDim.x * gridDim.y * gridDim.z;
;     unsigned sum, cnt, mine, sp = 0u;
;     for (;;) {
;         sum = 0u; cnt = 0u; mine = 0u;
; #pragma unroll
;         for (unsigned j = 0; j < 16; ++j) { const unsigned c = xb_ld(&bar[XB_XCNT(j)]); sum += c; cnt += (c > 0u) ? 1u : 0u; mine = (j == x) ? c : mine; }
;         if (sum == G) break;
;         __builtin_amdgcn_s_sleep(1);
;         if ((++sp & 255u) == 0u) { if (xb_ld(&bar[XB_TMO])) break; if (sp > XB_SPIN_CAP) { atomicAdd(&bar[XB_TMO], 1u); break; } }
;     }
.LBB0_15:
	global_load_dword v15, v161, s[10:11] sc1
	s_waitcnt lgkmcnt(0)
	global_load_dword v0, v161, s[12:13] sc1
	global_load_dword v1, v161, s[14:15] sc1
	global_load_dword v2, v161, s[16:17] sc1
	global_load_dword v3, v161, s[18:19] sc1
	global_load_dword v4, v161, s[20:21] sc1
	global_load_dword v5, v161, s[22:23] sc1
	global_load_dword v6, v161, s[24:25] sc1
	global_load_dword v7, v161, s[26:27] sc1
	global_load_dword v8, v161, s[28:29] sc1
	global_load_dword v9, v161, s[30:31] sc1
	global_load_dword v10, v161, s[34:35] sc1
	global_load_dword v11, v161, s[36:37] sc1
	global_load_dword v12, v161, s[38:39] sc1
	global_load_dword v13, v161, s[40:41] sc1
	global_load_dword v14, v161, s[42:43] sc1
	v_readlane_b32 s46, v253, 8
	s_mov_b64 s[44:45], -1
	s_waitcnt vmcnt(14)
	v_add_u32_e32 v16, v0, v15
	s_waitcnt vmcnt(13)
	v_add_u32_e32 v16, v16, v1
	s_waitcnt vmcnt(12)
	v_add_u32_e32 v16, v16, v2
	s_waitcnt vmcnt(11)
	v_add_u32_e32 v16, v16, v3
	s_waitcnt vmcnt(10)
	v_add_u32_e32 v16, v16, v4
	s_waitcnt vmcnt(9)
	v_add_u32_e32 v16, v16, v5
	s_waitcnt vmcnt(8)
	v_add_u32_e32 v16, v16, v6
	s_waitcnt vmcnt(7)
	v_add_u32_e32 v16, v16, v7
	s_waitcnt vmcnt(6)
	v_add_u32_e32 v16, v16, v8
	s_waitcnt vmcnt(5)
	v_add_u32_e32 v16, v16, v9
	s_waitcnt vmcnt(4)
	v_add_u32_e32 v16, v16, v10
	s_waitcnt vmcnt(3)
	v_add_u32_e32 v16, v16, v11
	s_waitcnt vmcnt(2)
	v_add_u32_e32 v16, v16, v12
	s_waitcnt vmcnt(1)
	v_add_u32_e32 v16, v16, v13
	s_waitcnt vmcnt(0)
	v_add_u32_e32 v16, v16, v14
	v_cmp_eq_u32_e32 vcc, s46, v16
	s_mov_b64 s[46:47], -1
	s_cbranch_vccnz .LBB0_14
	s_and_b32 s44, s50, 0xff
	s_cmp_eq_u32 s44, 0
	s_mov_b64 s[44:45], -1
	s_mov_b64 s[48:49], -1
	s_sleep 1
	s_cbranch_scc1 .LBB0_19
	s_and_b64 vcc, exec, s[48:49]
	s_cbranch_vccz .LBB0_14
	.p2align	6

; __device__ __forceinline__ unsigned xb_ld(unsigned* p)              { return __hip_atomic_load(p, __ATOMIC_RELAXED, __HIP_MEMORY_SCOPE_AGENT); }
; __device__ __forceinline__ unsigned xb_add(unsigned* p, unsigned v) { return __hip_atomic_fetch_add(p, v, __ATOMIC_RELAXED, __HIP_MEMORY_SCOPE_AGENT); }
; #define XB_SPIN(cond, bar) do { unsigned _sp = 0; while (cond) { __builtin_amdgcn_s_sleep(1); \
;     if ((++_sp & 255u) == 0u) { if (xb_ld(&(bar)[XB_TMO])) break; if (_sp > XB_SPIN_CAP) { atomicAdd(&(bar)[XB_TMO], 1u); break; } } } } while (0)
; __device__ __forceinline__ void xcd_barrier(const XcdBarrier& b) {
;     ...
;         const unsigned old = xb_add(&bar[XB_XSUB(b.x)], 1u);
;         const unsigned gen = old / nloc;
;         if (old + 1u == (gen + 1u) * nloc) {
;             __builtin_amdgcn_fence(__ATOMIC_RELEASE, "agent");
;             asm volatile("s_waitcnt vmcnt(0)" ::: "memory");
;             const unsigned og = xb_add(&bar[XB_TOP], 1u);
;             const unsigned tg = og / nx;
;             if (og + 1u == (tg + 1u) * nx) xb_add(&bar[XB_TOPGEN], 1u);
;             else XB_SPIN(xb_ld(&bar[XB_TOPGEN]) == tg, bar);
;             __builtin_amdgcn_fence(__ATOMIC_ACQUIRE, "agent");
;             xb_add(&bar[XB_XGEN(b.x)], 1u);
;             asm volatile("s_waitcnt vmcnt(0)" ::: "memory");
;         } else {
;             XB_SPIN(xb_ld(&bar[XB_XGEN(b.x)]) == gen, bar);
.LBB0_29:
	s_or_b64 exec, exec, s[12:13]
	v_cvt_f32_u32_e32 v4, v2
	s_waitcnt vmcnt(0)
	v_readfirstlane_b32 s10, v3
	v_sub_u32_e32 v3, 0, v2
	v_rcp_iflag_f32_e32 v4, v4
	v_add_u32_e32 v5, s10, v1
	v_mul_f32_e32 v4, 0x4f7ffffe, v4
	v_cvt_u32_f32_e32 v4, v4
	v_mul_lo_u32 v1, v3, v4
	v_mul_hi_u32 v1, v4, v1
	v_add_u32_e32 v1, v4, v1
	v_mul_hi_u32 v1, v5, v1
	v_mul_lo_u32 v3, v1, v2
	v_sub_u32_e32 v3, v5, v3
	v_add_u32_e32 v4, 1, v1
	v_cmp_ge_u32_e32 vcc, v3, v2
	s_nop 1
	v_cndmask_b32_e32 v1, v1, v4, vcc
	v_sub_u32_e32 v4, v3, v2
	v_cndmask_b32_e32 v3, v3, v4, vcc
	v_add_u32_e32 v4, 1, v1
	v_cmp_ge_u32_e32 vcc, v3, v2
	v_add_u32_e32 v3, 1, v5
	s_nop 0
	v_cndmask_b32_e32 v1, v1, v4, vcc
	v_mul_lo_u32 v4, v2, v1
	v_add_u32_e32 v2, v4, v2
	v_cmp_ne_u32_e32 vcc, v3, v2
	s_and_saveexec_b64 s[10:11], vcc
	s_xor_b64 s[10:11], exec, s[10:11]
	s_cbranch_execz .LBB0_43
	s_waitcnt lgkmcnt(0)
	v_mov_b32_e32 v0, 0x2000
	global_load_dword v0, v0, s[8:9] offset:1024 sc1
	s_add_u32 s16, s8, 0x2400
	s_addc_u32 s17, s9, 0
	s_waitcnt vmcnt(0)
	v_cmp_eq_u32_e32 vcc, v0, v1
	s_and_saveexec_b64 s[12:13], vcc
	s_cbranch_execz .LBB0_42
	s_add_u32 s14, s6, 0x380200
	s_addc_u32 s15, s7, 0
	s_mov_b32 s28, 1
	s_mov_b64 s[18:19], 0
	s_branch .LBB0_33
	.p2align	6

.LBB0_33:
	s_and_b32 s24, s28, 0xff
	s_mov_b64 s[22:23], -1
	s_cmp_lg_u32 s24, 0
	s_mov_b64 s[26:27], -1
	s_sleep 1
	s_cbranch_scc0 .LBB0_36
	s_and_b64 vcc, exec, s[26:27]
	s_cbranch_vccz .LBB0_32
	.p2align	6

; __device__ __forceinline__ unsigned xb_ld(unsigned* p)              { return __hip_atomic_load(p, __ATOMIC_RELAXED, __HIP_MEMORY_SCOPE_AGENT); }
; __device__ __forceinline__ unsigned xb_add(unsigned* p, unsigned v) { return __hip_atomic_fetch_add(p, v, __ATOMIC_RELAXED, __HIP_MEMORY_SCOPE_AGENT); }
; #define XB_SPIN(cond, bar) do { unsigned _sp = 0; while (cond) { __builtin_amdgcn_s_sleep(1); \
;     if ((++_sp & 255u) == 0u) { if (xb_ld(&(bar)[XB_TMO])) break; if (_sp > XB_SPIN_CAP) { atomicAdd(&(bar)[XB_TMO], 1u); break; } } } } while (0)
; __device__ __forceinline__ void xcd_barrier(const XcdBarrier& b) {
;     ...
;             const unsigned og = xb_add(&bar[XB_TOP], 1u);
;             const unsigned tg = og / nx;
;             if (og + 1u == (tg + 1u) * nx) xb_add(&bar[XB_TOPGEN], 1u);
;             else XB_SPIN(xb_ld(&bar[XB_TOPGEN]) == tg, bar);
.LBB0_46:
	s_or_b64 exec, exec, s[12:13]
	v_cvt_f32_u32_e32 v3, v0
	s_waitcnt vmcnt(0)
	v_readfirstlane_b32 s10, v2
	s_mov_b64 s[14:15], -1
	v_rcp_iflag_f32_e32 v3, v3
	v_add_u32_e32 v1, s10, v1
	v_add_u32_e32 v4, 1, v1
	s_add_u32 s10, s6, 0x383500
	v_mul_f32_e32 v2, 0x4f7ffffe, v3
	v_cvt_u32_f32_e32 v2, v2
	v_sub_u32_e32 v3, 0, v0
	s_addc_u32 s11, s7, 0
	v_mul_lo_u32 v3, v3, v2
	v_mul_hi_u32 v3, v2, v3
	v_add_u32_e32 v2, v2, v3
	v_mul_hi_u32 v2, v1, v2
	v_mul_lo_u32 v3, v2, v0
	v_sub_u32_e32 v1, v1, v3
	v_add_u32_e32 v5, 1, v2
	v_cmp_ge_u32_e32 vcc, v1, v0
	v_sub_u32_e32 v3, v1, v0
	s_nop 0
	v_cndmask_b32_e32 v2, v2, v5, vcc
	v_cndmask_b32_e32 v1, v1, v3, vcc
	v_add_u32_e32 v3, 1, v2
	v_cmp_ge_u32_e32 vcc, v1, v0
	s_nop 1
	v_cndmask_b32_e32 v2, v2, v3, vcc
	v_mul_lo_u32 v1, v0, v2
	v_add_u32_e32 v0, v1, v0
	v_cmp_ne_u32_e32 vcc, v4, v0
	v_mov_b64_e32 v[0:1], s[10:11]
	s_and_saveexec_b64 s[12:13], vcc
	s_cbranch_execz .LBB0_58
	global_load_dword v0, v161, s[10:11] sc1
	s_mov_b64 s[18:19], 0
	s_waitcnt vmcnt(0)
	v_cmp_eq_u32_e32 vcc, v0, v2
	s_and_saveexec_b64 s[16:17], vcc
	s_cbranch_execz .LBB0_57
	s_add_u32 s14, s6, 0x380200
	s_addc_u32 s15, s7, 0
	s_mov_b32 s26, 1
	s_mov_b64 s[6:7], 0
	s_branch .LBB0_50
	.p2align	6

.LBB0_50:
	s_and_b32 s22, s26, 0xff
	s_mov_b64 s[20:21], -1
	s_cmp_lg_u32 s22, 0
	s_mov_b64 s[24:25], -1
	s_sleep 1
	s_cbranch_scc0 .LBB0_53
	s_and_b64 vcc, exec, s[24:25]
	s_cbranch_vccz .LBB0_49
	.p2align	6

; #define LAS __attribute__((address_space(3)))
; __device__ __forceinline__ unsigned xb_xcc_id() { return (unsigned)__builtin_amdgcn_s_getreg((3 << 11) | 20) & 0xFu; }
; DI KArgP launder(KArgP p) { asm volatile("" : "+s"(p)); return p; }
; __global__ void __launch_bounds__(512, 2) fwd_kernel(Args a_unused) {
;     ...
;         if (p > ph_lo && coop) { if (p == ph_lo + 1) grid.sync(); else { XcdBarrier b2; b2.bar = (unsigned*)(launder(kp)->ws + WS_CTL); b2.x = xb_xcc_id(); b2.st = (volatile LAS unsigned*)((LAS unsigned char*)lds + (LDS_BYTES - 64)); xcd_barrier(b2); } }
.LBB0_71:
	s_or_b64 exec, exec, s[8:9]
	global_load_dword v2, v161, s[6:7] offset:32 sc1
	v_and_b32_e32 v0, 0xffff0000, v1
	s_waitcnt vmcnt(0)
	v_and_b32_e32 v1, 0xffff0000, v2
	v_cmp_eq_u32_e32 vcc, v1, v0
	s_and_b64 exec, exec, vcc
	s_cbranch_execz .LBB0_74
	s_mov_b64 s[8:9], 0
	.p2align	6

; #define PG8_LAS __attribute__((address_space(3)))
; DI KArgP launder(KArgP p) { asm volatile("" : "+s"(p)); return p; }
; #define SSA WSP(float, WS_SSA)
; #define SSB WSP(float, WS_SSB)
; DI void act_fixup(const Args& a, int l, int gtid, int ngt) {
;     bf16_t* ACT = (bf16_t*)(a.ws + WS_Z1); const float* sb = (const float*)(a.ws + WS_SB); const float* cw = a.in[17] + (size_t)l * 3 * DFF;
;     for (int idx = gtid; idx < 128 * 2 * DFF; idx += ngt) { const int c = idx % DFF, rr = idx / DFF, r = rr & 1, pm = rr >> 1, row = pm * 256 + r, tt = row & (SEQ - 1);
; __global__ void __launch_bounds__(512, 2) fwd_kernel(Args a_unused) {
;     ...
;         const Args a = load_args(launder(kp)); int tid = threadIdx.x; asm volatile("" : "+v"(tid)); int G = gridDim.x; asm volatile("" : "+s"(G)); const int bid = blockIdx.x, ngw = G * 8, ngt = G * 512;
;         const int lane = tid & 63, wave = __builtin_amdgcn_readfirstlane(tid >> 6), gw = bid * 8 + wave, gtid = bid * 512 + tid; float* scr = (float*)(lds + wave * 8448);
;         PG8_LAS unsigned char* glds = (PG8_LAS unsigned char*)lds;
;         const int l = (p == 0) ? 0 : (p - 1) / PPL, k = (p == 0) ? -1 : (p - 1) % PPL;
;         float* ss1 = SSA; float* ss2 = SSB; float* ss3 = SSA;
;         bool is_gemm = false; pg8::Gemm g{nullptr, nullptr, MROWS, 0, 0, 0, 0, 0}; pg8::EpiAny E{0, nullptr, 0, 0, nullptr, nullptr, nullptr, nullptr, nullptr};
;         switch (k) {
.LBB0_76:
.LBB0_77:
	v_readlane_b32 s0, v253, 2
	v_readlane_b32 s6, v253, 0
	v_readlane_b32 s1, v253, 3
	v_mov_b32_e32 v225, v163
	s_mov_b32 s52, s6
	s_load_dwordx16 s[8:23], s[0:1], 0x0
	v_readlane_b32 s7, v253, 1
	s_load_dwordx2 s[6:7], s[0:1], 0xa0
	s_mov_b32 s96, 0x358637bd
	v_readfirstlane_b32 s33, v225
	s_waitcnt lgkmcnt(0)
	v_writelane_b32 v253, s8, 35
	s_mov_b64 s[78:79], 0
	s_mov_b64 s[82:83], 0
	v_writelane_b32 v253, s9, 36
	v_writelane_b32 v253, s10, 37
	v_writelane_b32 v253, s11, 38
	v_writelane_b32 v253, s12, 39
	v_writelane_b32 v253, s13, 40
	v_writelane_b32 v253, s14, 41
	v_writelane_b32 v253, s15, 42
	v_writelane_b32 v253, s16, 43
	v_writelane_b32 v253, s17, 44
	v_writelane_b32 v253, s18, 45
	v_writelane_b32 v253, s19, 46
	v_writelane_b32 v253, s20, 47
	v_writelane_b32 v253, s21, 48
	v_writelane_b32 v253, s22, 49
	v_writelane_b32 v253, s23, 50
	s_load_dwordx16 s[8:23], s[0:1], 0x40
	s_waitcnt lgkmcnt(0)
	v_writelane_b32 v253, s8, 51
	s_nop 1
	v_writelane_b32 v253, s9, 52
	v_writelane_b32 v253, s10, 53
	v_writelane_b32 v253, s11, 54
	v_writelane_b32 v253, s12, 55
	v_writelane_b32 v253, s13, 56
	v_writelane_b32 v254, s21, 0
	v_writelane_b32 v253, s14, 57
	v_writelane_b32 v254, s22, 1
	v_writelane_b32 v253, s15, 58
	v_writelane_b32 v254, s23, 2
	s_load_dwordx8 s[8:15], s[0:1], 0x80
	v_writelane_b32 v254, s6, 3
	s_add_i32 s0, s29, -1
	s_mul_hi_i32 s1, s0, 0x38e38e39
	v_writelane_b32 v254, s7, 4
	s_waitcnt lgkmcnt(0)
	v_writelane_b32 v254, s8, 5
	v_writelane_b32 v253, s16, 59
	s_lshr_b32 s6, s1, 31
	v_writelane_b32 v254, s9, 6
	v_writelane_b32 v254, s10, 7
	v_writelane_b32 v254, s11, 8
	v_writelane_b32 v254, s12, 9
	v_writelane_b32 v254, s13, 10
	v_writelane_b32 v254, s14, 11
	s_ashr_i32 s1, s1, 1
	v_writelane_b32 v253, s17, 60
	v_writelane_b32 v254, s15, 12
	s_add_i32 s8, s1, s6
	v_writelane_b32 v253, s18, 61
	v_writelane_b32 v254, s29, 13
	s_mov_b32 s6, s8
	s_mul_i32 s1, s8, 9
	v_writelane_b32 v253, s19, 62
	v_writelane_b32 v254, s6, 14
	s_sub_i32 s63, s0, s1
	v_writelane_b32 v253, s20, 63
	v_writelane_b32 v254, s7, 15
	s_cmp_lt_i32 s63, 3
	s_mov_b64 s[0:1], -1
	s_mov_b64 s[16:17], 0
	s_cbranch_scc1 .LBB0_106
	s_mov_b64 s[18:19], 0
	s_cmp_gt_i32 s63, 4
	s_cbranch_scc0 .LBB0_96
	v_readlane_b32 s0, v254, 3
	v_readlane_b32 s1, v254, 4
	s_add_u32 s20, s0, 0x20280000
	s_addc_u32 s21, s1, 0
	s_mov_b64 s[0:1], -1
	s_mov_b64 s[22:23], 0
	s_cmp_gt_i32 s63, 5
	s_cbranch_scc0 .LBB0_94
	s_cmp_gt_i32 s63, 6
	s_cbranch_scc0 .LBB0_91
	s_cmp_eq_u32 s63, 7
	s_mov_b64 s[82:83], -1
	s_cbranch_scc0 .LBB0_90
	v_readlane_b32 s0, v253, 12
	s_nop 1
	v_add_u32_e32 v8, s0, v225
	s_mov_b32 s0, 0xb0000
	v_cmp_gt_i32_e32 vcc, s0, v8
	s_and_saveexec_b64 s[0:1], vcc
	s_cbranch_execz .LBB0_89
	v_readlane_b32 s8, v254, 3
	v_readlane_b32 s9, v254, 4
	s_add_u32 s6, s8, 0x7100000
	s_addc_u32 s7, s9, 0
	v_readlane_b32 s10, v254, 14
	s_add_u32 s8, s8, 0x1c680000
	v_readlane_b32 s11, v254, 15
	v_readlane_b32 s24, v254, 5
	s_addc_u32 s9, s9, 0
	s_mul_hi_i32 s11, s10, 0x8400
	s_mul_i32 s10, s10, 0x8400
	v_readlane_b32 s26, v254, 7
	v_readlane_b32 s27, v254, 8
	s_add_u32 s10, s26, s10
	s_addc_u32 s11, s27, s11
	s_lshl_b32 s24, s52, 9
	s_mov_b64 s[12:13], 0
	v_mov_b64_e32 v[0:1], s[8:9]
	v_readlane_b32 s25, v254, 6
	v_readlane_b32 s28, v254, 9
	v_readlane_b32 s29, v254, 10
	v_readlane_b32 s30, v254, 11
	v_readlane_b32 s31, v254, 12
	s_branch .LBB0_85
	.p2align	6

; #define PG8_LAS __attribute__((address_space(3)))
; DI KArgP launder(KArgP p) { asm volatile("" : "+s"(p)); return p; }
; __global__ void __launch_bounds__(512, 2) fwd_kernel(Args a_unused) {
;     ...
;         const Args a = load_args(launder(kp)); int tid = threadIdx.x; asm volatile("" : "+v"(tid)); int G = gridDim.x; asm volatile("" : "+s"(G)); const int bid = blockIdx.x, ngw = G * 8, ngt = G * 512;
;         const int lane = tid & 63, wave = __builtin_amdgcn_readfirstlane(tid >> 6), gw = bid * 8 + wave, gtid = bid * 512 + tid; float* scr = (float*)(lds + wave * 8448);
;         PG8_LAS unsigned char* glds = (PG8_LAS unsigned char*)lds;
;         const int l = (p == 0) ? 0 : (p - 1) / PPL, k = (p == 0) ? -1 : (p - 1) % PPL;
;     ...
;         case 2:
;             for (int pr0 = bid; pr0 < NB * 2 * 32; pr0 += G) {
;                 int pr = pr0; if (G == 256) { const int k = pr0 >> 8, x = pr0 & 7, slot = (pr0 >> 3) & 31; pr = ((x + 8 * k) << 5) | slot; }
;                 const int b = pr >> 6, gg = (pr >> 5) & 1, tb = pr & 31;
;                 nsa_wg_unit(a, l, b, gg, tb, lds, tid, true); nsa_wg_unit(a, l, b, gg, 63 - tb, lds, tid, false); }
.LBB0_106:
	s_lshl_b32 s38, s52, 3
	v_writelane_b32 v254, s38, 16
	v_writelane_b32 v254, s52, 17
	s_and_b64 vcc, exec, s[0:1]
	v_writelane_b32 v254, s63, 18
	s_cbranch_vccz .LBB0_272
	s_ashr_i32 s1, s33, 6
	v_readlane_b32 s0, v253, 33
	s_add_i32 s0, s1, s0
	v_and_b32_e32 v166, 63, v225
	v_writelane_b32 v254, s0, 19
	s_mul_i32 s0, s1, 0x2100
	v_writelane_b32 v254, s1, 20
	s_add_i32 s0, s0, 0
	v_writelane_b32 v254, s0, 21
	s_cmp_gt_i32 s63, 0
	s_mov_b64 s[0:1], -1
	s_mov_b32 s70, 0x358637bd
	s_mov_b64 s[72:73], 0x1e30
	s_cbranch_scc0 .LBB0_481
	s_cmp_gt_i32 s63, 1
	s_cbranch_scc0 .LBB0_275
	v_writelane_b32 v254, s82, 22
	v_readlane_b32 s0, v253, 13
	v_readlane_b32 s1, v253, 14
	v_writelane_b32 v254, s83, 23
	v_writelane_b32 v254, s78, 24
	s_andn2_b64 vcc, exec, s[0:1]
	s_movk_i32 s22, 0x90
	v_writelane_b32 v254, s79, 25
	s_mov_b32 s25, 0x42800000
	v_readlane_b32 s26, v253, 27
	s_movk_i32 s27, 0x88
	v_readlane_b32 s28, v253, 28
	s_cbranch_vccnz .LBB0_274
	s_cmpk_eq_i32 s52, 0x100
	s_cselect_b64 s[0:1], -1, 0
	v_writelane_b32 v254, s0, 26
	v_readlane_b32 s36, v253, 35
	v_readlane_b32 s44, v253, 43
	v_writelane_b32 v254, s1, 27
	v_readlane_b32 s45, v253, 44
	v_readlane_b32 s8, v254, 3
	v_readlane_b32 s9, v254, 4
	s_add_u32 s0, s8, 0x7100000
	v_writelane_b32 v254, s0, 28
	s_addc_u32 s0, s9, 0
	v_writelane_b32 v254, s0, 29
	s_add_u32 s0, s8, 0x280000
	v_writelane_b32 v254, s0, 30
	s_addc_u32 s0, s9, 0
	v_writelane_b32 v254, s0, 31
	s_add_u32 s0, s8, 0x6100000
	v_writelane_b32 v254, s0, 32
	s_addc_u32 s0, s9, 0
	v_writelane_b32 v254, s0, 34
	s_add_u32 s0, s8, 0x1a280000
	v_writelane_b32 v254, s0, 36
	s_addc_u32 s0, s9, 0
	v_writelane_b32 v254, s0, 37
	s_add_u32 s0, s8, 0x200000
	v_writelane_b32 v254, s0, 38
	s_addc_u32 s0, s9, 0
	v_writelane_b32 v254, s0, 39
	v_readlane_b32 s37, v253, 36
	v_readlane_b32 s0, v254, 14
	v_readlane_b32 s1, v254, 15
	s_mov_b32 s6, s0
	s_ashr_i32 s7, s0, 31
	v_writelane_b32 v254, s0, 14
	v_readlane_b32 s38, v253, 37
	v_readlane_b32 s39, v253, 38
	v_writelane_b32 v254, s1, 15
	s_lshl_b64 s[0:1], s[6:7], 10
	s_add_u32 s90, s44, s0
	s_addc_u32 s91, s45, s1
	s_add_u32 s0, s8, 0x68ffc80
	v_writelane_b32 v254, s0, 40
	s_addc_u32 s0, s9, 0
	v_writelane_b32 v254, s0, 41
	s_add_u32 s0, s8, 0x6d44000
	v_writelane_b32 v254, s0, 42
	s_addc_u32 s0, s9, 0
	v_writelane_b32 v254, s0, 43
	s_add_u32 s0, s8, 0x7101400
	v_writelane_b32 v254, s0, 44
	s_addc_u32 s0, s9, 0
	v_writelane_b32 v254, s0, 45
	s_add_u32 s0, s8, 0x6900000
	v_writelane_b32 v254, s0, 46
	s_addc_u32 s0, s9, 0
	v_writelane_b32 v254, s0, 47
	s_mov_b32 s7, s2
	v_readlane_b32 s40, v253, 39
	v_readlane_b32 s41, v253, 40
	v_readlane_b32 s42, v253, 41
	v_readlane_b32 s43, v253, 42
	v_readlane_b32 s46, v253, 45
	v_readlane_b32 s47, v253, 46
	v_readlane_b32 s48, v253, 47
	v_readlane_b32 s49, v253, 48
	v_readlane_b32 s50, v253, 49
	v_readlane_b32 s51, v253, 50
	s_branch .LBB0_112
	.p2align	6

; DI void nsa_wg_unit(const Args& a, int l, int b, int g, int tb, unsigned char* lds, int tid_in, bool stage) {
;     ...
;     const int rl = lane & 31, h = lane >> 5, head = rl & 3, t0 = tb * 64 + wave * 8, jt = tb;
;     int tk[NRT]; tk[0] = t0 + (rl >> 2);
;     const bf16_t* zb = Z1 + (size_t)b * SEQ * ZP;
;     LP L = (LP)lds;
;     __syncthreads();
;     if (stage) {
;     for (int i = tid; i < 2048; i += 512) { const int row = i >> 3, ch = i & 7; *(u32x4*)(lds + AL_KC + row * KC_PB + ch * 16) = *(const u32x4*)(KC + row * 64 + ch * 8); }
;     for (int i = tid; i < 2048; i += 512) { const int row = i >> 5, ch = i & 31; const u32x4 v = *(const u32x4*)(VCT + row * 256 + ch * 8); u32x2* d = (u32x2*)(lds + AL_VC + row * VC_PB + ch * 16); u32x2 lo, hi; lo.x = v.x; lo.y = v.y; hi.x = v.z; hi.y = v.w; d[0] = lo; d[1] = hi; }
;     }
;     bf16x8 qf[NRT][4]; float gt[NRT][3]; bf16_t* orow[NRT];
;     { const bf16_t* zr = zb + (size_t)tk[0] * ZP;
; #pragma unroll
;       for (int dc = 0; dc < 4; ++dc) qf[0][dc] = *(const bf16x8*)(zr + C_Q + (g * 4 + head) * 64 + dc * 16 + 8 * h);
;       { const float* qg = a.in[4] + (size_t)l * 4 * 64; float qv[4][8]; float qs = 0.f;
; #pragma unroll
;         for (int dc = 0; dc < 4; ++dc) { unpack8(__builtin_bit_cast(u32x4, qf[0][dc]), qv[dc]);
; #pragma unroll
;             for (int e = 0; e < 8; ++e) qs += qv[dc][e] * qv[dc][e]; }
;         qs += __shfl_xor(qs, 32); const float rs = rsqrtf(qs * (1.0f / 64.0f) + 1e-6f) * QSC;
; #pragma unroll
;         for (int dc = 0; dc < 4; ++dc) { const f32x4 g0 = *(const f32x4*)(qg + dc * 16 + 8 * h), g1 = *(const f32x4*)(qg + dc * 16 + 8 * h + 4);
; #pragma unroll
;             for (int e = 0; e < 4; ++e) { qv[dc][e] = qv[dc][e] * rs * g0[e]; qv[dc][4 + e] = qv[dc][4 + e] * rs * g1[e]; }
;             qf[0][dc] = __builtin_bit_cast(bf16x8, pack8(qv[dc])); } }
; #pragma unroll
;       for (int br = 0; br < 3; ++br) gt[0][br] = 1.0f / (1.0f + __expf(-bf1(zr[C_NG + (g * 4 + head) * 3 + br])));
;       orow[0] = OB + ((size_t)b * SEQ + tk[0]) * 512 + (g * 4 + head) * 64 + 4 * h; }
;     float cref[3];
;     { const float* qg = a.in[4] + (size_t)l * 4 * 64; float mx[4];
; #pragma unroll
;       for (int k4 = 0; k4 < 4; ++k4) { float v = fabsf(qg[k4 * 64 + lane]);
; #pragma unroll
;           for (int o = 1; o < 64; o <<= 1) v = fmaxf(v, __shfl_xor(v, o));
;           mx[k4] = v; }
; #pragma unroll
.LBB0_117:
	s_or_b64 exec, exec, s[0:1]
	s_and_b32 s33, s11, 31
	s_ashr_i32 s0, s10, 6
	s_lshl_b32 s1, s33, 6
	s_lshl_b32 s18, s0, 3
	v_writelane_b32 v254, s1, 51
	s_mul_i32 s6, s30, 0x2230000
	s_add_i32 s93, s18, s1
	v_readlane_b32 s1, v254, 28
	v_writelane_b32 v254, s6, 52
	s_mul_hi_i32 s2, s30, 0x2230000
	s_add_u32 s36, s1, s6
	v_readlane_b32 s1, v254, 29
	v_and_b32_e32 v33, 3, v71
	v_lshrrev_b32_e32 v74, 2, v70
	s_addc_u32 s37, s1, s2
	s_lshl_b32 s34, s24, 8
	v_or_b32_e32 v136, s93, v74
	v_mov_b64_e32 v[0:1], s[36:37]
	v_lshl_or_b32 v62, v33, 6, s34
	v_bfe_u32 v75, v71, 5, 1
	v_mad_i64_i32 v[80:81], s[6:7], v136, s3, v[0:1]
	v_lshlrev_b32_e32 v160, 1, v62
	v_lshl_add_u64 v[0:1], v[80:81], 0, v[160:161]
	v_lshlrev_b32_e32 v60, 4, v75
	v_mov_b32_e32 v61, v161
	v_lshl_add_u64 v[0:1], v[0:1], 0, v[60:61]
	global_load_dwordx4 v[76:79], v[0:1], off offset:3072
	global_load_dwordx4 v[64:67], v[0:1], off offset:3104
	global_load_dwordx4 v[50:53], v[0:1], off offset:3136
	global_load_dwordx4 v[42:45], v[0:1], off offset:3168
	s_lshl_b32 s29, s24, 2
	v_and_b32_e32 v149, 64, v217
	v_xor_b32_e32 v0, 32, v217
	v_add_u32_e32 v61, 64, v149
	v_cmp_lt_i32_e32 vcc, v0, v61
	s_mov_b64 s[6:7], 0x1600
	v_and_b32_e32 v73, 63, v71
	v_cndmask_b32_e32 v0, v217, v0, vcc
	v_and_b32_e32 v4, 32, v71
	v_lshlrev_b32_e32 v148, 2, v0
	global_load_dwordx4 v[24:27], v4, s[90:91] offset:16
	global_load_dwordx4 v[28:31], v4, s[90:91]
	global_load_dwordx4 v[16:19], v4, s[90:91] offset:80
	global_load_dwordx4 v[20:23], v4, s[90:91] offset:64
	global_load_dwordx4 v[8:11], v4, s[90:91] offset:144
	global_load_dwordx4 v[12:15], v4, s[90:91] offset:128
	global_load_dwordx4 v[0:3], v4, s[90:91] offset:208
	s_nop 0
	global_load_dwordx4 v[4:7], v4, s[90:91] offset:192
	s_mulk_i32 s0, 0x1080
	s_add_i32 s8, s0, 0
	s_add_i32 s9, s8, 0x19e00
	v_writelane_b32 v254, s2, 53
	v_ashrrev_i32_e32 v137, 31, v136
	v_lshlrev_b32_e32 v72, 3, v75
	s_mov_b64 s[0:1], 0
	s_movk_i32 s23, 0x3cf
	s_waitcnt vmcnt(0)
	v_lshlrev_b32_e32 v68, 16, v76
	v_and_b32_e32 v69, 0xffff0000, v76
	s_waitcnt vmcnt(9)
	v_lshlrev_b32_e32 v46, 16, v52
	s_waitcnt vmcnt(8)
	v_lshlrev_b32_e32 v36, 16, v43
	v_and_b32_e32 v37, 0xffff0000, v43
	v_lshlrev_b32_e32 v40, 16, v42
	v_and_b32_e32 v41, 0xffff0000, v42
	v_lshlrev_b32_e32 v42, 16, v53
	v_and_b32_e32 v43, 0xffff0000, v53
	v_and_b32_e32 v47, 0xffff0000, v52
	v_lshlrev_b32_e32 v52, 16, v65
	v_and_b32_e32 v53, 0xffff0000, v65
	v_lshlrev_b32_e32 v56, 16, v64
	v_and_b32_e32 v57, 0xffff0000, v64
	v_lshlrev_b32_e32 v64, 16, v77
	v_and_b32_e32 v65, 0xffff0000, v77
	v_pk_mul_f32 v[76:77], v[68:69], v[68:69]
	v_pk_mul_f32 v[108:109], v[64:65], v[64:65]
	v_add_f32_e32 v32, v76, v77
	v_lshlrev_b32_e32 v34, 16, v45
	v_and_b32_e32 v35, 0xffff0000, v45
	v_lshlrev_b32_e32 v38, 16, v44
	v_and_b32_e32 v39, 0xffff0000, v44
	v_lshlrev_b32_e32 v44, 16, v51
	v_and_b32_e32 v45, 0xffff0000, v51
	v_lshlrev_b32_e32 v48, 16, v50
	v_and_b32_e32 v49, 0xffff0000, v50
	v_lshlrev_b32_e32 v50, 16, v67
	v_and_b32_e32 v51, 0xffff0000, v67
	v_lshlrev_b32_e32 v54, 16, v66
	v_and_b32_e32 v55, 0xffff0000, v66
	v_lshlrev_b32_e32 v66, 16, v78
	v_and_b32_e32 v67, 0xffff0000, v78
	v_add_f32_e32 v32, v108, v32
	v_lshlrev_b32_e32 v58, 16, v79
	v_and_b32_e32 v59, 0xffff0000, v79
	v_pk_mul_f32 v[78:79], v[66:67], v[66:67]
	v_add_f32_e32 v32, v109, v32
	v_add_f32_e32 v32, v78, v32
	v_pk_mul_f32 v[106:107], v[58:59], v[58:59]
	v_add_f32_e32 v32, v79, v32
	v_add_f32_e32 v32, v106, v32
	v_pk_mul_f32 v[104:105], v[56:57], v[56:57]
	v_add_f32_e32 v32, v107, v32
	v_add_f32_e32 v32, v104, v32
	v_pk_mul_f32 v[100:101], v[52:53], v[52:53]
	v_add_f32_e32 v32, v105, v32
	v_add_f32_e32 v32, v100, v32
	v_pk_mul_f32 v[102:103], v[54:55], v[54:55]
	v_add_f32_e32 v32, v101, v32
	v_add_f32_e32 v32, v102, v32
	v_pk_mul_f32 v[98:99], v[50:51], v[50:51]
	v_add_f32_e32 v32, v103, v32
	v_add_f32_e32 v32, v98, v32
	v_pk_mul_f32 v[96:97], v[48:49], v[48:49]
	v_add_f32_e32 v32, v99, v32
	v_add_f32_e32 v32, v96, v32
	v_pk_mul_f32 v[92:93], v[44:45], v[44:45]
	v_add_f32_e32 v32, v97, v32
	v_add_f32_e32 v32, v92, v32
	v_pk_mul_f32 v[94:95], v[46:47], v[46:47]
	v_add_f32_e32 v32, v93, v32
	v_add_f32_e32 v32, v94, v32
	v_pk_mul_f32 v[90:91], v[42:43], v[42:43]
	v_add_f32_e32 v32, v95, v32
	v_add_f32_e32 v32, v90, v32
	v_pk_mul_f32 v[88:89], v[40:41], v[40:41]
	v_add_f32_e32 v32, v91, v32
	v_add_f32_e32 v32, v88, v32
	v_pk_mul_f32 v[84:85], v[36:37], v[36:37]
	v_add_f32_e32 v32, v89, v32
	v_add_f32_e32 v32, v84, v32
	v_pk_mul_f32 v[86:87], v[38:39], v[38:39]
	v_add_f32_e32 v32, v85, v32
	v_add_f32_e32 v32, v86, v32
	v_pk_mul_f32 v[82:83], v[34:35], v[34:35]
	v_add_f32_e32 v32, v87, v32
	v_add_f32_e32 v32, v82, v32
	v_add_f32_e32 v76, v83, v32
	v_or_b32_e32 v32, s29, v33
	v_mul_u32_u24_e32 v32, 3, v32
	v_lshlrev_b32_e32 v160, 1, v32
	v_lshl_add_u64 v[78:79], v[80:81], 0, v[160:161]
	v_lshl_add_u64 v[80:81], v[78:79], 0, s[6:7]
	v_add_co_u32_e32 v78, vcc, s85, v78
	ds_bpermute_b32 v77, v148, v76
	s_nop 0
	v_addc_co_u32_e32 v79, vcc, 0, v79, vcc
	global_load_dword v32, v[78:79], off offset:1536
	global_load_ushort v139, v[80:81], off offset:4
	v_lshlrev_b32_e32 v80, 2, v73
	global_load_dword v63, v80, s[90:91]
	global_load_dword v81, v80, s[90:91] offset:768
	global_load_dword v206, v80, s[90:91] offset:256
	global_load_dword v207, v80, s[90:91] offset:512
	v_xor_b32_e32 v79, 1, v217
	v_cmp_lt_i32_e32 vcc, v79, v61
	s_waitcnt vmcnt(3)
	v_and_b32_e32 v78, 0x7fffffff, v63
	v_cndmask_b32_e32 v79, v217, v79, vcc
	v_lshlrev_b32_e32 v152, 2, v79
	ds_bpermute_b32 v78, v152, v78
	v_max_f32_e64 v63, |v63|, |v63|
	s_waitcnt vmcnt(2)
; DI float bf1(bf16_t v) { return __uint_as_float(((unsigned)v) << 16); }
; DI u32x4 pack8(const float (&f)[8]) { u32x4 w; w.x = cvtpk(f[0], f[1]); w.y = cvtpk(f[2], f[3]); w.z = cvtpk(f[4], f[5]); w.w = cvtpk(f[6], f[7]); return w; }
; DI void nsa_wg_unit(const Args& a, int l, int b, int g, int tb, unsigned char* lds, int tid_in, bool stage) {
;     ...
;         qs += __shfl_xor(qs, 32); const float rs = rsqrtf(qs * (1.0f / 64.0f) + 1e-6f) * QSC;
; #pragma unroll
;         for (int dc = 0; dc < 4; ++dc) { const f32x4 g0 = *(const f32x4*)(qg + dc * 16 + 8 * h), g1 = *(const f32x4*)(qg + dc * 16 + 8 * h + 4);
; #pragma unroll
;             for (int e = 0; e < 4; ++e) { qv[dc][e] = qv[dc][e] * rs * g0[e]; qv[dc][4 + e] = qv[dc][4 + e] * rs * g1[e]; }
;             qf[0][dc] = __builtin_bit_cast(bf16x8, pack8(qv[dc])); } }
; #pragma unroll
;       for (int br = 0; br < 3; ++br) gt[0][br] = 1.0f / (1.0f + __expf(-bf1(zr[C_NG + (g * 4 + head) * 3 + br])));
;       orow[0] = OB + ((size_t)b * SEQ + tk[0]) * 512 + (g * 4 + head) * 64 + 4 * h; }
;     float cref[3];
;     { const float* qg = a.in[4] + (size_t)l * 4 * 64; float mx[4];
; #pragma unroll
;       for (int k4 = 0; k4 < 4; ++k4) { float v = fabsf(qg[k4 * 64 + lane]);
; #pragma unroll
;           for (int o = 1; o < 64; o <<= 1) v = fmaxf(v, __shfl_xor(v, o));
;           mx[k4] = v; }
; #pragma unroll
;       for (int br = 0; br < 3; ++br) { const float bnd = 64.0f * QSC * mx[0] * mx[1 + br]; cref[br] = bnd > 64.0f ? bnd : 0.f; } }
;     float* wl = (float*)(lds + AL_WT + wave * WT_SZ); float* IA = wl; float* IB = wl + NTOK * 65;
;     for (int i = lane; i < 2 * NTOK * 65; i += 64) wl[i] = 0.f;
;     __syncthreads();
;     AttnSt st;
;     int nv[NRT]; nv[0] = tk[0] >= 31 ? ((tk[0] - 31) >> 4) + 1 : 0;
;     const int nvmax = (t0 + NTOK - 1 >= 31) ? ((t0 + NTOK - 1 - 31) >> 4) + 1 : 0, nst = (nvmax + 31) >> 5;
;     st.l[0] = 0.f;
;     const LP kcl = L + AL_KC + rl * KC_PB + 16 * h, vcl = L + AL_VC + rl * VC_PB + 8 * h;
;     for (int T = 0; T < nst; ++T) { f32x16 s[NRT]; KV f; kv_load_lds(f, kcl + 32 * T * KC_PB, vcl + 64 * T, VC_PB); attn_scores(s, qf, f); float ps = 0.f;
	v_and_b32_e32 v82, 0x7fffffff, v81
	ds_bpermute_b32 v82, v152, v82
	v_max_f32_e64 v81, |v81|, |v81|
	s_waitcnt lgkmcnt(1)
	v_max_f32_e32 v78, v78, v78
	v_max_f32_e32 v63, v63, v78
	v_xor_b32_e32 v78, 2, v217
	v_cmp_lt_i32_e32 vcc, v78, v61
	s_waitcnt lgkmcnt(0)
	v_max_f32_e32 v82, v82, v82
	v_max_f32_e32 v81, v81, v82
	v_cndmask_b32_e32 v78, v217, v78, vcc
	v_lshlrev_b32_e32 v153, 2, v78
	ds_bpermute_b32 v78, v153, v63
	ds_bpermute_b32 v82, v153, v81
	s_waitcnt lgkmcnt(1)
	v_max_f32_e32 v78, v78, v78
	v_max_f32_e32 v63, v63, v78
	v_xor_b32_e32 v78, 4, v217
	v_cmp_lt_i32_e32 vcc, v78, v61
	s_waitcnt lgkmcnt(0)
	v_max_f32_e32 v82, v82, v82
	v_max_f32_e32 v81, v81, v82
	v_cndmask_b32_e32 v78, v217, v78, vcc
	v_lshlrev_b32_e32 v154, 2, v78
	ds_bpermute_b32 v78, v154, v63
	ds_bpermute_b32 v82, v154, v81
	s_waitcnt lgkmcnt(1)
	v_max_f32_e32 v78, v78, v78
	v_max_f32_e32 v63, v63, v78
	v_xor_b32_e32 v78, 8, v217
	v_cmp_lt_i32_e32 vcc, v78, v61
	s_waitcnt lgkmcnt(0)
	v_max_f32_e32 v82, v82, v82
	v_max_f32_e32 v81, v81, v82
	v_cndmask_b32_e32 v78, v217, v78, vcc
	v_lshlrev_b32_e32 v150, 2, v78
	ds_bpermute_b32 v78, v150, v63
	ds_bpermute_b32 v82, v150, v81
	s_waitcnt lgkmcnt(1)
	v_max_f32_e32 v78, v78, v78
	v_max_f32_e32 v63, v63, v78
	v_xor_b32_e32 v78, 16, v217
	v_cmp_lt_i32_e32 vcc, v78, v61
	s_waitcnt lgkmcnt(0)
	v_max_f32_e32 v82, v82, v82
	v_max_f32_e32 v81, v81, v82
	v_cndmask_b32_e32 v61, v217, v78, vcc
	v_lshlrev_b32_e32 v151, 2, v61
	ds_bpermute_b32 v61, v151, v63
	ds_bpermute_b32 v82, v151, v81
	s_waitcnt lgkmcnt(1)
	v_max_f32_e32 v61, v61, v61
	v_max_f32_e32 v78, v63, v61
	s_waitcnt lgkmcnt(0)
	v_max_f32_e32 v82, v82, v82
	v_max_f32_e32 v96, v81, v82
	ds_bpermute_b32 v79, v148, v78
	ds_bpermute_b32 v97, v148, v96
	v_or_b32_e32 v81, 0xffffffc0, v73
	s_waitcnt vmcnt(1)
	v_mov_b32_e32 v61, v206
	v_and_b32_e32 v63, 0x7fffffff, v61
	ds_bpermute_b32 v63, v152, v63
	v_max_f32_e64 v61, |v61|, |v61|
	s_waitcnt lgkmcnt(0)
	v_max_f32_e32 v63, v63, v63
	v_max_f32_e32 v61, v61, v63
	ds_bpermute_b32 v63, v153, v61
	s_waitcnt lgkmcnt(0)
	v_max_f32_e32 v63, v63, v63
	v_max_f32_e32 v61, v61, v63
	ds_bpermute_b32 v63, v154, v61
	s_waitcnt lgkmcnt(0)
	v_max_f32_e32 v63, v63, v63
	v_max_f32_e32 v61, v61, v63
	ds_bpermute_b32 v63, v150, v61
	s_waitcnt lgkmcnt(0)
	v_max_f32_e32 v63, v63, v63
	v_max_f32_e32 v61, v61, v63
	ds_bpermute_b32 v63, v151, v61
	s_waitcnt lgkmcnt(0)
	v_max_f32_e32 v63, v63, v63
	v_max_f32_e32 v98, v61, v63
	ds_bpermute_b32 v99, v148, v98
	v_add_u32_e32 v80, s9, v80
	s_waitcnt vmcnt(0)
	v_mov_b32_e32 v61, v207
	v_and_b32_e32 v63, 0x7fffffff, v61
	ds_bpermute_b32 v63, v152, v63
	v_max_f32_e64 v61, |v61|, |v61|
	s_waitcnt lgkmcnt(0)
	v_max_f32_e32 v63, v63, v63
	v_max_f32_e32 v61, v61, v63
	ds_bpermute_b32 v63, v153, v61
	s_waitcnt lgkmcnt(0)
	v_max_f32_e32 v63, v63, v63
	v_max_f32_e32 v61, v61, v63
	ds_bpermute_b32 v63, v154, v61
	s_waitcnt lgkmcnt(0)
	v_max_f32_e32 v63, v63, v63
	v_max_f32_e32 v61, v61, v63
	ds_bpermute_b32 v63, v150, v61
	s_waitcnt lgkmcnt(0)
	v_max_f32_e32 v63, v63, v63
	v_max_f32_e32 v61, v61, v63
	ds_bpermute_b32 v63, v151, v61
	s_waitcnt lgkmcnt(0)
	v_max_f32_e32 v63, v63, v63
	v_max_f32_e32 v61, v61, v63
	ds_bpermute_b32 v63, v148, v61
	.p2align	6
.LBB0_118:
	v_add_u32_e32 v81, 64, v81
	v_cmp_lt_u32_e32 vcc, s23, v81
	ds_write_b32 v80, v161
	s_or_b64 s[0:1], vcc, s[0:1]
	v_add_u32_e32 v80, 0x100, v80
	s_andn2_b64 exec, exec, s[0:1]
	s_cbranch_execnz .LBB0_118
	s_or_b64 exec, exec, s[0:1]
	v_add_f32_e32 v76, v76, v77
	v_fmamk_f32 v76, v76, 0x3c800000, v162
	v_mul_f32_e32 v77, 0x4b800000, v76
	v_cmp_gt_f32_e32 vcc, s71, v76
	s_sub_i32 s0, s93, 24
	s_lshr_b32 s0, s0, 4
	v_cndmask_b32_e32 v76, v76, v77, vcc
	v_rsq_f32_e32 v76, v76
	s_add_i32 s0, s0, 32
	s_or_b32 s96, s93, 7
	s_lshr_b32 s0, s0, 5
	v_mul_f32_e32 v77, 0x45800000, v76
	v_cndmask_b32_e32 v76, v76, v77, vcc
	v_mul_f32_e32 v76, 0x3e38aa3b, v76
	v_pk_mul_f32 v[66:67], v[76:77], v[66:67] op_sel_hi:[0,1]
	v_pk_mul_f32 v[24:25], v[24:25], v[66:67]
	v_pk_mul_f32 v[68:69], v[76:77], v[68:69] op_sel_hi:[0,1]
	v_cvt_pk_bf16_f32 v82, v24, v25
	v_pk_mul_f32 v[24:25], v[76:77], v[56:57] op_sel_hi:[0,1]
	v_pk_mul_f32 v[20:21], v[20:21], v[24:25]
	v_pk_mul_f32 v[24:25], v[76:77], v[54:55] op_sel_hi:[0,1]
	v_pk_mul_f32 v[16:17], v[16:17], v[24:25]
	v_pk_mul_f32 v[24:25], v[76:77], v[52:53] op_sel_hi:[0,1]
	v_cvt_pk_bf16_f32 v86, v16, v17
	v_pk_mul_f32 v[16:17], v[76:77], v[48:49] op_sel_hi:[0,1]
	v_pk_mul_f32 v[12:13], v[12:13], v[16:17]
	v_pk_mul_f32 v[16:17], v[76:77], v[46:47] op_sel_hi:[0,1]
	v_pk_mul_f32 v[8:9], v[8:9], v[16:17]
	v_pk_mul_f32 v[16:17], v[76:77], v[44:45] op_sel_hi:[0,1]
	v_cvt_pk_bf16_f32 v90, v8, v9
	v_pk_mul_f32 v[8:9], v[76:77], v[40:41] op_sel_hi:[0,1]
	v_pk_mul_f32 v[4:5], v[4:5], v[8:9]
	v_pk_mul_f32 v[8:9], v[76:77], v[38:39] op_sel_hi:[0,1]
	v_pk_mul_f32 v[0:1], v[0:1], v[8:9]
	v_pk_mul_f32 v[8:9], v[76:77], v[36:37] op_sel_hi:[0,1]
	v_pk_mul_f32 v[6:7], v[6:7], v[8:9]
	v_pk_mul_f32 v[8:9], v[76:77], v[34:35] op_sel_hi:[0,1]
	v_pk_mul_f32 v[2:3], v[2:3], v[8:9]
	v_cvt_pk_bf16_f32 v94, v0, v1
	v_max_f32_e32 v0, v79, v79
	v_max_f32_e32 v1, v78, v78
	v_cvt_pk_bf16_f32 v95, v2, v3
	v_max_f32_e32 v0, v1, v0
	v_max_f32_e32 v1, v99, v99
	v_max_f32_e32 v2, v98, v98
	v_max_f32_e32 v1, v2, v1
	v_mul_f32_e32 v157, 0x4138aa3b, v0
	v_mul_f32_e32 v0, v157, v1
	v_cmp_lt_f32_e32 vcc, s25, v0
	v_pk_mul_f32 v[64:65], v[76:77], v[64:65] op_sel_hi:[0,1]
	v_pk_mul_f32 v[58:59], v[76:77], v[58:59] op_sel_hi:[0,1]
	v_pk_mul_f32 v[22:23], v[22:23], v[24:25]
	v_pk_mul_f32 v[24:25], v[76:77], v[50:51] op_sel_hi:[0,1]
	v_pk_mul_f32 v[14:15], v[14:15], v[16:17]
	v_pk_mul_f32 v[16:17], v[76:77], v[42:43] op_sel_hi:[0,1]
	v_cndmask_b32_e32 v76, 0, v0, vcc
	v_subrev_u32_e32 v0, 31, v136
	s_cmp_gt_i32 s96, 30
	v_lshrrev_b32_e32 v0, 4, v0
	s_cselect_b32 s6, s0, 0
	v_pk_mul_f32 v[28:29], v[28:29], v[68:69]
	v_pk_mul_f32 v[30:31], v[30:31], v[64:65]
	v_pk_mul_f32 v[26:27], v[26:27], v[58:59]
	v_pk_mul_f32 v[18:19], v[18:19], v[24:25]
	v_pk_mul_f32 v[10:11], v[10:11], v[16:17]
	v_add_u32_e32 v0, 1, v0
	v_cmp_lt_i32_e32 vcc, 30, v136
	v_mul_u32_u24_e32 v65, 0x90, v70
	s_cmp_lg_u32 s6, 0
	v_cvt_pk_bf16_f32 v80, v28, v29
	v_cvt_pk_bf16_f32 v81, v30, v31
	v_cvt_pk_bf16_f32 v83, v26, v27
	v_cvt_pk_bf16_f32 v84, v20, v21
	v_cvt_pk_bf16_f32 v85, v22, v23
	v_cvt_pk_bf16_f32 v87, v18, v19
	v_cvt_pk_bf16_f32 v88, v12, v13
	v_cvt_pk_bf16_f32 v89, v14, v15
	v_cvt_pk_bf16_f32 v91, v10, v11
	v_cvt_pk_bf16_f32 v92, v4, v5
	v_cvt_pk_bf16_f32 v93, v6, v7
	v_lshlrev_b32_e32 v156, 2, v75
	v_mov_b32_e32 v16, 0
	v_cndmask_b32_e32 v64, 0, v0, vcc
	s_cselect_b64 s[0:1], -1, 0
	s_cmp_eq_u32 s6, 0
	v_add3_u32 v77, 0, v65, v60
	s_waitcnt lgkmcnt(0)
	s_barrier
	s_cbranch_scc1 .LBB0_122
	s_lshl_b32 s7, s6, 5
	v_mov_b32_e32 v16, 0
	s_mov_b32 s10, 0
	v_mov_b32_e32 v17, v77
	.p2align	6

; DI float bf1(bf16_t v) { return __uint_as_float(((unsigned)v) << 16); }
; DI int crow(int i, int h) { return (i & 3) + 8 * (i >> 2) + 4 * h; }
; DI void nsa_wg_unit(const Args& a, int l, int b, int g, int tb, unsigned char* lds, int tid_in, bool stage) {
;     ...
;       for (int br = 0; br < 3; ++br) gt[0][br] = 1.0f / (1.0f + __expf(-bf1(zr[C_NG + (g * 4 + head) * 3 + br])));
;       orow[0] = OB + ((size_t)b * SEQ + tk[0]) * 512 + (g * 4 + head) * 64 + 4 * h; }
;     float cref[3];
;     { const float* qg = a.in[4] + (size_t)l * 4 * 64; float mx[4];
; #pragma unroll
;       for (int k4 = 0; k4 < 4; ++k4) { float v = fabsf(qg[k4 * 64 + lane]);
; #pragma unroll
;           for (int o = 1; o < 64; o <<= 1) v = fmaxf(v, __shfl_xor(v, o));
;           mx[k4] = v; }
; #pragma unroll
;       for (int br = 0; br < 3; ++br) { const float bnd = 64.0f * QSC * mx[0] * mx[1 + br]; cref[br] = bnd > 64.0f ? bnd : 0.f; } }
;     float* wl = (float*)(lds + AL_WT + wave * WT_SZ); float* IA = wl; float* IB = wl + NTOK * 65;
;     for (int i = lane; i < 2 * NTOK * 65; i += 64) wl[i] = 0.f;
;     __syncthreads();
;     AttnSt st;
;     int nv[NRT]; nv[0] = tk[0] >= 31 ? ((tk[0] - 31) >> 4) + 1 : 0;
;     const int nvmax = (t0 + NTOK - 1 >= 31) ? ((t0 + NTOK - 1 - 31) >> 4) + 1 : 0, nst = (nvmax + 31) >> 5;
;     st.l[0] = 0.f;
;     const LP kcl = L + AL_KC + rl * KC_PB + 16 * h, vcl = L + AL_VC + rl * VC_PB + 8 * h;
;     for (int T = 0; T < nst; ++T) { f32x16 s[NRT]; KV f; kv_load_lds(f, kcl + 32 * T * KC_PB, vcl + 64 * T, VC_PB); attn_scores(s, qf, f); float ps = 0.f;
; #pragma unroll
;         for (int i = 0; i < 16; ++i) { const float sv = (32 * T + crow(i, h) >= nv[0]) ? -INFINITY : s[0][i] - cref[0]; ps += __builtin_amdgcn_exp2f(sv); }
;         st.l[0] += ps; }
;     float mu2, inv;
;     { const float lt = st.l[0] + __shfl_xor(st.l[0], 32); inv = lt > 0.f ? 1.0f / lt : 0.f; mu2 = cref[0]; }
;     attn_reset(st);
;     for (int T = 0; T < nst; ++T) { f32x16 s[NRT]; KV f; kv_load_lds(f, kcl + 32 * T * KC_PB, vcl + 64 * T, VC_PB); attn_scores(s, qf, f);
.LBB0_122:
	v_lshlrev_b32_e32 v0, 16, v32
	v_mul_f32_e32 v0, 0xbfb8aa3b, v0
	v_exp_f32_e32 v78, v0
	v_and_b32_e32 v0, 0xffff0000, v32
	v_mul_f32_e32 v0, 0xbfb8aa3b, v0
	v_exp_f32_e32 v159, v0
	v_max_f32_e32 v0, v63, v63
	v_max_f32_e32 v1, v61, v61
	v_max_f32_e32 v69, v1, v0
	v_max_f32_e32 v0, v97, v97
	v_max_f32_e32 v1, v96, v96
	v_max_f32_e32 v158, v1, v0
	ds_bpermute_b32 v0, v148, v16
	s_andn2_b64 vcc, exec, s[0:1]
	s_cbranch_vccnz .LBB0_137
	s_waitcnt lgkmcnt(0)
	v_add_f32_e32 v1, v16, v0
	v_div_scale_f32 v2, s[0:1], v1, v1, 1.0
	v_rcp_f32_e32 v3, v2
	s_movk_i32 s0, 0x41
	v_mov_b32_e32 v0, 0
	s_mov_b32 s10, 0
	v_fma_f32 v4, -v2, v3, 1.0
	v_fmac_f32_e32 v3, v4, v3
	v_div_scale_f32 v4, vcc, 1.0, v1, 1.0
	v_mul_f32_e32 v5, v4, v3
	v_fma_f32 v6, -v2, v5, v4
	v_fmac_f32_e32 v5, v6, v3
	v_fma_f32 v2, -v2, v5, v4
	v_div_fmas_f32 v2, v2, v3, v5
	v_div_fixup_f32 v2, v2, v1, 1.0
	v_cmp_lt_f32_e32 vcc, 0, v1
	v_mad_u32_u24 v1, v74, s0, v75
	s_movk_i32 s0, 0x178
	v_cndmask_b32_e32 v66, 0, v2, vcc
	v_lshl_add_u32 v79, v1, 2, s8
	v_mad_u32_u24 v1, v70, s0, v65
	s_add_i32 s0, 0, 0x9000
	v_cmp_eq_u32_e32 vcc, 0, v33
	v_mov_b32_e32 v61, v64
	v_mov_b32_e32 v67, v66
	s_lshl_b32 s11, s6, 5
	v_add3_u32 v96, v1, v72, s0
	v_mov_b32_e32 v1, v0
	v_mov_b32_e32 v2, v0
	v_mov_b32_e32 v3, v0
	v_mov_b32_e32 v4, v0
	v_mov_b32_e32 v5, v0
	v_mov_b32_e32 v6, v0
	v_mov_b32_e32 v7, v0
	v_mov_b32_e32 v8, v0
	v_mov_b32_e32 v9, v0
	v_mov_b32_e32 v10, v0
	v_mov_b32_e32 v11, v0
	v_mov_b32_e32 v12, v0
	v_mov_b32_e32 v13, v0
	v_mov_b32_e32 v14, v0
	v_mov_b32_e32 v15, v0
	v_mov_b32_e32 v16, v0
	v_mov_b32_e32 v17, v0
	v_mov_b32_e32 v18, v0
	v_mov_b32_e32 v19, v0
	v_mov_b32_e32 v20, v0
	v_mov_b32_e32 v21, v0
	v_mov_b32_e32 v22, v0
	v_mov_b32_e32 v23, v0
	v_mov_b32_e32 v24, v0
	v_mov_b32_e32 v25, v0
	v_mov_b32_e32 v26, v0
	v_mov_b32_e32 v27, v0
	v_mov_b32_e32 v28, v0
	v_mov_b32_e32 v29, v0
	v_mov_b32_e32 v30, v0
	v_mov_b32_e32 v31, v0
	s_branch .LBB0_125
	.p2align	6

; DI void nsa_wg_unit(const Args& a, int l, int b, int g, int tb, unsigned char* lds, int tid_in, bool stage) {
;     ...
;       while (j >= 0) {
;           rem &= rem - 1ull; const int nj = rem ? (int)__builtin_ctzll(rem) : -1;
;           if (nj >= 0) { kreg = *(const u32x4*)(kgb + (size_t)(64 * nj) * ZP * 2 + koff); vreg = *(const u32x4*)(vgb + (size_t)(64 * nj) * 2 + voff); }
.LBB0_167:
	s_add_u32 s78, s84, -1
	s_addc_u32 s79, s85, -1
	s_and_b64 s[84:85], s[78:79], s[84:85]
	s_cmp_eq_u64 s[84:85], 0
	s_cselect_b64 s[78:79], -1, 0
	s_cmp_lg_u64 s[84:85], 0
	s_cselect_b64 s[86:87], -1, 0
	s_ff1_i32_b64 s80, s[84:85]
	s_add_u32 s100, s84, -1
	s_addc_u32 s101, s85, -1
	s_and_b64 s[100:101], s[100:101], s[84:85]
	s_cmp_eq_u64 s[100:101], 0
	s_cbranch_scc1 .LBB0_169
	s_ff1_i32_b64 s98, s[100:101]
	s_mov_b32 s99, 0
	s_mul_i32 s88, s98, 0x88c00
	s_mov_b32 s89, 0
	s_lshl_b64 vcc, s[98:99], 7
	v_lshl_add_u64 v[48:49], v[144:145], 0, s[88:89]
	v_lshl_add_u64 v[50:51], v[146:147], 0, vcc
	.p2align	6

; DI void nsa_wg_unit(const Args& a, int l, int b, int g, int tb, unsigned char* lds, int tid_in, bool stage) {
;     ...
;           if (nj >= 0) { kreg = *(const u32x4*)(kgb + (size_t)(64 * nj) * ZP * 2 + koff); vreg = *(const u32x4*)(vgb + (size_t)(64 * nj) * 2 + voff); }
.Lsel1_ldb:
	global_load_dwordx4 v[228:231], v[48:49], off
	global_load_dwordx4 v[232:235], v[50:51], off
	.p2align	6

; DI void nsa_wg_unit(const Args& a, int l, int b, int g, int tb, unsigned char* lds, int tid_in, bool stage) {
;     ...
;     { float sc[NRT]; const float lt = st.l[0] + __shfl_xor(st.l[0], 32); sc[0] = lt > 0.f ? gt[0][1] / lt : 0.f; attn_flush<false>(st, sc, orow); }
;     attn_reset(st);
;     { const unsigned koff = (unsigned)(srow * ZP + sch * 8) * 2u, voff = (unsigned)(srow * SEQ + sch * 8) * 2u; const char* kgb = (const char*)(zb + C_KV + 4 * 128 + g * 64); const char* vgb = (const char*)VWT;
;       int j = tb - 8 < 0 ? 0 : tb - 8, bi = 0; u32x4 kreg, vreg;
;       { kreg = *(const u32x4*)(kgb + (size_t)(64 * j) * ZP * 2 + koff); vreg = *(const u32x4*)(vgb + (size_t)(64 * j) * 2 + voff);
;         *(u32x4*)(lds + AL_KR + srow * KR_PB + sch * 16) = kreg; u32x2* d = (u32x2*)(lds + AL_VR + srow * VR_PB + sch * 16); u32x2 lo2, hi2; lo2.x = vreg.x; lo2.y = vreg.y; hi2.x = vreg.z; hi2.y = vreg.w; d[0] = lo2; d[1] = hi2; }
;       __syncthreads();
.LBB0_183:
	v_mov_b64_e32 v[32:33], v[236:237]
	v_mov_b64_e32 v[34:35], v[238:239]
	v_mov_b64_e32 v[36:37], v[240:241]
	v_mov_b64_e32 v[38:39], v[242:243]
	v_mov_b64_e32 v[40:41], v[244:245]
	v_mov_b64_e32 v[42:43], v[246:247]
	v_mov_b64_e32 v[44:45], v[248:249]
	v_mov_b64_e32 v[46:47], v[250:251]
	v_add_f32_e32 v48, 1.0, v159
	v_div_scale_f32 v50, s[8:9], v48, v48, 1.0
	v_rcp_f32_e32 v52, v50
	v_div_scale_f32 v51, vcc, 1.0, v48, 1.0
	ds_bpermute_b32 v49, v148, v171
	v_fma_f32 v53, -v50, v52, 1.0
	v_fmac_f32_e32 v52, v53, v52
	v_mul_f32_e32 v53, v51, v52
	s_add_u32 s0, s46, s10
	v_fma_f32 v54, -v50, v53, v51
	s_addc_u32 s1, s47, 0
	v_fmac_f32_e32 v53, v54, v52
	s_lshl_b64 s[0:1], s[0:1], 19
	v_readlane_b32 s7, v254, 32
	v_fma_f32 v50, -v50, v53, v51
	s_add_u32 s0, s7, s0
	v_readlane_b32 s7, v254, 34
	v_div_fmas_f32 v50, v50, v52, v53
	s_addc_u32 s7, s7, s1
	s_waitcnt lgkmcnt(0)
	v_add_f32_e32 v49, v171, v49
	v_div_fixup_f32 v48, v50, v48, 1.0
	s_add_u32 s2, s0, 0x800000
	v_div_scale_f32 v50, s[0:1], v49, v49, v48
	v_rcp_f32_e32 v51, v50
	v_div_scale_f32 v52, vcc, v48, v49, v48
	s_addc_u32 s35, s7, 0
	v_fma_f32 v53, -v50, v51, 1.0
	v_fmac_f32_e32 v51, v53, v51
	v_mul_f32_e32 v53, v52, v51
	v_fma_f32 v54, -v50, v53, v52
	v_fmac_f32_e32 v53, v54, v51
	v_fma_f32 v50, -v50, v53, v52
	v_div_fmas_f32 v50, v50, v51, v53
	v_div_fixup_f32 v48, v50, v49, v48
	v_cmp_lt_f32_e32 vcc, 0, v49
	s_lshl_b32 s0, s6, 1
	s_add_u32 s0, s36, s0
	v_cndmask_b32_e32 v48, 0, v48, vcc
	s_addc_u32 s1, s37, 0
	s_add_u32 s45, s0, 0x1400
	s_addc_u32 s46, s1, 0
	s_max_i32 s0, s33, 8
	s_add_i32 s1, s0, -8
	s_lshl_b32 s6, s1, 6
	s_mul_i32 s7, s1, 0x88c00
	s_mul_hi_u32 s8, s6, 0x2230
	s_add_u32 s6, s45, s7
	s_addc_u32 s7, s46, s8
	v_add3_u32 v146, s26, v137, v138
	v_add3_u32 v138, s28, v168, v138
	s_waitcnt vmcnt(7)
	v_lshlrev_b32_e32 v50, 16, v32
	v_and_b32_e32 v51, 0xffff0000, v32
	v_lshlrev_b32_e32 v32, 16, v33
	v_and_b32_e32 v33, 0xffff0000, v33
	s_waitcnt vmcnt(6)
	v_lshlrev_b32_e32 v52, 16, v34
	v_and_b32_e32 v53, 0xffff0000, v34
	v_lshlrev_b32_e32 v34, 16, v35
	v_and_b32_e32 v35, 0xffff0000, v35
	s_waitcnt vmcnt(5)
	v_lshlrev_b32_e32 v54, 16, v36
	v_and_b32_e32 v55, 0xffff0000, v36
	v_lshlrev_b32_e32 v36, 16, v37
	v_and_b32_e32 v37, 0xffff0000, v37
	s_waitcnt vmcnt(4)
	v_lshlrev_b32_e32 v56, 16, v38
	v_and_b32_e32 v57, 0xffff0000, v38
	v_lshlrev_b32_e32 v38, 16, v39
	v_and_b32_e32 v39, 0xffff0000, v39
	v_pk_fma_f32 v[16:17], v[16:17], v[48:49], v[50:51] op_sel_hi:[1,0,1]
	v_pk_fma_f32 v[18:19], v[18:19], v[48:49], v[32:33] op_sel_hi:[1,0,1]
	v_pk_fma_f32 v[20:21], v[20:21], v[48:49], v[52:53] op_sel_hi:[1,0,1]
	v_pk_fma_f32 v[22:23], v[22:23], v[48:49], v[34:35] op_sel_hi:[1,0,1]
	v_pk_fma_f32 v[24:25], v[24:25], v[48:49], v[54:55] op_sel_hi:[1,0,1]
	v_pk_fma_f32 v[26:27], v[26:27], v[48:49], v[36:37] op_sel_hi:[1,0,1]
	v_pk_fma_f32 v[28:29], v[28:29], v[48:49], v[56:57] op_sel_hi:[1,0,1]
	v_pk_fma_f32 v[30:31], v[30:31], v[48:49], v[38:39] op_sel_hi:[1,0,1]
	v_cvt_pk_bf16_f32 v16, v16, v17
	v_cvt_pk_bf16_f32 v17, v18, v19
	v_cvt_pk_bf16_f32 v18, v20, v21
	v_cvt_pk_bf16_f32 v19, v22, v23
	v_cvt_pk_bf16_f32 v20, v24, v25
	v_cvt_pk_bf16_f32 v21, v26, v27
	v_cvt_pk_bf16_f32 v22, v28, v29
	v_cvt_pk_bf16_f32 v23, v30, v31
	v_mov_b64_e32 v[236:237], v[16:17]
	v_mov_b64_e32 v[238:239], v[18:19]
	v_mov_b64_e32 v[240:241], v[20:21]
	v_mov_b64_e32 v[242:243], v[22:23]
	s_waitcnt vmcnt(7)
	v_lshlrev_b32_e32 v16, 16, v40
	v_and_b32_e32 v17, 0xffff0000, v40
	v_pk_fma_f32 v[0:1], v[0:1], v[48:49], v[16:17] op_sel_hi:[1,0,1]
	v_lshlrev_b32_e32 v16, 16, v41
	v_and_b32_e32 v17, 0xffff0000, v41
	v_pk_fma_f32 v[2:3], v[2:3], v[48:49], v[16:17] op_sel_hi:[1,0,1]
	v_cvt_pk_bf16_f32 v0, v0, v1
	v_cvt_pk_bf16_f32 v1, v2, v3
	v_mov_b64_e32 v[244:245], v[0:1]
	s_waitcnt vmcnt(7)
	v_lshlrev_b32_e32 v0, 16, v42
	v_and_b32_e32 v1, 0xffff0000, v42
	v_lshlrev_b32_e32 v2, 16, v43
	v_and_b32_e32 v3, 0xffff0000, v43
	v_pk_fma_f32 v[0:1], v[4:5], v[48:49], v[0:1] op_sel_hi:[1,0,1]
	v_pk_fma_f32 v[2:3], v[6:7], v[48:49], v[2:3] op_sel_hi:[1,0,1]
	v_cvt_pk_bf16_f32 v0, v0, v1
	v_cvt_pk_bf16_f32 v1, v2, v3
	v_mov_b64_e32 v[246:247], v[0:1]
	s_waitcnt vmcnt(7)
	v_lshlrev_b32_e32 v0, 16, v44
	v_and_b32_e32 v1, 0xffff0000, v44
	v_lshlrev_b32_e32 v2, 16, v45
	v_and_b32_e32 v3, 0xffff0000, v45
	v_pk_fma_f32 v[0:1], v[8:9], v[48:49], v[0:1] op_sel_hi:[1,0,1]
	v_pk_fma_f32 v[2:3], v[10:11], v[48:49], v[2:3] op_sel_hi:[1,0,1]
	v_cvt_pk_bf16_f32 v0, v0, v1
	v_cvt_pk_bf16_f32 v1, v2, v3
	v_mov_b64_e32 v[248:249], v[0:1]
	s_waitcnt vmcnt(7)
	v_lshlrev_b32_e32 v0, 16, v46
	v_and_b32_e32 v1, 0xffff0000, v46
	v_lshlrev_b32_e32 v2, 16, v47
	v_and_b32_e32 v3, 0xffff0000, v47
	v_pk_fma_f32 v[0:1], v[12:13], v[48:49], v[0:1] op_sel_hi:[1,0,1]
	v_pk_fma_f32 v[2:3], v[14:15], v[48:49], v[2:3] op_sel_hi:[1,0,1]
	v_cvt_pk_bf16_f32 v0, v0, v1
	v_cvt_pk_bf16_f32 v1, v2, v3
	v_mov_b64_e32 v[250:251], v[0:1]
	v_lshl_add_u64 v[0:1], s[6:7], 0, v[142:143]
	s_lshl_b32 s6, s1, 7
	s_add_u32 s6, s2, s6
	s_addc_u32 s7, s35, 0
	v_lshl_add_u64 v[2:3], s[6:7], 0, v[160:161]
	global_load_dwordx4 v[96:99], v[0:1], off
	global_load_dwordx4 v[100:103], v[2:3], off
	v_mov_b32_e32 v15, 0
	v_mov_b32_e32 v14, v15
	v_mov_b32_e32 v13, v15
	v_mov_b32_e32 v12, v15
	v_mov_b32_e32 v11, v15
	v_mov_b32_e32 v10, v15
	v_mov_b32_e32 v9, v15
	v_mov_b32_e32 v8, v15
	v_mov_b32_e32 v7, v15
	v_mov_b32_e32 v6, v15
	v_mov_b32_e32 v5, v15
	v_mov_b32_e32 v4, v15
	v_mov_b32_e32 v3, v15
	v_mov_b32_e32 v2, v15
	v_mov_b32_e32 v1, v15
	v_mov_b32_e32 v0, v15
	v_mov_b32_e32 v31, v15
	v_mov_b32_e32 v30, v15
	s_cmp_gt_i32 s1, s33
	v_mov_b32_e32 v29, v15
	v_mov_b32_e32 v28, v15
	v_mov_b32_e32 v27, v15
	v_mov_b32_e32 v26, v15
	v_mov_b32_e32 v25, v15
	v_mov_b32_e32 v24, v15
	v_mov_b32_e32 v23, v15
	v_mov_b32_e32 v22, v15
	v_mov_b32_e32 v21, v15
	v_mov_b32_e32 v20, v15
	v_mov_b32_e32 v19, v15
	v_mov_b32_e32 v18, v15
	v_mov_b32_e32 v17, v15
	v_mov_b32_e32 v16, v15
	v_mov_b32_e32 v137, v15
	s_waitcnt vmcnt(1)
	ds_write_b128 v146, v[96:99]
	s_waitcnt vmcnt(0)
	ds_write2_b64 v138, v[100:101], v[102:103] offset1:1
	s_waitcnt lgkmcnt(0)
	s_barrier
; DI void nsa_wg_unit(const Args& a, int l, int b, int g, int tb, unsigned char* lds, int tid_in, bool stage) {
;     ...
;       for (; j <= tb; ++j) { const bool hn = j + 1 <= tb;
;           if (hn) { kreg = *(const u32x4*)(kgb + (size_t)(64 * (j + 1)) * ZP * 2 + koff); vreg = *(const u32x4*)(vgb + (size_t)(64 * (j + 1)) * 2 + voff); }
;           if (64 * j + 63 >= t0 - 511 && 64 * j <= t0 + NTOK - 1)
;               attn_block64(st, qf, kfl + bi * KR_SZ, vfl + bi * VR_SZ, KR_PB, VR_PB, cref[2], true, (64 * j + 63 > t0) || (64 * j <= t0 + NTOK - 1 - 512), MaskWindow{tk[0]}, 64 * j, h);
	s_cbranch_scc1 .LBB0_196
	v_readlane_b32 s8, v254, 56
	s_lshl_b32 s1, s0, 6
	v_readlane_b32 s9, v254, 57
	s_add_i32 s12, s93, 0xfffffe01
	s_add_i32 s13, s93, 0xfffffe07
	s_add_i32 s14, s1, 0xfffffe00
	s_add_i32 s15, s0, -9
	s_lshl_b64 s[8:9], s[8:9], 20
	s_lshl_b32 s1, s10, 19
	s_lshl_b32 s10, s0, 7
	v_readlane_b32 s11, v254, 40
	s_add_u32 s10, s11, s10
	v_readlane_b32 s11, v254, 41
	s_addc_u32 s11, s11, 0
	s_add_u32 s1, s10, s1
	s_addc_u32 s10, s11, 0
	s_add_u32 s8, s1, s8
	s_addc_u32 s9, s10, s9
	v_lshl_add_u64 v[144:145], s[8:9], 0, v[160:161]
	v_readlane_b32 s1, v254, 42
	v_readlane_b32 s8, v254, 55
	s_add_u32 s1, s1, s8
	v_readlane_b32 s8, v254, 43
	s_mul_i32 s0, s0, 0x88c00
	s_addc_u32 s8, s8, 0
	s_add_u32 s0, s1, s0
	v_mul_f32_e32 v0, v157, v158
	s_addc_u32 s1, s8, 0
	v_readlane_b32 s8, v254, 52
	v_cmp_lt_f32_e32 vcc, s25, v0
	s_add_u32 s0, s0, s8
	v_readlane_b32 s8, v254, 53
	v_mov_b32_e32 v137, 0
	v_cndmask_b32_e32 v32, 0, v0, vcc
	s_addc_u32 s1, s1, s8
	v_add_u32_e32 v147, 0xfffffe00, v136
	v_cmp_neq_f32_e64 s[6:7], 0, v32
	v_mov_b32_e32 v33, v32
	v_mov_b32_e32 v34, v32
	v_mov_b32_e32 v35, v32
	v_mov_b32_e32 v36, v32
	v_mov_b32_e32 v37, v32
	v_mov_b32_e32 v38, v32
	v_mov_b32_e32 v39, v32
	v_mov_b32_e32 v40, v32
	v_mov_b32_e32 v41, v32
	v_mov_b32_e32 v42, v32
	v_mov_b32_e32 v43, v32
	v_mov_b32_e32 v44, v32
	v_lshl_add_u64 v[142:143], s[0:1], 0, v[142:143]
	s_mov_b32 s16, 0
	v_mov_b32_e32 v0, 0
	v_mov_b32_e32 v1, v137
	v_mov_b32_e32 v2, v137
	v_mov_b32_e32 v3, v137
	v_mov_b32_e32 v4, v137
	v_mov_b32_e32 v5, v137
	v_mov_b32_e32 v6, v137
	v_mov_b32_e32 v7, v137
	v_mov_b32_e32 v8, v137
	v_mov_b32_e32 v9, v137
	v_mov_b32_e32 v10, v137
	v_mov_b32_e32 v11, v137
	v_mov_b32_e32 v12, v137
	v_mov_b32_e32 v13, v137
	v_mov_b32_e32 v14, v137
	v_mov_b32_e32 v15, v137
	v_mov_b32_e32 v16, 0
	v_mov_b32_e32 v17, v137
	v_mov_b32_e32 v18, v137
	v_mov_b32_e32 v19, v137
	v_mov_b32_e32 v20, v137
	v_mov_b32_e32 v21, v137
	v_mov_b32_e32 v22, v137
	v_mov_b32_e32 v23, v137
	v_mov_b32_e32 v24, v137
	v_mov_b32_e32 v25, v137
	v_mov_b32_e32 v26, v137
	v_mov_b32_e32 v27, v137
	v_mov_b32_e32 v28, v137
	v_mov_b32_e32 v29, v137
	v_mov_b32_e32 v30, v137
	v_mov_b32_e32 v31, v137
	v_mov_b32_e32 v45, v32
	v_mov_b32_e32 v46, v32
	v_mov_b32_e32 v47, v32
	s_branch .LBB0_186
	.p2align	6

; DI void nsa_wg_unit(const Args& a, int l, int b, int g, int tb, unsigned char* lds, int tid_in, bool stage) {
;     ...
;     const int rl = lane & 31, h = lane >> 5, head = rl & 3, t0 = tb * 64 + wave * 8, jt = tb;
;     int tk[NRT]; tk[0] = t0 + (rl >> 2);
;     const bf16_t* zb = Z1 + (size_t)b * SEQ * ZP;
;     LP L = (LP)lds;
;     __syncthreads();
;     if (stage) {
;     for (int i = tid; i < 2048; i += 512) { const int row = i >> 3, ch = i & 7; *(u32x4*)(lds + AL_KC + row * KC_PB + ch * 16) = *(const u32x4*)(KC + row * 64 + ch * 8); }
;     for (int i = tid; i < 2048; i += 512) { const int row = i >> 5, ch = i & 31; const u32x4 v = *(const u32x4*)(VCT + row * 256 + ch * 8); u32x2* d = (u32x2*)(lds + AL_VC + row * VC_PB + ch * 16); u32x2 lo, hi; lo.x = v.x; lo.y = v.y; hi.x = v.z; hi.y = v.w; d[0] = lo; d[1] = hi; }
;     }
;     bf16x8 qf[NRT][4]; float gt[NRT][3]; bf16_t* orow[NRT];
;     { const bf16_t* zr = zb + (size_t)tk[0] * ZP;
;     ...
;     { float sc[NRT]; const float lt = st.l[0] + __shfl_xor(st.l[0], 32); sc[0] = lt > 0.f ? gt[0][2] / lt : 0.f; attn_flush<false>(st, sc, orow); }
.LBB0_196:
	v_mov_b64_e32 v[32:33], v[236:237]
	v_mov_b64_e32 v[34:35], v[238:239]
	v_mov_b64_e32 v[36:37], v[240:241]
	v_mov_b64_e32 v[38:39], v[242:243]
	v_mov_b64_e32 v[40:41], v[244:245]
	v_lshlrev_b32_e32 v42, 16, v139
	v_mul_f32_e32 v42, 0xbfb8aa3b, v42
	v_exp_f32_e32 v136, v42
	v_mov_b64_e32 v[42:43], v[246:247]
	v_mov_b64_e32 v[46:47], v[248:249]
	v_mov_b64_e32 v[48:49], v[250:251]
	ds_bpermute_b32 v165, v148, v137
	v_mov_b32_e32 v74, v225
	s_xor_b32 s93, s33, 63
	s_lshl_b32 s68, s93, 6
	v_mov_b32_e32 v61, v161
	s_waitcnt lgkmcnt(0)
	v_pk_add_f32 v[44:45], v[136:137], v[164:165]
	s_waitcnt vmcnt(5)
	v_and_b32_e32 v55, 0xffff0000, v36
	v_div_scale_f32 v50, s[0:1], v44, v44, 1.0
	v_rcp_f32_e32 v51, v50
	v_div_scale_f32 v52, vcc, 1.0, v44, 1.0
	s_waitcnt vmcnt(3)
	v_lshlrev_b32_e32 v58, 16, v40
	v_fma_f32 v53, -v50, v51, 1.0
	v_fmac_f32_e32 v51, v53, v51
	v_mul_f32_e32 v53, v52, v51
	v_fma_f32 v54, -v50, v53, v52
	v_fmac_f32_e32 v53, v54, v51
	v_fma_f32 v50, -v50, v53, v52
	v_div_fmas_f32 v50, v50, v51, v53
	v_div_fixup_f32 v44, v50, v44, 1.0
	v_div_scale_f32 v50, s[0:1], v45, v45, v44
	v_rcp_f32_e32 v51, v50
	v_div_scale_f32 v52, vcc, v44, v45, v44
	v_and_b32_e32 v59, 0xffff0000, v40
	v_fma_f32 v53, -v50, v51, 1.0
	v_fmac_f32_e32 v51, v53, v51
	v_mul_f32_e32 v53, v52, v51
	v_fma_f32 v54, -v50, v53, v52
	v_fmac_f32_e32 v53, v54, v51
	v_fma_f32 v50, -v50, v53, v52
	v_div_fmas_f32 v50, v50, v51, v53
	v_div_fixup_f32 v44, v50, v45, v44
	v_cmp_lt_f32_e32 vcc, 0, v45
	v_lshlrev_b32_e32 v50, 16, v32
	v_and_b32_e32 v51, 0xffff0000, v32
	v_cndmask_b32_e32 v44, 0, v44, vcc
	v_lshlrev_b32_e32 v32, 16, v33
	v_and_b32_e32 v33, 0xffff0000, v33
	v_lshlrev_b32_e32 v40, 16, v41
	v_and_b32_e32 v41, 0xffff0000, v41
	v_lshlrev_b32_e32 v52, 16, v34
	v_and_b32_e32 v53, 0xffff0000, v34
	v_lshlrev_b32_e32 v34, 16, v35
	v_and_b32_e32 v35, 0xffff0000, v35
	v_lshlrev_b32_e32 v54, 16, v36
	v_lshlrev_b32_e32 v36, 16, v37
	v_and_b32_e32 v37, 0xffff0000, v37
	v_lshlrev_b32_e32 v56, 16, v38
	v_and_b32_e32 v57, 0xffff0000, v38
	v_lshlrev_b32_e32 v38, 16, v39
	v_and_b32_e32 v39, 0xffff0000, v39
	v_pk_fma_f32 v[16:17], v[16:17], v[44:45], v[50:51] op_sel_hi:[1,0,1]
	v_pk_fma_f32 v[18:19], v[18:19], v[44:45], v[32:33] op_sel_hi:[1,0,1]
	v_pk_fma_f32 v[0:1], v[0:1], v[44:45], v[58:59] op_sel_hi:[1,0,1]
	v_pk_fma_f32 v[2:3], v[2:3], v[44:45], v[40:41] op_sel_hi:[1,0,1]
	v_pk_fma_f32 v[20:21], v[20:21], v[44:45], v[52:53] op_sel_hi:[1,0,1]
	v_pk_fma_f32 v[22:23], v[22:23], v[44:45], v[34:35] op_sel_hi:[1,0,1]
	v_pk_fma_f32 v[24:25], v[24:25], v[44:45], v[54:55] op_sel_hi:[1,0,1]
	v_pk_fma_f32 v[26:27], v[26:27], v[44:45], v[36:37] op_sel_hi:[1,0,1]
	v_pk_fma_f32 v[28:29], v[28:29], v[44:45], v[56:57] op_sel_hi:[1,0,1]
	v_pk_fma_f32 v[30:31], v[30:31], v[44:45], v[38:39] op_sel_hi:[1,0,1]
	v_cvt_pk_bf16_f32 v16, v16, v17
	v_cvt_pk_bf16_f32 v17, v18, v19
	v_cvt_pk_bf16_f32 v0, v0, v1
	v_cvt_pk_bf16_f32 v1, v2, v3
	v_cvt_pk_bf16_f32 v18, v20, v21
	v_cvt_pk_bf16_f32 v19, v22, v23
	v_cvt_pk_bf16_f32 v20, v24, v25
	v_cvt_pk_bf16_f32 v21, v26, v27
	v_cvt_pk_bf16_f32 v22, v28, v29
	v_cvt_pk_bf16_f32 v23, v30, v31
	global_store_dwordx2 v[140:141], v[16:17], off
	global_store_dwordx2 v[140:141], v[18:19], off offset:16
	global_store_dwordx2 v[140:141], v[20:21], off offset:32
	global_store_dwordx2 v[140:141], v[22:23], off offset:48
	global_store_dwordx2 v[140:141], v[0:1], off offset:64
	s_waitcnt vmcnt(7)
	v_lshlrev_b32_e32 v0, 16, v42
	v_and_b32_e32 v1, 0xffff0000, v42
	v_lshlrev_b32_e32 v2, 16, v43
	v_and_b32_e32 v3, 0xffff0000, v43
	v_pk_fma_f32 v[0:1], v[4:5], v[44:45], v[0:1] op_sel_hi:[1,0,1]
	v_pk_fma_f32 v[2:3], v[6:7], v[44:45], v[2:3] op_sel_hi:[1,0,1]
	v_cvt_pk_bf16_f32 v0, v0, v1
	v_cvt_pk_bf16_f32 v1, v2, v3
	global_store_dwordx2 v[140:141], v[0:1], off offset:80
	s_waitcnt vmcnt(7)
	v_lshlrev_b32_e32 v0, 16, v46
	v_and_b32_e32 v1, 0xffff0000, v46
	v_lshlrev_b32_e32 v2, 16, v47
	v_and_b32_e32 v3, 0xffff0000, v47
	v_pk_fma_f32 v[0:1], v[8:9], v[44:45], v[0:1] op_sel_hi:[1,0,1]
	v_pk_fma_f32 v[2:3], v[10:11], v[44:45], v[2:3] op_sel_hi:[1,0,1]
	v_cvt_pk_bf16_f32 v0, v0, v1
	v_cvt_pk_bf16_f32 v1, v2, v3
	global_store_dwordx2 v[140:141], v[0:1], off offset:96
	s_waitcnt vmcnt(7)
	v_lshlrev_b32_e32 v0, 16, v48
	v_and_b32_e32 v1, 0xffff0000, v48
	v_lshlrev_b32_e32 v2, 16, v49
	v_and_b32_e32 v3, 0xffff0000, v49
	v_pk_fma_f32 v[0:1], v[12:13], v[44:45], v[0:1] op_sel_hi:[1,0,1]
	v_pk_fma_f32 v[2:3], v[14:15], v[44:45], v[2:3] op_sel_hi:[1,0,1]
	v_cvt_pk_bf16_f32 v0, v0, v1
	v_cvt_pk_bf16_f32 v1, v2, v3
	global_store_dwordx2 v[140:141], v[0:1], off offset:112
	v_mov_b64_e32 v[0:1], s[36:37]
	v_readfirstlane_b32 s0, v74
	s_ashr_i32 s0, s0, 6
	s_lshl_b32 s16, s0, 3
	v_and_b32_e32 v63, 3, v74
	s_add_i32 s96, s16, s68
	v_bfe_u32 v75, v74, 2, 3
	v_or_b32_e32 v136, s96, v75
	v_lshl_or_b32 v62, v63, 6, s34
	v_bfe_u32 v77, v74, 5, 1
	v_mad_i64_i32 v[36:37], s[6:7], v136, s3, v[0:1]
	v_lshlrev_b32_e32 v160, 1, v62
	v_lshl_add_u64 v[0:1], v[36:37], 0, v[160:161]
	v_lshlrev_b32_e32 v60, 4, v77
	v_lshl_add_u64 v[0:1], v[0:1], 0, v[60:61]
	s_barrier
; DI float bf1(bf16_t v) { return __uint_as_float(((unsigned)v) << 16); }
; DI void unpack8(const u32x4 w, float (&f)[8]) { f[0] = bflo(w.x); f[1] = bfhi(w.x); f[2] = bflo(w.y); f[3] = bfhi(w.y); f[4] = bflo(w.z); f[5] = bfhi(w.z); f[6] = bflo(w.w); f[7] = bfhi(w.w); }
; DI u32x4 pack8(const float (&f)[8]) { u32x4 w; w.x = cvtpk(f[0], f[1]); w.y = cvtpk(f[2], f[3]); w.z = cvtpk(f[4], f[5]); w.w = cvtpk(f[6], f[7]); return w; }
; DI void nsa_wg_unit(const Args& a, int l, int b, int g, int tb, unsigned char* lds, int tid_in, bool stage) {
;     ...
;     { const bf16_t* zr = zb + (size_t)tk[0] * ZP;
; #pragma unroll
;       for (int dc = 0; dc < 4; ++dc) qf[0][dc] = *(const bf16x8*)(zr + C_Q + (g * 4 + head) * 64 + dc * 16 + 8 * h);
;       { const float* qg = a.in[4] + (size_t)l * 4 * 64; float qv[4][8]; float qs = 0.f;
; #pragma unroll
;         for (int dc = 0; dc < 4; ++dc) { unpack8(__builtin_bit_cast(u32x4, qf[0][dc]), qv[dc]);
; #pragma unroll
;             for (int e = 0; e < 8; ++e) qs += qv[dc][e] * qv[dc][e]; }
;         qs += __shfl_xor(qs, 32); const float rs = rsqrtf(qs * (1.0f / 64.0f) + 1e-6f) * QSC;
; #pragma unroll
;         for (int dc = 0; dc < 4; ++dc) { const f32x4 g0 = *(const f32x4*)(qg + dc * 16 + 8 * h), g1 = *(const f32x4*)(qg + dc * 16 + 8 * h + 4);
; #pragma unroll
;             for (int e = 0; e < 4; ++e) { qv[dc][e] = qv[dc][e] * rs * g0[e]; qv[dc][4 + e] = qv[dc][4 + e] * rs * g1[e]; }
;             qf[0][dc] = __builtin_bit_cast(bf16x8, pack8(qv[dc])); } }
; #pragma unroll
;       for (int br = 0; br < 3; ++br) gt[0][br] = 1.0f / (1.0f + __expf(-bf1(zr[C_NG + (g * 4 + head) * 3 + br])));
;       orow[0] = OB + ((size_t)b * SEQ + tk[0]) * 512 + (g * 4 + head) * 64 + 4 * h; }
;     float cref[3];
;     { const float* qg = a.in[4] + (size_t)l * 4 * 64; float mx[4];
; #pragma unroll
;       for (int k4 = 0; k4 < 4; ++k4) { float v = fabsf(qg[k4 * 64 + lane]);
; #pragma unroll
;           for (int o = 1; o < 64; o <<= 1) v = fmaxf(v, __shfl_xor(v, o));
;           mx[k4] = v; }
; #pragma unroll
;       for (int br = 0; br < 3; ++br) { const float bnd = 64.0f * QSC * mx[0] * mx[1 + br]; cref[br] = bnd > 64.0f ? bnd : 0.f; } }
	global_load_dwordx4 v[46:49], v[0:1], off offset:3168
	global_load_dwordx4 v[54:57], v[0:1], off offset:3136
	global_load_dwordx4 v[66:69], v[0:1], off offset:3104
	global_load_dwordx4 v[32:35], v[0:1], off offset:3072
	v_and_b32_e32 v76, 63, v74
	v_and_b32_e32 v4, 32, v74
	v_lshlrev_b32_e32 v108, 2, v76
	global_load_dwordx4 v[24:27], v4, s[90:91] offset:16
	global_load_dwordx4 v[28:31], v4, s[90:91]
	global_load_dwordx4 v[16:19], v4, s[90:91] offset:80
	global_load_dwordx4 v[20:23], v4, s[90:91] offset:64
	global_load_dwordx4 v[8:11], v4, s[90:91] offset:144
	global_load_dwordx4 v[12:15], v4, s[90:91] offset:128
	global_load_dwordx4 v[0:3], v4, s[90:91] offset:208
	s_nop 0
	global_load_dwordx4 v[4:7], v4, s[90:91] offset:192
	s_mov_b64 s[6:7], 0x1600
	global_load_dword v61, v108, s[90:91]
	global_load_dword v109, v108, s[90:91] offset:256
	global_load_dword v110, v108, s[90:91] offset:512
	global_load_dword v111, v108, s[90:91] offset:768
	s_mulk_i32 s0, 0x1080
	s_add_i32 s8, s0, 0
	s_add_i32 s9, s8, 0x19e00
	v_and_b32_e32 v72, 31, v74
	v_lshlrev_b32_e32 v73, 3, v77
	v_ashrrev_i32_e32 v137, 31, v136
	s_mov_b64 s[0:1], 0
	s_waitcnt vmcnt(15)
	v_lshlrev_b32_e32 v40, 16, v47
	v_and_b32_e32 v41, 0xffff0000, v47
	v_lshlrev_b32_e32 v44, 16, v46
	v_and_b32_e32 v45, 0xffff0000, v46
	s_waitcnt vmcnt(14)
	v_lshlrev_b32_e32 v46, 16, v57
	v_and_b32_e32 v47, 0xffff0000, v57
	v_lshlrev_b32_e32 v50, 16, v56
	v_and_b32_e32 v51, 0xffff0000, v56
	s_waitcnt vmcnt(13)
	v_lshlrev_b32_e32 v56, 16, v67
	v_and_b32_e32 v57, 0xffff0000, v67
	v_lshlrev_b32_e32 v64, 16, v66
	v_and_b32_e32 v65, 0xffff0000, v66
	s_waitcnt vmcnt(12)
	v_lshlrev_b32_e32 v66, 16, v35
	v_and_b32_e32 v67, 0xffff0000, v35
	v_lshlrev_b32_e32 v70, 16, v34
	v_and_b32_e32 v71, 0xffff0000, v34
	v_lshlrev_b32_e32 v34, 16, v32
	v_and_b32_e32 v35, 0xffff0000, v32
	v_lshlrev_b32_e32 v38, 16, v49
	v_and_b32_e32 v39, 0xffff0000, v49
	v_lshlrev_b32_e32 v42, 16, v48
	v_and_b32_e32 v43, 0xffff0000, v48
	v_lshlrev_b32_e32 v48, 16, v55
	v_and_b32_e32 v49, 0xffff0000, v55
	v_lshlrev_b32_e32 v52, 16, v54
	v_and_b32_e32 v53, 0xffff0000, v54
	v_lshlrev_b32_e32 v54, 16, v69
	v_and_b32_e32 v55, 0xffff0000, v69
	v_lshlrev_b32_e32 v58, 16, v68
	v_and_b32_e32 v59, 0xffff0000, v68
	v_lshlrev_b32_e32 v68, 16, v33
	v_and_b32_e32 v69, 0xffff0000, v33
	v_pk_mul_f32 v[32:33], v[34:35], v[34:35]
	v_pk_mul_f32 v[104:105], v[68:69], v[68:69]
	v_add_f32_e32 v32, v32, v33
	v_add_f32_e32 v32, v104, v32
	v_pk_mul_f32 v[106:107], v[70:71], v[70:71]
	v_add_f32_e32 v32, v105, v32
	v_add_f32_e32 v32, v106, v32
	v_pk_mul_f32 v[102:103], v[66:67], v[66:67]
	v_add_f32_e32 v32, v107, v32
	v_add_f32_e32 v32, v102, v32
	v_pk_mul_f32 v[100:101], v[64:65], v[64:65]
	v_add_f32_e32 v32, v103, v32
	v_add_f32_e32 v32, v100, v32
	v_pk_mul_f32 v[96:97], v[56:57], v[56:57]
	v_add_f32_e32 v32, v101, v32
	v_add_f32_e32 v32, v96, v32
	v_pk_mul_f32 v[98:99], v[58:59], v[58:59]
	v_add_f32_e32 v32, v97, v32
	v_add_f32_e32 v32, v98, v32
	v_pk_mul_f32 v[94:95], v[54:55], v[54:55]
	v_add_f32_e32 v32, v99, v32
	v_add_f32_e32 v32, v94, v32
	v_pk_mul_f32 v[92:93], v[52:53], v[52:53]
	v_add_f32_e32 v32, v95, v32
	v_add_f32_e32 v32, v92, v32
	v_pk_mul_f32 v[88:89], v[48:49], v[48:49]
	v_add_f32_e32 v32, v93, v32
	v_add_f32_e32 v32, v88, v32
	v_pk_mul_f32 v[90:91], v[50:51], v[50:51]
	v_add_f32_e32 v32, v89, v32
	v_add_f32_e32 v32, v90, v32
	v_pk_mul_f32 v[86:87], v[46:47], v[46:47]
	v_add_f32_e32 v32, v91, v32
	v_add_f32_e32 v32, v86, v32
	v_pk_mul_f32 v[84:85], v[44:45], v[44:45]
	v_add_f32_e32 v32, v87, v32
	v_add_f32_e32 v32, v84, v32
	v_pk_mul_f32 v[80:81], v[40:41], v[40:41]
	v_add_f32_e32 v32, v85, v32
	v_add_f32_e32 v32, v80, v32
	v_add_f32_e32 v80, v81, v32
	v_or_b32_e32 v32, s29, v63
	v_mul_u32_u24_e32 v32, 3, v32
	v_lshlrev_b32_e32 v160, 1, v32
	v_lshl_add_u64 v[32:33], v[36:37], 0, v[160:161]
	v_lshl_add_u64 v[36:37], v[32:33], 0, s[6:7]
	v_add_co_u32_e32 v32, vcc, s17, v32
	s_waitcnt vmcnt(3)
	v_and_b32_e32 v81, 0x7fffffff, v61
	v_addc_co_u32_e32 v33, vcc, 0, v33, vcc
	global_load_dword v32, v[32:33], off offset:1536
	s_nop 0
	global_load_ushort v139, v[36:37], off offset:4
	ds_bpermute_b32 v81, v152, v81
	v_max_f32_e64 v33, |v61|, |v61|
	s_waitcnt vmcnt(4)
	v_and_b32_e32 v61, 0x7fffffff, v109
	ds_bpermute_b32 v61, v152, v61
	v_pk_mul_f32 v[82:83], v[42:43], v[42:43]
	s_waitcnt lgkmcnt(1)
	v_max_f32_e32 v36, v81, v81
	v_max_f32_e32 v33, v33, v36
	ds_bpermute_b32 v36, v153, v33
	v_add_f32_e32 v37, v82, v80
	v_max_f32_e64 v80, |v109|, |v109|
	s_waitcnt lgkmcnt(1)
	v_max_f32_e32 v61, v61, v61
	v_max_f32_e32 v61, v80, v61
	s_waitcnt lgkmcnt(0)
	v_max_f32_e32 v36, v36, v36
	v_max_f32_e32 v33, v33, v36
	ds_bpermute_b32 v36, v154, v33
	ds_bpermute_b32 v80, v153, v61
	v_pk_mul_f32 v[78:79], v[38:39], v[38:39]
	v_add_f32_e32 v37, v83, v37
	v_add_f32_e32 v37, v78, v37
	s_waitcnt lgkmcnt(1)
	v_max_f32_e32 v36, v36, v36
	v_max_f32_e32 v33, v33, v36
	ds_bpermute_b32 v36, v150, v33
	s_waitcnt lgkmcnt(1)
	v_max_f32_e32 v78, v80, v80
	v_max_f32_e32 v61, v61, v78
	ds_bpermute_b32 v78, v154, v61
	v_add_f32_e32 v80, v79, v37
	s_waitcnt lgkmcnt(1)
	v_max_f32_e32 v36, v36, v36
	v_max_f32_e32 v33, v33, v36
	ds_bpermute_b32 v36, v151, v33
	s_waitcnt lgkmcnt(1)
	v_max_f32_e32 v37, v78, v78
	v_max_f32_e32 v37, v61, v37
	ds_bpermute_b32 v61, v150, v37
	s_waitcnt vmcnt(2)
; DI float bf1(bf16_t v) { return __uint_as_float(((unsigned)v) << 16); }
; DI u32x4 pack8(const float (&f)[8]) { u32x4 w; w.x = cvtpk(f[0], f[1]); w.y = cvtpk(f[2], f[3]); w.z = cvtpk(f[4], f[5]); w.w = cvtpk(f[6], f[7]); return w; }
; DI void nsa_wg_unit(const Args& a, int l, int b, int g, int tb, unsigned char* lds, int tid_in, bool stage) {
;     ...
;         qs += __shfl_xor(qs, 32); const float rs = rsqrtf(qs * (1.0f / 64.0f) + 1e-6f) * QSC;
; #pragma unroll
;         for (int dc = 0; dc < 4; ++dc) { const f32x4 g0 = *(const f32x4*)(qg + dc * 16 + 8 * h), g1 = *(const f32x4*)(qg + dc * 16 + 8 * h + 4);
; #pragma unroll
;             for (int e = 0; e < 4; ++e) { qv[dc][e] = qv[dc][e] * rs * g0[e]; qv[dc][4 + e] = qv[dc][4 + e] * rs * g1[e]; }
;             qf[0][dc] = __builtin_bit_cast(bf16x8, pack8(qv[dc])); } }
; #pragma unroll
;       for (int br = 0; br < 3; ++br) gt[0][br] = 1.0f / (1.0f + __expf(-bf1(zr[C_NG + (g * 4 + head) * 3 + br])));
;       orow[0] = OB + ((size_t)b * SEQ + tk[0]) * 512 + (g * 4 + head) * 64 + 4 * h; }
;     float cref[3];
;     { const float* qg = a.in[4] + (size_t)l * 4 * 64; float mx[4];
; #pragma unroll
;       for (int k4 = 0; k4 < 4; ++k4) { float v = fabsf(qg[k4 * 64 + lane]);
; #pragma unroll
;           for (int o = 1; o < 64; o <<= 1) v = fmaxf(v, __shfl_xor(v, o));
;           mx[k4] = v; }
; #pragma unroll
;       for (int br = 0; br < 3; ++br) { const float bnd = 64.0f * QSC * mx[0] * mx[1 + br]; cref[br] = bnd > 64.0f ? bnd : 0.f; } }
;     float* wl = (float*)(lds + AL_WT + wave * WT_SZ); float* IA = wl; float* IB = wl + NTOK * 65;
;     for (int i = lane; i < 2 * NTOK * 65; i += 64) wl[i] = 0.f;
;     __syncthreads();
;     AttnSt st;
;     int nv[NRT]; nv[0] = tk[0] >= 31 ? ((tk[0] - 31) >> 4) + 1 : 0;
;     const int nvmax = (t0 + NTOK - 1 >= 31) ? ((t0 + NTOK - 1 - 31) >> 4) + 1 : 0, nst = (nvmax + 31) >> 5;
;     st.l[0] = 0.f;
;     const LP kcl = L + AL_KC + rl * KC_PB + 16 * h, vcl = L + AL_VC + rl * VC_PB + 8 * h;
;     for (int T = 0; T < nst; ++T) { f32x16 s[NRT]; KV f; kv_load_lds(f, kcl + 32 * T * KC_PB, vcl + 64 * T, VC_PB); attn_scores(s, qf, f); float ps = 0.f;
	v_max_f32_e64 v82, |v111|, |v111|
	s_waitcnt lgkmcnt(1)
	v_max_f32_e32 v36, v36, v36
	v_max_f32_e32 v78, v33, v36
	v_and_b32_e32 v36, 0x7fffffff, v110
	s_waitcnt lgkmcnt(0)
	v_max_f32_e32 v33, v61, v61
	ds_bpermute_b32 v36, v152, v36
	v_and_b32_e32 v61, 0x7fffffff, v111
	ds_bpermute_b32 v61, v152, v61
	v_max_f32_e32 v33, v37, v33
	v_max_f32_e64 v37, |v110|, |v110|
	s_waitcnt lgkmcnt(1)
	v_max_f32_e32 v36, v36, v36
	v_max_f32_e32 v36, v37, v36
	s_waitcnt lgkmcnt(0)
	v_max_f32_e32 v61, v61, v61
	ds_bpermute_b32 v37, v153, v36
	v_max_f32_e32 v61, v82, v61
	ds_bpermute_b32 v82, v153, v61
	ds_bpermute_b32 v83, v151, v33
	ds_bpermute_b32 v81, v148, v80
	s_waitcnt lgkmcnt(3)
	v_max_f32_e32 v37, v37, v37
	v_max_f32_e32 v36, v36, v37
	s_waitcnt lgkmcnt(2)
	v_max_f32_e32 v82, v82, v82
	ds_bpermute_b32 v37, v154, v36
	v_max_f32_e32 v61, v61, v82
	ds_bpermute_b32 v82, v154, v61
	s_waitcnt lgkmcnt(3)
	v_max_f32_e32 v83, v83, v83
	v_max_f32_e32 v96, v33, v83
	s_waitcnt lgkmcnt(1)
	v_max_f32_e32 v37, v37, v37
	v_max_f32_e32 v36, v36, v37
	s_waitcnt lgkmcnt(0)
	v_max_f32_e32 v82, v82, v82
	ds_bpermute_b32 v37, v150, v36
	v_max_f32_e32 v61, v61, v82
	ds_bpermute_b32 v82, v150, v61
	ds_bpermute_b32 v79, v148, v78
	ds_bpermute_b32 v97, v148, v96
	s_waitcnt lgkmcnt(3)
	v_max_f32_e32 v33, v37, v37
	v_max_f32_e32 v33, v36, v33
	s_waitcnt lgkmcnt(2)
	v_max_f32_e32 v37, v82, v82
	ds_bpermute_b32 v36, v151, v33
	v_max_f32_e32 v61, v61, v37
	ds_bpermute_b32 v82, v151, v61
	v_add_u32_e32 v83, s9, v108
	s_waitcnt lgkmcnt(1)
	v_max_f32_e32 v36, v36, v36
	v_max_f32_e32 v33, v33, v36
	s_waitcnt lgkmcnt(0)
	v_max_f32_e32 v36, v82, v82
	v_max_f32_e32 v36, v61, v36
	ds_bpermute_b32 v37, v148, v33
	ds_bpermute_b32 v61, v148, v36
	v_or_b32_e32 v82, 0xffffffc0, v76
	.p2align	6
.LBB0_197:
	v_add_u32_e32 v82, 64, v82
	v_cmp_lt_u32_e32 vcc, s23, v82
	ds_write_b32 v83, v161
	s_or_b64 s[0:1], vcc, s[0:1]
	v_add_u32_e32 v83, 0x100, v83
	s_andn2_b64 exec, exec, s[0:1]
	s_cbranch_execnz .LBB0_197
	s_or_b64 exec, exec, s[0:1]
	v_add_f32_e32 v80, v80, v81
	v_fmamk_f32 v80, v80, 0x3c800000, v162
	v_mul_f32_e32 v81, 0x4b800000, v80
	v_cmp_gt_f32_e32 vcc, s24, v80
	s_sub_i32 s0, s96, 24
	s_lshr_b32 s0, s0, 4
	v_cndmask_b32_e32 v80, v80, v81, vcc
	v_rsq_f32_e32 v80, v80
	s_add_i32 s0, s0, 32
	s_or_b32 s97, s96, 7
	s_lshr_b32 s0, s0, 5
	v_mul_f32_e32 v81, 0x45800000, v80
	v_cndmask_b32_e32 v80, v80, v81, vcc
	v_mul_f32_e32 v92, 0x3e38aa3b, v80
	v_pk_mul_f32 v[70:71], v[92:93], v[70:71] op_sel_hi:[0,1]
	v_pk_mul_f32 v[24:25], v[24:25], v[70:71]
	v_pk_mul_f32 v[34:35], v[92:93], v[34:35] op_sel_hi:[0,1]
	v_cvt_pk_bf16_f32 v82, v24, v25
	v_pk_mul_f32 v[24:25], v[92:93], v[64:65] op_sel_hi:[0,1]
	v_pk_mul_f32 v[20:21], v[20:21], v[24:25]
	v_pk_mul_f32 v[24:25], v[92:93], v[58:59] op_sel_hi:[0,1]
	v_pk_mul_f32 v[16:17], v[16:17], v[24:25]
	v_pk_mul_f32 v[28:29], v[28:29], v[34:35]
	v_cvt_pk_bf16_f32 v86, v16, v17
	v_pk_mul_f32 v[16:17], v[92:93], v[52:53] op_sel_hi:[0,1]
	v_pk_mul_f32 v[12:13], v[12:13], v[16:17]
	v_pk_mul_f32 v[16:17], v[92:93], v[50:51] op_sel_hi:[0,1]
	v_pk_mul_f32 v[8:9], v[8:9], v[16:17]
	v_pk_mul_f32 v[34:35], v[92:93], v[68:69] op_sel_hi:[0,1]
	v_cvt_pk_bf16_f32 v90, v8, v9
	v_pk_mul_f32 v[8:9], v[92:93], v[44:45] op_sel_hi:[0,1]
	v_pk_mul_f32 v[4:5], v[4:5], v[8:9]
	v_pk_mul_f32 v[8:9], v[92:93], v[42:43] op_sel_hi:[0,1]
	v_pk_mul_f32 v[0:1], v[0:1], v[8:9]
	v_pk_mul_f32 v[8:9], v[92:93], v[40:41] op_sel_hi:[0,1]
	v_pk_mul_f32 v[6:7], v[6:7], v[8:9]
	v_pk_mul_f32 v[8:9], v[92:93], v[38:39] op_sel_hi:[0,1]
	v_pk_mul_f32 v[2:3], v[2:3], v[8:9]
	v_cvt_pk_bf16_f32 v94, v0, v1
	v_max_f32_e32 v0, v79, v79
	v_max_f32_e32 v1, v78, v78
	v_cvt_pk_bf16_f32 v95, v2, v3
	v_max_f32_e32 v0, v1, v0
	v_max_f32_e32 v1, v97, v97
	v_max_f32_e32 v2, v96, v96
	v_max_f32_e32 v1, v2, v1
	v_mul_f32_e32 v156, 0x4138aa3b, v0
	v_mul_f32_e32 v0, v156, v1
	v_cmp_lt_f32_e32 vcc, s25, v0
	v_pk_mul_f32 v[24:25], v[92:93], v[56:57] op_sel_hi:[0,1]
	v_pk_mul_f32 v[16:17], v[92:93], v[48:49] op_sel_hi:[0,1]
	v_cndmask_b32_e32 v70, 0, v0, vcc
	v_subrev_u32_e32 v0, 31, v136
	s_cmp_gt_i32 s97, 30
	v_pk_mul_f32 v[30:31], v[30:31], v[34:35]
	v_pk_mul_f32 v[34:35], v[92:93], v[66:67] op_sel_hi:[0,1]
	v_pk_mul_f32 v[22:23], v[22:23], v[24:25]
	v_pk_mul_f32 v[24:25], v[92:93], v[54:55] op_sel_hi:[0,1]
	v_pk_mul_f32 v[14:15], v[14:15], v[16:17]
	v_pk_mul_f32 v[16:17], v[92:93], v[46:47] op_sel_hi:[0,1]
	v_lshrrev_b32_e32 v0, 4, v0
	s_cselect_b32 s6, s0, 0
	v_pk_mul_f32 v[26:27], v[26:27], v[34:35]
	v_pk_mul_f32 v[18:19], v[18:19], v[24:25]
	v_pk_mul_f32 v[10:11], v[10:11], v[16:17]
	v_add_u32_e32 v0, 1, v0
	v_cmp_lt_i32_e32 vcc, 30, v136
	v_mul_u32_u24_e32 v65, 0x90, v72
	s_cmp_lg_u32 s6, 0
	v_cvt_pk_bf16_f32 v80, v28, v29
	v_cvt_pk_bf16_f32 v81, v30, v31
	v_cvt_pk_bf16_f32 v83, v26, v27
	v_cvt_pk_bf16_f32 v84, v20, v21
	v_cvt_pk_bf16_f32 v85, v22, v23
	v_cvt_pk_bf16_f32 v87, v18, v19
	v_cvt_pk_bf16_f32 v88, v12, v13
	v_cvt_pk_bf16_f32 v89, v14, v15
	v_cvt_pk_bf16_f32 v91, v10, v11
	v_cvt_pk_bf16_f32 v92, v4, v5
	v_cvt_pk_bf16_f32 v93, v6, v7
	v_lshlrev_b32_e32 v154, 2, v77
	v_mov_b32_e32 v16, 0
	v_cndmask_b32_e32 v64, 0, v0, vcc
	s_cselect_b64 s[0:1], -1, 0
	s_cmp_eq_u32 s6, 0
	v_add3_u32 v71, 0, v65, v60
	s_waitcnt lgkmcnt(0)
	s_barrier
	s_cbranch_scc1 .LBB0_201
	s_lshl_b32 s7, s6, 5
	v_mov_b32_e32 v16, 0
	s_mov_b32 s10, 0
	v_mov_b32_e32 v17, v71
	.p2align	6

; DI float bf1(bf16_t v) { return __uint_as_float(((unsigned)v) << 16); }
; DI int crow(int i, int h) { return (i & 3) + 8 * (i >> 2) + 4 * h; }
; DI void nsa_wg_unit(const Args& a, int l, int b, int g, int tb, unsigned char* lds, int tid_in, bool stage) {
;     ...
;       for (int br = 0; br < 3; ++br) gt[0][br] = 1.0f / (1.0f + __expf(-bf1(zr[C_NG + (g * 4 + head) * 3 + br])));
;       orow[0] = OB + ((size_t)b * SEQ + tk[0]) * 512 + (g * 4 + head) * 64 + 4 * h; }
;     float cref[3];
;     { const float* qg = a.in[4] + (size_t)l * 4 * 64; float mx[4];
; #pragma unroll
;       for (int k4 = 0; k4 < 4; ++k4) { float v = fabsf(qg[k4 * 64 + lane]);
; #pragma unroll
;           for (int o = 1; o < 64; o <<= 1) v = fmaxf(v, __shfl_xor(v, o));
;           mx[k4] = v; }
; #pragma unroll
;       for (int br = 0; br < 3; ++br) { const float bnd = 64.0f * QSC * mx[0] * mx[1 + br]; cref[br] = bnd > 64.0f ? bnd : 0.f; } }
;     float* wl = (float*)(lds + AL_WT + wave * WT_SZ); float* IA = wl; float* IB = wl + NTOK * 65;
;     for (int i = lane; i < 2 * NTOK * 65; i += 64) wl[i] = 0.f;
;     __syncthreads();
;     AttnSt st;
;     int nv[NRT]; nv[0] = tk[0] >= 31 ? ((tk[0] - 31) >> 4) + 1 : 0;
;     const int nvmax = (t0 + NTOK - 1 >= 31) ? ((t0 + NTOK - 1 - 31) >> 4) + 1 : 0, nst = (nvmax + 31) >> 5;
;     st.l[0] = 0.f;
;     const LP kcl = L + AL_KC + rl * KC_PB + 16 * h, vcl = L + AL_VC + rl * VC_PB + 8 * h;
;     for (int T = 0; T < nst; ++T) { f32x16 s[NRT]; KV f; kv_load_lds(f, kcl + 32 * T * KC_PB, vcl + 64 * T, VC_PB); attn_scores(s, qf, f); float ps = 0.f;
; #pragma unroll
;         for (int i = 0; i < 16; ++i) { const float sv = (32 * T + crow(i, h) >= nv[0]) ? -INFINITY : s[0][i] - cref[0]; ps += __builtin_amdgcn_exp2f(sv); }
;         st.l[0] += ps; }
;     float mu2, inv;
;     { const float lt = st.l[0] + __shfl_xor(st.l[0], 32); inv = lt > 0.f ? 1.0f / lt : 0.f; mu2 = cref[0]; }
;     attn_reset(st);
;     for (int T = 0; T < nst; ++T) { f32x16 s[NRT]; KV f; kv_load_lds(f, kcl + 32 * T * KC_PB, vcl + 64 * T, VC_PB); attn_scores(s, qf, f);
.LBB0_201:
	s_waitcnt vmcnt(1)
	v_lshlrev_b32_e32 v0, 16, v32
	v_mul_f32_e32 v0, 0xbfb8aa3b, v0
	v_exp_f32_e32 v78, v0
	v_and_b32_e32 v0, 0xffff0000, v32
	v_mul_f32_e32 v0, 0xbfb8aa3b, v0
	v_exp_f32_e32 v158, v0
	v_max_f32_e32 v0, v37, v37
	v_max_f32_e32 v1, v33, v33
	v_max_f32_e32 v69, v1, v0
	v_max_f32_e32 v0, v61, v61
	v_max_f32_e32 v1, v36, v36
	v_max_f32_e32 v157, v1, v0
	ds_bpermute_b32 v0, v148, v16
	s_andn2_b64 vcc, exec, s[0:1]
	s_cbranch_vccnz .LBB0_216
	s_waitcnt lgkmcnt(0)
	v_add_f32_e32 v1, v16, v0
	v_div_scale_f32 v2, s[0:1], v1, v1, 1.0
	v_rcp_f32_e32 v3, v2
	s_movk_i32 s0, 0x41
	v_mov_b32_e32 v0, 0
	s_mov_b32 s10, 0
	v_fma_f32 v4, -v2, v3, 1.0
	v_fmac_f32_e32 v3, v4, v3
	v_div_scale_f32 v4, vcc, 1.0, v1, 1.0
	v_mul_f32_e32 v5, v4, v3
	v_fma_f32 v6, -v2, v5, v4
	v_fmac_f32_e32 v5, v6, v3
	v_fma_f32 v2, -v2, v5, v4
	v_div_fmas_f32 v2, v2, v3, v5
	v_div_fixup_f32 v2, v2, v1, 1.0
	v_cmp_lt_f32_e32 vcc, 0, v1
	v_mad_u32_u24 v1, v75, s0, v77
	s_movk_i32 s0, 0x178
	v_cndmask_b32_e32 v66, 0, v2, vcc
	v_lshl_add_u32 v79, v1, 2, s8
	v_mad_u32_u24 v1, v72, s0, v65
	s_add_i32 s0, 0, 0x9000
	v_cmp_eq_u32_e32 vcc, 0, v63
	v_mov_b32_e32 v61, v64
	v_mov_b32_e32 v67, v66
	s_lshl_b32 s11, s6, 5
	v_add3_u32 v96, v1, v73, s0
	v_mov_b32_e32 v1, v0
	v_mov_b32_e32 v2, v0
	v_mov_b32_e32 v3, v0
	v_mov_b32_e32 v4, v0
	v_mov_b32_e32 v5, v0
	v_mov_b32_e32 v6, v0
	v_mov_b32_e32 v7, v0
	v_mov_b32_e32 v8, v0
	v_mov_b32_e32 v9, v0
	v_mov_b32_e32 v10, v0
	v_mov_b32_e32 v11, v0
	v_mov_b32_e32 v12, v0
	v_mov_b32_e32 v13, v0
	v_mov_b32_e32 v14, v0
	v_mov_b32_e32 v15, v0
	v_mov_b32_e32 v16, v0
	v_mov_b32_e32 v17, v0
	v_mov_b32_e32 v18, v0
	v_mov_b32_e32 v19, v0
	v_mov_b32_e32 v20, v0
	v_mov_b32_e32 v21, v0
	v_mov_b32_e32 v22, v0
	v_mov_b32_e32 v23, v0
	v_mov_b32_e32 v24, v0
	v_mov_b32_e32 v25, v0
	v_mov_b32_e32 v26, v0
	v_mov_b32_e32 v27, v0
	v_mov_b32_e32 v28, v0
	v_mov_b32_e32 v29, v0
	v_mov_b32_e32 v30, v0
	v_mov_b32_e32 v31, v0
	s_branch .LBB0_204
	.p2align	6

; DI void nsa_wg_unit(const Args& a, int l, int b, int g, int tb, unsigned char* lds, int tid_in, bool stage) {
;     ...
;       for (int i = 0; i < 64; ++i) { const float vi = IA[tok * 65 + i];
; #pragma unroll
;           for (int c = 0; c < CPL; ++c) { const int j = qtr * CPL + c; cnt[c] += ((vi > mv[c]) || (vi == mv[c] && i < j)) ? 1 : 0; } }
.LBB0_234:
	v_cmp_le_u32_e64 s[6:7], s99, v32
	v_cmp_lt_u32_e64 s[8:9], s99, v32
	ds_read2_b32 v[58:59], v33 offset1:1
	ds_read2_b32 v[62:63], v33 offset0:2 offset1:3
	ds_read2_b32 v[66:67], v33 offset0:4 offset1:5
	ds_read_b32 v61, v33 offset:24
	ds_read_b32 v64, v33 offset:28
	v_cndmask_b32_e64 v17, v4, v1, s[6:7]
	v_cndmask_b32_e64 v19, v2, v3, s[6:7]
	v_cndmask_b32_e64 v21, v10, v5, s[6:7]
	v_cndmask_b32_e64 v23, v8, v7, s[6:7]
	v_cndmask_b32_e64 v25, v18, v9, s[6:7]
	v_cndmask_b32_e64 v27, v16, v11, s[6:7]
	v_cndmask_b32_e64 v29, v26, v13, s[6:7]
	v_cndmask_b32_e64 v30, v24, v15, s[6:7]
	v_cndmask_b32_e64 v50, v4, v1, s[8:9]
	v_cndmask_b32_e64 v51, v2, v3, s[8:9]
	v_cndmask_b32_e64 v52, v10, v5, s[8:9]
	v_cndmask_b32_e64 v53, v8, v7, s[8:9]
	v_cndmask_b32_e64 v54, v18, v9, s[8:9]
	v_cndmask_b32_e64 v55, v16, v11, s[8:9]
	v_cndmask_b32_e64 v56, v26, v13, s[8:9]
	v_cndmask_b32_e64 v57, v24, v15, s[8:9]
	s_waitcnt lgkmcnt(0)
	v_cmp_gt_f32_e64 s[8:9], v58, v50
	v_cmp_gt_f32_e64 s[10:11], v58, v19
	v_cmp_gt_f32_e64 s[12:13], v58, v21
	v_addc_co_u32_e64 v39, vcc, 0, v39, s[8:9]
	v_cmp_gt_f32_e64 s[14:15], v58, v23
	v_addc_co_u32_e64 v43, vcc, 0, v43, s[10:11]
	v_cmp_gt_f32_e64 s[8:9], v58, v25
	v_addc_co_u32_e64 v47, vcc, 0, v47, s[12:13]
	v_cmp_gt_f32_e64 s[10:11], v58, v27
	v_addc_co_u32_e64 v49, vcc, 0, v49, s[14:15]
	v_cmp_gt_f32_e64 s[12:13], v58, v29
	v_addc_co_u32_e64 v46, vcc, 0, v46, s[8:9]
	v_cmp_gt_f32_e64 s[14:15], v58, v30
	v_addc_co_u32_e64 v42, vcc, 0, v42, s[10:11]
	v_cmp_gt_f32_e64 s[8:9], v59, v50
	v_addc_co_u32_e64 v38, vcc, 0, v38, s[12:13]
	v_cmp_gt_f32_e64 s[10:11], v59, v51
	v_addc_co_u32_e64 v35, vcc, 0, v35, s[14:15]
	v_cmp_gt_f32_e64 s[12:13], v59, v21
	v_addc_co_u32_e64 v39, vcc, 0, v39, s[8:9]
	v_cmp_gt_f32_e64 s[14:15], v59, v23
	v_addc_co_u32_e64 v43, vcc, 0, v43, s[10:11]
	v_cmp_gt_f32_e64 s[8:9], v59, v25
	v_addc_co_u32_e64 v47, vcc, 0, v47, s[12:13]
	v_cmp_gt_f32_e64 s[10:11], v59, v27
	v_addc_co_u32_e64 v49, vcc, 0, v49, s[14:15]
	v_cmp_gt_f32_e64 s[12:13], v59, v29
	v_addc_co_u32_e64 v46, vcc, 0, v46, s[8:9]
	v_cmp_gt_f32_e64 s[14:15], v59, v30
	v_addc_co_u32_e64 v42, vcc, 0, v42, s[10:11]
	v_cmp_gt_f32_e64 s[8:9], v62, v50
	v_addc_co_u32_e64 v38, vcc, 0, v38, s[12:13]
	v_cmp_gt_f32_e64 s[10:11], v62, v51
	v_addc_co_u32_e64 v35, vcc, 0, v35, s[14:15]
	v_cmp_gt_f32_e64 s[12:13], v62, v52
	v_addc_co_u32_e64 v39, vcc, 0, v39, s[8:9]
	v_cmp_gt_f32_e64 s[14:15], v62, v23
	v_addc_co_u32_e64 v43, vcc, 0, v43, s[10:11]
	v_cmp_gt_f32_e64 s[8:9], v62, v25
	v_addc_co_u32_e64 v47, vcc, 0, v47, s[12:13]
	v_cmp_gt_f32_e64 s[10:11], v62, v27
	v_addc_co_u32_e64 v49, vcc, 0, v49, s[14:15]
	v_cmp_gt_f32_e64 s[12:13], v62, v29
	v_addc_co_u32_e64 v46, vcc, 0, v46, s[8:9]
	v_cmp_gt_f32_e64 s[14:15], v62, v30
	v_addc_co_u32_e64 v42, vcc, 0, v42, s[10:11]
	v_cmp_gt_f32_e64 s[8:9], v63, v50
	v_addc_co_u32_e64 v38, vcc, 0, v38, s[12:13]
	v_cmp_gt_f32_e64 s[10:11], v63, v51
	v_addc_co_u32_e64 v35, vcc, 0, v35, s[14:15]
	v_cmp_gt_f32_e64 s[12:13], v63, v52
	v_addc_co_u32_e64 v39, vcc, 0, v39, s[8:9]
	v_cmp_gt_f32_e64 s[14:15], v63, v53
	v_addc_co_u32_e64 v43, vcc, 0, v43, s[10:11]
	v_cmp_gt_f32_e64 s[8:9], v63, v25
	v_addc_co_u32_e64 v47, vcc, 0, v47, s[12:13]
	v_cmp_gt_f32_e64 s[10:11], v63, v27
	v_addc_co_u32_e64 v49, vcc, 0, v49, s[14:15]
	v_cmp_gt_f32_e64 s[12:13], v63, v29
	v_addc_co_u32_e64 v46, vcc, 0, v46, s[8:9]
	v_cmp_gt_f32_e64 s[14:15], v63, v30
	v_addc_co_u32_e64 v42, vcc, 0, v42, s[10:11]
	v_cmp_gt_f32_e64 s[8:9], v66, v50
	v_addc_co_u32_e64 v38, vcc, 0, v38, s[12:13]
	v_cmp_gt_f32_e64 s[10:11], v66, v51
	v_addc_co_u32_e64 v35, vcc, 0, v35, s[14:15]
	v_cmp_gt_f32_e64 s[12:13], v66, v52
	v_addc_co_u32_e64 v39, vcc, 0, v39, s[8:9]
	v_cmp_gt_f32_e64 s[14:15], v66, v53
	v_addc_co_u32_e64 v43, vcc, 0, v43, s[10:11]
	v_cmp_gt_f32_e64 s[8:9], v66, v54
	v_addc_co_u32_e64 v47, vcc, 0, v47, s[12:13]
	v_cmp_gt_f32_e64 s[10:11], v66, v27
	v_addc_co_u32_e64 v49, vcc, 0, v49, s[14:15]
	v_cmp_gt_f32_e64 s[12:13], v66, v29
	v_addc_co_u32_e64 v46, vcc, 0, v46, s[8:9]
	v_cmp_gt_f32_e64 s[14:15], v66, v30
	v_addc_co_u32_e64 v42, vcc, 0, v42, s[10:11]
	v_cmp_gt_f32_e64 s[8:9], v67, v50
	v_addc_co_u32_e64 v38, vcc, 0, v38, s[12:13]
	v_cmp_gt_f32_e64 s[10:11], v67, v51
	v_addc_co_u32_e64 v35, vcc, 0, v35, s[14:15]
	v_cmp_gt_f32_e64 s[12:13], v67, v52
	v_addc_co_u32_e64 v39, vcc, 0, v39, s[8:9]
	v_cmp_gt_f32_e64 s[14:15], v67, v53
	v_addc_co_u32_e64 v43, vcc, 0, v43, s[10:11]
	v_cmp_gt_f32_e64 s[8:9], v67, v54
	v_addc_co_u32_e64 v47, vcc, 0, v47, s[12:13]
	v_cmp_gt_f32_e64 s[10:11], v67, v55
	v_addc_co_u32_e64 v49, vcc, 0, v49, s[14:15]
	v_cmp_gt_f32_e64 s[12:13], v67, v29
	v_addc_co_u32_e64 v46, vcc, 0, v46, s[8:9]
	v_cmp_gt_f32_e64 s[14:15], v67, v30
	v_addc_co_u32_e64 v42, vcc, 0, v42, s[10:11]
	v_cmp_gt_f32_e64 s[8:9], v61, v50
	v_addc_co_u32_e64 v38, vcc, 0, v38, s[12:13]
	v_cmp_gt_f32_e64 s[10:11], v61, v51
	v_addc_co_u32_e64 v35, vcc, 0, v35, s[14:15]
	v_cmp_gt_f32_e64 s[12:13], v61, v52
	v_addc_co_u32_e64 v39, vcc, 0, v39, s[8:9]
	v_cmp_gt_f32_e64 s[14:15], v61, v53
	v_addc_co_u32_e64 v43, vcc, 0, v43, s[10:11]
	v_cmp_gt_f32_e64 s[8:9], v61, v54
	v_addc_co_u32_e64 v47, vcc, 0, v47, s[12:13]
	v_cmp_gt_f32_e64 s[10:11], v61, v55
	v_addc_co_u32_e64 v49, vcc, 0, v49, s[14:15]
	v_cmp_gt_f32_e64 s[12:13], v61, v56
	v_addc_co_u32_e64 v46, vcc, 0, v46, s[8:9]
	v_cmp_gt_f32_e64 s[14:15], v61, v30
	v_addc_co_u32_e64 v42, vcc, 0, v42, s[10:11]
	v_cmp_gt_f32_e64 s[8:9], v64, v50
	v_addc_co_u32_e64 v38, vcc, 0, v38, s[12:13]
	v_cmp_gt_f32_e64 s[10:11], v64, v51
	v_addc_co_u32_e64 v35, vcc, 0, v35, s[14:15]
	v_cmp_gt_f32_e64 s[12:13], v64, v52
	v_addc_co_u32_e64 v39, vcc, 0, v39, s[8:9]
	v_cmp_gt_f32_e64 s[14:15], v64, v53
	v_addc_co_u32_e64 v43, vcc, 0, v43, s[10:11]
	v_cmp_gt_f32_e64 s[8:9], v64, v54
	v_addc_co_u32_e64 v47, vcc, 0, v47, s[12:13]
	v_cmp_gt_f32_e64 s[10:11], v64, v55
	v_addc_co_u32_e64 v49, vcc, 0, v49, s[14:15]
	v_cmp_gt_f32_e64 s[12:13], v64, v56
	v_addc_co_u32_e64 v46, vcc, 0, v46, s[8:9]
	v_cmp_gt_f32_e64 s[14:15], v64, v57
	v_addc_co_u32_e64 v42, vcc, 0, v42, s[10:11]
	v_addc_co_u32_e64 v38, vcc, 0, v38, s[12:13]
	v_addc_co_u32_e64 v35, vcc, 0, v35, s[14:15]
	v_add_u32_e32 v33, 32, v33
	s_add_i32 s99, s99, 1
	s_cmp_lt_u32 s99, s98
	s_cbranch_scc1 .LBB0_234
; DI void nsa_wg_unit(const Args& a, int l, int b, int g, int tb, unsigned char* lds, int tid_in, bool stage) {
;     ...
;       unsigned mc = 0;
; #pragma unroll
;       for (int c = 0; c < CPL; ++c) mc |= (cnt[c] < 16) ? (1u << c) : 0u;
;       unsigned lo = 0, hi = 0;
; #pragma unroll
;       for (int k = 0; k < LPT / 2; ++k) { lo |= (unsigned)__shfl((int)mc, tok * LPT + k) << (CPL * k); hi |= (unsigned)__shfl((int)mc, tok * LPT + LPT / 2 + k) << (CPL * k); }
;       { const int src = (rl >> 2) * LPT; sel_lo[0] = (unsigned)__shfl((int)lo, src); sel_hi[0] = (unsigned)__shfl((int)hi, src); }
;       unsigned ul = lo, uh = hi;
; #pragma unroll
;       for (int o = LPT; o < 64; o <<= 1) { ul |= (unsigned)__shfl_xor((int)ul, o); uh |= (unsigned)__shfl_xor((int)uh, o); }
;       ulo = (unsigned)__builtin_amdgcn_readfirstlane((int)ul); uhi = (unsigned)__builtin_amdgcn_readfirstlane((int)uh); }
;     const unsigned long long myu = ((unsigned long long)uhi << 32) | (unsigned long long)ulo;
;     unsigned long long* UW = (unsigned long long*)(lds + AL_UW);
;     if (lane == 0) UW[wave] = myu;
;     __syncthreads();
;     unsigned long long wgu = 0ull;
; #pragma unroll
;     for (int w = 0; w < 8; ++w) wgu |= UW[w];
;     wgu = ((unsigned long long)(unsigned)__builtin_amdgcn_readfirstlane((int)(wgu >> 32)) << 32) | (unsigned long long)(unsigned)__builtin_amdgcn_readfirstlane((int)(unsigned)wgu);
;     const int srow = tid >> 3, sch = tid & 7;
;     const LP kfl = L + AL_KR + rl * KR_PB + 16 * h, vfl = L + AL_VR + rl * VR_PB + 8 * h;
;     attn_reset(st);
;     { unsigned long long rem = wgu & ((jt >= 63) ? ~0ull : ((1ull << (jt + 1)) - 1ull));
;       const unsigned koff = (unsigned)(srow * ZP + sch * 8) * 2u, voff = (unsigned)(srow * SEQ + sch * 8) * 2u;
;       const char* kgb = (const char*)(zb + C_KV + 2 * 128 + g * 64); const char* vgb = (const char*)VST;
;       int j = rem ? (int)__builtin_ctzll(rem) : -1, bi = 0; u32x4 kreg, vreg;
;       if (j >= 0) { kreg = *(const u32x4*)(kgb + (size_t)(64 * j) * ZP * 2 + koff); vreg = *(const u32x4*)(vgb + (size_t)(64 * j) * 2 + voff);
;           *(u32x4*)(lds + AL_KR + srow * KR_PB + sch * 16) = kreg; u32x2* d = (u32x2*)(lds + AL_VR + srow * VR_PB + sch * 16); u32x2 lo2, hi2; lo2.x = vreg.x; lo2.y = vreg.y; hi2.x = vreg.z; hi2.y = vreg.w; d[0] = lo2; d[1] = hi2; }
;       __syncthreads();
	v_add_u32_e32 v0, v36, v39
	v_add_u32_e32 v1, v40, v43
	v_cmp_gt_i32_e32 vcc, 16, v0
	v_add_u32_e32 v2, v44, v47
	v_add_u32_e32 v3, v48, v49
	v_cndmask_b32_e64 v0, 0, 1, vcc
	v_cmp_gt_i32_e32 vcc, 16, v1
	v_add_u32_e32 v4, v45, v46
	v_add_u32_e32 v5, v41, v42
	v_cndmask_b32_e64 v1, 0, 2, vcc
	v_cmp_gt_i32_e32 vcc, 16, v2
	v_or_b32_e32 v0, v1, v0
	v_add_u32_e32 v6, v37, v38
	v_cndmask_b32_e64 v1, 0, 4, vcc
	v_cmp_gt_i32_e32 vcc, 16, v3
	v_add_u32_e32 v7, v34, v35
	s_nop 0
	v_cndmask_b32_e64 v2, 0, 8, vcc
	v_cmp_gt_i32_e32 vcc, 16, v4
	v_or3_b32 v0, v0, v1, v2
	s_nop 0
	v_cndmask_b32_e64 v1, 0, 16, vcc
	v_cmp_gt_i32_e32 vcc, 16, v5
	s_nop 1
	v_cndmask_b32_e64 v2, 0, 32, vcc
	v_cmp_gt_i32_e32 vcc, 16, v6
	v_or3_b32 v0, v0, v1, v2
	s_nop 0
	v_cndmask_b32_e64 v1, 0, 64, vcc
	v_cmp_gt_i32_e32 vcc, 16, v7
	s_nop 1
	v_cndmask_b32_e32 v2, 0, v198, vcc
	v_or3_b32 v0, v0, v1, v2
	v_and_or_b32 v1, v74, 56, v149
	v_lshlrev_b32_e32 v1, 2, v1
	ds_bpermute_b32 v2, v1, v0
	ds_bpermute_b32 v3, v1, v0 offset:4
	ds_bpermute_b32 v4, v1, v0 offset:16
	ds_bpermute_b32 v5, v1, v0 offset:20
	ds_bpermute_b32 v6, v1, v0 offset:24
	ds_bpermute_b32 v7, v1, v0 offset:12
	s_waitcnt lgkmcnt(4)
	v_lshl_or_b32 v2, v3, 8, v2
	ds_bpermute_b32 v3, v1, v0 offset:8
	ds_bpermute_b32 v0, v1, v0 offset:28
	s_waitcnt lgkmcnt(4)
	v_lshl_or_b32 v4, v5, 8, v4
	s_waitcnt lgkmcnt(2)
	v_lshlrev_b32_e32 v5, 24, v7
	v_cmp_eq_u32_e32 vcc, 0, v76
	s_waitcnt lgkmcnt(1)
	v_lshlrev_b32_e32 v1, 16, v3
	v_lshlrev_b32_e32 v3, 16, v6
	s_waitcnt lgkmcnt(0)
	v_lshlrev_b32_e32 v0, 24, v0
	v_or3_b32 v1, v2, v1, v5
	v_or3_b32 v0, v4, v3, v0
	ds_bpermute_b32 v2, v150, v1
	ds_bpermute_b32 v3, v150, v0
	v_lshl_or_b32 v6, v75, 5, v155
	ds_bpermute_b32 v159, v6, v1
	ds_bpermute_b32 v165, v6, v0
	s_waitcnt lgkmcnt(3)
	v_or_b32_e32 v2, v2, v1
	s_waitcnt lgkmcnt(2)
	v_or_b32_e32 v3, v3, v0
	ds_bpermute_b32 v4, v151, v2
	ds_bpermute_b32 v5, v151, v3
	s_waitcnt lgkmcnt(1)
	v_or_b32_e32 v2, v4, v2
	s_waitcnt lgkmcnt(0)
	v_or_b32_e32 v3, v5, v3
	ds_bpermute_b32 v4, v148, v2
	ds_bpermute_b32 v5, v148, v3
	s_waitcnt lgkmcnt(1)
	v_or_b32_e32 v1, v4, v2
	s_waitcnt lgkmcnt(0)
	v_or_b32_e32 v0, v5, v3
	v_readfirstlane_b32 s0, v1
	v_readfirstlane_b32 s1, v0
	s_and_saveexec_b64 s[6:7], vcc
	s_add_i32 s8, s16, 0
	s_add_i32 s8, s8, 0x22200
	v_mov_b32_e32 v0, s8
	v_mov_b64_e32 v[2:3], s[0:1]
	ds_write_b64 v0, v[2:3]
	s_or_b64 exec, exec, s[6:7]
	v_mov_b32_e32 v0, s44
	s_waitcnt lgkmcnt(0)
	s_barrier
	ds_read_b128 v[0:3], v0
	v_readlane_b32 s6, v253, 24
	s_sub_i32 s8, 64, s33
	s_lshl_b64 s[8:9], -1, s8
	s_not_b64 s[8:9], s[8:9]
	s_waitcnt lgkmcnt(0)
	v_or_b32_e32 v4, v2, v0
	v_mov_b32_e32 v0, s6
	v_or_b32_e32 v5, v3, v1
	ds_read_b128 v[0:3], v0
	v_readlane_b32 s6, v253, 25
	s_cmp_lg_u32 s33, 0
	s_cselect_b32 s9, s9, -1
	s_cselect_b32 s8, s8, -1
	s_waitcnt lgkmcnt(0)
	v_or_b32_e32 v0, v4, v0
	v_or_b32_e32 v1, v5, v1
	v_or_b32_e32 v4, v0, v2
	v_mov_b32_e32 v0, s6
	v_or_b32_e32 v5, v1, v3
	ds_read_b128 v[0:3], v0
	v_readlane_b32 s6, v253, 26
	v_lshlrev_b32_e32 v138, 4, v32
	s_waitcnt lgkmcnt(0)
	v_or_b32_e32 v0, v4, v0
	v_or_b32_e32 v1, v5, v1
	v_or_b32_e32 v4, v0, v2
	v_mov_b32_e32 v0, s6
	v_or_b32_e32 v5, v1, v3
	ds_read_b128 v[0:3], v0
	s_waitcnt lgkmcnt(0)
	v_or_b32_e32 v0, v4, v0
	v_or_b32_e32 v1, v5, v1
	v_or_b32_e32 v0, v0, v2
	v_or_b32_e32 v1, v1, v3
	v_readfirstlane_b32 s6, v0
	v_readfirstlane_b32 s7, v1
	v_ashrrev_i32_e32 v0, 3, v74
	s_and_b64 s[78:79], s[6:7], s[8:9]
	s_waitcnt vmcnt(8)
	v_mad_u64_u32 v[142:143], s[6:7], v0, s3, v[138:139]
	s_cmp_lg_u64 s[78:79], 0
	s_cselect_b64 s[6:7], -1, 0
	v_lshl_or_b32 v160, v0, 13, v138
	s_ff1_i32_b64 s80, s[78:79]
	v_mov_b32_e32 v143, v161
	s_and_b64 vcc, exec, s[6:7]
	v_mul_lo_u32 v152, v0, s22
	v_mul_lo_u32 v153, v0, s27
	s_cbranch_vccz .LBB0_255
	s_lshl_b64 s[8:9], s[80:81], 7
	s_mul_i32 s10, s80, 0x88c00
	s_add_u32 s10, s40, s10
	s_addc_u32 s11, s41, 0
	global_load_dwordx4 v[96:99], v142, s[10:11]
	s_add_u32 s8, s38, s8
	s_addc_u32 s9, s39, s9
	global_load_dwordx4 v[100:103], v160, s[8:9]
	v_mul_lo_u32 v1, v0, s22
	v_add3_u32 v1, s26, v1, v138
	s_waitcnt vmcnt(1)
	ds_write_b128 v1, v[96:99]
	v_mul_lo_u32 v1, v0, s27
	v_add3_u32 v1, s28, v1, v138
	s_waitcnt vmcnt(0)
	ds_write2_b64 v1, v[100:101], v[102:103] offset1:1
	s_cbranch_execnz .LBB0_240
	.p2align	6

; DI void nsa_wg_unit(const Args& a, int l, int b, int g, int tb, unsigned char* lds, int tid_in, bool stage) {
;     ...
;       while (j >= 0) {
;           rem &= rem - 1ull; const int nj = rem ? (int)__builtin_ctzll(rem) : -1;
;           if (nj >= 0) { kreg = *(const u32x4*)(kgb + (size_t)(64 * nj) * ZP * 2 + koff); vreg = *(const u32x4*)(vgb + (size_t)(64 * nj) * 2 + voff); }
.LBB0_242:
	s_add_u32 s82, s78, -1
	s_addc_u32 s83, s79, -1
	s_and_b64 s[78:79], s[82:83], s[78:79]
	s_cmp_eq_u64 s[78:79], 0
	s_cselect_b64 s[82:83], -1, 0
	s_cmp_lg_u64 s[78:79], 0
	s_cselect_b64 s[84:85], -1, 0
	s_ff1_i32_b64 s80, s[78:79]
	s_add_u32 s100, s78, -1
	s_addc_u32 s101, s79, -1
	s_and_b64 s[100:101], s[100:101], s[78:79]
	s_cmp_eq_u64 s[100:101], 0
	s_cbranch_scc1 .LBB0_244
	s_ff1_i32_b64 s98, s[100:101]
	s_mov_b32 s99, 0
	s_mul_i32 s94, s98, 0x88c00
	s_mov_b32 s95, 0
	s_lshl_b64 s[88:89], s[98:99], 7
	v_lshl_add_u64 v[48:49], v[144:145], 0, s[94:95]
	v_lshl_add_u64 v[50:51], v[146:147], 0, s[88:89]
	.p2align	6

; DI void nsa_wg_unit(const Args& a, int l, int b, int g, int tb, unsigned char* lds, int tid_in, bool stage) {
;     ...
;     { float sc[NRT]; const float lt = st.l[0] + __shfl_xor(st.l[0], 32); sc[0] = lt > 0.f ? gt[0][1] / lt : 0.f; attn_flush<false>(st, sc, orow); }
;     attn_reset(st);
;     { const unsigned koff = (unsigned)(srow * ZP + sch * 8) * 2u, voff = (unsigned)(srow * SEQ + sch * 8) * 2u; const char* kgb = (const char*)(zb + C_KV + 4 * 128 + g * 64); const char* vgb = (const char*)VWT;
;       int j = tb - 8 < 0 ? 0 : tb - 8, bi = 0; u32x4 kreg, vreg;
;       { kreg = *(const u32x4*)(kgb + (size_t)(64 * j) * ZP * 2 + koff); vreg = *(const u32x4*)(vgb + (size_t)(64 * j) * 2 + voff);
;         *(u32x4*)(lds + AL_KR + srow * KR_PB + sch * 16) = kreg; u32x2* d = (u32x2*)(lds + AL_VR + srow * VR_PB + sch * 16); u32x2 lo2, hi2; lo2.x = vreg.x; lo2.y = vreg.y; hi2.x = vreg.z; hi2.y = vreg.w; d[0] = lo2; d[1] = hi2; }
;       __syncthreads();
.LBB0_259:
	v_mov_b64_e32 v[32:33], v[236:237]
	v_mov_b64_e32 v[34:35], v[238:239]
	v_mov_b64_e32 v[36:37], v[240:241]
	v_mov_b64_e32 v[38:39], v[242:243]
	v_mov_b64_e32 v[40:41], v[244:245]
	v_mov_b64_e32 v[42:43], v[246:247]
	v_mov_b64_e32 v[44:45], v[248:249]
	v_mov_b64_e32 v[46:47], v[250:251]
	v_add_f32_e32 v48, 1.0, v158
	v_div_scale_f32 v50, s[0:1], v48, v48, 1.0
	v_rcp_f32_e32 v51, v50
	v_div_scale_f32 v52, vcc, 1.0, v48, 1.0
	ds_bpermute_b32 v49, v148, v155
	v_fma_f32 v53, -v50, v51, 1.0
	v_fmac_f32_e32 v51, v53, v51
	v_mul_f32_e32 v53, v52, v51
	v_fma_f32 v54, -v50, v53, v52
	v_fmac_f32_e32 v53, v54, v51
	v_fma_f32 v50, -v50, v53, v52
	v_div_fmas_f32 v50, v50, v51, v53
	s_waitcnt lgkmcnt(0)
	v_add_f32_e32 v49, v155, v49
	v_div_fixup_f32 v48, v50, v48, 1.0
	v_div_scale_f32 v50, s[0:1], v49, v49, v48
	v_rcp_f32_e32 v51, v50
	v_div_scale_f32 v52, vcc, v48, v49, v48
	s_sub_i32 s10, 55, s33
	v_fma_f32 v53, -v50, v51, 1.0
	v_fmac_f32_e32 v51, v53, v51
	v_mul_f32_e32 v53, v52, v51
	v_fma_f32 v54, -v50, v53, v52
	v_fmac_f32_e32 v53, v54, v51
	v_fma_f32 v50, -v50, v53, v52
	v_div_fmas_f32 v50, v50, v51, v53
	v_div_fixup_f32 v48, v50, v49, v48
	v_cmp_lt_f32_e32 vcc, 0, v49
	s_mul_i32 s0, s10, 0x88c00
	s_add_u32 s0, s45, s0
	v_cndmask_b32_e32 v48, 0, v48, vcc
	s_addc_u32 s1, s46, 0
	v_add3_u32 v146, s26, v137, v138
	v_add3_u32 v138, s28, v151, v138
	s_waitcnt vmcnt(7)
	v_lshlrev_b32_e32 v50, 16, v32
	v_and_b32_e32 v51, 0xffff0000, v32
	v_lshlrev_b32_e32 v32, 16, v33
	v_and_b32_e32 v33, 0xffff0000, v33
	s_waitcnt vmcnt(3)
	v_lshlrev_b32_e32 v58, 16, v40
	v_and_b32_e32 v59, 0xffff0000, v40
	v_lshlrev_b32_e32 v40, 16, v41
	v_and_b32_e32 v41, 0xffff0000, v41
	v_lshlrev_b32_e32 v52, 16, v34
	v_and_b32_e32 v53, 0xffff0000, v34
	v_lshlrev_b32_e32 v34, 16, v35
	v_and_b32_e32 v35, 0xffff0000, v35
	v_lshlrev_b32_e32 v54, 16, v36
	v_and_b32_e32 v55, 0xffff0000, v36
	v_lshlrev_b32_e32 v36, 16, v37
	v_and_b32_e32 v37, 0xffff0000, v37
	v_lshlrev_b32_e32 v56, 16, v38
	v_and_b32_e32 v57, 0xffff0000, v38
	v_lshlrev_b32_e32 v38, 16, v39
	v_and_b32_e32 v39, 0xffff0000, v39
	v_pk_fma_f32 v[16:17], v[16:17], v[48:49], v[50:51] op_sel_hi:[1,0,1]
	v_pk_fma_f32 v[18:19], v[18:19], v[48:49], v[32:33] op_sel_hi:[1,0,1]
	v_pk_fma_f32 v[0:1], v[0:1], v[48:49], v[58:59] op_sel_hi:[1,0,1]
	v_pk_fma_f32 v[2:3], v[2:3], v[48:49], v[40:41] op_sel_hi:[1,0,1]
	v_pk_fma_f32 v[20:21], v[20:21], v[48:49], v[52:53] op_sel_hi:[1,0,1]
	v_pk_fma_f32 v[22:23], v[22:23], v[48:49], v[34:35] op_sel_hi:[1,0,1]
	v_pk_fma_f32 v[24:25], v[24:25], v[48:49], v[54:55] op_sel_hi:[1,0,1]
	v_pk_fma_f32 v[26:27], v[26:27], v[48:49], v[36:37] op_sel_hi:[1,0,1]
	v_pk_fma_f32 v[28:29], v[28:29], v[48:49], v[56:57] op_sel_hi:[1,0,1]
	v_pk_fma_f32 v[30:31], v[30:31], v[48:49], v[38:39] op_sel_hi:[1,0,1]
	v_cvt_pk_bf16_f32 v16, v16, v17
	v_cvt_pk_bf16_f32 v17, v18, v19
	v_cvt_pk_bf16_f32 v0, v0, v1
	v_cvt_pk_bf16_f32 v1, v2, v3
	v_cvt_pk_bf16_f32 v18, v20, v21
	v_cvt_pk_bf16_f32 v19, v22, v23
	v_cvt_pk_bf16_f32 v20, v24, v25
	v_cvt_pk_bf16_f32 v21, v26, v27
	v_cvt_pk_bf16_f32 v22, v28, v29
	v_cvt_pk_bf16_f32 v23, v30, v31
	v_mov_b64_e32 v[236:237], v[16:17]
	v_mov_b64_e32 v[238:239], v[18:19]
	v_mov_b64_e32 v[240:241], v[20:21]
	v_mov_b64_e32 v[242:243], v[22:23]
	v_mov_b64_e32 v[244:245], v[0:1]
	s_waitcnt vmcnt(7)
	v_lshlrev_b32_e32 v0, 16, v42
	v_and_b32_e32 v1, 0xffff0000, v42
	v_lshlrev_b32_e32 v2, 16, v43
	v_and_b32_e32 v3, 0xffff0000, v43
	v_pk_fma_f32 v[0:1], v[4:5], v[48:49], v[0:1] op_sel_hi:[1,0,1]
	v_pk_fma_f32 v[2:3], v[6:7], v[48:49], v[2:3] op_sel_hi:[1,0,1]
	v_cvt_pk_bf16_f32 v0, v0, v1
	v_cvt_pk_bf16_f32 v1, v2, v3
	v_mov_b64_e32 v[246:247], v[0:1]
	s_waitcnt vmcnt(7)
	v_lshlrev_b32_e32 v0, 16, v44
	v_and_b32_e32 v1, 0xffff0000, v44
	v_lshlrev_b32_e32 v2, 16, v45
	v_and_b32_e32 v3, 0xffff0000, v45
	v_pk_fma_f32 v[0:1], v[8:9], v[48:49], v[0:1] op_sel_hi:[1,0,1]
	v_pk_fma_f32 v[2:3], v[10:11], v[48:49], v[2:3] op_sel_hi:[1,0,1]
	v_cvt_pk_bf16_f32 v0, v0, v1
	v_cvt_pk_bf16_f32 v1, v2, v3
	v_mov_b64_e32 v[248:249], v[0:1]
	s_waitcnt vmcnt(7)
	v_lshlrev_b32_e32 v0, 16, v46
	v_and_b32_e32 v1, 0xffff0000, v46
	v_lshlrev_b32_e32 v2, 16, v47
	v_and_b32_e32 v3, 0xffff0000, v47
	v_pk_fma_f32 v[0:1], v[12:13], v[48:49], v[0:1] op_sel_hi:[1,0,1]
	v_pk_fma_f32 v[2:3], v[14:15], v[48:49], v[2:3] op_sel_hi:[1,0,1]
	v_cvt_pk_bf16_f32 v0, v0, v1
	v_cvt_pk_bf16_f32 v1, v2, v3
	v_mov_b64_e32 v[250:251], v[0:1]
	v_lshl_add_u64 v[0:1], s[0:1], 0, v[142:143]
	s_lshl_b32 s0, s10, 7
	s_add_u32 s0, s2, s0
	s_addc_u32 s1, s35, 0
	v_lshl_add_u64 v[2:3], s[0:1], 0, v[160:161]
	global_load_dwordx4 v[96:99], v[0:1], off
	global_load_dwordx4 v[100:103], v[2:3], off
	v_mov_b32_e32 v15, 0
	v_mov_b32_e32 v14, v15
	v_mov_b32_e32 v13, v15
	v_mov_b32_e32 v12, v15
	v_mov_b32_e32 v11, v15
	v_mov_b32_e32 v10, v15
	v_mov_b32_e32 v9, v15
	v_mov_b32_e32 v8, v15
	v_mov_b32_e32 v7, v15
	v_mov_b32_e32 v6, v15
	v_mov_b32_e32 v5, v15
	v_mov_b32_e32 v4, v15
	v_mov_b32_e32 v3, v15
	v_mov_b32_e32 v2, v15
	v_mov_b32_e32 v1, v15
	v_mov_b32_e32 v0, v15
	v_mov_b32_e32 v31, v15
	v_mov_b32_e32 v30, v15
	v_mov_b32_e32 v29, v15
	v_mov_b32_e32 v28, v15
	v_mov_b32_e32 v27, v15
	v_mov_b32_e32 v26, v15
	v_mov_b32_e32 v25, v15
	v_mov_b32_e32 v24, v15
	v_mov_b32_e32 v23, v15
	v_mov_b32_e32 v22, v15
	v_mov_b32_e32 v21, v15
	v_mov_b32_e32 v20, v15
	v_mov_b32_e32 v19, v15
	v_mov_b32_e32 v18, v15
	v_mov_b32_e32 v17, v15
	v_mov_b32_e32 v16, v15
	s_cmp_gt_u32 s10, s93
	v_mov_b32_e32 v137, v15
	s_waitcnt vmcnt(1)
	ds_write_b128 v146, v[96:99]
	s_waitcnt vmcnt(0)
	ds_write2_b64 v138, v[100:101], v[102:103] offset1:1
	s_waitcnt lgkmcnt(0)
	s_barrier
; DI void nsa_wg_unit(const Args& a, int l, int b, int g, int tb, unsigned char* lds, int tid_in, bool stage) {
;     ...
;     { const unsigned koff = (unsigned)(srow * ZP + sch * 8) * 2u, voff = (unsigned)(srow * SEQ + sch * 8) * 2u; const char* kgb = (const char*)(zb + C_KV + 4 * 128 + g * 64); const char* vgb = (const char*)VWT;
;       int j = tb - 8 < 0 ? 0 : tb - 8, bi = 0; u32x4 kreg, vreg;
;       { kreg = *(const u32x4*)(kgb + (size_t)(64 * j) * ZP * 2 + koff); vreg = *(const u32x4*)(vgb + (size_t)(64 * j) * 2 + voff);
;         *(u32x4*)(lds + AL_KR + srow * KR_PB + sch * 16) = kreg; u32x2* d = (u32x2*)(lds + AL_VR + srow * VR_PB + sch * 16); u32x2 lo2, hi2; lo2.x = vreg.x; lo2.y = vreg.y; hi2.x = vreg.z; hi2.y = vreg.w; d[0] = lo2; d[1] = hi2; }
;       __syncthreads();
;       for (; j <= tb; ++j) { const bool hn = j + 1 <= tb;
;           if (hn) { kreg = *(const u32x4*)(kgb + (size_t)(64 * (j + 1)) * ZP * 2 + koff); vreg = *(const u32x4*)(vgb + (size_t)(64 * (j + 1)) * 2 + voff); }
;           if (64 * j + 63 >= t0 - 511 && 64 * j <= t0 + NTOK - 1)
;               attn_block64(st, qf, kfl + bi * KR_SZ, vfl + bi * VR_SZ, KR_PB, VR_PB, cref[2], true, (64 * j + 63 > t0) || (64 * j <= t0 + NTOK - 1 - 512), MaskWindow{tk[0]}, 64 * j, h);
	s_cbranch_scc1 .LBB0_111
	v_readlane_b32 s0, v254, 51
	s_add_i32 s11, s96, 0xfffffe01
	s_add_i32 s12, s96, 0xfffffe07
	s_sub_i32 s14, 0, s0
	s_sub_i32 s8, 0xe00, s0
	v_readlane_b32 s1, v254, 44
	v_readlane_b32 s9, v254, 55
	s_add_u32 s1, s1, s9
	v_readlane_b32 s9, v254, 45
	v_subrev_u32_e32 v151, s0, v154
	s_mul_i32 s0, s8, 0x2230
	s_addc_u32 s9, s9, 0
	s_add_u32 s0, s1, s0
	s_addc_u32 s1, s9, 0
	v_readlane_b32 s9, v254, 52
	s_add_u32 s0, s0, s9
	v_readlane_b32 s9, v254, 53
	s_addc_u32 s1, s1, s9
	v_lshl_add_u64 v[142:143], s[0:1], 0, v[142:143]
	v_readlane_b32 s0, v254, 56
	v_readlane_b32 s1, v254, 57
	v_readlane_b32 s2, v254, 48
	s_lshl_b64 s[0:1], s[0:1], 20
	s_lshl_b32 s9, s2, 19
	s_lshl_b32 s8, s8, 1
	v_readlane_b32 s15, v254, 46
	s_add_u32 s8, s15, s8
	v_readlane_b32 s15, v254, 47
	s_addc_u32 s15, s15, 0
	s_add_u32 s8, s8, s9
	v_mul_f32_e32 v0, v156, v157
	s_addc_u32 s9, s15, 0
	v_cmp_lt_f32_e32 vcc, s25, v0
	s_add_u32 s0, s8, s0
	v_mov_b32_e32 v137, 0
	v_cndmask_b32_e32 v32, 0, v0, vcc
	s_addc_u32 s1, s9, s1
	v_add_u32_e32 v147, 0xfffffe00, v136
	v_cmp_neq_f32_e64 s[6:7], 0, v32
	v_mov_b32_e32 v33, v32
	v_mov_b32_e32 v34, v32
	v_mov_b32_e32 v35, v32
	v_mov_b32_e32 v36, v32
	v_mov_b32_e32 v37, v32
	v_mov_b32_e32 v38, v32
	v_mov_b32_e32 v39, v32
	v_mov_b32_e32 v40, v32
	v_mov_b32_e32 v41, v32
	v_mov_b32_e32 v42, v32
	v_mov_b32_e32 v43, v32
	v_mov_b32_e32 v44, v32
	s_mov_b32 s13, 0
	v_lshl_add_u64 v[144:145], s[0:1], 0, v[160:161]
	s_mov_b32 s15, 0
	v_mov_b32_e32 v0, v137
	v_mov_b32_e32 v1, v137
	v_mov_b32_e32 v2, v137
	v_mov_b32_e32 v3, v137
	v_mov_b32_e32 v4, v137
	v_mov_b32_e32 v5, v137
	v_mov_b32_e32 v6, v137
	v_mov_b32_e32 v7, v137
	v_mov_b32_e32 v8, v137
	v_mov_b32_e32 v9, v137
	v_mov_b32_e32 v10, v137
	v_mov_b32_e32 v11, v137
	v_mov_b32_e32 v12, v137
	v_mov_b32_e32 v13, v137
	v_mov_b32_e32 v14, v137
	v_mov_b32_e32 v15, v137
	v_mov_b32_e32 v16, v137
	v_mov_b32_e32 v17, v137
	v_mov_b32_e32 v18, v137
	v_mov_b32_e32 v19, v137
	v_mov_b32_e32 v20, v137
	v_mov_b32_e32 v21, v137
	v_mov_b32_e32 v22, v137
	v_mov_b32_e32 v23, v137
	v_mov_b32_e32 v24, v137
	v_mov_b32_e32 v25, v137
	v_mov_b32_e32 v26, v137
	v_mov_b32_e32 v27, v137
	v_mov_b32_e32 v28, v137
	v_mov_b32_e32 v29, v137
	v_mov_b32_e32 v30, v137
	v_mov_b32_e32 v31, v137
	v_mov_b32_e32 v45, v32
	v_mov_b32_e32 v46, v32
	v_mov_b32_e32 v47, v32
	s_branch .LBB0_262
	.p2align	6

; #define LAS __attribute__((address_space(3)))
; __device__ __forceinline__ unsigned xb_xcc_id() { return (unsigned)__builtin_amdgcn_s_getreg((3 << 11) | 20) & 0xFu; }
; DI KArgP launder(KArgP p) { asm volatile("" : "+s"(p)); return p; }
; __global__ void __launch_bounds__(512, 2) fwd_kernel(Args a_unused) {
;     ...
;     for (int p = ph_lo; p < ph_hi; ++p) {
;         if (p > ph_lo && coop) { if (p == ph_lo + 1) grid.sync(); else { XcdBarrier b2; b2.bar = (unsigned*)(launder(kp)->ws + WS_CTL); b2.x = xb_xcc_id(); b2.st = (volatile LAS unsigned*)((LAS unsigned char*)lds + (LDS_BYTES - 64)); xcd_barrier(b2); } }
.LBB0_272:
	s_and_b64 vcc, exec, s[82:83]
	s_cbranch_vccz .LBB0_488
	.p2align	6

; DI unsigned cvtpk(float lo, float hi) { return pg8::cvt_pk_bf16(lo, hi); }
; #define LDS_FENCE() asm volatile("s_waitcnt lgkmcnt(0)" ::: "memory")
; DI void tr_tile(const float* __restrict__ src, int srcN, int k0, int n0, int mode, const float* __restrict__ gk, bf16_t* dst, size_t dpitch, int ncopies, float* scr, int lane) {
;     ...
;     LDS_FENCE();
;     const int c = lane & 7;
; #pragma unroll
;     for (int j = 0; j < 4; ++j) { const int nr = (lane >> 3) + 8 * j; const float* s = scr + (8 * c) * 33 + nr; const int drow = n0 + nr;
;         u32x4 o; o.x = cvtpk(s[0], s[33]); o.y = cvtpk(s[2 * 33], s[3 * 33]); o.z = cvtpk(s[4 * 33], s[5 * 33]); o.w = cvtpk(s[6 * 33], s[7 * 33]);
;         const bool skip = (mode == 1) && drow >= C_PL && drow < C_PL + 512;
;         if (!skip) for (int cp = 0; cp < ncopies; ++cp) *(u32x4*)(dst + (size_t)drow * dpitch + cp * 1024 + k0 + 8 * c) = o; }
;     LDS_FENCE();
; DI void convert_second(const Args& a, int l, float* scr, int gw, int ngw, int lane) {
;     unsigned char* ws = a.ws;
;     bf16_t* WUP = (bf16_t*)(ws + WS_WUP); bf16_t* WDN = (bf16_t*)(ws + WS_WDN);
;     constexpr int I_UP = 16 * (GUP / 32), I_DN = (DFF / 64) * 32;
;     for (int it = gw; it < I_UP + I_DN; it += ngw) {
;         int r = it;
;         if (r < I_UP) { const int kt = r / (GUP / 32), nt = r % (GUP / 32); tr_tile(a.in[16] + (size_t)l * 1024 * GUP, GUP, kt * 64, nt * 32, 2, a.in[15] + l * 1024, WUP, 1024, 1, scr, lane); continue; } r -= I_UP;
;         { const int kt = r >> 5, nt = r & 31; tr_tile(a.in[18] + (size_t)l * DFF * 1024, 1024, kt * 64, nt * 32, 0, nullptr, WDN, DFF, 1, scr, lane); }
.LBB0_275:
	s_and_b64 vcc, exec, s[0:1]
	s_cbranch_vccz .LBB0_480
	v_readlane_b32 s0, v254, 19
	s_cmpk_gt_i32 s0, 0x107f
	v_readlane_b32 s26, v254, 16
	s_cbranch_scc1 .LBB0_299
	v_and_b32_e32 v26, 31, v225
	v_lshrrev_b32_e32 v0, 5, v166
	v_mul_u32_u24_e32 v1, 33, v0
	v_readlane_b32 s6, v254, 21
	v_lshlrev_b32_e32 v3, 2, v26
	v_lshlrev_b32_e32 v1, 2, v1
	v_add_u32_e32 v6, s6, v3
	v_add_u32_e32 v2, s6, v1
	v_add_u32_e32 v28, v6, v1
	v_mov_b32_e32 v1, 0x1080
	v_readlane_b32 s0, v254, 14
	v_lshl_or_b32 v1, v166, 2, v1
	v_readlane_b32 s1, v254, 15
	v_add_u32_e32 v29, v2, v1
	v_lshlrev_b32_e32 v1, 3, v166
	s_mov_b32 s12, s0
	s_mul_hi_i32 s8, s0, 0xb00000
	s_mul_i32 s9, s0, 0xb00000
	v_and_b32_e32 v1, 56, v1
	v_readlane_b32 s0, v254, 3
	v_lshrrev_b32_e32 v30, 3, v166
	v_lshlrev_b32_e32 v160, 1, v1
	v_readlane_b32 s1, v254, 4
	v_mul_u32_u24_e32 v7, 0x84, v1
	v_lshlrev_b32_e32 v1, 2, v30
	v_lshl_add_u64 v[4:5], s[0:1], 0, v[160:161]
	s_mov_b64 s[0:1], 0x1b00000
	v_add_u32_e32 v27, v2, v3
	v_lshl_add_u64 v[2:3], v[4:5], 0, s[0:1]
	v_add3_u32 v31, s6, v7, v1
	s_mul_hi_i32 s10, s12, 0x1600000
	s_mul_i32 s11, s12, 0x1600000
	s_lshl_b32 s6, s12, 10
	v_or_b32_e32 v1, 2, v0
	s_movk_i32 s0, 0x84
	v_readlane_b32 s12, v254, 5
	s_ashr_i32 s7, s6, 31
	v_mad_u32_u24 v35, v1, s0, v6
	s_mov_b64 s[0:1], 0x20480000
	v_readlane_b32 s16, v254, 9
	v_lshl_add_u64 v[4:5], v[4:5], 0, s[0:1]
	v_readlane_b32 s17, v254, 10
	s_add_u32 s0, s16, s9
	s_addc_u32 s1, s17, s8
	v_readlane_b32 s13, v254, 6
	s_add_u32 s8, s12, s11
	v_readlane_b32 s36, v253, 51
	s_addc_u32 s9, s13, s10
	s_lshl_b64 s[6:7], s[6:7], 2
	v_readlane_b32 s50, v254, 1
	v_readlane_b32 s51, v254, 2
	s_add_u32 s10, s50, s6
	s_addc_u32 s11, s51, s7
	v_readlane_b32 s18, v254, 11
	v_readlane_b32 s19, v254, 12
	s_cmp_lg_u64 s[50:51], 0
	v_readlane_b32 s24, v254, 19
	v_or_b32_e32 v32, 8, v30
	v_or_b32_e32 v33, 16, v30
	v_or_b32_e32 v34, 24, v30
	v_add_u32_e32 v36, 0x108, v35
	v_add_u32_e32 v37, 0x210, v35
	v_add_u32_e32 v38, 0x318, v35
	v_add_u32_e32 v39, 0x420, v35
	v_add_u32_e32 v40, 0x528, v35
	v_add_u32_e32 v41, 0x630, v35
	v_add_u32_e32 v42, 0x738, v35
	v_add_u32_e32 v43, 0x840, v35
	v_add_u32_e32 v44, 0x948, v35
	v_add_u32_e32 v45, 0xa50, v35
	v_add_u32_e32 v46, 0xb58, v35
	v_add_u32_e32 v47, 0xc60, v35
	v_add_u32_e32 v48, 0xd68, v35
	v_add_u32_e32 v49, 0xe70, v35
	v_add_u32_e32 v50, 0xf78, v35
	v_add_u32_e32 v51, 0x1080, v35
	v_add_u32_e32 v52, 0x1188, v35
	v_add_u32_e32 v53, 0x1290, v35
	v_add_u32_e32 v54, 0x1398, v35
	v_add_u32_e32 v55, 0x14a0, v35
	v_add_u32_e32 v56, 0x15a8, v35
	v_add_u32_e32 v57, 0x16b0, v35
	v_add_u32_e32 v58, 0x17b8, v35
	v_add_u32_e32 v59, 0x18c0, v35
	v_add_u32_e32 v60, 0x19c8, v35
	v_add_u32_e32 v61, 0x1ad0, v35
	v_add_u32_e32 v62, 0x1bd8, v35
	v_add_u32_e32 v63, 0x1ce0, v35
	v_add_u32_e32 v64, 0x1de8, v35
	v_add_u32_e32 v65, 0x1ef0, v35
	s_cselect_b64 s[12:13], -1, 0
	v_mov_b32_e32 v1, v161
	s_lshl_b32 s18, s24, 5
	s_lshl_b32 s19, s52, 8
	s_lshl_b32 s20, s24, 4
	s_lshl_b32 s21, s52, 7
	s_lshl_b32 s22, s24, 1
	s_lshl_b32 s23, s52, 4
	v_readlane_b32 s14, v254, 7
	v_readlane_b32 s15, v254, 8
	v_readlane_b32 s37, v253, 52
	v_readlane_b32 s38, v253, 53
	v_readlane_b32 s39, v253, 54
	v_readlane_b32 s40, v253, 55
	v_readlane_b32 s41, v253, 56
	v_readlane_b32 s42, v253, 57
	v_readlane_b32 s43, v253, 58
	v_readlane_b32 s44, v253, 59
	v_readlane_b32 s45, v253, 60
	v_readlane_b32 s46, v253, 61
	v_readlane_b32 s47, v253, 62
	v_readlane_b32 s48, v253, 63
	v_readlane_b32 s49, v254, 0
	s_branch .LBB0_281
	.p2align	6
.LBB0_278:
	s_ashr_i32 s15, s14, 31
	s_waitcnt vmcnt(3)
	v_mov_b32_e32 v10, v8
	s_waitcnt vmcnt(2)
	v_mov_b32_e32 v11, v9
	s_waitcnt vmcnt(1)
	v_mov_b32_e32 v12, v6
	s_waitcnt vmcnt(0)
	v_mov_b32_e32 v13, v7
	ds_write_b32 v58, v66
	ds_write_b32 v59, v67
	ds_write_b32 v60, v68
	ds_write_b32 v61, v69
	.p2align	6
.LBB0_279:
	s_waitcnt vmcnt(9)
	ds_write_b32 v62, v10
	s_waitcnt vmcnt(8)
	ds_write_b32 v63, v11
	ds_write_b32 v64, v12
	ds_write_b32 v65, v13
	s_waitcnt lgkmcnt(0)
	ds_read2_b32 v[12:13], v31 offset0:33 offset1:41
	ds_read2_b32 v[14:15], v31 offset1:8
	ds_read2_b32 v[16:17], v31 offset0:66 offset1:74
	ds_read2_b32 v[18:19], v31 offset0:99 offset1:107
	ds_read2_b32 v[20:21], v31 offset0:132 offset1:140
	ds_read2_b32 v[22:23], v31 offset0:165 offset1:173
	ds_read2_b32 v[24:25], v31 offset0:198 offset1:206
	s_waitcnt vmcnt(6)
	ds_read2_b32 v[66:67], v31 offset0:231 offset1:239
	s_waitcnt vmcnt(5)
	v_add_u32_e32 v68, s25, v30
	s_waitcnt vmcnt(4)
	v_ashrrev_i32_e32 v69, 31, v68
	v_lshl_add_u64 v[10:11], s[14:15], 1, v[4:5]
	v_lshlrev_b64 v[70:71], 11, v[68:69]
	s_waitcnt vmcnt(1) lgkmcnt(6)
	v_cvt_pk_bf16_f32 v6, v14, v12
	s_waitcnt vmcnt(0) lgkmcnt(4)
	v_cvt_pk_bf16_f32 v7, v16, v18
	s_waitcnt lgkmcnt(2)
	v_cvt_pk_bf16_f32 v8, v20, v22
	s_waitcnt lgkmcnt(0)
	v_cvt_pk_bf16_f32 v9, v24, v66
	v_lshl_add_u64 v[70:71], v[10:11], 0, v[70:71]
	v_add_u32_e32 v12, 8, v68
	global_store_dwordx4 v[70:71], v[6:9], off
	v_add_u32_e32 v70, 16, v68
	v_ashrrev_i32_e32 v71, 31, v70
	v_cvt_pk_bf16_f32 v6, v15, v13
	v_ashrrev_i32_e32 v13, 31, v12
	v_lshlrev_b64 v[12:13], 11, v[12:13]
	v_cvt_pk_bf16_f32 v7, v17, v19
	v_cvt_pk_bf16_f32 v8, v21, v23
	v_cvt_pk_bf16_f32 v9, v25, v67
	v_lshl_add_u64 v[12:13], v[10:11], 0, v[12:13]
	global_store_dwordx4 v[12:13], v[6:9], off
	ds_read2_b32 v[12:13], v31 offset0:49 offset1:57
	ds_read2_b32 v[14:15], v31 offset0:16 offset1:24
	ds_read2_b32 v[16:17], v31 offset0:82 offset1:90
	ds_read2_b32 v[18:19], v31 offset0:115 offset1:123
	ds_read2_b32 v[20:21], v31 offset0:148 offset1:156
	ds_read2_b32 v[22:23], v31 offset0:181 offset1:189
	ds_read2_b32 v[24:25], v31 offset0:214 offset1:222
	ds_read2_b32 v[66:67], v31 offset0:247 offset1:255
	v_lshlrev_b64 v[70:71], 11, v[70:71]
	s_waitcnt lgkmcnt(6)
	v_cvt_pk_bf16_f32 v6, v14, v12
	s_waitcnt lgkmcnt(4)
	v_cvt_pk_bf16_f32 v7, v16, v18
	s_waitcnt lgkmcnt(2)
	v_cvt_pk_bf16_f32 v8, v20, v22
	s_waitcnt lgkmcnt(0)
	v_cvt_pk_bf16_f32 v9, v24, v66
	v_lshl_add_u64 v[70:71], v[10:11], 0, v[70:71]
	v_add_u32_e32 v12, 24, v68
	global_store_dwordx4 v[70:71], v[6:9], off
	s_nop 1
	v_cvt_pk_bf16_f32 v6, v15, v13
	v_ashrrev_i32_e32 v13, 31, v12
	v_lshlrev_b64 v[12:13], 11, v[12:13]
	v_cvt_pk_bf16_f32 v7, v17, v19
	v_cvt_pk_bf16_f32 v8, v21, v23
	v_cvt_pk_bf16_f32 v9, v25, v67
	v_lshl_add_u64 v[10:11], v[10:11], 0, v[12:13]
	global_store_dwordx4 v[10:11], v[6:9], off
	s_waitcnt lgkmcnt(0)
	.p2align	6

; DI void tr_tile(const float* __restrict__ src, int srcN, int k0, int n0, int mode, const float* __restrict__ gk, bf16_t* dst, size_t dpitch, int ncopies, float* scr, int lane) {
;     const int nn = lane & 31, n = n0 + nn; int sc = n; bool valid = true;
;     if (mode == 1) { if (n >= 4608) { const int q = n - 4608, rho = q & 255; sc = ZP + (2 * (rho >> 7) + ((rho >> 2) & 1)) * 1024 + 64 * (q >> 8) + 16 * ((rho >> 5) & 3) + 4 * ((rho >> 3) & 3) + (rho & 3); } else if (n >= ZP) { sc = 0; valid = false; } }
;     if (mode == 2) sc = ((n >> 7) & 1) * DFF + 128 * (n >> 8) + (n & 127);
;     float v32[32];
; #pragma unroll
;     for (int i = 0; i < 32; ++i) { const int kk = 2 * i + (lane >> 5); v32[i] = valid ? src[(size_t)(k0 + kk) * srcN + sc] : 0.f; }
; #pragma unroll
;     for (int i = 0; i < 32; ++i) { const int kk = 2 * i + (lane >> 5); float v = v32[i]; if (gk) v *= gk[k0 + kk]; scr[kk * 33 + nn] = v; }
.LBB0_283:
	s_andn2_b64 vcc, exec, s[6:7]
	s_cbranch_vccnz .LBB0_280
	s_mul_hi_i32 s6, s24, 0x2e8ba2e9
	s_lshr_b32 s7, s6, 31
	s_ashr_i32 s6, s6, 5
	s_add_i32 s6, s6, s7
	s_lshl_b32 s14, s6, 6
	s_mul_i32 s7, s6, 0xffffea00
	s_mulk_i32 s6, 0xf500
	s_add_i32 s25, s18, s7
	s_bfe_i32 s7, s24, 0x10002
	s_add_i32 s6, s20, s6
	s_and_b32 s7, s7, 0xb00
	s_and_b32 s6, s6, 0xffffff80
	s_add_i32 s7, s7, s6
	s_and_b32 s6, s25, 0x60
	s_or_b32 s6, s7, s6
	v_or_b32_e32 v6, s6, v26
	v_or_b32_e32 v22, s14, v0
	v_ashrrev_i32_e32 v7, 31, v6
	v_lshl_add_u64 v[6:7], v[6:7], 2, s[8:9]
	v_or_b32_e32 v18, 10, v22
	v_or_b32_e32 v20, 12, v22
	v_mad_i64_i32 v[8:9], s[6:7], v22, s88, v[6:7]
	v_or_b32_e32 v10, 2, v22
	v_or_b32_e32 v12, 4, v22
	v_or_b32_e32 v14, 6, v22
	v_or_b32_e32 v16, 8, v22
	v_mad_i64_i32 v[18:19], s[6:7], v18, s88, v[6:7]
	v_mad_i64_i32 v[24:25], s[6:7], v20, s88, v[6:7]
	v_or_b32_e32 v20, 14, v22
	v_or_b32_e32 v23, 26, v22
	v_mad_i64_i32 v[10:11], s[6:7], v10, s88, v[6:7]
	v_mad_i64_i32 v[12:13], s[6:7], v12, s88, v[6:7]
	v_mad_i64_i32 v[14:15], s[6:7], v14, s88, v[6:7]
	v_mad_i64_i32 v[16:17], s[6:7], v16, s88, v[6:7]
	v_mad_i64_i32 v[66:67], s[6:7], v20, s88, v[6:7]
	global_load_dword v78, v[8:9], off
	global_load_dword v79, v[10:11], off
	global_load_dword v80, v[12:13], off
	global_load_dword v81, v[14:15], off
	global_load_dword v20, v[16:17], off
	global_load_dword v21, v[18:19], off
	s_nop 0
	global_load_dword v18, v[24:25], off
	global_load_dword v19, v[66:67], off
	v_mad_i64_i32 v[24:25], s[6:7], v23, s88, v[6:7]
	v_or_b32_e32 v23, 28, v22
	v_or_b32_e32 v8, 16, v22
	v_or_b32_e32 v14, 22, v22
	v_or_b32_e32 v16, 24, v22
	v_mad_i64_i32 v[66:67], s[6:7], v23, s88, v[6:7]
	v_or_b32_e32 v23, 30, v22
	v_mad_i64_i32 v[8:9], s[6:7], v8, s88, v[6:7]
	v_or_b32_e32 v10, 18, v22
	v_or_b32_e32 v12, 20, v22
	v_mad_i64_i32 v[14:15], s[6:7], v14, s88, v[6:7]
	v_mad_i64_i32 v[16:17], s[6:7], v16, s88, v[6:7]
	v_mad_i64_i32 v[68:69], s[6:7], v23, s88, v[6:7]
	v_or_b32_e32 v23, 38, v22
	v_mad_i64_i32 v[10:11], s[6:7], v10, s88, v[6:7]
	v_mad_i64_i32 v[12:13], s[6:7], v12, s88, v[6:7]
	global_load_dword v74, v[8:9], off
	global_load_dword v75, v[10:11], off
	global_load_dword v76, v[12:13], off
	global_load_dword v77, v[14:15], off
	s_nop 0
	global_load_dword v16, v[16:17], off
	s_nop 0
	global_load_dword v17, v[24:25], off
	global_load_dword v14, v[66:67], off
	global_load_dword v15, v[68:69], off
	v_mad_i64_i32 v[24:25], s[6:7], v23, s88, v[6:7]
	v_or_b32_e32 v23, 40, v22
	v_mad_i64_i32 v[66:67], s[6:7], v23, s88, v[6:7]
	v_or_b32_e32 v23, 42, v22
	v_mad_i64_i32 v[68:69], s[6:7], v23, s88, v[6:7]
	v_or_b32_e32 v23, 44, v22
	v_or_b32_e32 v8, 32, v22
	v_or_b32_e32 v10, 34, v22
	v_or_b32_e32 v12, 36, v22
	v_mad_i64_i32 v[82:83], s[6:7], v23, s88, v[6:7]
	v_or_b32_e32 v23, 46, v22
	v_mad_i64_i32 v[8:9], s[6:7], v8, s88, v[6:7]
	v_mad_i64_i32 v[10:11], s[6:7], v10, s88, v[6:7]
	v_mad_i64_i32 v[12:13], s[6:7], v12, s88, v[6:7]
	v_mad_i64_i32 v[84:85], s[6:7], v23, s88, v[6:7]
	v_or_b32_e32 v23, 50, v22
	global_load_dword v70, v[8:9], off
	global_load_dword v71, v[10:11], off
	global_load_dword v72, v[12:13], off
	global_load_dword v73, v[24:25], off
	s_nop 0
	global_load_dword v12, v[66:67], off
	global_load_dword v13, v[68:69], off
	global_load_dword v10, v[82:83], off
	global_load_dword v11, v[84:85], off
	v_mad_i64_i32 v[24:25], s[6:7], v23, s88, v[6:7]
	v_or_b32_e32 v23, 52, v22
	v_mad_i64_i32 v[68:69], s[6:7], v23, s88, v[6:7]
	v_or_b32_e32 v23, 54, v22
	v_mad_i64_i32 v[82:83], s[6:7], v23, s88, v[6:7]
	v_or_b32_e32 v23, 56, v22
	v_mad_i64_i32 v[84:85], s[6:7], v23, s88, v[6:7]
	v_or_b32_e32 v23, 58, v22
	v_or_b32_e32 v8, 48, v22
	v_mad_i64_i32 v[86:87], s[6:7], v23, s88, v[6:7]
	v_or_b32_e32 v23, 60, v22
	v_mad_i64_i32 v[8:9], s[6:7], v8, s88, v[6:7]
	v_mad_i64_i32 v[88:89], s[6:7], v23, s88, v[6:7]
	v_or_b32_e32 v23, 62, v22
	v_mad_i64_i32 v[90:91], s[6:7], v23, s88, v[6:7]
	global_load_dword v66, v[8:9], off
	global_load_dword v67, v[24:25], off
	s_nop 0
	global_load_dword v68, v[68:69], off
	s_nop 0
	global_load_dword v69, v[82:83], off
	global_load_dword v8, v[84:85], off
	global_load_dword v9, v[86:87], off
	global_load_dword v6, v[88:89], off
	global_load_dword v7, v[90:91], off
	v_cndmask_b32_e64 v23, 0, 1, s[12:13]
	v_cmp_ne_u32_e64 s[6:7], 1, v23
	s_andn2_b64 vcc, exec, s[12:13]
	s_cbranch_vccnz .LBB0_295
	v_ashrrev_i32_e32 v23, 31, v22
	s_ashr_i32 s15, s14, 31
	v_lshl_add_u64 v[22:23], v[22:23], 2, s[10:11]
	v_lshl_add_u64 v[24:25], s[14:15], 0, v[0:1]
	v_lshl_add_u64 v[24:25], v[24:25], 2, s[10:11]
	global_load_dword v84, v[22:23], off
	global_load_dword v85, v[24:25], off offset:8
	global_load_dword v86, v[24:25], off offset:16
	global_load_dword v87, v[24:25], off offset:24
	s_nop 0
	global_load_dword v22, v[24:25], off offset:32
	global_load_dword v23, v[24:25], off offset:40
	global_load_dword v82, v[24:25], off offset:48
	global_load_dword v83, v[24:25], off offset:56
	s_waitcnt vmcnt(0)
	v_mul_f32_e32 v24, v78, v84
	s_waitcnt vmcnt(6)
	v_mul_f32_e32 v84, v79, v85
	ds_write_b32 v27, v24
	s_waitcnt vmcnt(5)
	v_mul_f32_e32 v85, v80, v86
	s_waitcnt vmcnt(4)
	v_mul_f32_e32 v86, v81, v87
	s_waitcnt vmcnt(2)
	v_pk_mul_f32 v[22:23], v[20:21], v[22:23]
	ds_write_b32 v35, v84
	ds_write_b32 v36, v85
	ds_write_b32 v37, v86
	s_waitcnt vmcnt(0)
	v_pk_mul_f32 v[24:25], v[18:19], v[82:83]
	s_cbranch_execnz .LBB0_287
	.p2align	6

; DI void tr_tile(const float* __restrict__ src, int srcN, int k0, int n0, int mode, const float* __restrict__ gk, bf16_t* dst, size_t dpitch, int ncopies, float* scr, int lane) {
;     ...
; #pragma unroll
;     for (int i = 0; i < 32; ++i) { const int kk = 2 * i + (lane >> 5); v32[i] = valid ? src[(size_t)(k0 + kk) * srcN + sc] : 0.f; }
; #pragma unroll
;     for (int i = 0; i < 32; ++i) { const int kk = 2 * i + (lane >> 5); float v = v32[i]; if (gk) v *= gk[k0 + kk]; scr[kk * 33 + nn] = v; }
.LBB0_287:
	s_and_b64 vcc, exec, s[6:7]
	ds_write_b32 v38, v22
	ds_write_b32 v39, v23
	ds_write_b32 v40, v24
	ds_write_b32 v41, v25
	s_cbranch_vccnz .LBB0_296
	s_ashr_i32 s15, s14, 31
	s_waitcnt vmcnt(0)
	v_lshl_add_u64 v[18:19], s[14:15], 0, v[0:1]
	v_lshl_add_u64 v[18:19], v[18:19], 2, s[10:11]
	global_load_dword v24, v[18:19], off offset:64
	global_load_dword v25, v[18:19], off offset:72
	global_load_dword v78, v[18:19], off offset:80
	global_load_dword v79, v[18:19], off offset:88
	global_load_dword v20, v[18:19], off offset:96
	global_load_dword v21, v[18:19], off offset:104
	global_load_dword v22, v[18:19], off offset:112
	global_load_dword v23, v[18:19], off offset:120
	s_waitcnt vmcnt(7)
	v_mul_f32_e32 v24, v74, v24
	s_waitcnt vmcnt(6)
	v_mul_f32_e32 v25, v75, v25
	s_waitcnt vmcnt(5)
	v_mul_f32_e32 v78, v76, v78
	s_waitcnt vmcnt(4)
	v_mul_f32_e32 v79, v77, v79
	ds_write_b32 v42, v24
	ds_write_b32 v43, v25
	ds_write_b32 v44, v78
	ds_write_b32 v45, v79
	s_waitcnt vmcnt(2)
	v_pk_mul_f32 v[18:19], v[16:17], v[20:21]
	s_waitcnt vmcnt(0)
	v_pk_mul_f32 v[20:21], v[14:15], v[22:23]
	s_cbranch_execnz .LBB0_290
	.p2align	6

; DI void tr_tile(const float* __restrict__ src, int srcN, int k0, int n0, int mode, const float* __restrict__ gk, bf16_t* dst, size_t dpitch, int ncopies, float* scr, int lane) {
;     ...
; #pragma unroll
;     for (int i = 0; i < 32; ++i) { const int kk = 2 * i + (lane >> 5); v32[i] = valid ? src[(size_t)(k0 + kk) * srcN + sc] : 0.f; }
; #pragma unroll
;     for (int i = 0; i < 32; ++i) { const int kk = 2 * i + (lane >> 5); float v = v32[i]; if (gk) v *= gk[k0 + kk]; scr[kk * 33 + nn] = v; }
.LBB0_290:
	s_and_b64 vcc, exec, s[6:7]
	s_waitcnt vmcnt(0)
	ds_write_b32 v46, v18
	s_waitcnt vmcnt(24)
	ds_write_b32 v47, v19
	ds_write_b32 v48, v20
	ds_write_b32 v49, v21
	s_cbranch_vccnz .LBB0_297
	s_ashr_i32 s15, s14, 31
	s_waitcnt vmcnt(16)
	v_lshl_add_u64 v[14:15], s[14:15], 0, v[0:1]
	v_lshl_add_u64 v[14:15], v[14:15], 2, s[10:11]
	global_load_dword v20, v[14:15], off offset:128
	global_load_dword v21, v[14:15], off offset:136
	global_load_dword v22, v[14:15], off offset:144
	global_load_dword v23, v[14:15], off offset:152
	global_load_dword v16, v[14:15], off offset:160
	global_load_dword v17, v[14:15], off offset:168
	global_load_dword v18, v[14:15], off offset:176
	global_load_dword v19, v[14:15], off offset:184
	s_waitcnt vmcnt(7)
	v_mul_f32_e32 v20, v70, v20
	s_waitcnt vmcnt(6)
	v_mul_f32_e32 v21, v71, v21
	s_waitcnt vmcnt(5)
	v_mul_f32_e32 v22, v72, v22
	s_waitcnt vmcnt(4)
	v_mul_f32_e32 v23, v73, v23
	ds_write_b32 v50, v20
	ds_write_b32 v51, v21
	ds_write_b32 v52, v22
	ds_write_b32 v53, v23
	s_waitcnt vmcnt(2)
	v_pk_mul_f32 v[14:15], v[12:13], v[16:17]
	s_waitcnt vmcnt(0)
	v_pk_mul_f32 v[16:17], v[10:11], v[18:19]
	s_cbranch_execnz .LBB0_293
	.p2align	6

; __global__ void __launch_bounds__(512, 2) fwd_kernel(Args a_unused) {
;     ...
;             convert_second(a, l, scr, gw, ngw, lane);
;             __syncthreads();
;             for (int it = bid; it < 1824; it += G) {
;                 int t2 = tid; asm volatile("" : "+v"(t2));
;                 if (it < 256) sgu_item(a, l, it, lds, t2);
;                 else if (it < 768) prep_item(a, l, it - 256, lds, t2);
;                 else if (it < 1280) mix_ac_item(a, l, it - 768, t2);
;                 else compress_item(a, l, it - 1280, lds, t2);
;             }
.LBB0_299:
	v_readlane_b32 s0, v253, 15
	v_readlane_b32 s1, v253, 16
	s_andn2_b64 vcc, exec, s[0:1]
	s_barrier
	s_cbranch_vccnz .LBB0_480
	v_readlane_b32 s10, v254, 3
	v_readlane_b32 s11, v254, 4
	s_add_u32 s75, s10, 0x200000
	s_addc_u32 s69, s11, 0
	s_add_u32 s84, s10, 0x300000
	v_readlane_b32 s0, v254, 14
	s_addc_u32 s90, s11, 0
	v_readlane_b32 s1, v254, 15
	s_mov_b32 s8, s0
	s_ashr_i32 s9, s0, 31
	v_readlane_b32 s16, v253, 35
	s_lshl_b64 s[12:13], s[8:9], 1
	s_lshl_b64 s[0:1], s[8:9], 10
	v_readlane_b32 s24, v253, 43
	v_readlane_b32 s25, v253, 44
	s_add_u32 s14, s24, s0
	s_addc_u32 s15, s25, s1
	s_add_u32 s0, s10, 0x280000
	s_addc_u32 s1, s11, 0
	v_writelane_b32 v254, s0, 48
	s_add_u32 s94, s10, 0x18280000
	v_readlane_b32 s20, v253, 39
	v_readlane_b32 s22, v253, 41
	v_writelane_b32 v254, s1, 49
	s_addc_u32 s95, s11, 0
	s_mul_i32 s1, s8, 0x1800
	v_readlane_b32 s21, v253, 40
	v_readlane_b32 s23, v253, 42
	s_mul_hi_i32 s0, s8, 0x1800
	s_add_u32 s20, s22, s1
	s_addc_u32 s21, s23, s0
	s_add_u32 s22, s10, 0x7100000
	s_addc_u32 s23, s11, 0
	s_add_u32 s86, s10, 0x1c280000
	s_addc_u32 s87, s11, 0
	s_add_u32 s96, s10, 0x6100000
	s_addc_u32 s97, s11, 0
	s_lshl_b32 s0, s8, 9
	s_ashr_i32 s1, s0, 31
	v_readlane_b32 s36, v253, 51
	v_readlane_b32 s26, v253, 45
	s_lshl_b64 s[0:1], s[0:1], 2
	v_readlane_b32 s40, v253, 55
	s_mov_b32 s6, s8
	v_readlane_b32 s27, v253, 46
	v_readlane_b32 s41, v253, 56
	v_readlane_b32 s49, v254, 0
	v_readlane_b32 s50, v254, 1
	v_readlane_b32 s51, v254, 2
	s_add_u32 s26, s40, s0
	v_writelane_b32 v254, s6, 14
	v_readlane_b32 s28, v253, 47
	v_readlane_b32 s44, v253, 59
	s_addc_u32 s27, s41, s1
	v_writelane_b32 v254, s7, 15
	s_lshl_b64 s[6:7], s[8:9], 18
	v_readlane_b32 s29, v253, 48
	v_readlane_b32 s45, v253, 60
	s_add_u32 s28, s44, s0
	v_readlane_b32 s30, v253, 49
	s_addc_u32 s29, s45, s1
	v_readlane_b32 s31, v253, 50
	s_add_u32 s30, s10, 0x1e280000
	v_readlane_b32 s42, v253, 57
	s_addc_u32 s31, s11, 0
	v_readlane_b32 s17, v253, 36
	v_readlane_b32 s18, v253, 37
	v_readlane_b32 s19, v253, 38
	v_readlane_b32 s43, v253, 58
	s_add_u32 s33, s42, s6
	s_addc_u32 s16, s43, s7
	s_lshl_b32 s17, s52, 6
	s_lshl_b32 s18, s52, 7
	v_readlane_b32 s19, v253, 19
	v_readlane_b32 s24, v253, 18
	s_mov_b32 s25, s2
	v_readlane_b32 s37, v253, 52
	v_readlane_b32 s38, v253, 53
	v_readlane_b32 s39, v253, 54
	v_readlane_b32 s46, v253, 61
	v_readlane_b32 s47, v253, 62
	v_readlane_b32 s48, v253, 63
	s_mov_b32 s99, 0
	s_branch .LBB0_302
	.p2align	6

; DI void unpack8(const u32x4 w, float (&f)[8]) { f[0] = bflo(w.x); f[1] = bfhi(w.x); f[2] = bflo(w.y); f[3] = bfhi(w.y); f[4] = bflo(w.z); f[5] = bfhi(w.z); f[6] = bflo(w.w); f[7] = bfhi(w.w); }
; DI u32x4 pack8(const float (&f)[8]) { u32x4 w; w.x = cvtpk(f[0], f[1]); w.y = cvtpk(f[2], f[3]); w.z = cvtpk(f[4], f[5]); w.w = cvtpk(f[6], f[7]); return w; }
; DI void mix_ac_item(const Args& a, int l, int item, int tid) {
;     ...
;         for (int t = 0; t < 4; ++t) { const int m = m0 + tk0 + 8 * (4 * b4 + t); float abf[8], acc[8]; unpack8(ab[t], abf);
; #pragma unroll
;             for (int e = 0; e < 8; ++e) acc[e] = 0.f;
; #pragma unroll
;             for (int j = 0; j < 3; ++j) { float c_[8], x_[8]; unpack8(cc[t][j], c_); unpack8(xx[t][j], x_);
; #pragma unroll
;                 for (int e = 0; e < 4; ++e) { acc[e] += w[j][0][e] * (c_[e] * x_[e]); acc[4 + e] += w[j][1][e] * (c_[4 + e] * x_[4 + e]); } }
; #pragma unroll
;             for (int e = 0; e < 8; ++e) acc[e] *= abf[e];
;             *(u32x4*)(OA + (size_t)m * 512 + c0) = pack8(acc); } }
.LBB0_384:
	s_or_b64 exec, exec, s[0:1]
	global_load_dwordx4 v[88:91], v[96:97], off offset:2048
	s_nop 0
	global_load_dwordx4 v[96:99], v[96:97], off offset:1024
	s_waitcnt vmcnt(12)
	v_lshlrev_b32_e32 v152, 16, v92
	v_and_b32_e32 v153, 0xffff0000, v92
	s_waitcnt vmcnt(11)
	v_lshlrev_b32_e32 v154, 16, v100
	v_and_b32_e32 v155, 0xffff0000, v100
	v_lshlrev_b32_e32 v92, 16, v93
	v_and_b32_e32 v93, 0xffff0000, v93
	v_lshlrev_b32_e32 v100, 16, v101
	v_and_b32_e32 v101, 0xffff0000, v101
	v_pk_mul_f32 v[152:153], v[152:153], v[154:155]
	v_lshlrev_b32_e32 v154, 16, v76
	v_and_b32_e32 v155, 0xffff0000, v76
	v_pk_mul_f32 v[92:93], v[92:93], v[100:101]
	v_lshlrev_b32_e32 v76, 16, v77
	v_and_b32_e32 v77, 0xffff0000, v77
	v_lshlrev_b32_e32 v100, 16, v125
	v_and_b32_e32 v101, 0xffff0000, v125
	v_pk_fma_f32 v[92:93], v[22:23], v[92:93], 0 op_sel_hi:[1,1,0]
	v_pk_mul_f32 v[76:77], v[76:77], v[100:101]
	s_waitcnt vmcnt(9)
	v_lshlrev_b32_e32 v100, 16, v129
	v_pk_fma_f32 v[76:77], v[18:19], v[76:77], v[92:93]
	v_lshlrev_b32_e32 v92, 16, v133
	v_and_b32_e32 v93, 0xffff0000, v133
	v_and_b32_e32 v101, 0xffff0000, v129
	v_pk_mul_f32 v[92:93], v[92:93], v[100:101]
	v_lshlrev_b32_e32 v100, 16, v102
	v_pk_fma_f32 v[76:77], v[14:15], v[92:93], v[76:77]
	v_lshlrev_b32_e32 v92, 16, v94
	v_and_b32_e32 v93, 0xffff0000, v94
	v_and_b32_e32 v101, 0xffff0000, v102
	v_lshlrev_b32_e32 v156, 16, v124
	v_and_b32_e32 v157, 0xffff0000, v124
	v_pk_mul_f32 v[92:93], v[92:93], v[100:101]
	v_lshlrev_b32_e32 v100, 16, v78
	v_and_b32_e32 v101, 0xffff0000, v78
	v_lshlrev_b32_e32 v124, 16, v126
	v_and_b32_e32 v125, 0xffff0000, v126
	v_pk_fma_f32 v[92:93], v[8:9], v[92:93], 0 op_sel_hi:[1,1,0]
	v_pk_mul_f32 v[100:101], v[100:101], v[124:125]
	v_lshlrev_b32_e32 v124, 16, v130
	v_pk_fma_f32 v[92:93], v[0:1], v[100:101], v[92:93]
	v_lshlrev_b32_e32 v100, 16, v134
	v_and_b32_e32 v101, 0xffff0000, v134
	v_and_b32_e32 v125, 0xffff0000, v130
	v_lshlrev_b32_e32 v150, 16, v80
	v_and_b32_e32 v151, 0xffff0000, v80
	v_lshlrev_b32_e32 v80, 16, v81
	v_and_b32_e32 v81, 0xffff0000, v81
	v_pk_mul_f32 v[100:101], v[100:101], v[124:125]
	v_pk_mul_f32 v[80:81], v[76:77], v[80:81]
	v_lshlrev_b32_e32 v76, 16, v82
	v_and_b32_e32 v77, 0xffff0000, v82
	v_pk_fma_f32 v[92:93], v[4:5], v[100:101], v[92:93]
	v_lshlrev_b32_e32 v82, 16, v95
	v_pk_mul_f32 v[92:93], v[92:93], v[76:77]
	v_lshlrev_b32_e32 v76, 16, v83
	v_and_b32_e32 v77, 0xffff0000, v83
	v_and_b32_e32 v83, 0xffff0000, v95
	v_lshlrev_b32_e32 v94, 16, v103
	v_and_b32_e32 v95, 0xffff0000, v103
	v_pk_mul_f32 v[82:83], v[82:83], v[94:95]
	v_lshlrev_b32_e32 v78, 16, v79
	v_and_b32_e32 v79, 0xffff0000, v79
	v_lshlrev_b32_e32 v94, 16, v127
	v_and_b32_e32 v95, 0xffff0000, v127
	v_pk_fma_f32 v[152:153], v[20:21], v[152:153], 0 op_sel_hi:[1,1,0]
	v_pk_mul_f32 v[154:155], v[154:155], v[156:157]
	v_pk_fma_f32 v[82:83], v[10:11], v[82:83], 0 op_sel_hi:[1,1,0]
	v_pk_mul_f32 v[78:79], v[78:79], v[94:95]
	v_pk_fma_f32 v[152:153], v[16:17], v[154:155], v[152:153]
	v_lshlrev_b32_e32 v154, 16, v132
	v_and_b32_e32 v155, 0xffff0000, v132
	v_lshlrev_b32_e32 v156, 16, v128
	v_and_b32_e32 v157, 0xffff0000, v128
	v_pk_fma_f32 v[78:79], v[2:3], v[78:79], v[82:83]
	v_lshlrev_b32_e32 v82, 16, v135
	v_and_b32_e32 v83, 0xffff0000, v135
	v_lshlrev_b32_e32 v94, 16, v131
	v_and_b32_e32 v95, 0xffff0000, v131
	v_pk_mul_f32 v[154:155], v[154:155], v[156:157]
	v_pk_mul_f32 v[82:83], v[82:83], v[94:95]
	v_ashrrev_i32_e32 v145, 31, v144
	v_pk_fma_f32 v[152:153], v[12:13], v[154:155], v[152:153]
	v_pk_fma_f32 v[78:79], v[6:7], v[82:83], v[78:79]
	v_pk_mul_f32 v[150:151], v[152:153], v[150:151]
	v_pk_mul_f32 v[82:83], v[78:79], v[76:77]
	v_cvt_pk_bf16_f32 v77, v80, v81
	v_lshlrev_b64 v[80:81], 10, v[144:145]
	v_cvt_pk_bf16_f32 v76, v150, v151
	v_cvt_pk_bf16_f32 v78, v92, v93
	v_cvt_pk_bf16_f32 v79, v82, v83
	v_lshl_add_u64 v[80:81], v[136:137], 0, v[80:81]
	global_store_dwordx4 v[80:81], v[76:79], off
	s_waitcnt vmcnt(9)
	v_lshlrev_b32_e32 v80, 16, v72
	v_and_b32_e32 v81, 0xffff0000, v72
	v_lshlrev_b32_e32 v78, 16, v68
	v_and_b32_e32 v79, 0xffff0000, v68
	v_lshlrev_b32_e32 v68, 16, v69
	v_and_b32_e32 v69, 0xffff0000, v69
	v_lshlrev_b32_e32 v72, 16, v73
	v_and_b32_e32 v73, 0xffff0000, v73
	v_pk_mul_f32 v[78:79], v[78:79], v[80:81]
	v_lshlrev_b32_e32 v80, 16, v56
	v_and_b32_e32 v81, 0xffff0000, v56
	v_lshlrev_b32_e32 v82, 16, v112
	v_and_b32_e32 v83, 0xffff0000, v112
	v_pk_mul_f32 v[68:69], v[68:69], v[72:73]
	v_lshlrev_b32_e32 v56, 16, v57
	v_and_b32_e32 v57, 0xffff0000, v57
	v_lshlrev_b32_e32 v72, 16, v113
	v_and_b32_e32 v73, 0xffff0000, v113
	v_pk_fma_f32 v[78:79], v[20:21], v[78:79], 0 op_sel_hi:[1,1,0]
	v_pk_mul_f32 v[80:81], v[80:81], v[82:83]
	v_pk_fma_f32 v[68:69], v[22:23], v[68:69], 0 op_sel_hi:[1,1,0]
	v_pk_mul_f32 v[56:57], v[56:57], v[72:73]
	v_pk_fma_f32 v[78:79], v[16:17], v[80:81], v[78:79]
	s_waitcnt vmcnt(8)
	v_lshlrev_b32_e32 v80, 16, v120
	v_and_b32_e32 v81, 0xffff0000, v120
	s_waitcnt vmcnt(7)
; DI void unpack8(const u32x4 w, float (&f)[8]) { f[0] = bflo(w.x); f[1] = bfhi(w.x); f[2] = bflo(w.y); f[3] = bfhi(w.y); f[4] = bflo(w.z); f[5] = bfhi(w.z); f[6] = bflo(w.w); f[7] = bfhi(w.w); }
; DI u32x4 pack8(const float (&f)[8]) { u32x4 w; w.x = cvtpk(f[0], f[1]); w.y = cvtpk(f[2], f[3]); w.z = cvtpk(f[4], f[5]); w.w = cvtpk(f[6], f[7]); return w; }
; DI void mix_ac_item(const Args& a, int l, int item, int tid) {
;     ...
;         for (int t = 0; t < 4; ++t) { const int m = m0 + tk0 + 8 * (4 * b4 + t); float abf[8], acc[8]; unpack8(ab[t], abf);
; #pragma unroll
;             for (int e = 0; e < 8; ++e) acc[e] = 0.f;
; #pragma unroll
;             for (int j = 0; j < 3; ++j) { float c_[8], x_[8]; unpack8(cc[t][j], c_); unpack8(xx[t][j], x_);
; #pragma unroll
;                 for (int e = 0; e < 4; ++e) { acc[e] += w[j][0][e] * (c_[e] * x_[e]); acc[4 + e] += w[j][1][e] * (c_[4 + e] * x_[4 + e]); } }
; #pragma unroll
;             for (int e = 0; e < 8; ++e) acc[e] *= abf[e];
;             *(u32x4*)(OA + (size_t)m * 512 + c0) = pack8(acc); } }
	v_lshlrev_b32_e32 v82, 16, v116
	v_and_b32_e32 v83, 0xffff0000, v116
	v_pk_fma_f32 v[56:57], v[18:19], v[56:57], v[68:69]
	v_lshlrev_b32_e32 v68, 16, v121
	v_and_b32_e32 v69, 0xffff0000, v121
	v_lshlrev_b32_e32 v72, 16, v117
	v_and_b32_e32 v73, 0xffff0000, v117
	v_pk_mul_f32 v[80:81], v[80:81], v[82:83]
	v_pk_mul_f32 v[68:69], v[68:69], v[72:73]
	v_lshlrev_b32_e32 v76, 16, v60
	v_and_b32_e32 v77, 0xffff0000, v60
	v_pk_fma_f32 v[78:79], v[12:13], v[80:81], v[78:79]
	v_pk_fma_f32 v[56:57], v[14:15], v[68:69], v[56:57]
	v_lshlrev_b32_e32 v68, 16, v70
	v_and_b32_e32 v69, 0xffff0000, v70
	v_lshlrev_b32_e32 v72, 16, v74
	v_and_b32_e32 v73, 0xffff0000, v74
	v_pk_mul_f32 v[76:77], v[78:79], v[76:77]
	v_pk_mul_f32 v[68:69], v[68:69], v[72:73]
	v_lshlrev_b32_e32 v72, 16, v58
	v_and_b32_e32 v73, 0xffff0000, v58
	v_lshlrev_b32_e32 v78, 16, v114
	v_and_b32_e32 v79, 0xffff0000, v114
	v_pk_fma_f32 v[68:69], v[8:9], v[68:69], 0 op_sel_hi:[1,1,0]
	v_pk_mul_f32 v[72:73], v[72:73], v[78:79]
	v_lshlrev_b32_e32 v78, 16, v118
	v_pk_fma_f32 v[68:69], v[0:1], v[72:73], v[68:69]
	v_lshlrev_b32_e32 v72, 16, v122
	v_and_b32_e32 v73, 0xffff0000, v122
	v_and_b32_e32 v79, 0xffff0000, v118
	v_lshlrev_b32_e32 v60, 16, v61
	v_and_b32_e32 v61, 0xffff0000, v61
	v_pk_mul_f32 v[72:73], v[72:73], v[78:79]
	v_pk_mul_f32 v[60:61], v[56:57], v[60:61]
	v_lshlrev_b32_e32 v56, 16, v62
	v_and_b32_e32 v57, 0xffff0000, v62
	v_pk_fma_f32 v[68:69], v[4:5], v[72:73], v[68:69]
	v_lshlrev_b32_e32 v62, 16, v71
	v_pk_mul_f32 v[68:69], v[68:69], v[56:57]
	v_lshlrev_b32_e32 v56, 16, v63
	v_and_b32_e32 v57, 0xffff0000, v63
	v_and_b32_e32 v63, 0xffff0000, v71
	v_lshlrev_b32_e32 v70, 16, v75
	v_and_b32_e32 v71, 0xffff0000, v75
	v_pk_mul_f32 v[62:63], v[62:63], v[70:71]
	v_lshlrev_b32_e32 v58, 16, v59
	v_and_b32_e32 v59, 0xffff0000, v59
	v_lshlrev_b32_e32 v70, 16, v115
	v_and_b32_e32 v71, 0xffff0000, v115
	v_pk_fma_f32 v[62:63], v[10:11], v[62:63], 0 op_sel_hi:[1,1,0]
	v_pk_mul_f32 v[58:59], v[58:59], v[70:71]
	v_lshlrev_b32_e32 v70, 16, v119
	v_pk_fma_f32 v[58:59], v[2:3], v[58:59], v[62:63]
	v_lshlrev_b32_e32 v62, 16, v123
	v_and_b32_e32 v63, 0xffff0000, v123
	v_and_b32_e32 v71, 0xffff0000, v119
	v_pk_mul_f32 v[62:63], v[62:63], v[70:71]
	v_ashrrev_i32_e32 v143, 31, v142
	v_pk_fma_f32 v[58:59], v[6:7], v[62:63], v[58:59]
	v_ashrrev_i32_e32 v141, 31, v140
	v_pk_mul_f32 v[62:63], v[58:59], v[56:57]
	v_cvt_pk_bf16_f32 v57, v60, v61
	v_lshlrev_b64 v[60:61], 10, v[142:143]
	v_cvt_pk_bf16_f32 v56, v76, v77
	v_cvt_pk_bf16_f32 v58, v68, v69
	v_cvt_pk_bf16_f32 v59, v62, v63
	v_lshl_add_u64 v[60:61], v[136:137], 0, v[60:61]
	global_store_dwordx4 v[60:61], v[56:59], off
	s_waitcnt vmcnt(7)
	v_lshlrev_b32_e32 v60, 16, v52
	v_and_b32_e32 v61, 0xffff0000, v52
	v_lshlrev_b32_e32 v58, 16, v48
	v_and_b32_e32 v59, 0xffff0000, v48
	v_lshlrev_b32_e32 v48, 16, v49
	v_and_b32_e32 v49, 0xffff0000, v49
	v_lshlrev_b32_e32 v52, 16, v53
	v_and_b32_e32 v53, 0xffff0000, v53
	v_pk_mul_f32 v[58:59], v[58:59], v[60:61]
	v_lshlrev_b32_e32 v60, 16, v40
	v_and_b32_e32 v61, 0xffff0000, v40
	v_lshlrev_b32_e32 v62, 16, v84
	v_and_b32_e32 v63, 0xffff0000, v84
	v_pk_mul_f32 v[48:49], v[48:49], v[52:53]
	v_lshlrev_b32_e32 v40, 16, v41
	v_and_b32_e32 v41, 0xffff0000, v41
	v_lshlrev_b32_e32 v52, 16, v85
	v_and_b32_e32 v53, 0xffff0000, v85
	v_pk_fma_f32 v[58:59], v[20:21], v[58:59], 0 op_sel_hi:[1,1,0]
	v_pk_mul_f32 v[60:61], v[60:61], v[62:63]
	v_pk_fma_f32 v[48:49], v[22:23], v[48:49], 0 op_sel_hi:[1,1,0]
	v_pk_mul_f32 v[40:41], v[40:41], v[52:53]
	v_pk_fma_f32 v[58:59], v[16:17], v[60:61], v[58:59]
	s_waitcnt vmcnt(6)
	v_lshlrev_b32_e32 v60, 16, v108
	v_and_b32_e32 v61, 0xffff0000, v108
	s_waitcnt vmcnt(5)
; DI void unpack8(const u32x4 w, float (&f)[8]) { f[0] = bflo(w.x); f[1] = bfhi(w.x); f[2] = bflo(w.y); f[3] = bfhi(w.y); f[4] = bflo(w.z); f[5] = bfhi(w.z); f[6] = bflo(w.w); f[7] = bfhi(w.w); }
; DI u32x4 pack8(const float (&f)[8]) { u32x4 w; w.x = cvtpk(f[0], f[1]); w.y = cvtpk(f[2], f[3]); w.z = cvtpk(f[4], f[5]); w.w = cvtpk(f[6], f[7]); return w; }
; DI void mix_ac_item(const Args& a, int l, int item, int tid) {
;     ...
;         for (int t = 0; t < 4; ++t) { const int m = m0 + tk0 + 8 * (4 * b4 + t); float abf[8], acc[8]; unpack8(ab[t], abf);
; #pragma unroll
;             for (int e = 0; e < 8; ++e) acc[e] = 0.f;
; #pragma unroll
;             for (int j = 0; j < 3; ++j) { float c_[8], x_[8]; unpack8(cc[t][j], c_); unpack8(xx[t][j], x_);
; #pragma unroll
;                 for (int e = 0; e < 4; ++e) { acc[e] += w[j][0][e] * (c_[e] * x_[e]); acc[4 + e] += w[j][1][e] * (c_[4 + e] * x_[4 + e]); } }
; #pragma unroll
;             for (int e = 0; e < 8; ++e) acc[e] *= abf[e];
;             *(u32x4*)(OA + (size_t)m * 512 + c0) = pack8(acc); } }
;     const int gi = ch >> 4, wn = 2 << gi;
;     for (int b2 = 0; b2 < 4; ++b2) { u32x4 pq[2][16];
	v_lshlrev_b32_e32 v62, 16, v104
	v_and_b32_e32 v63, 0xffff0000, v104
	v_pk_fma_f32 v[40:41], v[18:19], v[40:41], v[48:49]
	v_lshlrev_b32_e32 v48, 16, v109
	v_and_b32_e32 v49, 0xffff0000, v109
	v_lshlrev_b32_e32 v52, 16, v105
	v_and_b32_e32 v53, 0xffff0000, v105
	v_pk_mul_f32 v[60:61], v[60:61], v[62:63]
	v_pk_mul_f32 v[48:49], v[48:49], v[52:53]
	v_lshlrev_b32_e32 v56, 16, v44
	v_and_b32_e32 v57, 0xffff0000, v44
	v_pk_fma_f32 v[58:59], v[12:13], v[60:61], v[58:59]
	v_pk_fma_f32 v[40:41], v[14:15], v[48:49], v[40:41]
	v_lshlrev_b32_e32 v48, 16, v50
	v_and_b32_e32 v49, 0xffff0000, v50
	v_lshlrev_b32_e32 v52, 16, v54
	v_and_b32_e32 v53, 0xffff0000, v54
	v_pk_mul_f32 v[56:57], v[58:59], v[56:57]
	v_pk_mul_f32 v[48:49], v[48:49], v[52:53]
	v_lshlrev_b32_e32 v52, 16, v42
	v_and_b32_e32 v53, 0xffff0000, v42
	v_lshlrev_b32_e32 v58, 16, v86
	v_and_b32_e32 v59, 0xffff0000, v86
	v_pk_fma_f32 v[48:49], v[8:9], v[48:49], 0 op_sel_hi:[1,1,0]
	v_pk_mul_f32 v[52:53], v[52:53], v[58:59]
	v_lshlrev_b32_e32 v58, 16, v106
	v_pk_fma_f32 v[48:49], v[0:1], v[52:53], v[48:49]
	v_lshlrev_b32_e32 v52, 16, v110
	v_and_b32_e32 v53, 0xffff0000, v110
	v_and_b32_e32 v59, 0xffff0000, v106
	v_lshlrev_b32_e32 v44, 16, v45
	v_and_b32_e32 v45, 0xffff0000, v45
	v_pk_mul_f32 v[52:53], v[52:53], v[58:59]
	v_pk_mul_f32 v[44:45], v[40:41], v[44:45]
	v_lshlrev_b32_e32 v40, 16, v46
	v_and_b32_e32 v41, 0xffff0000, v46
	v_pk_fma_f32 v[48:49], v[4:5], v[52:53], v[48:49]
	v_lshlrev_b32_e32 v46, 16, v51
	v_pk_mul_f32 v[48:49], v[48:49], v[40:41]
	v_lshlrev_b32_e32 v40, 16, v47
	v_and_b32_e32 v41, 0xffff0000, v47
	v_and_b32_e32 v47, 0xffff0000, v51
	v_lshlrev_b32_e32 v50, 16, v55
	v_and_b32_e32 v51, 0xffff0000, v55
	v_pk_mul_f32 v[46:47], v[46:47], v[50:51]
	v_lshlrev_b32_e32 v42, 16, v43
	v_and_b32_e32 v43, 0xffff0000, v43
	v_lshlrev_b32_e32 v50, 16, v87
	v_and_b32_e32 v51, 0xffff0000, v87
	v_pk_fma_f32 v[46:47], v[10:11], v[46:47], 0 op_sel_hi:[1,1,0]
	v_pk_mul_f32 v[42:43], v[42:43], v[50:51]
	v_lshlrev_b32_e32 v50, 16, v107
	v_pk_fma_f32 v[42:43], v[2:3], v[42:43], v[46:47]
	v_lshlrev_b32_e32 v46, 16, v111
	v_and_b32_e32 v47, 0xffff0000, v111
	v_and_b32_e32 v51, 0xffff0000, v107
	v_pk_mul_f32 v[46:47], v[46:47], v[50:51]
	v_ashrrev_i32_e32 v139, 31, v138
	v_pk_fma_f32 v[42:43], v[6:7], v[46:47], v[42:43]
	v_lshl_add_u64 v[128:129], s[86:87], 0, v[160:161]
	v_pk_mul_f32 v[46:47], v[42:43], v[40:41]
	v_cvt_pk_bf16_f32 v41, v44, v45
	v_lshlrev_b64 v[44:45], 10, v[140:141]
	v_cvt_pk_bf16_f32 v40, v56, v57
	v_cvt_pk_bf16_f32 v42, v48, v49
	v_cvt_pk_bf16_f32 v43, v46, v47
	v_lshl_add_u64 v[44:45], v[136:137], 0, v[44:45]
	global_store_dwordx4 v[44:45], v[40:43], off
	s_waitcnt vmcnt(5)
	v_lshlrev_b32_e32 v44, 16, v36
	v_and_b32_e32 v45, 0xffff0000, v36
	v_lshlrev_b32_e32 v42, 16, v32
	v_and_b32_e32 v43, 0xffff0000, v32
	v_pk_mul_f32 v[42:43], v[42:43], v[44:45]
	v_lshlrev_b32_e32 v44, 16, v64
	v_pk_fma_f32 v[20:21], v[20:21], v[42:43], 0 op_sel_hi:[1,1,0]
	v_lshlrev_b32_e32 v42, 16, v24
	v_and_b32_e32 v43, 0xffff0000, v24
	v_and_b32_e32 v45, 0xffff0000, v64
	v_pk_mul_f32 v[42:43], v[42:43], v[44:45]
	v_lshlrev_b32_e32 v40, 16, v28
	v_pk_fma_f32 v[16:17], v[16:17], v[42:43], v[20:21]
	s_waitcnt vmcnt(3)
	v_lshlrev_b32_e32 v20, 16, v96
	v_and_b32_e32 v21, 0xffff0000, v96
	v_lshlrev_b32_e32 v42, 16, v88
	v_and_b32_e32 v43, 0xffff0000, v88
	v_pk_mul_f32 v[20:21], v[42:43], v[20:21]
	v_and_b32_e32 v41, 0xffff0000, v28
	v_pk_fma_f32 v[12:13], v[12:13], v[20:21], v[16:17]
	v_lshlrev_b32_e32 v16, 16, v29
	v_and_b32_e32 v17, 0xffff0000, v29
	v_lshlrev_b32_e32 v20, 16, v33
	v_and_b32_e32 v21, 0xffff0000, v33
	v_lshlrev_b32_e32 v28, 16, v37
	v_and_b32_e32 v29, 0xffff0000, v37
	v_pk_mul_f32 v[20:21], v[20:21], v[28:29]
	v_lshlrev_b32_e32 v24, 16, v65
	v_pk_fma_f32 v[20:21], v[22:23], v[20:21], 0 op_sel_hi:[1,1,0]
	v_lshlrev_b32_e32 v22, 16, v25
	v_and_b32_e32 v23, 0xffff0000, v25
	v_and_b32_e32 v25, 0xffff0000, v65
	v_pk_mul_f32 v[22:23], v[22:23], v[24:25]
	v_pk_mul_f32 v[12:13], v[12:13], v[40:41]
	v_pk_fma_f32 v[18:19], v[18:19], v[22:23], v[20:21]
	v_lshlrev_b32_e32 v20, 16, v97
	v_and_b32_e32 v21, 0xffff0000, v97
	v_lshlrev_b32_e32 v22, 16, v89
	v_and_b32_e32 v23, 0xffff0000, v89
	v_pk_mul_f32 v[20:21], v[22:23], v[20:21]
	s_movk_i32 s8, 0xffc0
	v_pk_fma_f32 v[14:15], v[14:15], v[20:21], v[18:19]
	v_lshlrev_b32_e32 v18, 16, v34
	v_and_b32_e32 v19, 0xffff0000, v34
	v_lshlrev_b32_e32 v20, 16, v38
	v_and_b32_e32 v21, 0xffff0000, v38
	v_pk_mul_f32 v[18:19], v[18:19], v[20:21]
	v_lshlrev_b32_e32 v20, 16, v66
	v_pk_fma_f32 v[8:9], v[8:9], v[18:19], 0 op_sel_hi:[1,1,0]
	v_lshlrev_b32_e32 v18, 16, v26
	v_and_b32_e32 v19, 0xffff0000, v26
	v_and_b32_e32 v21, 0xffff0000, v66
	v_pk_mul_f32 v[18:19], v[18:19], v[20:21]
	v_pk_mul_f32 v[14:15], v[14:15], v[16:17]
	v_pk_fma_f32 v[0:1], v[0:1], v[18:19], v[8:9]
	v_lshlrev_b32_e32 v8, 16, v98
	v_and_b32_e32 v9, 0xffff0000, v98
	v_lshlrev_b32_e32 v18, 16, v90
	v_and_b32_e32 v19, 0xffff0000, v90
	v_pk_mul_f32 v[8:9], v[18:19], v[8:9]
	v_lshlrev_b32_e32 v16, 16, v30
	v_and_b32_e32 v17, 0xffff0000, v30
	v_pk_fma_f32 v[0:1], v[4:5], v[8:9], v[0:1]
	v_lshlrev_b32_e32 v8, 16, v35
	v_pk_mul_f32 v[4:5], v[0:1], v[16:17]
	v_and_b32_e32 v9, 0xffff0000, v35
	v_lshlrev_b32_e32 v16, 16, v39
	v_and_b32_e32 v17, 0xffff0000, v39
	v_pk_mul_f32 v[8:9], v[8:9], v[16:17]
	v_lshlrev_b32_e32 v16, 16, v67
	v_pk_fma_f32 v[8:9], v[10:11], v[8:9], 0 op_sel_hi:[1,1,0]
	v_lshlrev_b32_e32 v10, 16, v27
	v_and_b32_e32 v11, 0xffff0000, v27
	v_and_b32_e32 v17, 0xffff0000, v67
	v_pk_mul_f32 v[10:11], v[10:11], v[16:17]
	v_lshlrev_b32_e32 v0, 16, v31
	v_pk_fma_f32 v[2:3], v[2:3], v[10:11], v[8:9]
	v_lshlrev_b32_e32 v8, 16, v99
	v_and_b32_e32 v9, 0xffff0000, v99
	v_lshlrev_b32_e32 v10, 16, v91
	v_and_b32_e32 v11, 0xffff0000, v91
	v_pk_mul_f32 v[8:9], v[10:11], v[8:9]
	v_and_b32_e32 v1, 0xffff0000, v31
	v_pk_fma_f32 v[2:3], v[6:7], v[8:9], v[2:3]
	s_nop 0
	v_pk_mul_f32 v[6:7], v[2:3], v[0:1]
	v_cvt_pk_bf16_f32 v2, v4, v5
	v_lshlrev_b64 v[4:5], 10, v[138:139]
	v_cvt_pk_bf16_f32 v0, v12, v13
	v_cvt_pk_bf16_f32 v1, v14, v15
	v_cvt_pk_bf16_f32 v3, v6, v7
	v_lshl_add_u64 v[4:5], v[136:137], 0, v[4:5]
	global_store_dwordx4 v[4:5], v[0:3], off
	v_add_u32_e32 v137, s24, v148
	s_nop 0
	v_lshrrev_b32_e32 v0, 4, v147
	v_lshlrev_b32_e64 v136, v0, 2
	s_branch .LBB0_386
	.p2align	6

; DI float bf1(bf16_t v) { return __uint_as_float(((unsigned)v) << 16); }
; DI void sgu_item(const Args& a, int l, int item, unsigned char* lds, int tid) {
;     ...
;     bf16_t* vT = (bf16_t*)lds; const int m0 = item * 128, lane = tid & 63, wave = __builtin_amdgcn_readfirstlane(tid >> 6);
;     float ngv[8];
; #pragma unroll
;     for (int e = 0; e < 8; ++e) ngv[e] = ng[e * 64 + lane];
;     for (int s4 = 0; s4 < 4; ++s4) {
;         bf16_t raw[4][8];
; #pragma unroll
;         for (int rr = 0; rr < 4; ++rr) { const bf16_t* zr = Z1 + (size_t)(m0 + wave + 8 * (4 * s4 + rr)) * ZP + C_SG + 512 + lane;
; #pragma unroll
;             for (int e = 0; e < 8; ++e) raw[rr][e] = zr[e * 64]; }
; #pragma unroll
;         for (int rr = 0; rr < 4; ++rr) { const int s = wave + 8 * (4 * s4 + rr); float v[8]; float q = 0.f;
; #pragma unroll
;             for (int e = 0; e < 8; ++e) { v[e] = gelu_erf(bf1(raw[rr][e])); q += v[e] * v[e]; }
.LBB0_449:
	v_and_b32_e32 v0, 63, v146
	v_lshlrev_b32_e32 v2, 2, v0
	global_load_dword v1, v2, s[26:27]
	global_load_dword v32, v2, s[26:27] offset:256
	global_load_dword v33, v2, s[26:27] offset:512
	global_load_dword v34, v2, s[26:27] offset:768
	global_load_dword v35, v2, s[26:27] offset:1024
	global_load_dword v36, v2, s[26:27] offset:1280
	global_load_dword v37, v2, s[26:27] offset:1536
	global_load_dword v38, v2, s[26:27] offset:1792
	v_and_b32_e32 v2, 64, v217
	v_add_u32_e32 v2, 64, v2
	v_xor_b32_e32 v3, 1, v217
	v_cmp_lt_i32_e32 vcc, v3, v2
	v_readfirstlane_b32 s0, v146
	s_ashr_i32 s6, s0, 6
	v_cndmask_b32_e32 v3, v217, v3, vcc
	v_lshlrev_b32_e32 v39, 2, v3
	v_xor_b32_e32 v3, 2, v217
	v_cmp_lt_i32_e32 vcc, v3, v2
	s_lshl_b32 s7, s6, 1
	s_add_i32 s7, s7, 0
	v_cndmask_b32_e32 v3, v217, v3, vcc
	v_lshlrev_b32_e32 v40, 2, v3
	v_xor_b32_e32 v3, 4, v217
	v_cmp_lt_i32_e32 vcc, v3, v2
	v_mov_b32_e32 v215, 0x80
	s_mov_b32 s1, 0
	v_cndmask_b32_e32 v3, v217, v3, vcc
	v_lshlrev_b32_e32 v41, 2, v3
	v_xor_b32_e32 v3, 8, v217
	v_cmp_lt_i32_e32 vcc, v3, v2
	s_add_i32 s8, s6, s19
	s_nop 0
	v_cndmask_b32_e32 v3, v217, v3, vcc
	v_lshlrev_b32_e32 v42, 2, v3
	v_xor_b32_e32 v3, 16, v217
	v_cmp_lt_i32_e32 vcc, v3, v2
	s_nop 1
	v_cndmask_b32_e32 v3, v217, v3, vcc
	v_lshlrev_b32_e32 v43, 2, v3
	v_xor_b32_e32 v3, 32, v217
	v_cmp_lt_i32_e32 vcc, v3, v2
	s_nop 1
	v_cndmask_b32_e32 v2, v217, v3, vcc
	v_lshlrev_b32_e32 v44, 2, v2
	v_mov_b32_e32 v2, s7
	s_movk_i32 s7, 0x110
	v_mad_u32_u24 v45, v0, s7, v2
	.p2align	6
.LBB0_450:
	s_mul_i32 s9, s8, 0x2230
	s_mul_hi_i32 s7, s8, 0x2230
	s_add_u32 s6, s22, s9
	s_addc_u32 s7, s23, s7
	v_lshlrev_b32_e32 v160, 1, v0
	v_lshl_add_u64 v[22:23], s[6:7], 0, v[160:161]
	v_lshl_add_u64 v[20:21], v[22:23], 0, s[72:73]
	global_load_ushort v2, v[20:21], off offset:512
	global_load_ushort v3, v[20:21], off offset:640
	s_add_i32 s6, s8, 8
	s_mul_hi_i32 s7, s6, 0x2230
	s_add_i32 s6, s9, 0x11180
	s_add_u32 s6, s22, s6
	s_addc_u32 s7, s23, s7
	v_lshl_add_u64 v[24:25], s[6:7], 0, v[160:161]
	s_add_i32 s6, s8, 16
	s_mul_hi_i32 s7, s6, 0x2230
	s_add_i32 s6, s9, 0x22300
	s_add_u32 s6, s22, s6
	s_addc_u32 s7, s23, s7
	v_lshl_add_u64 v[10:11], s[6:7], 0, v[160:161]
	s_add_i32 s6, s8, 24
	s_add_i32 s9, s9, 0x33480
	s_mul_hi_i32 s7, s6, 0x2230
	s_add_u32 s6, s22, s9
	s_addc_u32 s7, s23, s7
	v_lshl_add_u64 v[12:13], s[6:7], 0, v[160:161]
	s_mov_b32 s6, 0xbf3a00e3
	v_lshl_add_u64 v[18:19], v[24:25], 0, s[72:73]
	v_lshl_add_u64 v[4:5], v[10:11], 0, s[72:73]
	v_lshl_add_u64 v[8:9], v[12:13], 0, s[72:73]
	v_add_u32_e32 v46, s1, v45
	v_add_u32_e32 v50, 0x11000, v46
	v_add_u32_e32 v49, 0x15400, v46
	v_add_u32_e32 v48, 0x19800, v46
	v_add_u32_e32 v47, 0x1dc00, v46
	s_add_i32 s1, s1, 64
	s_add_i32 s8, s8, 32
	s_cmpk_eq_i32 s1, 0x100
	s_waitcnt vmcnt(0)
	v_lshlrev_b32_e32 v6, 16, v2
	s_waitcnt vmcnt(0)
	v_lshlrev_b32_e32 v7, 16, v3
	v_fma_f32 v2, |v6|, s77, 1.0
	v_pk_mul_f32 v[16:17], v[6:7], v[6:7]
	v_rcp_f32_e32 v14, v2
	v_mul_f32_e32 v2, 0xbf38aa3b, v16
	v_exp_f32_e32 v16, v2
	v_fma_f32 v2, |v7|, s77, 1.0
	v_rcp_f32_e32 v15, v2
	v_mov_b64_e32 v[2:3], s[6:7]
	v_mul_f32_e32 v17, 0xbf38aa3b, v17
	v_exp_f32_e32 v17, v17
	v_pk_fma_f32 v[26:27], v[14:15], s[92:93], v[2:3] op_sel_hi:[1,0,0]
	v_cmp_gt_f32_e32 vcc, 0, v6
	v_pk_fma_f32 v[26:27], v[14:15], v[26:27], s[74:75] op_sel_hi:[1,1,0]
	v_cmp_gt_f32_e64 s[6:7], 0, v7
	v_pk_fma_f32 v[26:27], v[14:15], v[26:27], s[58:59] op_sel_hi:[1,1,0]
	s_nop 0
	v_pk_fma_f32 v[26:27], v[14:15], v[26:27], s[76:77] op_sel_hi:[1,1,0]
	s_nop 0
	v_pk_mul_f32 v[14:15], v[14:15], v[26:27]
	s_nop 0
	v_pk_mul_f32 v[14:15], v[16:17], v[14:15]
	s_nop 0
	v_pk_mul_f32 v[16:17], v[14:15], v[6:7]
	v_pk_fma_f32 v[6:7], v[14:15], v[6:7], v[6:7] neg_lo:[1,0,0] neg_hi:[1,0,0]
	s_nop 0
	v_cndmask_b32_e64 v15, v7, v17, s[6:7]
	v_cndmask_b32_e32 v14, v6, v16, vcc
	global_load_ushort v6, v[20:21], off offset:768
	global_load_ushort v7, v[20:21], off offset:896
	v_pk_mul_f32 v[28:29], v[14:15], v[14:15]
	s_waitcnt vmcnt(1)
	v_lshlrev_b32_e32 v6, 16, v6
	s_waitcnt vmcnt(0)
	v_lshlrev_b32_e32 v7, 16, v7
	v_pk_mul_f32 v[26:27], v[6:7], v[6:7]
	v_fma_f32 v16, |v6|, s77, 1.0
	v_mul_f32_e32 v17, 0xbf38aa3b, v26
	v_exp_f32_e32 v26, v17
	v_fma_f32 v17, |v7|, s77, 1.0
	v_rcp_f32_e32 v16, v16
	v_rcp_f32_e32 v17, v17
	v_mul_f32_e32 v27, 0xbf38aa3b, v27
	v_exp_f32_e32 v27, v27
	v_cmp_gt_f32_e32 vcc, 0, v6
	v_pk_fma_f32 v[30:31], v[16:17], s[92:93], v[2:3] op_sel_hi:[1,0,0]
	v_cmp_gt_f32_e64 s[6:7], 0, v7
	v_pk_fma_f32 v[30:31], v[16:17], v[30:31], s[74:75] op_sel_hi:[1,1,0]
	s_nop 0
	v_pk_fma_f32 v[30:31], v[16:17], v[30:31], s[58:59] op_sel_hi:[1,1,0]
	s_nop 0
	v_pk_fma_f32 v[30:31], v[16:17], v[30:31], s[76:77] op_sel_hi:[1,1,0]
	s_nop 0
	v_pk_mul_f32 v[16:17], v[16:17], v[30:31]
	s_nop 0
	v_pk_mul_f32 v[16:17], v[26:27], v[16:17]
	s_nop 0
	v_pk_mul_f32 v[26:27], v[16:17], v[6:7]
	v_pk_fma_f32 v[6:7], v[16:17], v[6:7], v[6:7] neg_lo:[1,0,0] neg_hi:[1,0,0]
	s_nop 0
	v_cndmask_b32_e64 v17, v7, v27, s[6:7]
	v_cndmask_b32_e32 v16, v6, v26, vcc
	global_load_ushort v6, v[18:19], off offset:512
	global_load_ushort v7, v[18:19], off offset:640
	v_pk_mul_f32 v[30:31], v[16:17], v[16:17]
	s_waitcnt vmcnt(1)
	v_lshlrev_b32_e32 v6, 16, v6
	s_waitcnt vmcnt(0)
; DI float bf1(bf16_t v) { return __uint_as_float(((unsigned)v) << 16); }
; DI float gelu_erf(float v) {
;     const float av = fabsf(v), t = __builtin_amdgcn_rcpf(av * 0.2316418882f + 1.0f);
;     float q = t * 0.5307027145f + (-0.7265760135f); q = q * t + 0.7107068705f; q = q * t + (-0.142248368f); q = q * t + 0.127414796f; q = q * t;
;     const float e = __builtin_amdgcn_exp2f((v * v) * (-0.72134752044f)); const float m = v * (q * e);
;     return v < 0.f ? m : v - m;
; DI void sgu_item(const Args& a, int l, int item, unsigned char* lds, int tid) {
;     ...
;         for (int rr = 0; rr < 4; ++rr) { const bf16_t* zr = Z1 + (size_t)(m0 + wave + 8 * (4 * s4 + rr)) * ZP + C_SG + 512 + lane;
; #pragma unroll
;             for (int e = 0; e < 8; ++e) raw[rr][e] = zr[e * 64]; }
; #pragma unroll
;         for (int rr = 0; rr < 4; ++rr) { const int s = wave + 8 * (4 * s4 + rr); float v[8]; float q = 0.f;
; #pragma unroll
;             for (int e = 0; e < 8; ++e) { v[e] = gelu_erf(bf1(raw[rr][e])); q += v[e] * v[e]; }
	v_lshlrev_b32_e32 v7, 16, v7
	v_pk_mul_f32 v[52:53], v[6:7], v[6:7]
	v_fma_f32 v26, |v6|, s77, 1.0
	v_mul_f32_e32 v27, 0xbf38aa3b, v52
	v_exp_f32_e32 v52, v27
	v_fma_f32 v27, |v7|, s77, 1.0
	v_rcp_f32_e32 v26, v26
	v_rcp_f32_e32 v27, v27
	v_mul_f32_e32 v51, 0xbf38aa3b, v53
	v_exp_f32_e32 v53, v51
	v_cmp_gt_f32_e32 vcc, 0, v6
	v_pk_fma_f32 v[54:55], v[26:27], s[92:93], v[2:3] op_sel_hi:[1,0,0]
	v_cmp_gt_f32_e64 s[6:7], 0, v7
	v_pk_fma_f32 v[54:55], v[26:27], v[54:55], s[74:75] op_sel_hi:[1,1,0]
	s_nop 0
	v_pk_fma_f32 v[54:55], v[26:27], v[54:55], s[58:59] op_sel_hi:[1,1,0]
	s_nop 0
	v_pk_fma_f32 v[54:55], v[26:27], v[54:55], s[76:77] op_sel_hi:[1,1,0]
	s_nop 0
	v_pk_mul_f32 v[26:27], v[26:27], v[54:55]
	s_nop 0
	v_pk_mul_f32 v[26:27], v[52:53], v[26:27]
	s_nop 0
	v_pk_mul_f32 v[52:53], v[26:27], v[6:7]
	v_pk_fma_f32 v[6:7], v[26:27], v[6:7], v[6:7] neg_lo:[1,0,0] neg_hi:[1,0,0]
	s_nop 0
	v_cndmask_b32_e32 v6, v6, v52, vcc
	v_add_co_u32_e32 v24, vcc, s85, v24
	v_cndmask_b32_e64 v7, v7, v53, s[6:7]
	s_nop 0
	v_addc_co_u32_e32 v25, vcc, 0, v25, vcc
	v_add_co_u32_e32 v22, vcc, s85, v22
	global_load_ushort v24, v[24:25], off offset:3632
	s_nop 0
	v_addc_co_u32_e32 v23, vcc, 0, v23, vcc
	global_load_ushort v22, v[22:23], off offset:3632
	v_pk_mul_f32 v[52:53], v[6:7], v[6:7]
	s_waitcnt vmcnt(0)
	v_lshlrev_b32_e32 v23, 16, v22
	v_lshlrev_b32_e32 v22, 16, v24
	v_fma_f32 v24, |v23|, s77, 1.0
	v_pk_mul_f32 v[26:27], v[22:23], v[22:23]
	v_rcp_f32_e32 v25, v24
	v_mul_f32_e32 v24, 0xbf38aa3b, v27
	v_exp_f32_e32 v27, v24
	global_load_ushort v24, v[18:19], off offset:128
	global_load_ushort v51, v[20:21], off offset:128
	v_cmp_gt_f32_e32 vcc, 0, v22
	v_cmp_gt_f32_e64 s[6:7], 0, v23
	s_waitcnt vmcnt(1)
	v_lshlrev_b32_e32 v54, 16, v24
	s_waitcnt vmcnt(0)
	v_lshlrev_b32_e32 v55, 16, v51
	v_fma_f32 v24, |v55|, s77, 1.0
	v_pk_mul_f32 v[58:59], v[54:55], v[54:55]
	v_rcp_f32_e32 v57, v24
	v_mul_f32_e32 v24, 0xbf38aa3b, v59
	v_exp_f32_e32 v59, v24
	global_load_ushort v24, v[18:19], off offset:256
	global_load_ushort v51, v[20:21], off offset:256
	s_waitcnt vmcnt(1)
	v_lshlrev_b32_e32 v60, 16, v24
	s_waitcnt vmcnt(0)
	v_lshlrev_b32_e32 v61, 16, v51
	v_fma_f32 v24, |v61|, s77, 1.0
	v_pk_mul_f32 v[64:65], v[60:61], v[60:61]
	v_rcp_f32_e32 v63, v24
	v_mul_f32_e32 v24, 0xbf38aa3b, v65
	v_exp_f32_e32 v65, v24
	global_load_ushort v24, v[18:19], off offset:384
	s_nop 0
	global_load_ushort v20, v[20:21], off offset:384
	v_mul_f32_e32 v51, 0xbf38aa3b, v64
	v_exp_f32_e32 v64, v51
	s_waitcnt vmcnt(1)
	v_lshlrev_b32_e32 v66, 16, v24
	s_waitcnt vmcnt(0)
	v_lshlrev_b32_e32 v67, 16, v20
	v_fma_f32 v20, |v67|, s77, 1.0
	v_pk_mul_f32 v[70:71], v[66:67], v[66:67]
	v_rcp_f32_e32 v69, v20
	v_mul_f32_e32 v20, 0xbf38aa3b, v71
	v_exp_f32_e32 v71, v20
	v_fma_f32 v20, |v22|, s77, 1.0
	v_rcp_f32_e32 v24, v20
	v_mul_f32_e32 v51, 0xbf38aa3b, v70
	v_exp_f32_e32 v70, v51
	v_pk_fma_f32 v[20:21], v[24:25], s[92:93], v[2:3] op_sel_hi:[1,0,0]
	s_nop 0
	v_pk_fma_f32 v[20:21], v[24:25], v[20:21], s[74:75] op_sel_hi:[1,1,0]
	s_nop 0
	v_pk_fma_f32 v[20:21], v[24:25], v[20:21], s[58:59] op_sel_hi:[1,1,0]
	s_nop 0
	v_pk_fma_f32 v[20:21], v[24:25], v[20:21], s[76:77] op_sel_hi:[1,1,0]
	s_nop 0
	v_pk_mul_f32 v[20:21], v[24:25], v[20:21]
	v_mul_f32_e32 v24, 0xbf38aa3b, v26
	v_exp_f32_e32 v26, v24
	s_nop 0
	v_pk_mul_f32 v[20:21], v[26:27], v[20:21]
	s_nop 0
	v_pk_mul_f32 v[24:25], v[20:21], v[22:23]
	v_pk_fma_f32 v[20:21], v[20:21], v[22:23], v[22:23] neg_lo:[1,0,0] neg_hi:[1,0,0]
	v_fma_f32 v22, |v54|, s77, 1.0
	v_rcp_f32_e32 v56, v22
	v_cndmask_b32_e32 v20, v20, v24, vcc
	v_mul_f32_e32 v24, 0xbf38aa3b, v58
	v_exp_f32_e32 v58, v24
	v_pk_fma_f32 v[22:23], v[56:57], s[92:93], v[2:3] op_sel_hi:[1,0,0]
	v_cndmask_b32_e64 v21, v21, v25, s[6:7]
	v_pk_fma_f32 v[22:23], v[56:57], v[22:23], s[74:75] op_sel_hi:[1,1,0]
	v_cmp_gt_f32_e32 vcc, 0, v54
	v_pk_fma_f32 v[22:23], v[56:57], v[22:23], s[58:59] op_sel_hi:[1,1,0]
	v_cmp_gt_f32_e64 s[6:7], 0, v55
	v_pk_fma_f32 v[22:23], v[56:57], v[22:23], s[76:77] op_sel_hi:[1,1,0]
	s_nop 0
	v_pk_mul_f32 v[22:23], v[56:57], v[22:23]
	s_nop 0
	v_pk_mul_f32 v[22:23], v[58:59], v[22:23]
	s_nop 0
	v_pk_mul_f32 v[24:25], v[22:23], v[54:55]
	v_pk_fma_f32 v[22:23], v[22:23], v[54:55], v[54:55] neg_lo:[1,0,0] neg_hi:[1,0,0]
	s_nop 0
	v_cndmask_b32_e64 v23, v23, v25, s[6:7]
	v_cndmask_b32_e32 v22, v22, v24, vcc
	v_pk_mul_f32 v[24:25], v[22:23], v[22:23]
	v_cmp_gt_f32_e32 vcc, 0, v60
	v_pk_fma_f32 v[26:27], v[20:21], v[20:21], v[24:25]
	v_fma_f32 v24, |v60|, s77, 1.0
	v_rcp_f32_e32 v62, v24
	v_cmp_gt_f32_e64 s[6:7], 0, v61
	v_pk_fma_f32 v[24:25], v[62:63], s[92:93], v[2:3] op_sel_hi:[1,0,0]
	s_nop 0
	v_pk_fma_f32 v[24:25], v[62:63], v[24:25], s[74:75] op_sel_hi:[1,1,0]
	s_nop 0
	v_pk_fma_f32 v[24:25], v[62:63], v[24:25], s[58:59] op_sel_hi:[1,1,0]
	s_nop 0
	v_pk_fma_f32 v[24:25], v[62:63], v[24:25], s[76:77] op_sel_hi:[1,1,0]
	s_nop 0
	v_pk_mul_f32 v[24:25], v[62:63], v[24:25]
	s_nop 0
	v_pk_mul_f32 v[24:25], v[64:65], v[24:25]
	s_nop 0
	v_pk_mul_f32 v[54:55], v[24:25], v[60:61]
	v_pk_fma_f32 v[24:25], v[24:25], v[60:61], v[60:61] neg_lo:[1,0,0] neg_hi:[1,0,0]
	s_nop 0
	v_cndmask_b32_e64 v25, v25, v55, s[6:7]
	v_cndmask_b32_e32 v24, v24, v54, vcc
	v_pk_fma_f32 v[54:55], v[24:25], v[24:25], v[26:27]
	v_fma_f32 v26, |v66|, s77, 1.0
	v_rcp_f32_e32 v68, v26
	v_cmp_gt_f32_e64 s[6:7], 0, v67
	v_cmp_gt_f32_e32 vcc, 0, v66
	v_pk_fma_f32 v[26:27], v[68:69], s[92:93], v[2:3] op_sel_hi:[1,0,0]
	s_nop 0
	v_pk_fma_f32 v[26:27], v[68:69], v[26:27], s[74:75] op_sel_hi:[1,1,0]
	s_nop 0
	v_pk_fma_f32 v[26:27], v[68:69], v[26:27], s[58:59] op_sel_hi:[1,1,0]
	s_nop 0
	v_pk_fma_f32 v[26:27], v[68:69], v[26:27], s[76:77] op_sel_hi:[1,1,0]
	s_nop 0
	v_pk_mul_f32 v[26:27], v[68:69], v[26:27]
	s_nop 0
	v_pk_mul_f32 v[26:27], v[70:71], v[26:27]
	s_nop 0
	v_pk_mul_f32 v[56:57], v[26:27], v[66:67]
	v_pk_fma_f32 v[26:27], v[26:27], v[66:67], v[66:67] neg_lo:[1,0,0] neg_hi:[1,0,0]
	s_nop 0
	v_cndmask_b32_e64 v27, v27, v57, s[6:7]
	v_mov_b32_e32 v57, v28
	global_load_ushort v28, v[18:19], off offset:768
	s_nop 0
	global_load_ushort v18, v[18:19], off offset:896
	v_cndmask_b32_e32 v26, v26, v56, vcc
	v_pk_fma_f32 v[54:55], v[26:27], v[26:27], v[54:55]
	v_mov_b32_e32 v56, v52
	v_pk_add_f32 v[54:55], v[54:55], v[56:57]
	s_waitcnt vmcnt(0)
; DI float bf1(bf16_t v) { return __uint_as_float(((unsigned)v) << 16); }
; DI bf16_t f2bf(float f) { return (bf16_t)(cvtpk(f, 0.f) & 0xffffu); }
; DI void sgu_item(const Args& a, int l, int item, unsigned char* lds, int tid) {
;     ...
;         for (int rr = 0; rr < 4; ++rr) { const int s = wave + 8 * (4 * s4 + rr); float v[8]; float q = 0.f;
; #pragma unroll
;             for (int e = 0; e < 8; ++e) { v[e] = gelu_erf(bf1(raw[rr][e])); q += v[e] * v[e]; }
;             q = wave_sum(q); const float rs = rsqrtf(q * (1.0f / 512.0f) + 1e-6f);
; #pragma unroll
;             for (int e = 0; e < 8; ++e) vT[(size_t)(e * 64 + lane) * VP + s] = f2bf(v[e] * rs * ngv[e]); }
	v_lshlrev_b32_e32 v19, 16, v18
	v_lshlrev_b32_e32 v18, 16, v28
	v_fma_f32 v28, |v18|, s77, 1.0
	v_pk_mul_f32 v[58:59], v[18:19], v[18:19]
	v_rcp_f32_e32 v56, v28
	v_mul_f32_e32 v28, 0xbf38aa3b, v58
	v_exp_f32_e32 v58, v28
	v_fma_f32 v28, |v19|, s77, 1.0
	v_rcp_f32_e32 v57, v28
	v_mul_f32_e32 v28, 0xbf38aa3b, v59
	v_exp_f32_e32 v59, v28
	v_cmp_gt_f32_e32 vcc, 0, v18
	v_pk_fma_f32 v[60:61], v[56:57], s[92:93], v[2:3] op_sel_hi:[1,0,0]
	v_cmp_gt_f32_e64 s[6:7], 0, v19
	v_pk_fma_f32 v[60:61], v[56:57], v[60:61], s[74:75] op_sel_hi:[1,1,0]
	v_mov_b32_e32 v28, v53
	v_pk_fma_f32 v[60:61], v[56:57], v[60:61], s[58:59] op_sel_hi:[1,1,0]
	v_pk_add_f32 v[28:29], v[54:55], v[28:29]
	v_pk_fma_f32 v[60:61], v[56:57], v[60:61], s[76:77] op_sel_hi:[1,1,0]
	v_mov_b32_e32 v53, v30
	v_pk_mul_f32 v[56:57], v[56:57], v[60:61]
	s_nop 0
	v_pk_mul_f32 v[56:57], v[58:59], v[56:57]
	s_nop 0
	v_pk_mul_f32 v[58:59], v[56:57], v[18:19]
	v_pk_fma_f32 v[18:19], v[56:57], v[18:19], v[18:19] neg_lo:[1,0,0] neg_hi:[1,0,0]
	s_nop 0
	v_cndmask_b32_e64 v19, v19, v59, s[6:7]
	v_cndmask_b32_e32 v18, v18, v58, vcc
	v_pk_mul_f32 v[56:57], v[18:19], v[18:19]
	global_load_ushort v65, v[4:5], off offset:512
	global_load_ushort v66, v[4:5], off offset:640
	global_load_ushort v60, v[4:5], off offset:768
	global_load_ushort v61, v[4:5], off offset:896
	global_load_ushort v58, v[8:9], off offset:512
	global_load_ushort v59, v[8:9], off offset:640
	v_mov_b32_e32 v52, v56
	v_pk_add_f32 v[28:29], v[28:29], v[52:53]
	v_mov_b32_e32 v30, v57
	v_pk_add_f32 v[28:29], v[28:29], v[30:31]
	ds_bpermute_b32 v31, v39, v29
	ds_bpermute_b32 v30, v39, v28
	s_waitcnt lgkmcnt(0)
	v_pk_add_f32 v[28:29], v[28:29], v[30:31]
	ds_bpermute_b32 v31, v40, v29
	ds_bpermute_b32 v30, v40, v28
	s_waitcnt lgkmcnt(0)
	v_pk_add_f32 v[28:29], v[28:29], v[30:31]
	ds_bpermute_b32 v31, v41, v29
	ds_bpermute_b32 v30, v41, v28
	s_waitcnt lgkmcnt(0)
	v_pk_add_f32 v[28:29], v[28:29], v[30:31]
	ds_bpermute_b32 v31, v42, v29
	ds_bpermute_b32 v30, v42, v28
	s_waitcnt lgkmcnt(0)
	v_pk_add_f32 v[28:29], v[28:29], v[30:31]
	ds_bpermute_b32 v31, v43, v29
	ds_bpermute_b32 v30, v43, v28
	s_waitcnt lgkmcnt(0)
	v_pk_add_f32 v[28:29], v[28:29], v[30:31]
	ds_bpermute_b32 v31, v44, v29
	ds_bpermute_b32 v30, v44, v28
	s_waitcnt lgkmcnt(0)
	v_pk_add_f32 v[30:31], v[28:29], v[30:31]
	v_mov_b64_e32 v[28:29], s[70:71]
	v_pk_fma_f32 v[62:63], v[30:31], s[60:61], v[28:29] op_sel_hi:[1,0,0]
	s_nop 0
	v_mul_f32_e32 v30, 0x4b800000, v63
	v_cmp_gt_f32_e64 s[6:7], s71, v63
	v_cmp_gt_f32_e32 vcc, s71, v62
	s_nop 0
	v_cndmask_b32_e64 v30, v63, v30, s[6:7]
	v_rsq_f32_e32 v30, v30
	s_nop 0
	v_mul_f32_e32 v31, 0x45800000, v30
	v_cndmask_b32_e64 v63, v30, v31, s[6:7]
	v_add_co_u32_e64 v12, s[6:7], s85, v12
	v_mul_f32_e32 v21, v21, v63
	s_nop 0
	v_addc_co_u32_e64 v13, s[6:7], 0, v13, s[6:7]
	v_add_co_u32_e64 v10, s[6:7], s85, v10
	v_mul_f32_e32 v21, v1, v21
	s_nop 0
	v_addc_co_u32_e64 v11, s[6:7], 0, v11, s[6:7]
	v_cvt_pk_bf16_f32 v64, v21, s0
	global_load_ushort v56, v[12:13], off offset:3632
	global_load_ushort v57, v[10:11], off offset:3632
	global_load_ushort v54, v[8:9], off offset:128
	global_load_ushort v55, v[4:5], off offset:128
	global_load_ushort v52, v[8:9], off offset:256
	global_load_ushort v53, v[4:5], off offset:256
	global_load_ushort v31, v[8:9], off offset:384
	global_load_ushort v51, v[4:5], off offset:384
	global_load_ushort v21, v[8:9], off offset:768
	global_load_ushort v30, v[8:9], off offset:896
	v_mul_f32_e32 v4, v23, v63
	v_mul_f32_e32 v4, v32, v4
	v_cvt_pk_bf16_f32 v4, v4, s0
	ds_write_b16 v46, v4 offset:17408
	v_mul_f32_e32 v4, v25, v63
	v_mul_f32_e32 v4, v33, v4
	v_cvt_pk_bf16_f32 v4, v4, s0
	ds_write_b16 v46, v4 offset:34816
	v_mul_f32_e32 v4, v27, v63
	v_mul_f32_e32 v4, v34, v4
	v_cvt_pk_bf16_f32 v4, v4, s0
	ds_write_b16 v46, v4 offset:52224
	v_mul_f32_e32 v4, v14, v63
	v_mul_f32_e32 v4, v35, v4
	v_cvt_pk_bf16_f32 v4, v4, s0
	ds_write_b16 v50, v4
	v_mul_f32_e32 v4, v15, v63
	v_mul_f32_e32 v4, v36, v4
	v_cvt_pk_bf16_f32 v4, v4, s0
	ds_write_b16 v49, v4
	v_mul_f32_e32 v4, v16, v63
	v_mul_f32_e32 v4, v37, v4
	v_cvt_pk_bf16_f32 v4, v4, s0
	ds_write_b16 v48, v4
	v_mul_f32_e32 v4, v17, v63
	v_mul_f32_e32 v4, v38, v4
	v_cvt_pk_bf16_f32 v4, v4, s0
	ds_write_b16 v47, v4
	v_mul_f32_e32 v4, 0x4b800000, v62
	v_cndmask_b32_e32 v4, v62, v4, vcc
	v_rsq_f32_e32 v4, v4
	v_add_u32_e32 v47, 0x11020, v46
	ds_write_b16 v46, v64
	v_add_u32_e32 v64, 0x15420, v46
	v_mul_f32_e32 v5, 0x45800000, v4
	v_cndmask_b32_e32 v4, v4, v5, vcc
	v_mul_f32_e32 v5, v20, v4
	v_mul_f32_e32 v5, v1, v5
	v_cvt_pk_bf16_f32 v5, v5, s0
	ds_write_b16 v46, v5 offset:16
	v_mul_f32_e32 v5, v22, v4
	v_mul_f32_e32 v5, v32, v5
	v_cvt_pk_bf16_f32 v5, v5, s0
	ds_write_b16 v46, v5 offset:17424
	v_mul_f32_e32 v5, v24, v4
	v_mul_f32_e32 v5, v33, v5
	v_cvt_pk_bf16_f32 v5, v5, s0
	ds_write_b16 v46, v5 offset:34832
	v_mul_f32_e32 v5, v26, v4
	v_mul_f32_e32 v5, v34, v5
	v_cvt_pk_bf16_f32 v5, v5, s0
	ds_write_b16 v46, v5 offset:52240
	v_mul_f32_e32 v5, v6, v4
	v_mul_f32_e32 v5, v35, v5
	v_cvt_pk_bf16_f32 v5, v5, s0
	v_add_u32_e32 v6, 0x11010, v46
	ds_write_b16 v6, v5
	v_mul_f32_e32 v5, v7, v4
	v_mul_f32_e32 v5, v36, v5
	v_cvt_pk_bf16_f32 v5, v5, s0
	v_add_u32_e32 v6, 0x15410, v46
	ds_write_b16 v6, v5
	v_mul_f32_e32 v5, v18, v4
	v_mul_f32_e32 v5, v37, v5
	v_mul_f32_e32 v4, v19, v4
	v_cvt_pk_bf16_f32 v5, v5, s0
	v_add_u32_e32 v6, 0x19810, v46
	v_mul_f32_e32 v4, v38, v4
	ds_write_b16 v6, v5
	v_cvt_pk_bf16_f32 v4, v4, s0
	v_add_u32_e32 v5, 0x1dc10, v46
	ds_write_b16 v5, v4
	s_waitcnt vmcnt(14)
; DI float bf1(bf16_t v) { return __uint_as_float(((unsigned)v) << 16); }
; DI float gelu_erf(float v) {
;     const float av = fabsf(v), t = __builtin_amdgcn_rcpf(av * 0.2316418882f + 1.0f);
;     float q = t * 0.5307027145f + (-0.7265760135f); q = q * t + 0.7107068705f; q = q * t + (-0.142248368f); q = q * t + 0.127414796f; q = q * t;
;     const float e = __builtin_amdgcn_exp2f((v * v) * (-0.72134752044f)); const float m = v * (q * e);
;     return v < 0.f ? m : v - m;
; DI void sgu_item(const Args& a, int l, int item, unsigned char* lds, int tid) {
;     ...
;         for (int rr = 0; rr < 4; ++rr) { const int s = wave + 8 * (4 * s4 + rr); float v[8]; float q = 0.f;
; #pragma unroll
;             for (int e = 0; e < 8; ++e) { v[e] = gelu_erf(bf1(raw[rr][e])); q += v[e] * v[e]; }
	v_lshlrev_b32_e32 v5, 16, v66
	v_lshlrev_b32_e32 v4, 16, v65
	v_pk_mul_f32 v[8:9], v[4:5], v[4:5]
	v_fma_f32 v6, |v4|, s77, 1.0
	v_mul_f32_e32 v7, 0xbf38aa3b, v8
	v_exp_f32_e32 v8, v7
	v_fma_f32 v7, |v5|, s77, 1.0
	v_rcp_f32_e32 v6, v6
	v_rcp_f32_e32 v7, v7
	v_mul_f32_e32 v9, 0xbf38aa3b, v9
	v_exp_f32_e32 v9, v9
	v_cmp_gt_f32_e32 vcc, 0, v4
	v_pk_fma_f32 v[10:11], v[6:7], s[92:93], v[2:3] op_sel_hi:[1,0,0]
	v_cmp_gt_f32_e64 s[6:7], 0, v5
	v_pk_fma_f32 v[10:11], v[6:7], v[10:11], s[74:75] op_sel_hi:[1,1,0]
	s_waitcnt vmcnt(6)
	v_lshlrev_b32_e32 v25, 16, v55
	v_pk_fma_f32 v[10:11], v[6:7], v[10:11], s[58:59] op_sel_hi:[1,1,0]
	v_lshlrev_b32_e32 v24, 16, v54
	v_pk_fma_f32 v[10:11], v[6:7], v[10:11], s[76:77] op_sel_hi:[1,1,0]
	v_pk_mul_f32 v[48:49], v[24:25], v[24:25]
	v_pk_mul_f32 v[6:7], v[6:7], v[10:11]
	s_waitcnt vmcnt(4)
	v_lshlrev_b32_e32 v53, 16, v53
	v_pk_mul_f32 v[6:7], v[8:9], v[6:7]
	v_lshlrev_b32_e32 v52, 16, v52
	v_pk_mul_f32 v[8:9], v[6:7], v[4:5]
	v_pk_fma_f32 v[4:5], v[6:7], v[4:5], v[4:5] neg_lo:[1,0,0] neg_hi:[1,0,0]
	s_waitcnt vmcnt(2)
	v_lshlrev_b32_e32 v51, 16, v51
	v_cndmask_b32_e64 v7, v5, v9, s[6:7]
	v_cndmask_b32_e32 v6, v4, v8, vcc
	v_lshlrev_b32_e32 v5, 16, v61
	v_lshlrev_b32_e32 v4, 16, v60
	v_pk_mul_f32 v[12:13], v[4:5], v[4:5]
	v_fma_f32 v8, |v4|, s77, 1.0
	v_mul_f32_e32 v9, 0xbf38aa3b, v12
	v_exp_f32_e32 v12, v9
	v_fma_f32 v9, |v5|, s77, 1.0
	v_rcp_f32_e32 v8, v8
	v_rcp_f32_e32 v9, v9
	v_mul_f32_e32 v13, 0xbf38aa3b, v13
	v_exp_f32_e32 v13, v13
	v_cmp_gt_f32_e32 vcc, 0, v4
	v_pk_fma_f32 v[14:15], v[8:9], s[92:93], v[2:3] op_sel_hi:[1,0,0]
	v_cmp_gt_f32_e64 s[6:7], 0, v5
	v_pk_fma_f32 v[14:15], v[8:9], v[14:15], s[74:75] op_sel_hi:[1,1,0]
	v_lshlrev_b32_e32 v50, 16, v31
	v_pk_fma_f32 v[14:15], v[8:9], v[14:15], s[58:59] op_sel_hi:[1,1,0]
	v_pk_mul_f32 v[60:61], v[50:51], v[50:51]
	v_pk_fma_f32 v[14:15], v[8:9], v[14:15], s[76:77] op_sel_hi:[1,1,0]
	v_pk_mul_f32 v[10:11], v[6:7], v[6:7]
	v_pk_mul_f32 v[8:9], v[8:9], v[14:15]
	s_waitcnt vmcnt(0)
	v_lshlrev_b32_e32 v31, 16, v30
	v_pk_mul_f32 v[8:9], v[12:13], v[8:9]
	v_lshlrev_b32_e32 v30, 16, v21
	v_pk_mul_f32 v[12:13], v[8:9], v[4:5]
	v_pk_fma_f32 v[4:5], v[8:9], v[4:5], v[4:5] neg_lo:[1,0,0] neg_hi:[1,0,0]
	v_add_u32_e32 v65, 0x19820, v46
	v_cndmask_b32_e64 v9, v5, v13, s[6:7]
	v_cndmask_b32_e32 v8, v4, v12, vcc
	v_lshlrev_b32_e32 v5, 16, v59
	v_lshlrev_b32_e32 v4, 16, v58
	v_pk_mul_f32 v[16:17], v[4:5], v[4:5]
	v_fma_f32 v14, |v4|, s77, 1.0
	v_mul_f32_e32 v15, 0xbf38aa3b, v16
	v_exp_f32_e32 v16, v15
	v_fma_f32 v15, |v5|, s77, 1.0
	v_rcp_f32_e32 v14, v14
	v_rcp_f32_e32 v15, v15
	v_mul_f32_e32 v17, 0xbf38aa3b, v17
	v_exp_f32_e32 v17, v17
	v_cmp_gt_f32_e32 vcc, 0, v4
	v_pk_fma_f32 v[18:19], v[14:15], s[92:93], v[2:3] op_sel_hi:[1,0,0]
	v_cmp_gt_f32_e64 s[6:7], 0, v5
	v_pk_fma_f32 v[18:19], v[14:15], v[18:19], s[74:75] op_sel_hi:[1,1,0]
	v_pk_mul_f32 v[12:13], v[8:9], v[8:9]
	v_pk_fma_f32 v[18:19], v[14:15], v[18:19], s[58:59] op_sel_hi:[1,1,0]
	v_add_u32_e32 v66, 0x1dc20, v46
	v_pk_fma_f32 v[18:19], v[14:15], v[18:19], s[76:77] op_sel_hi:[1,1,0]
	s_nop 0
	v_pk_mul_f32 v[14:15], v[14:15], v[18:19]
	s_nop 0
	v_pk_mul_f32 v[14:15], v[16:17], v[14:15]
	s_nop 0
	v_pk_mul_f32 v[16:17], v[14:15], v[4:5]
	v_pk_fma_f32 v[4:5], v[14:15], v[4:5], v[4:5] neg_lo:[1,0,0] neg_hi:[1,0,0]
	s_nop 0
	v_cndmask_b32_e64 v5, v5, v17, s[6:7]
	v_cndmask_b32_e32 v4, v4, v16, vcc
	v_lshlrev_b32_e32 v17, 16, v57
	v_lshlrev_b32_e32 v16, 16, v56
	v_fma_f32 v18, |v17|, s77, 1.0
	v_pk_mul_f32 v[22:23], v[16:17], v[16:17]
	v_rcp_f32_e32 v19, v18
	v_mul_f32_e32 v18, 0xbf38aa3b, v23
	v_exp_f32_e32 v23, v18
	v_fma_f32 v18, |v25|, s77, 1.0
	v_rcp_f32_e32 v27, v18
	v_mul_f32_e32 v18, 0xbf38aa3b, v49
	v_exp_f32_e32 v49, v18
	v_fma_f32 v18, |v53|, s77, 1.0
	v_pk_mul_f32 v[56:57], v[52:53], v[52:53]
	v_rcp_f32_e32 v55, v18
	v_mul_f32_e32 v18, 0xbf38aa3b, v57
	v_exp_f32_e32 v57, v18
	v_fma_f32 v18, |v51|, s77, 1.0
	v_rcp_f32_e32 v59, v18
	v_mul_f32_e32 v18, 0xbf38aa3b, v61
	v_exp_f32_e32 v61, v18
	v_fma_f32 v18, |v16|, s77, 1.0
	v_rcp_f32_e32 v18, v18
	v_mul_f32_e32 v20, 0xbf38aa3b, v22
	v_exp_f32_e32 v22, v20
	v_cmp_gt_f32_e32 vcc, 0, v16
	v_pk_fma_f32 v[62:63], v[18:19], s[92:93], v[2:3] op_sel_hi:[1,0,0]
	v_cmp_gt_f32_e64 s[6:7], 0, v17
	v_pk_fma_f32 v[62:63], v[18:19], v[62:63], s[74:75] op_sel_hi:[1,1,0]
	v_mul_f32_e32 v20, 0xbf38aa3b, v48
	v_pk_fma_f32 v[62:63], v[18:19], v[62:63], s[58:59] op_sel_hi:[1,1,0]
	v_exp_f32_e32 v48, v20
	v_pk_fma_f32 v[62:63], v[18:19], v[62:63], s[76:77] op_sel_hi:[1,1,0]
	v_fma_f32 v20, |v52|, s77, 1.0
	v_pk_mul_f32 v[18:19], v[18:19], v[62:63]
	v_rcp_f32_e32 v54, v20
	v_pk_mul_f32 v[18:19], v[22:23], v[18:19]
	v_mul_f32_e32 v20, 0xbf38aa3b, v56
	v_pk_mul_f32 v[22:23], v[18:19], v[16:17]
	v_pk_fma_f32 v[16:17], v[18:19], v[16:17], v[16:17] neg_lo:[1,0,0] neg_hi:[1,0,0]
	v_fma_f32 v18, |v24|, s77, 1.0
	v_rcp_f32_e32 v26, v18
	v_cndmask_b32_e64 v17, v17, v23, s[6:7]
	v_cndmask_b32_e32 v16, v16, v22, vcc
	v_cmp_gt_f32_e32 vcc, 0, v24
	v_pk_fma_f32 v[18:19], v[26:27], s[92:93], v[2:3] op_sel_hi:[1,0,0]
	v_cmp_gt_f32_e64 s[6:7], 0, v25
	v_pk_fma_f32 v[18:19], v[26:27], v[18:19], s[74:75] op_sel_hi:[1,1,0]
	v_exp_f32_e32 v56, v20
	v_pk_fma_f32 v[18:19], v[26:27], v[18:19], s[58:59] op_sel_hi:[1,1,0]
	v_fma_f32 v20, |v50|, s77, 1.0
	v_pk_fma_f32 v[18:19], v[26:27], v[18:19], s[76:77] op_sel_hi:[1,1,0]
	v_rcp_f32_e32 v58, v20
	v_pk_mul_f32 v[18:19], v[26:27], v[18:19]
	v_mul_f32_e32 v20, 0xbf38aa3b, v60
	v_pk_mul_f32 v[18:19], v[48:49], v[18:19]
	v_exp_f32_e32 v60, v20
	v_pk_mul_f32 v[22:23], v[18:19], v[24:25]
	v_pk_fma_f32 v[18:19], v[18:19], v[24:25], v[24:25] neg_lo:[1,0,0] neg_hi:[1,0,0]
; DI float bf1(bf16_t v) { return __uint_as_float(((unsigned)v) << 16); }
; DI bf16_t f2bf(float f) { return (bf16_t)(cvtpk(f, 0.f) & 0xffffu); }
; DI void sgu_item(const Args& a, int l, int item, unsigned char* lds, int tid) {
;     ...
;         for (int rr = 0; rr < 4; ++rr) { const int s = wave + 8 * (4 * s4 + rr); float v[8]; float q = 0.f;
; #pragma unroll
;             for (int e = 0; e < 8; ++e) { v[e] = gelu_erf(bf1(raw[rr][e])); q += v[e] * v[e]; }
;             q = wave_sum(q); const float rs = rsqrtf(q * (1.0f / 512.0f) + 1e-6f);
; #pragma unroll
;             for (int e = 0; e < 8; ++e) vT[(size_t)(e * 64 + lane) * VP + s] = f2bf(v[e] * rs * ngv[e]); }
	v_pk_fma_f32 v[24:25], v[54:55], s[92:93], v[2:3] op_sel_hi:[1,0,0]
	v_cndmask_b32_e64 v19, v19, v23, s[6:7]
	v_pk_fma_f32 v[24:25], v[54:55], v[24:25], s[74:75] op_sel_hi:[1,1,0]
	v_cndmask_b32_e32 v18, v18, v22, vcc
	v_pk_fma_f32 v[24:25], v[54:55], v[24:25], s[58:59] op_sel_hi:[1,1,0]
	v_cmp_gt_f32_e32 vcc, 0, v52
	v_pk_fma_f32 v[24:25], v[54:55], v[24:25], s[76:77] op_sel_hi:[1,1,0]
	v_cmp_gt_f32_e64 s[6:7], 0, v53
	v_pk_mul_f32 v[24:25], v[54:55], v[24:25]
	v_pk_mul_f32 v[22:23], v[18:19], v[18:19]
	v_pk_mul_f32 v[24:25], v[56:57], v[24:25]
	v_pk_fma_f32 v[22:23], v[16:17], v[16:17], v[22:23]
	v_pk_mul_f32 v[26:27], v[24:25], v[52:53]
	v_pk_fma_f32 v[24:25], v[24:25], v[52:53], v[52:53] neg_lo:[1,0,0] neg_hi:[1,0,0]
	v_pk_mul_f32 v[14:15], v[4:5], v[4:5]
	v_cndmask_b32_e64 v25, v25, v27, s[6:7]
	v_cndmask_b32_e32 v24, v24, v26, vcc
	v_pk_fma_f32 v[26:27], v[58:59], s[92:93], v[2:3] op_sel_hi:[1,0,0]
	v_cmp_gt_f32_e32 vcc, 0, v50
	v_pk_fma_f32 v[26:27], v[58:59], v[26:27], s[74:75] op_sel_hi:[1,1,0]
	v_cmp_gt_f32_e64 s[6:7], 0, v51
	v_pk_fma_f32 v[26:27], v[58:59], v[26:27], s[58:59] op_sel_hi:[1,1,0]
	v_pk_fma_f32 v[22:23], v[24:25], v[24:25], v[22:23]
	v_pk_fma_f32 v[26:27], v[58:59], v[26:27], s[76:77] op_sel_hi:[1,1,0]
	s_nop 0
	v_pk_mul_f32 v[26:27], v[58:59], v[26:27]
	s_nop 0
	v_pk_mul_f32 v[26:27], v[60:61], v[26:27]
	s_nop 0
	v_pk_mul_f32 v[48:49], v[26:27], v[50:51]
	v_pk_fma_f32 v[26:27], v[26:27], v[50:51], v[50:51] neg_lo:[1,0,0] neg_hi:[1,0,0]
	s_nop 0
	v_cndmask_b32_e64 v27, v27, v49, s[6:7]
	v_cndmask_b32_e32 v26, v26, v48, vcc
	v_pk_fma_f32 v[22:23], v[26:27], v[26:27], v[22:23]
	v_mov_b32_e32 v48, v14
	v_mov_b32_e32 v49, v10
	v_pk_add_f32 v[22:23], v[22:23], v[48:49]
	v_fma_f32 v10, |v30|, s77, 1.0
	v_pk_mul_f32 v[48:49], v[30:31], v[30:31]
	v_rcp_f32_e32 v20, v10
	v_mul_f32_e32 v10, 0xbf38aa3b, v48
	v_exp_f32_e32 v48, v10
	v_fma_f32 v10, |v31|, s77, 1.0
	v_rcp_f32_e32 v21, v10
	v_mul_f32_e32 v10, 0xbf38aa3b, v49
	v_exp_f32_e32 v49, v10
	v_cmp_gt_f32_e32 vcc, 0, v30
	v_pk_fma_f32 v[2:3], v[20:21], s[92:93], v[2:3] op_sel_hi:[1,0,0]
	v_cmp_gt_f32_e64 s[6:7], 0, v31
	v_pk_fma_f32 v[2:3], v[20:21], v[2:3], s[74:75] op_sel_hi:[1,1,0]
	v_mov_b32_e32 v10, v15
	v_pk_fma_f32 v[2:3], v[20:21], v[2:3], s[58:59] op_sel_hi:[1,1,0]
	v_pk_add_f32 v[10:11], v[22:23], v[10:11]
	v_pk_fma_f32 v[2:3], v[20:21], v[2:3], s[76:77] op_sel_hi:[1,1,0]
	v_mov_b32_e32 v15, v12
	v_pk_mul_f32 v[2:3], v[20:21], v[2:3]
	s_nop 0
	v_pk_mul_f32 v[2:3], v[48:49], v[2:3]
	s_nop 0
	v_pk_mul_f32 v[20:21], v[2:3], v[30:31]
	v_pk_fma_f32 v[2:3], v[2:3], v[30:31], v[30:31] neg_lo:[1,0,0] neg_hi:[1,0,0]
	s_nop 0
	v_cndmask_b32_e64 v3, v3, v21, s[6:7]
	v_cndmask_b32_e32 v2, v2, v20, vcc
	v_pk_mul_f32 v[20:21], v[2:3], v[2:3]
	s_nop 0
	v_mov_b32_e32 v14, v20
	v_pk_add_f32 v[10:11], v[10:11], v[14:15]
	v_mov_b32_e32 v12, v21
	v_pk_add_f32 v[10:11], v[10:11], v[12:13]
	ds_bpermute_b32 v13, v39, v11
	ds_bpermute_b32 v12, v39, v10
	s_waitcnt lgkmcnt(0)
	v_pk_add_f32 v[10:11], v[10:11], v[12:13]
	ds_bpermute_b32 v13, v40, v11
	ds_bpermute_b32 v12, v40, v10
	s_waitcnt lgkmcnt(0)
	v_pk_add_f32 v[10:11], v[10:11], v[12:13]
	ds_bpermute_b32 v13, v41, v11
	ds_bpermute_b32 v12, v41, v10
	s_waitcnt lgkmcnt(0)
	v_pk_add_f32 v[10:11], v[10:11], v[12:13]
	ds_bpermute_b32 v13, v42, v11
	ds_bpermute_b32 v12, v42, v10
	s_waitcnt lgkmcnt(0)
	v_pk_add_f32 v[10:11], v[10:11], v[12:13]
	ds_bpermute_b32 v13, v43, v11
	ds_bpermute_b32 v12, v43, v10
	s_waitcnt lgkmcnt(0)
	v_pk_add_f32 v[10:11], v[10:11], v[12:13]
	ds_bpermute_b32 v13, v44, v11
	ds_bpermute_b32 v12, v44, v10
	s_waitcnt lgkmcnt(0)
	v_pk_add_f32 v[10:11], v[10:11], v[12:13]
	s_nop 0
	v_pk_fma_f32 v[10:11], v[10:11], s[60:61], v[28:29] op_sel_hi:[1,0,0]
	s_nop 0
	v_mul_f32_e32 v12, 0x4b800000, v11
	v_cmp_gt_f32_e64 s[6:7], s71, v11
	v_cmp_gt_f32_e32 vcc, s71, v10
	s_nop 0
	v_cndmask_b32_e64 v11, v11, v12, s[6:7]
	v_rsq_f32_e32 v11, v11
	s_nop 0
	v_mul_f32_e32 v12, 0x45800000, v11
	v_cndmask_b32_e64 v11, v11, v12, s[6:7]
	v_mul_f32_e32 v6, v6, v11
	v_mul_f32_e32 v6, v35, v6
	v_cvt_pk_bf16_f32 v6, v6, s0
	ds_write_b16 v47, v6
	v_mul_f32_e32 v6, v7, v11
	v_mul_f32_e32 v6, v36, v6
	v_cvt_pk_bf16_f32 v6, v6, s0
	ds_write_b16 v64, v6
	v_mul_f32_e32 v6, v8, v11
	v_mul_f32_e32 v6, v37, v6
	v_cvt_pk_bf16_f32 v6, v6, s0
	ds_write_b16 v65, v6
	v_mul_f32_e32 v6, v9, v11
	v_mul_f32_e32 v6, v38, v6
	v_cvt_pk_bf16_f32 v6, v6, s0
	ds_write_b16 v66, v6
	v_mul_f32_e32 v6, 0x4b800000, v10
	v_cndmask_b32_e32 v6, v10, v6, vcc
	v_rsq_f32_e32 v6, v6
	v_mul_f32_e32 v12, v17, v11
	v_mul_f32_e32 v12, v1, v12
	v_cvt_pk_bf16_f32 v12, v12, s0
	v_mul_f32_e32 v7, 0x45800000, v6
	v_cndmask_b32_e32 v6, v6, v7, vcc
	v_mul_f32_e32 v7, v16, v6
	v_mul_f32_e32 v7, v1, v7
	v_cvt_pk_bf16_f32 v7, v7, s0
	ds_write_b16 v46, v7 offset:48
	v_mul_f32_e32 v7, v18, v6
	v_mul_f32_e32 v7, v32, v7
	v_cvt_pk_bf16_f32 v7, v7, s0
	ds_write_b16 v46, v7 offset:17456
	v_mul_f32_e32 v7, v24, v6
	v_mul_f32_e32 v7, v33, v7
	v_cvt_pk_bf16_f32 v7, v7, s0
	ds_write_b16 v46, v7 offset:34864
	v_mul_f32_e32 v7, v26, v6
	v_mul_f32_e32 v7, v34, v7
	v_mul_f32_e32 v4, v4, v6
	ds_write_b16 v46, v12 offset:32
	v_mul_f32_e32 v12, v19, v11
	v_cvt_pk_bf16_f32 v7, v7, s0
	v_mul_f32_e32 v4, v35, v4
	v_mul_f32_e32 v12, v32, v12
	ds_write_b16 v46, v7 offset:52272
	v_cvt_pk_bf16_f32 v4, v4, s0
	v_add_u32_e32 v7, 0x11030, v46
	v_cvt_pk_bf16_f32 v12, v12, s0
	ds_write_b16 v7, v4
	v_mul_f32_e32 v4, v5, v6
	ds_write_b16 v46, v12 offset:17440
	v_mul_f32_e32 v12, v25, v11
	v_mul_f32_e32 v4, v36, v4
	v_mul_f32_e32 v2, v2, v6
	v_mul_f32_e32 v12, v33, v12
	v_cvt_pk_bf16_f32 v4, v4, s0
	v_add_u32_e32 v5, 0x15430, v46
	v_mul_f32_e32 v2, v37, v2
	v_cvt_pk_bf16_f32 v12, v12, s0
	ds_write_b16 v5, v4
	v_cvt_pk_bf16_f32 v2, v2, s0
	v_add_u32_e32 v4, 0x19830, v46
	ds_write_b16 v46, v12 offset:34848
	v_mul_f32_e32 v12, v27, v11
	ds_write_b16 v4, v2
	v_mul_f32_e32 v2, v3, v6
	v_mul_f32_e32 v12, v34, v12
	v_mul_f32_e32 v2, v38, v2
	v_cvt_pk_bf16_f32 v12, v12, s0
	v_cvt_pk_bf16_f32 v2, v2, s0
	v_add_u32_e32 v3, 0x1dc30, v46
	ds_write_b16 v46, v12 offset:52256
	ds_write_b16 v3, v2
	s_cbranch_scc0 .LBB0_450
; DI void sgu_item(const Args& a, int l, int item, unsigned char* lds, int tid) {
;     ...
;     __syncthreads();
;     const int g = wave >> 1, hw = wave & 1, rl = lane & 31, h = lane >> 5;
;     for (int q2 = 0; q2 < 2; ++q2) { const int tt = (q2 == 0) ? (hw ? 1 : 0) : (hw ? 2 : 3); const int t = 32 * tt + rl;
;         f32x16 acc[4];
; #pragma unroll
;         for (int ct = 0; ct < 4; ++ct)
; #pragma unroll
;             for (int i = 0; i < 16; ++i) acc[ct][i] = 0.f;
;         const float* wrow = sw + ((size_t)g * 128 + t) * 128;
;         f32x4 wq[8][2];
; #pragma unroll
;         for (int ks = 0; ks < 8; ++ks) { const int s0 = 16 * ks + 8 * h; if (ks < 2 * (tt + 1)) { wq[ks][0] = *(const f32x4*)(wrow + s0); wq[ks][1] = *(const f32x4*)(wrow + s0 + 4); } else { wq[ks][0] = (f32x4){0.f, 0.f, 0.f, 0.f}; wq[ks][1] = (f32x4){0.f, 0.f, 0.f, 0.f}; } }
; #pragma unroll
;         for (int ks = 0; ks < 8; ++ks) { if (ks < 2 * (tt + 1)) { const int s0 = 16 * ks + 8 * h; f32x4 w0 = wq[ks][0], w1 = wq[ks][1];
	s_ashr_i32 s6, s0, 7
	s_bfe_u32 s51, s0, 0x10006
	s_ashr_i32 s7, s6, 31
	s_lshl_b32 s50, s25, 7
	s_xor_b32 s52, s51, 3
	s_lshl_b64 s[6:7], s[6:7], 16
	s_add_u32 s6, s33, s6
	v_and_b32_e32 v165, 31, v146
	s_addc_u32 s7, s16, s7
	s_and_b32 s34, s0, 0xffffff80
	v_lshrrev_b32_e32 v1, 5, v0
	v_or_b32_e32 v2, s34, v165
	s_movk_i32 s0, 0x110
	v_lshlrev_b32_e32 v167, 3, v1
	v_lshlrev_b32_e32 v188, 2, v1
	v_lshl_add_u32 v1, v1, 4, 0
	v_mul_lo_u32 v3, v2, s0
	v_add_u32_e32 v189, v1, v3
	s_waitcnt lgkmcnt(0)
	s_barrier
	ds_read_b128 v[64:67], v189
	ds_read_b128 v[68:71], v189 offset:32
	ds_read_b128 v[72:75], v189 offset:8704
	ds_read_b128 v[76:79], v189 offset:8736
	ds_read_b128 v[80:83], v189 offset:17408
	ds_read_b128 v[84:87], v189 offset:17440
	ds_read_b128 v[88:91], v189 offset:26112
	ds_read_b128 v[92:95], v189 offset:26144
	v_or_b32_e32 v4, 32, v2
	v_or_b32_e32 v6, 64, v2
	v_or_b32_e32 v8, 0x60, v2
	v_mul_lo_u32 v10, v4, s0
	v_ashrrev_i32_e32 v3, 31, v2
	v_and_b32_e32 v160, 32, v0
	v_ashrrev_i32_e32 v5, 31, v4
	v_ashrrev_i32_e32 v7, 31, v6
	v_ashrrev_i32_e32 v9, 31, v8
	v_or_b32_e32 v190, 51, v167
	v_or_b32_e32 v191, 55, v167
	v_or_b32_e32 v192, 64, v167
	v_or_b32_e32 v193, 0x44, v167
	v_or_b32_e32 v194, 0x41, v167
	v_or_b32_e32 v195, 0x45, v167
	v_or_b32_e32 v196, 0x42, v167
	v_or_b32_e32 v197, 0x46, v167
	v_or_b32_e32 v198, 0x43, v167
	v_or_b32_e32 v199, 0x47, v167
	v_or_b32_e32 v200, 0x50, v167
	v_or_b32_e32 v201, 0x54, v167
	v_or_b32_e32 v202, 0x51, v167
	v_or_b32_e32 v203, 0x55, v167
	v_or_b32_e32 v204, 0x52, v167
	v_or_b32_e32 v205, 0x56, v167
	v_or_b32_e32 v206, 0x53, v167
	v_or_b32_e32 v207, 0x57, v167
	v_or_b32_e32 v208, 0x60, v167
	v_or_b32_e32 v209, 0x64, v167
	v_or_b32_e32 v210, 0x61, v167
	v_or_b32_e32 v211, 0x65, v167
	v_or_b32_e32 v212, 0x62, v167
	v_or_b32_e32 v213, 0x66, v167
	v_or_b32_e32 v226, 0x63, v167
	v_or_b32_e32 v227, 0x67, v167
	v_or_b32_e32 v228, 0x70, v167
	v_or_b32_e32 v229, 0x74, v167
	v_or_b32_e32 v230, 0x71, v167
	v_or_b32_e32 v231, 0x75, v167
	v_or_b32_e32 v232, 0x72, v167
	v_or_b32_e32 v233, 0x76, v167
	v_or_b32_e32 v234, 0x73, v167
	v_or_b32_e32 v235, 0x77, v167
	v_lshl_add_u64 v[152:153], v[2:3], 1, s[30:31]
	v_lshl_add_u64 v[154:155], s[6:7], 0, v[160:161]
	s_ashr_i32 s35, s34, 31
	s_or_b32 s53, s50, 1
	s_or_b32 s54, s50, 2
	s_or_b32 s55, s50, 3
	s_or_b32 s56, s50, 8
	s_or_b32 s57, s50, 9
	s_or_b32 s58, s50, 10
	s_or_b32 s59, s50, 11
	s_or_b32 s60, s50, 16
	s_or_b32 s61, s50, 17
	s_or_b32 s62, s50, 18
	s_or_b32 s63, s50, 19
	s_or_b32 s64, s50, 24
	s_or_b32 s65, s50, 25
	s_or_b32 s66, s50, 26
	s_or_b32 s67, s50, 27
	s_mov_b64 s[36:37], -1
	v_add_u32_e32 v236, v1, v10
	v_lshlrev_b64 v[156:157], 1, v[2:3]
	v_lshlrev_b64 v[158:159], 1, v[4:5]
	v_lshlrev_b64 v[168:169], 1, v[6:7]
	v_lshlrev_b64 v[170:171], 1, v[8:9]
	s_branch .LBB0_453
	.p2align	6

; DI unsigned cvtpk(float lo, float hi) { return pg8::cvt_pk_bf16(lo, hi); }
; DI void sgu_item(const Args& a, int l, int item, unsigned char* lds, int tid) {
;     ...
;         for (int ks = 0; ks < 8; ++ks) { if (ks < 2 * (tt + 1)) { const int s0 = 16 * ks + 8 * h; f32x4 w0 = wq[ks][0], w1 = wq[ks][1];
; #pragma unroll
;             for (int e = 0; e < 4; ++e) { if (s0 + e > t) w0[e] = 0.f; if (s0 + 4 + e > t) w1[e] = 0.f; }
;             u32x4 wp; wp.x = cvtpk(w0[0], w0[1]); wp.y = cvtpk(w0[2], w0[3]); wp.z = cvtpk(w1[0], w1[1]); wp.w = cvtpk(w1[2], w1[3]); const bf16x8 af = __builtin_bit_cast(bf16x8, wp);
; #pragma unroll
;             for (int ct = 0; ct < 4; ++ct) { const bf16x8 bfr = *(const bf16x8*)(vT + (size_t)(g * 128 + ct * 32 + rl) * VP + s0); acc[ct] = __builtin_amdgcn_mfma_f32_32x32x16_bf16(af, bfr, acc[ct], 0, 0, 0); } } }
.LBB0_469:
	s_and_b64 vcc, exec, s[8:9]
	s_cbranch_vccnz .LBB0_473
	v_cmp_le_u32_e32 vcc, v192, v172
	s_nop 1
	v_cndmask_b32_e32 v116, 0, v128, vcc
	v_cmp_le_u32_e32 vcc, v193, v172
	s_nop 1
	v_cndmask_b32_e32 v118, 0, v124, vcc
	v_cmp_le_u32_e32 vcc, v194, v172
	s_nop 1
	v_cndmask_b32_e32 v117, 0, v129, vcc
	v_cmp_le_u32_e32 vcc, v195, v172
	v_cvt_pk_bf16_f32 v116, v116, v117
	s_nop 0
	v_cndmask_b32_e32 v119, 0, v125, vcc
	v_cmp_le_u32_e32 vcc, v196, v172
	v_cvt_pk_bf16_f32 v118, v118, v119
	s_nop 0
	v_cndmask_b32_e32 v124, 0, v130, vcc
	v_cmp_le_u32_e32 vcc, v197, v172
	s_nop 1
	v_cndmask_b32_e32 v125, 0, v126, vcc
	v_cmp_le_u32_e32 vcc, v198, v172
	s_nop 1
	v_cndmask_b32_e32 v126, 0, v131, vcc
	v_cmp_le_u32_e32 vcc, v199, v172
	v_cvt_pk_bf16_f32 v117, v124, v126
	s_nop 0
	v_cndmask_b32_e32 v127, 0, v127, vcc
	v_cvt_pk_bf16_f32 v119, v125, v127
	ds_read_b128 v[124:127], v189 offset:128
	s_waitcnt lgkmcnt(0)
	v_mfma_f32_32x32x16_bf16 v[48:63], v[116:119], v[124:127], v[48:63]
	ds_read_b128 v[124:127], v189 offset:8832
	s_waitcnt lgkmcnt(0)
	v_mfma_f32_32x32x16_bf16 v[32:47], v[116:119], v[124:127], v[32:47]
	ds_read_b128 v[124:127], v189 offset:17536
	s_waitcnt lgkmcnt(0)
	v_mfma_f32_32x32x16_bf16 v[16:31], v[116:119], v[124:127], v[16:31]
	ds_read_b128 v[124:127], v189 offset:26240
	s_waitcnt lgkmcnt(0)
	v_mfma_f32_32x32x16_bf16 v[0:15], v[116:119], v[124:127], v[0:15]
	s_and_b64 vcc, exec, s[8:9]
	s_cbranch_vccz .LBB0_474
	.p2align	6
.LBB0_471:
	s_and_b64 vcc, exec, s[6:7]
	s_cbranch_vccnz .LBB0_475
	.p2align	6

; #define PG8_STAGE(bufoff, gbase, voff) do { _Pragma("unroll") for (int _i = 0; _i < 2; ++_i) \
;         __builtin_amdgcn_global_load_lds((const unsigned*)((const char*)(gbase) + (voff)[_i]), (PG8_LAS unsigned*)(lds + (bufoff) + ldsw + _i * 8192), 16, 0, 0); } while (0)
; #define PG8_WAIT_V(n) asm volatile("s_waitcnt vmcnt(" #n ")" ::: "memory")
; #define PG8_BAR __builtin_amdgcn_s_barrier()
;     __host__ __device__ bool next(int i, Unit& u) const {
;         const int nr = nwg / G; const long L = (long)((rev && nwg % G == 0) ? (i < nr ? nr - 1 - i : i) : i) * G + c; if (L >= nwg) return false;
;         int wgid = (int)L; { const int q = nwg / NXCD, r = nwg % NXCD, xcd = wgid % NXCD, off = wgid / NXCD; wgid = (xcd < r ? xcd * (q + 1) : r * (q + 1) + (xcd - r) * q) + off; }
;         const int nig = WGM * nN, gid = wgid / nig, fm = gid * WGM, gsz = (nM - fm) < WGM ? (nM - fm) : WGM;
;         u.pm = fm + ((wgid % nig) % gsz); u.pn = (wgid % nig) / gsz; return true;
;     }
; template <class Epi, class Sched, bool ALIGN_EPI = false, bool SP2 = false>
; __device__ __forceinline__ void gemm_phase(PG8_LAS unsigned char* lds, const Gemm g, const Sched& S, const Epi& E) {
;     ...
;         PG8_STAGE(PG8_SB(0, 0), cB, voffB); PG8_STAGE(PG8_SB(0, 1), cB + hstepB, voffB); PG8_STAGE(PG8_SA(0, 0), cA, voffA); PG8_STAGE(PG8_SA(0, 1), cA + hstepA, voffA);
;         if (wr == 1) PG8_BAR;
;         PG8_WAIT_V(2); PG8_BAR;
;         PG8_STAGE(PG8_SB(1, 0), cB + kstep, voffB); PG8_STAGE(PG8_SA(1, 0), cA + kstep, voffA); PG8_STAGE(PG8_SB(1, 1), cB + hstepB + kstep, voffB);
;         PG8_WAIT_V(6); PG8_BAR;
.LBB0_502:
	s_add_i32 m0, s79, 0x18000
	v_lshl_add_u64 v[0:1], v[0:1], 0, s[4:5]
	s_waitcnt vmcnt(2)
	s_barrier
	global_load_lds_dwordx4 v[0:1], off
	v_lshl_add_u64 v[0:1], v[2:3], 0, s[4:5]
	s_add_i32 m0, s79, 0x1a000
	s_add_i32 s91, s79, 0x8000
	global_load_lds_dwordx4 v[0:1], off
	v_lshl_add_u64 v[0:1], v[8:9], 0, s[4:5]
	s_mov_b32 m0, s91
	s_add_i32 s94, s79, 0xa000
	global_load_lds_dwordx4 v[0:1], off
	v_lshl_add_u64 v[0:1], v[10:11], 0, s[4:5]
	s_mov_b32 m0, s94
	s_and_b32 s53, s0, 3
	global_load_lds_dwordx4 v[0:1], off
	s_add_i32 m0, s79, 0x1c000
	v_lshl_add_u64 v[0:1], v[4:5], 0, s[4:5]
	global_load_lds_dwordx4 v[0:1], off
	v_lshl_add_u64 v[0:1], v[6:7], 0, s[4:5]
	s_add_i32 m0, s79, 0x1e000
	s_lshr_b32 s86, s11, 6
	global_load_lds_dwordx4 v[0:1], off
	s_lshl_b32 s87, s1, 6
	s_lshl_b32 s0, s1, 13
	s_lshl_b32 s90, s53, 5
	s_lshl_b32 s6, s53, 12
	s_add_i32 s95, s86, -2
	s_cmpk_lt_u32 s12, 0x100
	s_cselect_b64 s[46:47], -1, 0
	s_lshl_b32 s7, s53, 4
	v_writelane_b32 v254, s7, 48
	s_lshl_b32 s7, s1, 11
	s_lshl_b32 s1, s1, 3
	s_lshl_b32 s11, s53, 1
	v_cndmask_b32_e64 v0, 0, 1, s[42:43]
	s_or_b32 s1, s11, s1
	v_readfirstlane_b32 s12, v0
	s_lshl_b32 s11, s1, 1
	s_or_b32 s1, s1, s12
	s_lshl_b32 s1, s1, 1
	s_xor_b32 s11, s11, 16
	s_xor_b32 s1, s1, 16
	s_lshl_b32 s9, s53, 9
	v_writelane_b32 v254, s11, 51
	s_lshl_b32 s11, s11, 7
	s_mov_b32 s93, s1
	s_lshl_b32 s1, s1, 7
	s_lshl_b32 s50, s10, 4
	s_lshl_b32 s56, s10, 3
	s_cmp_eq_u64 s[34:35], 0
	s_cselect_b64 s[12:13], -1, 0
	v_writelane_b32 v254, s12, 32
	s_cmp_lg_u64 s[34:35], 0
	v_bfe_u32 v165, v12, 4, 2
	v_writelane_b32 v254, s13, 33
	s_cselect_b64 s[12:13], -1, 0
	s_cmp_lg_u64 s[20:21], 0
	v_writelane_b32 v254, s12, 34
	s_cselect_b64 s[16:17], -1, 0
	s_add_i32 s9, s51, s9
	v_writelane_b32 v254, s13, 35
	s_add_i32 s7, s9, s7
	v_writelane_b32 v254, s7, 55
	s_add_i32 s7, s51, s11
	s_add_u32 s10, s30, 0x5800
	v_writelane_b32 v254, s7, 50
	s_addc_u32 s11, s31, 0
	v_writelane_b32 v254, s10, 56
	v_and_b32_e32 v167, 15, v12
	v_lshlrev_b32_e32 v19, 4, v165
	v_writelane_b32 v254, s11, 57
	s_add_u32 s10, s30, 0x2c00
	s_addc_u32 s11, s31, 0
	s_abs_i32 s7, s52
	v_cvt_f32_u32_e32 v0, s7
	v_lshlrev_b32_e32 v1, 2, v12
	v_lshl_or_b32 v19, v167, 6, v19
	v_writelane_b32 v254, s10, 53
	v_rcp_iflag_f32_e32 v0, v0
	v_and_b32_e32 v1, 32, v1
	v_writelane_b32 v254, s11, 54
	v_bitop3_b32 v2, v19, s0, v1 bitop3:0xde
	v_mul_f32_e32 v0, 0x4f7ffffe, v0
	v_cvt_u32_f32_e32 v0, v0
	s_add_i32 s0, s51, s1
	v_writelane_b32 v254, s0, 52
	s_sub_i32 s0, 0, s7
	v_readfirstlane_b32 s1, v0
	s_mul_i32 s0, s0, s1
	s_mul_hi_u32 s0, s1, s0
	s_add_i32 s1, s1, s0
	s_mul_i32 s0, s37, s1
	s_mul_hi_u32 s1, s36, s1
	s_add_i32 s0, s1, s0
	s_mul_i32 s1, s0, s7
	v_cvt_f32_u32_e32 v0, s56
	s_sub_i32 s1, s80, s1
	v_bitop3_b32 v226, v19, s6, v1 bitop3:0xde
	s_add_i32 s6, s0, 1
	s_sub_i32 s9, s1, s7
	s_cmp_ge_u32 s1, s7
	s_cselect_b32 s0, s6, s0
	v_rcp_iflag_f32_e32 v0, v0
	s_cselect_b32 s1, s9, s1
	s_add_i32 s6, s0, 1
	s_cmp_ge_u32 s1, s7
	s_cselect_b32 s0, s6, s0
	s_xor_b32 s0, s0, s8
	v_mul_f32_e32 v0, 0x4f7ffffe, v0
	s_sub_i32 s57, s0, s8
	v_cvt_u32_f32_e32 v0, v0
	s_mul_i32 s0, s57, s52
	s_sub_i32 s0, s80, s0
	s_cmp_eq_u32 s0, 0
	s_cselect_b64 s[60:61], -1, 0
	s_sub_i32 s0, 0, s56
	v_readfirstlane_b32 s1, v0
	v_add_u32_e32 v0, v15, v13
	s_waitcnt vmcnt(6)
	s_mul_i32 s0, s0, s1
	v_add_lshl_u32 v160, v0, v14, 1
	v_add_u32_e32 v0, v18, v16
	s_mul_hi_u32 s0, s1, s0
	v_lshl_add_u64 v[176:177], s[38:39], 0, v[160:161]
	v_add_lshl_u32 v160, v0, v17, 1
	s_mov_b32 s58, 0
	s_add_i32 s59, s1, s0
	s_add_i32 s97, s73, 0xffffff80
	v_lshl_add_u64 v[178:179], s[38:39], 0, v[160:161]
	v_add_u32_e32 v227, 0, v2
	v_readlane_b32 s75, v253, 17
	s_barrier
	s_branch .LBB0_505
	.p2align	6
.LBB0_503:
	s_mov_b64 s[0:1], 0
	.p2align	6

; __device__ __forceinline__ float bf_lo(unsigned w) { return __uint_as_float(w << 16); }
; __device__ __forceinline__ float bf_hi(unsigned w) { return __uint_as_float(w & 0xffff0000u); }
;     __device__ __forceinline__ void operator()(f32x4 (&acc)[2][2][4][2], const Unit& u, int wr, int wc, int fr, int fq) const {
;     ...
;                 for (int bj = 0; bj < 2; ++bj) { const u32x4 h4 = hh[m][bj], l4 = ll[m][bj]; f32x4 v0, v1;
;                     v0[0] = acc[ai][bj][m][0][0] + (bf_lo(h4.x) + bf_lo(l4.x)); v0[1] = acc[ai][bj][m][0][1] + (bf_hi(h4.x) + bf_hi(l4.x)); v0[2] = acc[ai][bj][m][0][2] + (bf_lo(h4.y) + bf_lo(l4.y)); v0[3] = acc[ai][bj][m][0][3] + (bf_hi(h4.y) + bf_hi(l4.y));
;                     v1[0] = acc[ai][bj][m][1][0] + (bf_lo(h4.z) + bf_lo(l4.z)); v1[1] = acc[ai][bj][m][1][1] + (bf_hi(h4.z) + bf_hi(l4.z)); v1[2] = acc[ai][bj][m][1][2] + (bf_lo(h4.w) + bf_lo(l4.w)); v1[3] = acc[ai][bj][m][1][3] + (bf_hi(h4.w) + bf_hi(l4.w));
;                     if (fout) { *(f32x4*)(fout + off + bj * HALF) = v0; *(f32x4*)(fout + off + bj * HALF + 4) = v1; }
.LBB0_553:
	v_lshlrev_b32_e32 v141, 16, v129
	v_lshlrev_b32_e32 v140, 16, v128
	v_lshlrev_b32_e32 v143, 16, v133
	v_lshlrev_b32_e32 v142, 16, v132
	v_and_b32_e32 v129, 0xffff0000, v129
	v_and_b32_e32 v128, 0xffff0000, v128
	v_and_b32_e32 v133, 0xffff0000, v133
	v_and_b32_e32 v132, 0xffff0000, v132
	v_pk_add_f32 v[140:141], v[140:141], v[142:143]
	v_pk_add_f32 v[132:133], v[128:129], v[132:133]
	v_mov_b32_e32 v128, v100
	v_mov_b32_e32 v129, v102
	v_pk_add_f32 v[128:129], v[128:129], v[140:141]
	v_mov_b32_e32 v140, v101
	v_mov_b32_e32 v141, v103
	v_pk_add_f32 v[132:133], v[140:141], v[132:133]
	v_lshlrev_b32_e32 v141, 16, v131
	v_lshlrev_b32_e32 v140, 16, v130
	v_lshlrev_b32_e32 v143, 16, v135
	v_lshlrev_b32_e32 v142, 16, v134
	v_and_b32_e32 v131, 0xffff0000, v131
	v_and_b32_e32 v130, 0xffff0000, v130
	v_and_b32_e32 v135, 0xffff0000, v135
	v_and_b32_e32 v134, 0xffff0000, v134
	v_pk_add_f32 v[140:141], v[140:141], v[142:143]
	v_pk_add_f32 v[134:135], v[130:131], v[134:135]
	v_mov_b32_e32 v130, v96
	v_mov_b32_e32 v131, v98
	v_pk_add_f32 v[130:131], v[130:131], v[140:141]
	v_mov_b32_e32 v140, v97
	v_mov_b32_e32 v141, v99
	v_pk_add_f32 v[134:135], v[140:141], v[134:135]
	s_and_b64 vcc, exec, s[8:9]
	s_mov_b64 s[0:1], -1
	s_cbranch_vccnz .LBB0_556
	v_mov_b32_e32 v140, v128
	v_mov_b32_e32 v141, v132
	v_mov_b32_e32 v142, v129
	v_mov_b32_e32 v143, v133
	global_store_dwordx4 v[138:139], v[140:143], off offset:512
	s_nop 1
	v_mov_b32_e32 v140, v130
	v_mov_b32_e32 v141, v134
	v_mov_b32_e32 v142, v131
	v_mov_b32_e32 v143, v135
	global_store_dwordx4 v[138:139], v[140:143], off offset:528
	s_cbranch_execz .LBB0_557
	.p2align	6

; __device__ __forceinline__ float bf_lo(unsigned w) { return __uint_as_float(w << 16); }
; __device__ __forceinline__ float bf_hi(unsigned w) { return __uint_as_float(w & 0xffff0000u); }
;     __device__ __forceinline__ void operator()(f32x4 (&acc)[2][2][4][2], const Unit& u, int wr, int wc, int fr, int fq) const {
;     ...
;                 for (int bj = 0; bj < 2; ++bj) { const u32x4 h4 = hh[m][bj], l4 = ll[m][bj]; f32x4 v0, v1;
;                     v0[0] = acc[ai][bj][m][0][0] + (bf_lo(h4.x) + bf_lo(l4.x)); v0[1] = acc[ai][bj][m][0][1] + (bf_hi(h4.x) + bf_hi(l4.x)); v0[2] = acc[ai][bj][m][0][2] + (bf_lo(h4.y) + bf_lo(l4.y)); v0[3] = acc[ai][bj][m][0][3] + (bf_hi(h4.y) + bf_hi(l4.y));
;                     v1[0] = acc[ai][bj][m][1][0] + (bf_lo(h4.z) + bf_lo(l4.z)); v1[1] = acc[ai][bj][m][1][1] + (bf_hi(h4.z) + bf_hi(l4.z)); v1[2] = acc[ai][bj][m][1][2] + (bf_lo(h4.w) + bf_lo(l4.w)); v1[3] = acc[ai][bj][m][1][3] + (bf_hi(h4.w) + bf_hi(l4.w));
;                     if (fout) { *(f32x4*)(fout + off + bj * HALF) = v0; *(f32x4*)(fout + off + bj * HALF + 4) = v1; }
.LBB0_565:
	s_waitcnt vmcnt(5)
	v_lshlrev_b32_e32 v189, 16, v149
	v_lshlrev_b32_e32 v188, 16, v148
	s_waitcnt vmcnt(4)
	v_lshlrev_b32_e32 v191, 16, v145
	v_lshlrev_b32_e32 v190, 16, v144
	v_and_b32_e32 v149, 0xffff0000, v149
	v_and_b32_e32 v148, 0xffff0000, v148
	v_and_b32_e32 v145, 0xffff0000, v145
	v_and_b32_e32 v144, 0xffff0000, v144
	v_pk_add_f32 v[188:189], v[188:189], v[190:191]
	v_pk_add_f32 v[148:149], v[148:149], v[144:145]
	v_mov_b32_e32 v144, v84
	v_mov_b32_e32 v145, v86
	v_pk_add_f32 v[144:145], v[144:145], v[188:189]
	v_mov_b32_e32 v188, v85
	v_mov_b32_e32 v189, v87
	v_pk_add_f32 v[148:149], v[188:189], v[148:149]
	v_lshlrev_b32_e32 v189, 16, v151
	v_lshlrev_b32_e32 v188, 16, v150
	v_lshlrev_b32_e32 v191, 16, v147
	v_lshlrev_b32_e32 v190, 16, v146
	v_and_b32_e32 v151, 0xffff0000, v151
	v_and_b32_e32 v150, 0xffff0000, v150
	v_and_b32_e32 v147, 0xffff0000, v147
	v_and_b32_e32 v146, 0xffff0000, v146
	v_pk_add_f32 v[188:189], v[188:189], v[190:191]
	v_pk_add_f32 v[150:151], v[150:151], v[146:147]
	v_mov_b32_e32 v146, v80
	v_mov_b32_e32 v147, v82
	v_pk_add_f32 v[146:147], v[146:147], v[188:189]
	v_mov_b32_e32 v188, v81
	v_mov_b32_e32 v189, v83
	v_pk_add_f32 v[150:151], v[188:189], v[150:151]
	s_and_b64 vcc, exec, s[8:9]
	s_mov_b64 s[0:1], -1
	s_cbranch_vccnz .LBB0_568
	v_mov_b32_e32 v188, v144
	v_mov_b32_e32 v189, v148
	v_mov_b32_e32 v190, v145
	v_mov_b32_e32 v191, v149
	global_store_dwordx4 v[196:197], v[188:191], off offset:512
	s_nop 1
	v_mov_b32_e32 v188, v146
	v_mov_b32_e32 v189, v150
	v_mov_b32_e32 v190, v147
	v_mov_b32_e32 v191, v151
	global_store_dwordx4 v[196:197], v[188:191], off offset:528
	s_cbranch_execz .LBB0_569
	.p2align	6

; __device__ __forceinline__ float bf_lo(unsigned w) { return __uint_as_float(w << 16); }
; __device__ __forceinline__ float bf_hi(unsigned w) { return __uint_as_float(w & 0xffff0000u); }
;     __device__ __forceinline__ void operator()(f32x4 (&acc)[2][2][4][2], const Unit& u, int wr, int wc, int fr, int fq) const {
;     ...
;                 for (int bj = 0; bj < 2; ++bj) { const u32x4 h4 = hh[m][bj], l4 = ll[m][bj]; f32x4 v0, v1;
;                     v0[0] = acc[ai][bj][m][0][0] + (bf_lo(h4.x) + bf_lo(l4.x)); v0[1] = acc[ai][bj][m][0][1] + (bf_hi(h4.x) + bf_hi(l4.x)); v0[2] = acc[ai][bj][m][0][2] + (bf_lo(h4.y) + bf_lo(l4.y)); v0[3] = acc[ai][bj][m][0][3] + (bf_hi(h4.y) + bf_hi(l4.y));
;                     v1[0] = acc[ai][bj][m][1][0] + (bf_lo(h4.z) + bf_lo(l4.z)); v1[1] = acc[ai][bj][m][1][1] + (bf_hi(h4.z) + bf_hi(l4.z)); v1[2] = acc[ai][bj][m][1][2] + (bf_lo(h4.w) + bf_lo(l4.w)); v1[3] = acc[ai][bj][m][1][3] + (bf_hi(h4.w) + bf_hi(l4.w));
;                     if (fout) { *(f32x4*)(fout + off + bj * HALF) = v0; *(f32x4*)(fout + off + bj * HALF + 4) = v1; }
.LBB0_577:
	s_waitcnt vmcnt(1)
	v_lshlrev_b32_e32 v141, 16, v129
	v_lshlrev_b32_e32 v140, 16, v128
	s_waitcnt vmcnt(0)
	v_lshlrev_b32_e32 v143, 16, v133
	v_lshlrev_b32_e32 v142, 16, v132
	v_and_b32_e32 v129, 0xffff0000, v129
	v_and_b32_e32 v128, 0xffff0000, v128
	v_and_b32_e32 v133, 0xffff0000, v133
	v_and_b32_e32 v132, 0xffff0000, v132
	v_pk_add_f32 v[140:141], v[140:141], v[142:143]
	v_pk_add_f32 v[132:133], v[128:129], v[132:133]
	v_mov_b32_e32 v128, v68
	v_mov_b32_e32 v129, v70
	v_pk_add_f32 v[128:129], v[128:129], v[140:141]
	v_mov_b32_e32 v140, v69
	v_mov_b32_e32 v141, v71
	v_pk_add_f32 v[132:133], v[140:141], v[132:133]
	v_lshlrev_b32_e32 v141, 16, v131
	v_lshlrev_b32_e32 v140, 16, v130
	v_lshlrev_b32_e32 v143, 16, v135
	v_lshlrev_b32_e32 v142, 16, v134
	v_and_b32_e32 v131, 0xffff0000, v131
	v_and_b32_e32 v130, 0xffff0000, v130
	v_and_b32_e32 v135, 0xffff0000, v135
	v_and_b32_e32 v134, 0xffff0000, v134
	v_pk_add_f32 v[140:141], v[140:141], v[142:143]
	v_pk_add_f32 v[134:135], v[130:131], v[134:135]
	v_mov_b32_e32 v130, v64
	v_mov_b32_e32 v131, v66
	v_pk_add_f32 v[130:131], v[130:131], v[140:141]
	v_mov_b32_e32 v140, v65
	v_mov_b32_e32 v141, v67
	v_pk_add_f32 v[134:135], v[140:141], v[134:135]
	s_and_b64 vcc, exec, s[8:9]
	s_mov_b64 s[0:1], -1
	s_cbranch_vccnz .LBB0_580
	v_mov_b32_e32 v140, v128
	v_mov_b32_e32 v141, v132
	v_mov_b32_e32 v142, v129
	v_mov_b32_e32 v143, v133
	global_store_dwordx4 v[138:139], v[140:143], off offset:512
	s_nop 1
	v_mov_b32_e32 v140, v130
	v_mov_b32_e32 v141, v134
	v_mov_b32_e32 v142, v131
	v_mov_b32_e32 v143, v135
	global_store_dwordx4 v[138:139], v[140:143], off offset:528
	s_cbranch_execz .LBB0_581
	.p2align	6

; __device__ __forceinline__ float bf_lo(unsigned w) { return __uint_as_float(w << 16); }
; __device__ __forceinline__ float bf_hi(unsigned w) { return __uint_as_float(w & 0xffff0000u); }
;     __device__ __forceinline__ void operator()(f32x4 (&acc)[2][2][4][2], const Unit& u, int wr, int wc, int fr, int fq) const {
;     ...
;                 for (int bj = 0; bj < 2; ++bj) { const u32x4 h4 = hh[m][bj], l4 = ll[m][bj]; f32x4 v0, v1;
;                     v0[0] = acc[ai][bj][m][0][0] + (bf_lo(h4.x) + bf_lo(l4.x)); v0[1] = acc[ai][bj][m][0][1] + (bf_hi(h4.x) + bf_hi(l4.x)); v0[2] = acc[ai][bj][m][0][2] + (bf_lo(h4.y) + bf_lo(l4.y)); v0[3] = acc[ai][bj][m][0][3] + (bf_hi(h4.y) + bf_hi(l4.y));
;                     v1[0] = acc[ai][bj][m][1][0] + (bf_lo(h4.z) + bf_lo(l4.z)); v1[1] = acc[ai][bj][m][1][1] + (bf_hi(h4.z) + bf_hi(l4.z)); v1[2] = acc[ai][bj][m][1][2] + (bf_lo(h4.w) + bf_lo(l4.w)); v1[3] = acc[ai][bj][m][1][3] + (bf_hi(h4.w) + bf_hi(l4.w));
;                     if (fout) { *(f32x4*)(fout + off + bj * HALF) = v0; *(f32x4*)(fout + off + bj * HALF + 4) = v1; }
.LBB0_589:
	s_waitcnt vmcnt(5)
	v_lshlrev_b32_e32 v189, 16, v149
	v_lshlrev_b32_e32 v188, 16, v148
	s_waitcnt vmcnt(4)
	v_lshlrev_b32_e32 v191, 16, v145
	v_lshlrev_b32_e32 v190, 16, v144
	v_and_b32_e32 v149, 0xffff0000, v149
	v_and_b32_e32 v148, 0xffff0000, v148
	v_and_b32_e32 v145, 0xffff0000, v145
	v_and_b32_e32 v144, 0xffff0000, v144
	v_pk_add_f32 v[188:189], v[188:189], v[190:191]
	v_pk_add_f32 v[148:149], v[148:149], v[144:145]
	v_mov_b32_e32 v144, v52
	v_mov_b32_e32 v145, v54
	v_pk_add_f32 v[144:145], v[144:145], v[188:189]
	v_mov_b32_e32 v188, v53
	v_mov_b32_e32 v189, v55
	v_pk_add_f32 v[148:149], v[188:189], v[148:149]
	v_lshlrev_b32_e32 v189, 16, v151
	v_lshlrev_b32_e32 v188, 16, v150
	v_lshlrev_b32_e32 v191, 16, v147
	v_lshlrev_b32_e32 v190, 16, v146
	v_and_b32_e32 v151, 0xffff0000, v151
	v_and_b32_e32 v150, 0xffff0000, v150
	v_and_b32_e32 v147, 0xffff0000, v147
	v_and_b32_e32 v146, 0xffff0000, v146
	v_pk_add_f32 v[188:189], v[188:189], v[190:191]
	v_pk_add_f32 v[150:151], v[150:151], v[146:147]
	v_mov_b32_e32 v146, v48
	v_mov_b32_e32 v147, v50
	v_pk_add_f32 v[146:147], v[146:147], v[188:189]
	v_mov_b32_e32 v188, v49
	v_mov_b32_e32 v189, v51
	v_pk_add_f32 v[150:151], v[188:189], v[150:151]
	s_and_b64 vcc, exec, s[8:9]
	s_mov_b64 s[0:1], -1
	s_cbranch_vccnz .LBB0_592
	v_mov_b32_e32 v188, v144
	v_mov_b32_e32 v189, v148
	v_mov_b32_e32 v190, v145
	v_mov_b32_e32 v191, v149
	global_store_dwordx4 v[196:197], v[188:191], off offset:512
	s_nop 1
	v_mov_b32_e32 v188, v146
	v_mov_b32_e32 v189, v150
	v_mov_b32_e32 v190, v147
	v_mov_b32_e32 v191, v151
	global_store_dwordx4 v[196:197], v[188:191], off offset:528
	s_cbranch_execz .LBB0_593
	.p2align	6

; __device__ __forceinline__ float bf_lo(unsigned w) { return __uint_as_float(w << 16); }
; __device__ __forceinline__ float bf_hi(unsigned w) { return __uint_as_float(w & 0xffff0000u); }
;     __device__ __forceinline__ void operator()(f32x4 (&acc)[2][2][4][2], const Unit& u, int wr, int wc, int fr, int fq) const {
;     ...
;                 for (int bj = 0; bj < 2; ++bj) { const u32x4 h4 = hh[m][bj], l4 = ll[m][bj]; f32x4 v0, v1;
;                     v0[0] = acc[ai][bj][m][0][0] + (bf_lo(h4.x) + bf_lo(l4.x)); v0[1] = acc[ai][bj][m][0][1] + (bf_hi(h4.x) + bf_hi(l4.x)); v0[2] = acc[ai][bj][m][0][2] + (bf_lo(h4.y) + bf_lo(l4.y)); v0[3] = acc[ai][bj][m][0][3] + (bf_hi(h4.y) + bf_hi(l4.y));
;                     v1[0] = acc[ai][bj][m][1][0] + (bf_lo(h4.z) + bf_lo(l4.z)); v1[1] = acc[ai][bj][m][1][1] + (bf_hi(h4.z) + bf_hi(l4.z)); v1[2] = acc[ai][bj][m][1][2] + (bf_lo(h4.w) + bf_lo(l4.w)); v1[3] = acc[ai][bj][m][1][3] + (bf_hi(h4.w) + bf_hi(l4.w));
;                     if (fout) { *(f32x4*)(fout + off + bj * HALF) = v0; *(f32x4*)(fout + off + bj * HALF + 4) = v1; }
.LBB0_601:
	s_waitcnt vmcnt(1)
	v_lshlrev_b32_e32 v141, 16, v129
	v_lshlrev_b32_e32 v140, 16, v128
	s_waitcnt vmcnt(0)
	v_lshlrev_b32_e32 v143, 16, v133
	v_lshlrev_b32_e32 v142, 16, v132
	v_and_b32_e32 v129, 0xffff0000, v129
	v_and_b32_e32 v128, 0xffff0000, v128
	v_and_b32_e32 v133, 0xffff0000, v133
	v_and_b32_e32 v132, 0xffff0000, v132
	v_pk_add_f32 v[140:141], v[140:141], v[142:143]
	v_pk_add_f32 v[132:133], v[128:129], v[132:133]
	v_mov_b32_e32 v128, v36
	v_mov_b32_e32 v129, v38
	v_pk_add_f32 v[128:129], v[128:129], v[140:141]
	v_mov_b32_e32 v140, v37
	v_mov_b32_e32 v141, v39
	v_pk_add_f32 v[132:133], v[140:141], v[132:133]
	v_lshlrev_b32_e32 v141, 16, v131
	v_lshlrev_b32_e32 v140, 16, v130
	v_lshlrev_b32_e32 v143, 16, v135
	v_lshlrev_b32_e32 v142, 16, v134
	v_and_b32_e32 v131, 0xffff0000, v131
	v_and_b32_e32 v130, 0xffff0000, v130
	v_and_b32_e32 v135, 0xffff0000, v135
	v_and_b32_e32 v134, 0xffff0000, v134
	v_pk_add_f32 v[140:141], v[140:141], v[142:143]
	v_pk_add_f32 v[134:135], v[130:131], v[134:135]
	v_mov_b32_e32 v130, v32
	v_mov_b32_e32 v131, v34
	v_pk_add_f32 v[130:131], v[130:131], v[140:141]
	v_mov_b32_e32 v140, v33
	v_mov_b32_e32 v141, v35
	v_pk_add_f32 v[134:135], v[140:141], v[134:135]
	s_and_b64 vcc, exec, s[8:9]
	s_mov_b64 s[0:1], -1
	s_cbranch_vccnz .LBB0_604
	v_mov_b32_e32 v140, v128
	v_mov_b32_e32 v141, v132
	v_mov_b32_e32 v142, v129
	v_mov_b32_e32 v143, v133
	global_store_dwordx4 v[138:139], v[140:143], off offset:512
	s_nop 1
	v_mov_b32_e32 v140, v130
	v_mov_b32_e32 v141, v134
	v_mov_b32_e32 v142, v131
	v_mov_b32_e32 v143, v135
	global_store_dwordx4 v[138:139], v[140:143], off offset:528
	s_cbranch_execz .LBB0_605
	.p2align	6

; __device__ __forceinline__ float bf_lo(unsigned w) { return __uint_as_float(w << 16); }
; __device__ __forceinline__ float bf_hi(unsigned w) { return __uint_as_float(w & 0xffff0000u); }
;     __device__ __forceinline__ void operator()(f32x4 (&acc)[2][2][4][2], const Unit& u, int wr, int wc, int fr, int fq) const {
;     ...
;                 for (int bj = 0; bj < 2; ++bj) { const u32x4 h4 = hh[m][bj], l4 = ll[m][bj]; f32x4 v0, v1;
;                     v0[0] = acc[ai][bj][m][0][0] + (bf_lo(h4.x) + bf_lo(l4.x)); v0[1] = acc[ai][bj][m][0][1] + (bf_hi(h4.x) + bf_hi(l4.x)); v0[2] = acc[ai][bj][m][0][2] + (bf_lo(h4.y) + bf_lo(l4.y)); v0[3] = acc[ai][bj][m][0][3] + (bf_hi(h4.y) + bf_hi(l4.y));
;                     v1[0] = acc[ai][bj][m][1][0] + (bf_lo(h4.z) + bf_lo(l4.z)); v1[1] = acc[ai][bj][m][1][1] + (bf_hi(h4.z) + bf_hi(l4.z)); v1[2] = acc[ai][bj][m][1][2] + (bf_lo(h4.w) + bf_lo(l4.w)); v1[3] = acc[ai][bj][m][1][3] + (bf_hi(h4.w) + bf_hi(l4.w));
;                     if (fout) { *(f32x4*)(fout + off + bj * HALF) = v0; *(f32x4*)(fout + off + bj * HALF + 4) = v1; }
.LBB0_613:
	s_waitcnt vmcnt(5)
	v_lshlrev_b32_e32 v185, 16, v149
	v_lshlrev_b32_e32 v184, 16, v148
	s_waitcnt vmcnt(4)
	v_lshlrev_b32_e32 v187, 16, v145
	v_lshlrev_b32_e32 v186, 16, v144
	v_and_b32_e32 v149, 0xffff0000, v149
	v_and_b32_e32 v148, 0xffff0000, v148
	v_and_b32_e32 v145, 0xffff0000, v145
	v_and_b32_e32 v144, 0xffff0000, v144
	v_pk_add_f32 v[184:185], v[184:185], v[186:187]
	v_pk_add_f32 v[148:149], v[148:149], v[144:145]
	v_mov_b32_e32 v144, v20
	v_mov_b32_e32 v145, v22
	v_pk_add_f32 v[144:145], v[144:145], v[184:185]
	v_mov_b32_e32 v184, v21
	v_mov_b32_e32 v185, v23
	v_pk_add_f32 v[148:149], v[184:185], v[148:149]
	v_lshlrev_b32_e32 v185, 16, v151
	v_lshlrev_b32_e32 v184, 16, v150
	v_lshlrev_b32_e32 v187, 16, v147
	v_lshlrev_b32_e32 v186, 16, v146
	v_and_b32_e32 v151, 0xffff0000, v151
	v_and_b32_e32 v150, 0xffff0000, v150
	v_and_b32_e32 v147, 0xffff0000, v147
	v_and_b32_e32 v146, 0xffff0000, v146
	v_pk_add_f32 v[184:185], v[184:185], v[186:187]
	v_pk_add_f32 v[150:151], v[150:151], v[146:147]
	v_mov_b32_e32 v146, v16
	v_mov_b32_e32 v147, v18
	v_pk_add_f32 v[146:147], v[146:147], v[184:185]
	v_mov_b32_e32 v184, v17
	v_mov_b32_e32 v185, v19
	v_pk_add_f32 v[150:151], v[184:185], v[150:151]
	s_and_b64 vcc, exec, s[8:9]
	s_mov_b64 s[0:1], -1
	s_cbranch_vccnz .LBB0_616
	v_mov_b32_e32 v184, v144
	v_mov_b32_e32 v185, v148
	v_mov_b32_e32 v186, v145
	v_mov_b32_e32 v187, v149
	global_store_dwordx4 v[192:193], v[184:187], off offset:512
	s_nop 1
	v_mov_b32_e32 v184, v146
	v_mov_b32_e32 v185, v150
	v_mov_b32_e32 v186, v147
	v_mov_b32_e32 v187, v151
	global_store_dwordx4 v[192:193], v[184:187], off offset:528
	s_cbranch_execz .LBB0_617
	.p2align	6

; __device__ __forceinline__ float bf_lo(unsigned w) { return __uint_as_float(w << 16); }
; __device__ __forceinline__ float bf_hi(unsigned w) { return __uint_as_float(w & 0xffff0000u); }
;     __device__ __forceinline__ void operator()(f32x4 (&acc)[2][2][4][2], const Unit& u, int wr, int wc, int fr, int fq) const {
;     ...
;                 for (int bj = 0; bj < 2; ++bj) { const u32x4 h4 = hh[m][bj], l4 = ll[m][bj]; f32x4 v0, v1;
;                     v0[0] = acc[ai][bj][m][0][0] + (bf_lo(h4.x) + bf_lo(l4.x)); v0[1] = acc[ai][bj][m][0][1] + (bf_hi(h4.x) + bf_hi(l4.x)); v0[2] = acc[ai][bj][m][0][2] + (bf_lo(h4.y) + bf_lo(l4.y)); v0[3] = acc[ai][bj][m][0][3] + (bf_hi(h4.y) + bf_hi(l4.y));
;                     v1[0] = acc[ai][bj][m][1][0] + (bf_lo(h4.z) + bf_lo(l4.z)); v1[1] = acc[ai][bj][m][1][1] + (bf_hi(h4.z) + bf_hi(l4.z)); v1[2] = acc[ai][bj][m][1][2] + (bf_lo(h4.w) + bf_lo(l4.w)); v1[3] = acc[ai][bj][m][1][3] + (bf_hi(h4.w) + bf_hi(l4.w));
;                     if (fout) { *(f32x4*)(fout + off + bj * HALF) = v0; *(f32x4*)(fout + off + bj * HALF + 4) = v1; }
.LBB0_625:
	s_waitcnt vmcnt(1)
	v_lshlrev_b32_e32 v141, 16, v129
	v_lshlrev_b32_e32 v140, 16, v128
	s_waitcnt vmcnt(0)
	v_lshlrev_b32_e32 v143, 16, v133
	v_lshlrev_b32_e32 v142, 16, v132
	v_and_b32_e32 v129, 0xffff0000, v129
	v_and_b32_e32 v128, 0xffff0000, v128
	v_and_b32_e32 v133, 0xffff0000, v133
	v_and_b32_e32 v132, 0xffff0000, v132
	v_pk_add_f32 v[140:141], v[140:141], v[142:143]
	v_pk_add_f32 v[132:133], v[128:129], v[132:133]
	v_mov_b32_e32 v128, v4
	v_mov_b32_e32 v129, v6
	v_pk_add_f32 v[128:129], v[128:129], v[140:141]
	v_mov_b32_e32 v140, v5
	v_mov_b32_e32 v141, v7
	v_pk_add_f32 v[132:133], v[140:141], v[132:133]
	v_lshlrev_b32_e32 v141, 16, v131
	v_lshlrev_b32_e32 v140, 16, v130
	v_lshlrev_b32_e32 v143, 16, v135
	v_lshlrev_b32_e32 v142, 16, v134
	v_and_b32_e32 v131, 0xffff0000, v131
	v_and_b32_e32 v130, 0xffff0000, v130
	v_and_b32_e32 v135, 0xffff0000, v135
	v_and_b32_e32 v134, 0xffff0000, v134
	v_pk_add_f32 v[140:141], v[140:141], v[142:143]
	v_pk_add_f32 v[134:135], v[130:131], v[134:135]
	v_mov_b32_e32 v130, v0
	v_mov_b32_e32 v131, v2
	v_pk_add_f32 v[130:131], v[130:131], v[140:141]
	v_mov_b32_e32 v140, v1
	v_mov_b32_e32 v141, v3
	v_pk_add_f32 v[134:135], v[140:141], v[134:135]
	s_and_b64 vcc, exec, s[8:9]
	s_mov_b64 s[0:1], -1
	s_cbranch_vccnz .LBB0_628
	v_mov_b32_e32 v140, v128
	v_mov_b32_e32 v141, v132
	v_mov_b32_e32 v142, v129
	v_mov_b32_e32 v143, v133
	global_store_dwordx4 v[138:139], v[140:143], off offset:512
	s_nop 1
	v_mov_b32_e32 v140, v130
	v_mov_b32_e32 v141, v134
	v_mov_b32_e32 v142, v131
	v_mov_b32_e32 v143, v135
	global_store_dwordx4 v[138:139], v[140:143], off offset:528
	s_cbranch_execz .LBB0_629
	.p2align	6

;     __device__ __forceinline__ void operator()(f32x4 (&acc)[2][2][4][2], const Unit& u, int wr, int wc, int fr, int fq) const {
;         const int row0 = u.pm * BM + wr * 64 + fr; const int col0 = u.pn * BM + wc * 32 + 8 * fq;
;         float rs[2][4];
;         if (ss) { f32x4 pv[2][4];
; #pragma unroll
;             for (int ai = 0; ai < 2; ++ai)
; #pragma unroll
;                 for (int m = 0; m < 4; ++m) pv[ai][m] = *(const f32x4*)(ss + (size_t)(row0 + ai * HALF + m * 16) * 16 + 4 * fq);
; #pragma unroll
;             for (int ai = 0; ai < 2; ++ai)
; #pragma unroll
;                 for (int m = 0; m < 4; ++m) { float sq = (pv[ai][m][0] + pv[ai][m][1]) + (pv[ai][m][2] + pv[ai][m][3]); sq += __shfl_xor(sq, 16); sq += __shfl_xor(sq, 32); rs[ai][m] = rsqrtf(sq * (1.0f / 1024.0f) + 1e-6f); } }
;     __device__ __forceinline__ void operator()(f32x4 (&acc)[2][2][4][2], const Unit& u, int wr, int wc, int fr_in, int fq_in) const {
;     ...
;         if (mode == 0) { EpiScale<0> e{O, ldc, ncols, ss}; e(acc, u, wr, wc, fr, fq); }
;         else if (mode == 1) { EpiScale<1> e{O, ldc, ncols, ss}; e(acc, u, wr, wc, fr, fq); }
.LBB0_637:
	s_andn2_b64 vcc, exec, s[0:1]
	s_cbranch_vccnz .LBB0_712
	s_cmp_gt_i32 s70, 0
	s_mov_b64 s[0:1], -1
	s_cbranch_scc0 .LBB0_675
	s_lshl_b32 s0, s62, 8
	s_add_i32 s0, s0, s87
	v_add_u32_e32 v152, s0, v229
	s_and_b64 vcc, exec, s[16:17]
	v_ashrrev_i32_e32 v153, 31, v152
	s_cbranch_vccz .LBB0_715
	v_lshlrev_b32_e32 v128, 2, v228
	s_waitcnt lgkmcnt(0)
	v_ashrrev_i32_e32 v129, 31, v128
	v_lshl_add_u64 v[128:129], v[128:129], 2, s[20:21]
	v_lshlrev_b64 v[130:131], 6, v[152:153]
	v_lshl_add_u64 v[128:129], v[128:129], 0, v[130:131]
	global_load_dwordx4 v[180:183], v[128:129], off
	global_load_dwordx4 v[184:187], v[128:129], off offset:1024
	global_load_dwordx4 v[148:151], v[128:129], off offset:2048
	global_load_dwordx4 v[144:147], v[128:129], off offset:3072
	v_add_co_u32_e32 v128, vcc, 0x2000, v128
	v_and_b32_e32 v155, 64, v217
	s_nop 0
	v_addc_co_u32_e32 v129, vcc, 0, v129, vcc
	global_load_dwordx4 v[136:139], v[128:129], off
	global_load_dwordx4 v[140:143], v[128:129], off offset:1024
	global_load_dwordx4 v[132:135], v[128:129], off offset:2048
	s_nop 0
	global_load_dwordx4 v[128:131], v[128:129], off offset:3072
	v_xor_b32_e32 v154, 16, v217
	v_add_u32_e32 v155, 64, v155
	v_cmp_lt_i32_e32 vcc, v154, v155
	s_mov_b32 s10, 0x3a800000
	s_mov_b32 s0, 0x45800000
	v_cndmask_b32_e32 v154, v217, v154, vcc
	v_lshlrev_b32_e32 v157, 2, v154
	v_xor_b32_e32 v154, 32, v217
	v_cmp_lt_i32_e32 vcc, v154, v155
	s_waitcnt vmcnt(0)
	v_mov_b32_e32 v158, v180
	v_mov_b32_e32 v159, v184
	v_mov_b32_e32 v184, v181
	v_mov_b32_e32 v180, v182
	v_mov_b32_e32 v181, v186
	v_mov_b32_e32 v186, v183
	v_pk_add_f32 v[158:159], v[158:159], v[184:185]
	v_pk_add_f32 v[180:181], v[180:181], v[186:187]
	v_cndmask_b32_e32 v154, v217, v154, vcc
	v_pk_add_f32 v[158:159], v[158:159], v[180:181]
	ds_bpermute_b32 v180, v157, v158
	ds_bpermute_b32 v181, v157, v159
	v_lshlrev_b32_e32 v155, 2, v154
	s_waitcnt lgkmcnt(0)
	v_pk_add_f32 v[158:159], v[158:159], v[180:181]
	ds_bpermute_b32 v180, v155, v158
	ds_bpermute_b32 v181, v155, v159
	s_waitcnt lgkmcnt(0)
	v_pk_add_f32 v[180:181], v[158:159], v[180:181]
	v_mov_b64_e32 v[158:159], s[96:97]
	v_pk_fma_f32 v[180:181], v[180:181], s[10:11], v[158:159] op_sel_hi:[1,0,0]
	s_nop 0
	v_mul_f32_e32 v154, 0x4b800000, v180
	v_cmp_gt_f32_e64 s[8:9], s71, v180
	v_cmp_gt_f32_e32 vcc, s71, v181
	s_nop 0
	v_cndmask_b32_e64 v154, v180, v154, s[8:9]
	v_rsq_f32_e32 v180, v154
	v_mul_f32_e32 v154, 0x4b800000, v181
	v_cndmask_b32_e32 v154, v181, v154, vcc
	v_rsq_f32_e32 v181, v154
	s_nop 0
	v_pk_mul_f32 v[182:183], v[180:181], s[0:1] op_sel_hi:[1,0]
	s_nop 0
	v_cndmask_b32_e64 v156, v180, v182, s[8:9]
	v_cndmask_b32_e32 v154, v181, v183, vcc
	v_mov_b32_e32 v180, v148
	v_mov_b32_e32 v181, v144
	v_mov_b32_e32 v144, v149
	v_mov_b32_e32 v148, v150
	v_mov_b32_e32 v149, v146
	v_mov_b32_e32 v146, v151
	v_pk_add_f32 v[144:145], v[180:181], v[144:145]
	v_pk_add_f32 v[146:147], v[148:149], v[146:147]
	v_mov_b32_e32 v148, v136
	v_pk_add_f32 v[144:145], v[144:145], v[146:147]
	ds_bpermute_b32 v146, v157, v144
	ds_bpermute_b32 v147, v157, v145
	v_mov_b32_e32 v149, v140
	v_mov_b32_e32 v140, v137
	v_pk_add_f32 v[136:137], v[148:149], v[140:141]
	v_mov_b32_e32 v140, v138
	s_waitcnt lgkmcnt(0)
	v_pk_add_f32 v[144:145], v[144:145], v[146:147]
	v_mov_b32_e32 v141, v142
	v_mov_b32_e32 v142, v139
	ds_bpermute_b32 v146, v155, v144
	ds_bpermute_b32 v147, v155, v145
	v_pk_add_f32 v[138:139], v[140:141], v[142:143]
	v_mov_b32_e32 v140, v132
	v_pk_add_f32 v[136:137], v[136:137], v[138:139]
	ds_bpermute_b32 v138, v157, v136
	ds_bpermute_b32 v139, v157, v137
	s_waitcnt lgkmcnt(2)
	v_pk_add_f32 v[144:145], v[144:145], v[146:147]
	v_mov_b32_e32 v141, v128
	v_pk_fma_f32 v[144:145], v[144:145], s[10:11], v[158:159] op_sel_hi:[1,0,0]
	v_mov_b32_e32 v128, v133
	v_mul_f32_e32 v146, 0x4b800000, v144
	v_cmp_gt_f32_e64 s[8:9], s71, v144
	s_waitcnt lgkmcnt(0)
	v_pk_add_f32 v[136:137], v[136:137], v[138:139]
	v_mov_b32_e32 v132, v134
	v_mov_b32_e32 v133, v130
	v_mov_b32_e32 v130, v135
	v_cmp_gt_f32_e32 vcc, s71, v145
	v_cndmask_b32_e64 v144, v144, v146, s[8:9]
	v_mul_f32_e32 v146, 0x4b800000, v145
	ds_bpermute_b32 v138, v155, v136
	ds_bpermute_b32 v139, v155, v137
	v_pk_add_f32 v[128:129], v[140:141], v[128:129]
	v_pk_add_f32 v[130:131], v[132:133], v[130:131]
	v_cndmask_b32_e32 v145, v145, v146, vcc
	v_pk_add_f32 v[128:129], v[128:129], v[130:131]
	v_rsq_f32_e32 v144, v144
	v_rsq_f32_e32 v145, v145
	ds_bpermute_b32 v130, v157, v128
	ds_bpermute_b32 v131, v157, v129
	s_waitcnt lgkmcnt(2)
	v_pk_add_f32 v[136:137], v[136:137], v[138:139]
	v_pk_mul_f32 v[146:147], v[144:145], s[0:1] op_sel_hi:[1,0]
	v_pk_fma_f32 v[136:137], v[136:137], s[10:11], v[158:159] op_sel_hi:[1,0,0]
	v_cndmask_b32_e64 v146, v144, v146, s[8:9]
	v_mul_f32_e32 v138, 0x4b800000, v136
	v_cmp_gt_f32_e64 s[8:9], s71, v136
	s_waitcnt lgkmcnt(0)
	v_pk_add_f32 v[128:129], v[128:129], v[130:131]
	v_cndmask_b32_e32 v144, v145, v147, vcc
	v_cmp_gt_f32_e32 vcc, s71, v137
	v_cndmask_b32_e64 v136, v136, v138, s[8:9]
	v_mul_f32_e32 v138, 0x4b800000, v137
	ds_bpermute_b32 v130, v155, v128
	ds_bpermute_b32 v131, v155, v129
	v_cndmask_b32_e32 v137, v137, v138, vcc
	v_rsq_f32_e32 v136, v136
	v_rsq_f32_e32 v137, v137
	s_waitcnt lgkmcnt(0)
	v_pk_add_f32 v[128:129], v[128:129], v[130:131]
	s_nop 0
	v_pk_fma_f32 v[128:129], v[128:129], s[10:11], v[158:159] op_sel_hi:[1,0,0]
	v_pk_mul_f32 v[138:139], v[136:137], s[0:1] op_sel_hi:[1,0]
	v_mul_f32_e32 v130, 0x4b800000, v128
	v_cndmask_b32_e64 v138, v136, v138, s[8:9]
	v_cmp_gt_f32_e64 s[8:9], s71, v128
	v_cndmask_b32_e32 v136, v137, v139, vcc
	v_cmp_gt_f32_e32 vcc, s71, v129
	v_cndmask_b32_e64 v128, v128, v130, s[8:9]
	v_mul_f32_e32 v130, 0x4b800000, v129
	v_cndmask_b32_e32 v129, v129, v130, vcc
	v_rsq_f32_e32 v128, v128
	v_rsq_f32_e32 v129, v129
	s_nop 0
	v_pk_mul_f32 v[130:131], v[128:129], s[0:1] op_sel_hi:[1,0]
	s_nop 0
	v_cndmask_b32_e64 v132, v128, v130, s[8:9]
	v_cndmask_b32_e32 v130, v129, v131, vcc
	s_cbranch_execnz .LBB0_642
	.p2align	6

;     __device__ __forceinline__ void operator()(f32x4 (&acc)[2][2][4][2], const Unit& u, int wr, int wc, int fr, int fq) const {
;         const int row0 = u.pm * BM + wr * 64 + fr; const int col0 = u.pn * BM + wc * 32 + 8 * fq;
;         float rs[2][4];
;         if (ss) { f32x4 pv[2][4];
; #pragma unroll
;             for (int ai = 0; ai < 2; ++ai)
; #pragma unroll
;                 for (int m = 0; m < 4; ++m) pv[ai][m] = *(const f32x4*)(ss + (size_t)(row0 + ai * HALF + m * 16) * 16 + 4 * fq);
; #pragma unroll
;             for (int ai = 0; ai < 2; ++ai)
; #pragma unroll
;                 for (int m = 0; m < 4; ++m) { float sq = (pv[ai][m][0] + pv[ai][m][1]) + (pv[ai][m][2] + pv[ai][m][3]); sq += __shfl_xor(sq, 16); sq += __shfl_xor(sq, 32); rs[ai][m] = rsqrtf(sq * (1.0f / 1024.0f) + 1e-6f); } }
;     __device__ __forceinline__ void operator()(f32x4 (&acc)[2][2][4][2], const Unit& u, int wr, int wc, int fr_in, int fq_in) const {
;     ...
;         else if (mode == 1) { EpiScale<1> e{O, ldc, ncols, ss}; e(acc, u, wr, wc, fr, fq); }
.LBB0_675:
	s_and_b64 vcc, exec, s[0:1]
	s_cbranch_vccz .LBB0_712
	s_lshl_b32 s0, s62, 8
	s_add_i32 s0, s0, s87
	v_add_u32_e32 v152, s0, v229
	s_and_b64 vcc, exec, s[16:17]
	v_ashrrev_i32_e32 v153, 31, v152
	s_cbranch_vccz .LBB0_716
	v_lshlrev_b32_e32 v128, 2, v228
	s_waitcnt lgkmcnt(0)
	v_ashrrev_i32_e32 v129, 31, v128
	v_lshl_add_u64 v[128:129], v[128:129], 2, s[20:21]
	v_lshlrev_b64 v[130:131], 6, v[152:153]
	v_lshl_add_u64 v[128:129], v[128:129], 0, v[130:131]
	global_load_dwordx4 v[154:157], v[128:129], off
	global_load_dwordx4 v[180:183], v[128:129], off offset:1024
	global_load_dwordx4 v[148:151], v[128:129], off offset:2048
	global_load_dwordx4 v[144:147], v[128:129], off offset:3072
	v_add_co_u32_e32 v128, vcc, 0x2000, v128
	v_and_b32_e32 v159, 64, v217
	s_nop 0
	v_addc_co_u32_e32 v129, vcc, 0, v129, vcc
	global_load_dwordx4 v[136:139], v[128:129], off
	global_load_dwordx4 v[140:143], v[128:129], off offset:1024
	global_load_dwordx4 v[132:135], v[128:129], off offset:2048
	s_nop 0
	global_load_dwordx4 v[128:131], v[128:129], off offset:3072
	v_xor_b32_e32 v158, 16, v217
	v_add_u32_e32 v160, 64, v159
	v_cmp_lt_i32_e32 vcc, v158, v160
	s_mov_b32 s10, 0x3a800000
	s_mov_b32 s0, 0x45800000
	v_cndmask_b32_e32 v158, v217, v158, vcc
	v_lshlrev_b32_e32 v159, 2, v158
	v_xor_b32_e32 v158, 32, v217
	v_cmp_lt_i32_e32 vcc, v158, v160
	s_waitcnt vmcnt(0)
	v_mov_b32_e32 v184, v154
	v_mov_b32_e32 v185, v180
	v_mov_b32_e32 v180, v155
	v_pk_add_f32 v[154:155], v[184:185], v[180:181]
	v_mov_b32_e32 v180, v156
	v_mov_b32_e32 v181, v182
	v_mov_b32_e32 v182, v157
	v_pk_add_f32 v[156:157], v[180:181], v[182:183]
	v_cndmask_b32_e32 v158, v217, v158, vcc
	v_pk_add_f32 v[154:155], v[154:155], v[156:157]
	ds_bpermute_b32 v156, v159, v154
	ds_bpermute_b32 v157, v159, v155
	v_lshlrev_b32_e32 v158, 2, v158
	s_waitcnt lgkmcnt(0)
	v_pk_add_f32 v[154:155], v[154:155], v[156:157]
	ds_bpermute_b32 v156, v158, v154
	ds_bpermute_b32 v157, v158, v155
	s_waitcnt lgkmcnt(0)
	v_pk_add_f32 v[154:155], v[154:155], v[156:157]
	v_mov_b64_e32 v[156:157], s[96:97]
	v_pk_fma_f32 v[154:155], v[154:155], s[10:11], v[156:157] op_sel_hi:[1,0,0]
	s_nop 0
	v_mul_f32_e32 v160, 0x4b800000, v154
	v_cmp_gt_f32_e64 s[8:9], s71, v154
	v_cmp_gt_f32_e32 vcc, s71, v155
	s_nop 0
	v_cndmask_b32_e64 v154, v154, v160, s[8:9]
	v_mul_f32_e32 v160, 0x4b800000, v155
	v_cndmask_b32_e32 v155, v155, v160, vcc
	v_rsq_f32_e32 v154, v154
	v_rsq_f32_e32 v155, v155
	s_nop 0
	v_pk_mul_f32 v[180:181], v[154:155], s[0:1] op_sel_hi:[1,0]
	s_nop 0
	v_cndmask_b32_e64 v154, v154, v180, s[8:9]
	v_cndmask_b32_e32 v155, v155, v181, vcc
	v_mov_b32_e32 v180, v148
	v_mov_b32_e32 v181, v144
	v_mov_b32_e32 v144, v149
	v_mov_b32_e32 v148, v150
	v_mov_b32_e32 v149, v146
	v_mov_b32_e32 v146, v151
	v_pk_add_f32 v[144:145], v[180:181], v[144:145]
	v_pk_add_f32 v[146:147], v[148:149], v[146:147]
	s_nop 0
	v_pk_add_f32 v[144:145], v[144:145], v[146:147]
	ds_bpermute_b32 v146, v159, v144
	ds_bpermute_b32 v147, v159, v145
	s_waitcnt lgkmcnt(0)
	v_pk_add_f32 v[144:145], v[144:145], v[146:147]
	ds_bpermute_b32 v146, v158, v144
	ds_bpermute_b32 v147, v158, v145
	s_waitcnt lgkmcnt(0)
	v_pk_add_f32 v[144:145], v[144:145], v[146:147]
	s_nop 0
	v_pk_fma_f32 v[144:145], v[144:145], s[10:11], v[156:157] op_sel_hi:[1,0,0]
	s_nop 0
	v_mul_f32_e32 v146, 0x4b800000, v144
	v_cmp_gt_f32_e64 s[8:9], s71, v144
	v_cmp_gt_f32_e32 vcc, s71, v145
	s_nop 0
	v_cndmask_b32_e64 v144, v144, v146, s[8:9]
	v_mul_f32_e32 v146, 0x4b800000, v145
	v_cndmask_b32_e32 v145, v145, v146, vcc
	v_rsq_f32_e32 v144, v144
	v_rsq_f32_e32 v145, v145
	s_nop 0
	v_pk_mul_f32 v[146:147], v[144:145], s[0:1] op_sel_hi:[1,0]
	s_nop 0
	v_cndmask_b32_e64 v144, v144, v146, s[8:9]
	v_cndmask_b32_e32 v145, v145, v147, vcc
	v_mov_b32_e32 v146, v136
	v_mov_b32_e32 v147, v140
	v_mov_b32_e32 v140, v137
	v_pk_add_f32 v[136:137], v[146:147], v[140:141]
	v_mov_b32_e32 v140, v138
	v_mov_b32_e32 v141, v142
	v_mov_b32_e32 v142, v139
	v_pk_add_f32 v[138:139], v[140:141], v[142:143]
	s_nop 0
	v_pk_add_f32 v[136:137], v[136:137], v[138:139]
	ds_bpermute_b32 v138, v159, v136
	ds_bpermute_b32 v139, v159, v137
	s_waitcnt lgkmcnt(0)
	v_pk_add_f32 v[136:137], v[136:137], v[138:139]
	ds_bpermute_b32 v138, v158, v136
	ds_bpermute_b32 v139, v158, v137
	s_waitcnt lgkmcnt(0)
	v_pk_add_f32 v[136:137], v[136:137], v[138:139]
	s_nop 0
	v_pk_fma_f32 v[136:137], v[136:137], s[10:11], v[156:157] op_sel_hi:[1,0,0]
	s_nop 0
	v_mul_f32_e32 v138, 0x4b800000, v136
	v_cmp_gt_f32_e64 s[8:9], s71, v136
	v_cmp_gt_f32_e32 vcc, s71, v137
	s_nop 0
	v_cndmask_b32_e64 v136, v136, v138, s[8:9]
	v_mul_f32_e32 v138, 0x4b800000, v137
	v_cndmask_b32_e32 v137, v137, v138, vcc
	v_rsq_f32_e32 v136, v136
	v_rsq_f32_e32 v137, v137
	s_nop 0
	v_pk_mul_f32 v[138:139], v[136:137], s[0:1] op_sel_hi:[1,0]
	s_nop 0
	v_cndmask_b32_e64 v136, v136, v138, s[8:9]
	v_cndmask_b32_e32 v137, v137, v139, vcc
	v_mov_b32_e32 v138, v132
	v_mov_b32_e32 v139, v128
	v_mov_b32_e32 v128, v133
	v_mov_b32_e32 v132, v134
	v_mov_b32_e32 v133, v130
	v_mov_b32_e32 v130, v135
	v_pk_add_f32 v[128:129], v[138:139], v[128:129]
	v_pk_add_f32 v[130:131], v[132:133], v[130:131]
	s_nop 0
	v_pk_add_f32 v[128:129], v[128:129], v[130:131]
	ds_bpermute_b32 v130, v159, v128
	ds_bpermute_b32 v131, v159, v129
	s_waitcnt lgkmcnt(0)
	v_pk_add_f32 v[128:129], v[128:129], v[130:131]
	ds_bpermute_b32 v130, v158, v128
	ds_bpermute_b32 v131, v158, v129
	s_waitcnt lgkmcnt(0)
	v_pk_add_f32 v[128:129], v[128:129], v[130:131]
	s_nop 0
	v_pk_fma_f32 v[128:129], v[128:129], s[10:11], v[156:157] op_sel_hi:[1,0,0]
	s_nop 0
	v_mul_f32_e32 v130, 0x4b800000, v128
	v_cmp_gt_f32_e64 s[8:9], s71, v128
	v_cmp_gt_f32_e32 vcc, s71, v129
	s_nop 0
	v_cndmask_b32_e64 v128, v128, v130, s[8:9]
	v_mul_f32_e32 v130, 0x4b800000, v129
	v_cndmask_b32_e32 v129, v129, v130, vcc
	v_rsq_f32_e32 v128, v128
	v_rsq_f32_e32 v129, v129
	s_nop 0
	v_pk_mul_f32 v[130:131], v[128:129], s[0:1] op_sel_hi:[1,0]
	s_nop 0
	v_cndmask_b32_e64 v128, v128, v130, s[8:9]
	v_cndmask_b32_e32 v129, v129, v131, vcc
	s_cbranch_execnz .LBB0_679
	.p2align	6

; __global__ void __launch_bounds__(512, 2) fwd_kernel(Args a_unused) {
;     ...
;         case -1:
;             for (int m = gw; m < MROWS; m += 2 * ngw) {
;                 const int m2 = m + ngw; const bool two = m2 < MROWS;
;                 f32x4 va[4], vb[4];
; #pragma unroll
;                 for (int j = 0; j < 4; ++j) { va[j] = ((const f32x4*)(a.in[0] + (size_t)m * DM) + lane)[64 * j]; vb[j] = two ? ((const f32x4*)(a.in[0] + (size_t)m2 * DM) + lane)[64 * j] : (f32x4){0.f, 0.f, 0.f, 0.f}; }
;                 float sa = 0.f, sbq = 0.f;
; #pragma unroll
;                 for (int j = 0; j < 4; ++j) { sa += (va[j].x * va[j].x + va[j].y * va[j].y) + (va[j].z * va[j].z + va[j].w * va[j].w); sbq += (vb[j].x * vb[j].x + vb[j].y * vb[j].y) + (vb[j].z * vb[j].z + vb[j].w * vb[j].w); }
;                 sa = wave_sum(sa); sbq = wave_sum(sbq);
.LBB0_718:
	s_and_b64 vcc, exec, s[16:17]
	s_movk_i32 s94, 0x1ff
	s_mov_b32 s97, 0x16000
	s_movk_i32 s86, 0x4000
	s_movk_i32 s87, 0x6000
	s_mov_b32 s75, 0x18000
	s_mov_b32 s82, 0x1a000
	s_mov_b32 s78, 0xa000
	s_mov_b32 s79, 0x1c000
	s_mov_b32 s84, 0x1e000
	s_mov_b32 s95, 0xc000
	s_mov_b32 s90, 0xe000
	s_movk_i32 s83, 0x1118
	s_mov_b32 s28, 0x22000
	s_mov_b32 s96, 0x24000
	s_mov_b32 s68, 0x26000
	s_mov_b32 s69, 0x2a000
	s_mov_b32 s73, 0x2e000
	s_mov_b32 s70, 0x34000
	s_mov_b32 s72, 0x38000
	v_readlane_b32 s29, v254, 13
	s_mov_b64 s[30:31], 0x2000
	s_cbranch_vccz .LBB0_854
	v_readlane_b32 s0, v254, 19
	s_cmpk_gt_i32 s0, 0x7fff
	s_cbranch_scc1 .LBB0_741
	v_readlane_b32 s8, v253, 35
	v_readlane_b32 s9, v253, 36
	v_mov_b32_e32 v167, v161
	v_mov_b32_e32 v0, s8
	v_mov_b32_e32 v1, s9
	v_lshl_add_u64 v[32:33], v[166:167], 4, v[0:1]
	v_and_b32_e32 v0, 64, v217
	v_add_u32_e32 v0, 64, v0
	v_xor_b32_e32 v1, 1, v217
	v_cmp_lt_i32_e32 vcc, v1, v0
	v_readlane_b32 s10, v253, 37
	v_readlane_b32 s11, v253, 38
	v_cndmask_b32_e32 v1, v217, v1, vcc
	v_lshlrev_b32_e32 v48, 2, v1
	v_xor_b32_e32 v1, 2, v217
	v_cmp_lt_i32_e32 vcc, v1, v0
	v_readlane_b32 s12, v253, 39
	v_readlane_b32 s13, v253, 40
	v_cndmask_b32_e32 v1, v217, v1, vcc
	v_lshlrev_b32_e32 v49, 2, v1
	v_xor_b32_e32 v1, 4, v217
	v_cmp_lt_i32_e32 vcc, v1, v0
	v_readlane_b32 s14, v253, 41
	v_readlane_b32 s15, v253, 42
	v_cndmask_b32_e32 v1, v217, v1, vcc
	v_lshlrev_b32_e32 v50, 2, v1
	v_xor_b32_e32 v1, 8, v217
	v_cmp_lt_i32_e32 vcc, v1, v0
	v_readlane_b32 s16, v253, 43
	v_readlane_b32 s17, v253, 44
	v_cndmask_b32_e32 v1, v217, v1, vcc
	v_lshlrev_b32_e32 v51, 2, v1
	v_xor_b32_e32 v1, 16, v217
	v_cmp_lt_i32_e32 vcc, v1, v0
	v_readlane_b32 s18, v253, 45
	v_readlane_b32 s19, v253, 46
	v_cndmask_b32_e32 v1, v217, v1, vcc
	v_lshlrev_b32_e32 v52, 2, v1
	v_xor_b32_e32 v1, 32, v217
	v_cmp_lt_i32_e32 vcc, v1, v0
	v_readlane_b32 s10, v254, 3
	v_readlane_b32 s11, v254, 4
	v_cndmask_b32_e32 v0, v217, v1, vcc
	v_lshlrev_b32_e32 v53, 2, v0
	v_lshlrev_b64 v[0:1], 3, v[166:167]
	v_readlane_b32 s12, v254, 5
	v_lshl_add_u64 v[2:3], s[10:11], 0, v[0:1]
	s_mov_b64 s[0:1], 0x2100000
	v_readlane_b32 s18, v254, 11
	v_readlane_b32 s19, v254, 12
	v_lshl_add_u64 v[34:35], v[2:3], 0, s[0:1]
	s_mov_b64 s[0:1], 0x4000000
	v_lshl_add_u64 v[0:1], s[18:19], 0, v[0:1]
	v_lshl_add_u64 v[36:37], v[0:1], 0, s[0:1]
	v_readlane_b32 s0, v254, 19
	v_cmp_gt_u32_e64 s[6:7], 16, v166
	v_cmp_eq_u32_e64 s[8:9], 0, v166
	v_lshl_add_u64 v[38:39], v[166:167], 2, s[10:11]
	s_mov_b32 s12, s0
	v_readlane_b32 s20, v253, 47
	v_readlane_b32 s21, v253, 48
	v_readlane_b32 s22, v253, 49
	v_readlane_b32 s23, v253, 50
	v_readlane_b32 s13, v254, 6
	v_readlane_b32 s14, v254, 7
	v_readlane_b32 s15, v254, 8
	v_readlane_b32 s16, v254, 9
	v_readlane_b32 s17, v254, 10
	s_branch .LBB0_722
	.p2align	6

; DI void tr_tile(const float* __restrict__ src, int srcN, int k0, int n0, int mode, const float* __restrict__ gk, bf16_t* dst, size_t dpitch, int ncopies, float* scr, int lane) {
;     const int nn = lane & 31, n = n0 + nn; int sc = n; bool valid = true;
;     if (mode == 1) { if (n >= 4608) { const int q = n - 4608, rho = q & 255; sc = ZP + (2 * (rho >> 7) + ((rho >> 2) & 1)) * 1024 + 64 * (q >> 8) + 16 * ((rho >> 5) & 3) + 4 * ((rho >> 3) & 3) + (rho & 3); } else if (n >= ZP) { sc = 0; valid = false; } }
; DI void convert_first(const Args& a, int l, float* scr, int gw, int ngw, int lane) {
;     unsigned char* ws = a.ws;
;     bf16_t* WIN = (bf16_t*)(ws + WS_WIN); bf16_t* WB = (bf16_t*)(ws + WS_WB); bf16_t* WO = (bf16_t*)(ws + WS_WO); bf16_t* W1T = (bf16_t*)(ws + WS_W1T);
;     const float* win = a.in[2] + (size_t)l * 1024 * NIN; const float* g1 = a.in[1] + l * 1024;
;     constexpr int I_WIN = 16 * (NWIN / 32), I_PF = 2048, I_WB = 4 * 8 * 32, I_WO = 16 * 32, I_W1 = 2 * 32 * 2;
;     for (int it = gw; it < I_WIN + I_PF + I_WB + I_WO + I_W1; it += ngw) {
;         int r = it;
;         if (r < I_WIN) { const int kt = r / (NWIN / 32), nt = r % (NWIN / 32); tr_tile(win, NIN, kt * 64, nt * 32, 1, g1, WIN, 1024, 1, scr, lane); continue; } r -= I_WIN;
.LBB0_741:
	v_readlane_b32 s0, v254, 19
	s_cmpk_gt_i32 s0, 0x1f7f
	s_cbranch_scc1 .LBB0_854
	v_and_b32_e32 v3, 31, v225
	v_lshrrev_b32_e32 v0, 5, v166
	v_mul_u32_u24_e32 v1, 33, v0
	v_readlane_b32 s0, v254, 21
	v_lshlrev_b32_e32 v4, 2, v3
	v_readlane_b32 s6, v254, 3
	v_lshlrev_b32_e32 v1, 2, v1
	v_add_u32_e32 v6, s0, v4
	v_readlane_b32 s7, v254, 4
	s_add_u32 s8, s6, 0x400000
	v_add_u32_e32 v2, s0, v1
	v_add_u32_e32 v29, v6, v1
	v_mov_b32_e32 v1, 0x1080
	s_addc_u32 s9, s7, 0
	v_lshl_or_b32 v1, v166, 2, v1
	s_add_u32 s14, s6, 0x1500000
	v_add_u32_e32 v30, v2, v1
	v_lshlrev_b32_e32 v1, 3, v166
	s_addc_u32 s15, s7, 0
	v_add_u32_e32 v28, v2, v4
	v_lshrrev_b32_e32 v31, 3, v166
	v_and_b32_e32 v2, 56, v1
	s_add_u32 s16, s6, 0x300000
	v_mul_u32_u24_e32 v1, 0x84, v2
	v_lshlrev_b32_e32 v4, 2, v31
	v_lshlrev_b32_e32 v160, 1, v2
	v_readlane_b32 s44, v253, 35
	s_addc_u32 s17, s7, 0
	v_add3_u32 v32, s0, v1, v4
	v_lshl_add_u64 v[4:5], s[6:7], 0, v[160:161]
	s_mov_b64 s[0:1], 0x1900000
	v_mov_b32_e32 v1, 0x1118
	v_readlane_b32 s45, v253, 36
	v_readlane_b32 s46, v253, 37
	v_readlane_b32 s47, v253, 38
	v_readlane_b32 s48, v253, 39
	v_readlane_b32 s49, v253, 40
	v_readlane_b32 s50, v253, 41
	v_readlane_b32 s51, v253, 42
	v_readlane_b32 s52, v253, 43
	v_readlane_b32 s53, v253, 44
	v_readlane_b32 s54, v253, 45
	v_readlane_b32 s55, v253, 46
	v_readlane_b32 s56, v253, 47
	v_readlane_b32 s57, v253, 48
	v_readlane_b32 s58, v253, 49
	v_readlane_b32 s59, v253, 50
	v_lshl_add_u64 v[4:5], v[4:5], 0, s[0:1]
	v_and_or_b32 v38, v225, 3, v1
	s_cmp_lg_u64 s[46:47], 0
	v_or_b32_e32 v1, 2, v0
	s_movk_i32 s0, 0x84
	v_readlane_b32 s44, v253, 51
	s_cselect_b64 s[10:11], -1, 0
	v_mad_u32_u24 v39, v1, s0, v6
	v_readlane_b32 s45, v253, 52
	s_add_u32 s18, s44, 0x1e00
	v_readlane_b32 s0, v253, 20
	v_readlane_b32 s1, v254, 20
	s_addc_u32 s19, s45, 0
	s_add_i32 s0, s0, s1
	v_readlane_b32 s1, v254, 17
	v_or_b32_e32 v33, 8, v31
	v_or_b32_e32 v34, 16, v31
	v_or_b32_e32 v35, 24, v31
	v_and_b32_e32 v36, 4, v31
	v_bfe_u32 v37, v225, 2, 1
	v_add_u32_e32 v40, 0x108, v39
	v_add_u32_e32 v41, 0x210, v39
	v_add_u32_e32 v42, 0x318, v39
	v_add_u32_e32 v43, 0x420, v39
	v_add_u32_e32 v44, 0x528, v39
	v_add_u32_e32 v45, 0x630, v39
	v_add_u32_e32 v46, 0x738, v39
	v_add_u32_e32 v47, 0x840, v39
	v_add_u32_e32 v48, 0x948, v39
	v_add_u32_e32 v49, 0xa50, v39
	v_add_u32_e32 v50, 0xb58, v39
	v_add_u32_e32 v51, 0xc60, v39
	v_add_u32_e32 v52, 0xd68, v39
	v_add_u32_e32 v53, 0xe70, v39
	v_add_u32_e32 v54, 0xf78, v39
	s_waitcnt lgkmcnt(0)
	v_add_u32_e32 v55, 0x1080, v39
	v_add_u32_e32 v56, 0x1188, v39
	v_add_u32_e32 v57, 0x1290, v39
	v_add_u32_e32 v58, 0x1398, v39
	v_add_u32_e32 v59, 0x14a0, v39
	v_add_u32_e32 v60, 0x15a8, v39
	v_add_u32_e32 v61, 0x16b0, v39
	v_add_u32_e32 v62, 0x17b8, v39
	v_add_u32_e32 v63, 0x18c0, v39
	v_add_u32_e32 v64, 0x19c8, v39
	v_add_u32_e32 v65, 0x1ad0, v39
	v_add_u32_e32 v66, 0x1bd8, v39
	v_add_u32_e32 v67, 0x1ce0, v39
	v_add_u32_e32 v68, 0x1de8, v39
	v_add_u32_e32 v69, 0x1ef0, v39
	v_lshl_add_u64 v[6:7], s[8:9], 0, v[160:161]
	v_mov_b32_e32 v1, v161
	s_lshl_b32 s20, s0, 12
	s_lshl_b32 s21, s1, 15
	s_lshl_b32 s22, s0, 5
	s_lshl_b32 s23, s1, 8
	v_readlane_b32 s24, v254, 19
	v_readlane_b32 s46, v253, 53
	v_readlane_b32 s47, v253, 54
	v_readlane_b32 s48, v253, 55
	v_readlane_b32 s49, v253, 56
	v_readlane_b32 s50, v253, 57
	v_readlane_b32 s51, v253, 58
	v_readlane_b32 s52, v253, 59
	v_readlane_b32 s53, v253, 60
	v_readlane_b32 s54, v253, 61
	v_readlane_b32 s55, v253, 62
	v_readlane_b32 s56, v253, 63
	v_readlane_b32 s57, v254, 0
	v_readlane_b32 s58, v254, 1
	v_readlane_b32 s59, v254, 2
	s_branch .LBB0_745
	.p2align	6
.LBB0_743:
	s_or_b64 exec, exec, s[0:1]
	s_waitcnt lgkmcnt(0)
	.p2align	6

; DI void tr_tile(const float* __restrict__ src, int srcN, int k0, int n0, int mode, const float* __restrict__ gk, bf16_t* dst, size_t dpitch, int ncopies, float* scr, int lane) {
;     ...
; #pragma unroll
;     for (int i = 0; i < 32; ++i) { const int kk = 2 * i + (lane >> 5); v32[i] = valid ? src[(size_t)(k0 + kk) * srcN + sc] : 0.f; }
; #pragma unroll
;     for (int i = 0; i < 32; ++i) { const int kk = 2 * i + (lane >> 5); float v = v32[i]; if (gk) v *= gk[k0 + kk]; scr[kk * 33 + nn] = v; }
.LBB0_830:
	s_or_b64 exec, exec, s[12:13]
	v_cndmask_b32_e64 v11, 0, 1, s[10:11]
	v_cmp_ne_u32_e64 s[6:7], 1, v11
	s_andn2_b64 vcc, exec, s[10:11]
	s_cbranch_vccnz .LBB0_850
	v_readlane_b32 s44, v253, 35
	v_readlane_b32 s46, v253, 37
	v_readlane_b32 s47, v253, 38
	v_ashrrev_i32_e32 v11, 31, v10
	s_mov_b64 s[42:43], s[46:47]
	s_ashr_i32 s1, s0, 31
	v_lshl_add_u64 v[10:11], v[10:11], 2, s[42:43]
	v_lshl_add_u64 v[26:27], s[0:1], 0, v[0:1]
	v_lshl_add_u64 v[26:27], v[26:27], 2, s[42:43]
	global_load_dword v88, v[10:11], off
	global_load_dword v89, v[26:27], off offset:8
	global_load_dword v90, v[26:27], off offset:16
	global_load_dword v91, v[26:27], off offset:24
	s_nop 0
	global_load_dword v10, v[26:27], off offset:32
	global_load_dword v11, v[26:27], off offset:40
	global_load_dword v86, v[26:27], off offset:48
	global_load_dword v87, v[26:27], off offset:56
	v_readlane_b32 s45, v253, 36
	v_readlane_b32 s48, v253, 39
	v_readlane_b32 s49, v253, 40
	v_readlane_b32 s50, v253, 41
	v_readlane_b32 s51, v253, 42
	v_readlane_b32 s52, v253, 43
	v_readlane_b32 s53, v253, 44
	v_readlane_b32 s54, v253, 45
	v_readlane_b32 s55, v253, 46
	v_readlane_b32 s56, v253, 47
	v_readlane_b32 s57, v253, 48
	v_readlane_b32 s58, v253, 49
	v_readlane_b32 s59, v253, 50
	s_waitcnt vmcnt(0)
	v_mul_f32_e32 v26, v71, v88
	v_mul_f32_e32 v88, v70, v89
	ds_write_b32 v28, v26
	v_mul_f32_e32 v89, v79, v90
	v_mul_f32_e32 v90, v78, v91
	v_pk_mul_f32 v[10:11], v[8:9], v[10:11]
	ds_write_b32 v39, v88
	ds_write_b32 v40, v89
	ds_write_b32 v41, v90
	v_pk_mul_f32 v[26:27], v[18:19], v[86:87]
	s_cbranch_execnz .LBB0_833
	.p2align	6

; DI void tr_tile(const float* __restrict__ src, int srcN, int k0, int n0, int mode, const float* __restrict__ gk, bf16_t* dst, size_t dpitch, int ncopies, float* scr, int lane) {
;     ...
; #pragma unroll
;     for (int i = 0; i < 32; ++i) { const int kk = 2 * i + (lane >> 5); v32[i] = valid ? src[(size_t)(k0 + kk) * srcN + sc] : 0.f; }
; #pragma unroll
;     for (int i = 0; i < 32; ++i) { const int kk = 2 * i + (lane >> 5); float v = v32[i]; if (gk) v *= gk[k0 + kk]; scr[kk * 33 + nn] = v; }
.LBB0_833:
	s_and_b64 vcc, exec, s[6:7]
	ds_write_b32 v42, v10
	ds_write_b32 v43, v11
	ds_write_b32 v44, v26
	ds_write_b32 v45, v27
	s_cbranch_vccnz .LBB0_851
	s_ashr_i32 s1, s0, 31
	v_readlane_b32 s44, v253, 35
	s_waitcnt vmcnt(0)
	v_lshl_add_u64 v[8:9], s[0:1], 0, v[0:1]
	v_readlane_b32 s46, v253, 37
	v_readlane_b32 s47, v253, 38
	v_readlane_b32 s45, v253, 36
	s_nop 0
	v_lshl_add_u64 v[8:9], v[8:9], 2, s[46:47]
	global_load_dword v26, v[8:9], off offset:64
	global_load_dword v27, v[8:9], off offset:72
	global_load_dword v70, v[8:9], off offset:80
	global_load_dword v71, v[8:9], off offset:88
	global_load_dword v10, v[8:9], off offset:96
	global_load_dword v11, v[8:9], off offset:104
	global_load_dword v18, v[8:9], off offset:112
	global_load_dword v19, v[8:9], off offset:120
	v_readlane_b32 s48, v253, 39
	v_readlane_b32 s49, v253, 40
	v_readlane_b32 s50, v253, 41
	v_readlane_b32 s51, v253, 42
	v_readlane_b32 s52, v253, 43
	v_readlane_b32 s53, v253, 44
	v_readlane_b32 s54, v253, 45
	v_readlane_b32 s55, v253, 46
	v_readlane_b32 s56, v253, 47
	v_readlane_b32 s57, v253, 48
	v_readlane_b32 s58, v253, 49
	v_readlane_b32 s59, v253, 50
	s_waitcnt vmcnt(7)
	v_mul_f32_e32 v26, v73, v26
	s_waitcnt vmcnt(6)
	v_mul_f32_e32 v27, v72, v27
	s_waitcnt vmcnt(5)
	v_mul_f32_e32 v70, v81, v70
	s_waitcnt vmcnt(4)
	v_mul_f32_e32 v71, v80, v71
	ds_write_b32 v46, v26
	ds_write_b32 v47, v27
	ds_write_b32 v48, v70
	ds_write_b32 v49, v71
	s_waitcnt vmcnt(2)
	v_pk_mul_f32 v[8:9], v[14:15], v[10:11]
	s_waitcnt vmcnt(0)
	v_pk_mul_f32 v[10:11], v[22:23], v[18:19]
	s_cbranch_execnz .LBB0_836
	.p2align	6

; DI void tr_tile(const float* __restrict__ src, int srcN, int k0, int n0, int mode, const float* __restrict__ gk, bf16_t* dst, size_t dpitch, int ncopies, float* scr, int lane) {
;     ...
; #pragma unroll
;     for (int i = 0; i < 32; ++i) { const int kk = 2 * i + (lane >> 5); v32[i] = valid ? src[(size_t)(k0 + kk) * srcN + sc] : 0.f; }
; #pragma unroll
;     for (int i = 0; i < 32; ++i) { const int kk = 2 * i + (lane >> 5); float v = v32[i]; if (gk) v *= gk[k0 + kk]; scr[kk * 33 + nn] = v; }
.LBB0_836:
	s_and_b64 vcc, exec, s[6:7]
	s_waitcnt vmcnt(0)
	ds_write_b32 v50, v8
	ds_write_b32 v51, v9
	ds_write_b32 v52, v10
	ds_write_b32 v53, v11
	s_cbranch_vccnz .LBB0_852
	s_ashr_i32 s1, s0, 31
	v_readlane_b32 s44, v253, 35
	v_lshl_add_u64 v[8:9], s[0:1], 0, v[0:1]
	v_readlane_b32 s46, v253, 37
	v_readlane_b32 s47, v253, 38
	v_readlane_b32 s45, v253, 36
	s_nop 0
	v_lshl_add_u64 v[8:9], v[8:9], 2, s[46:47]
	global_load_dword v18, v[8:9], off offset:128
	global_load_dword v19, v[8:9], off offset:136
	global_load_dword v22, v[8:9], off offset:144
	global_load_dword v23, v[8:9], off offset:152
	global_load_dword v10, v[8:9], off offset:160
	global_load_dword v11, v[8:9], off offset:168
	global_load_dword v14, v[8:9], off offset:176
	global_load_dword v15, v[8:9], off offset:184
	v_readlane_b32 s48, v253, 39
	v_readlane_b32 s49, v253, 40
	v_readlane_b32 s50, v253, 41
	v_readlane_b32 s51, v253, 42
	v_readlane_b32 s52, v253, 43
	v_readlane_b32 s53, v253, 44
	v_readlane_b32 s54, v253, 45
	v_readlane_b32 s55, v253, 46
	v_readlane_b32 s56, v253, 47
	v_readlane_b32 s57, v253, 48
	v_readlane_b32 s58, v253, 49
	v_readlane_b32 s59, v253, 50
	s_waitcnt vmcnt(7)
	v_mul_f32_e32 v18, v76, v18
	s_waitcnt vmcnt(6)
	v_mul_f32_e32 v19, v74, v19
	s_waitcnt vmcnt(5)
	v_mul_f32_e32 v22, v84, v22
	s_waitcnt vmcnt(4)
	v_mul_f32_e32 v23, v82, v23
	ds_write_b32 v54, v18
	ds_write_b32 v55, v19
	ds_write_b32 v56, v22
	ds_write_b32 v57, v23
	s_waitcnt vmcnt(2)
	v_pk_mul_f32 v[8:9], v[16:17], v[10:11]
	s_waitcnt vmcnt(0)
	v_pk_mul_f32 v[10:11], v[24:25], v[14:15]
	s_cbranch_execnz .LBB0_839
	.p2align	6

; DI void tr_tile(const float* __restrict__ src, int srcN, int k0, int n0, int mode, const float* __restrict__ gk, bf16_t* dst, size_t dpitch, int ncopies, float* scr, int lane) {
;     ...
;     for (int i = 0; i < 32; ++i) { const int kk = 2 * i + (lane >> 5); v32[i] = valid ? src[(size_t)(k0 + kk) * srcN + sc] : 0.f; }
; #pragma unroll
;     for (int i = 0; i < 32; ++i) { const int kk = 2 * i + (lane >> 5); float v = v32[i]; if (gk) v *= gk[k0 + kk]; scr[kk * 33 + nn] = v; }
.LBB0_839:
	s_and_b64 vcc, exec, s[6:7]
	ds_write_b32 v58, v8
	ds_write_b32 v59, v9
	ds_write_b32 v60, v10
	ds_write_b32 v61, v11
	s_cbranch_vccnz .LBB0_853
	s_ashr_i32 s1, s0, 31
	v_readlane_b32 s44, v253, 35
	v_lshl_add_u64 v[8:9], s[0:1], 0, v[0:1]
	v_readlane_b32 s46, v253, 37
	v_readlane_b32 s47, v253, 38
	v_readlane_b32 s45, v253, 36
	s_nop 0
	v_lshl_add_u64 v[8:9], v[8:9], 2, s[46:47]
	global_load_dword v16, v[8:9], off offset:192
	global_load_dword v17, v[8:9], off offset:200
	global_load_dword v18, v[8:9], off offset:208
	global_load_dword v19, v[8:9], off offset:216
	global_load_dword v10, v[8:9], off offset:224
	global_load_dword v11, v[8:9], off offset:232
	global_load_dword v14, v[8:9], off offset:240
	global_load_dword v15, v[8:9], off offset:248
	v_readlane_b32 s48, v253, 39
	v_readlane_b32 s49, v253, 40
	v_readlane_b32 s50, v253, 41
	v_readlane_b32 s51, v253, 42
	v_readlane_b32 s52, v253, 43
	v_readlane_b32 s53, v253, 44
	v_readlane_b32 s54, v253, 45
	v_readlane_b32 s55, v253, 46
	v_readlane_b32 s56, v253, 47
	v_readlane_b32 s57, v253, 48
	v_readlane_b32 s58, v253, 49
	v_readlane_b32 s59, v253, 50
	s_waitcnt vmcnt(7)
	v_mul_f32_e32 v16, v77, v16
	s_waitcnt vmcnt(6)
	v_mul_f32_e32 v17, v75, v17
	s_waitcnt vmcnt(5)
	v_mul_f32_e32 v18, v85, v18
	s_waitcnt vmcnt(4)
	v_mul_f32_e32 v19, v83, v19
	ds_write_b32 v62, v16
	ds_write_b32 v63, v17
	ds_write_b32 v64, v18
	ds_write_b32 v65, v19
	s_waitcnt vmcnt(2)
	v_pk_mul_f32 v[8:9], v[12:13], v[10:11]
	s_waitcnt vmcnt(0)
	v_pk_mul_f32 v[10:11], v[20:21], v[14:15]
	s_cbranch_execnz .LBB0_842
	.p2align	6

; DI void tr_tile(const float* __restrict__ src, int srcN, int k0, int n0, int mode, const float* __restrict__ gk, bf16_t* dst, size_t dpitch, int ncopies, float* scr, int lane) {
;     const int nn = lane & 31, n = n0 + nn; int sc = n; bool valid = true;
;     if (mode == 1) { if (n >= 4608) { const int q = n - 4608, rho = q & 255; sc = ZP + (2 * (rho >> 7) + ((rho >> 2) & 1)) * 1024 + 64 * (q >> 8) + 16 * ((rho >> 5) & 3) + 4 * ((rho >> 3) & 3) + (rho & 3); } else if (n >= ZP) { sc = 0; valid = false; } }
;     if (mode == 2) sc = ((n >> 7) & 1) * DFF + 128 * (n >> 8) + (n & 127);
;     float v32[32];
; #pragma unroll
;     for (int i = 0; i < 32; ++i) { const int kk = 2 * i + (lane >> 5); v32[i] = valid ? src[(size_t)(k0 + kk) * srcN + sc] : 0.f; }
; #pragma unroll
;     for (int i = 0; i < 32; ++i) { const int kk = 2 * i + (lane >> 5); float v = v32[i]; if (gk) v *= gk[k0 + kk]; scr[kk * 33 + nn] = v; }
; DI void convert_first(const Args& a, int l, float* scr, int gw, int ngw, int lane) {
;     unsigned char* ws = a.ws;
;     bf16_t* WIN = (bf16_t*)(ws + WS_WIN); bf16_t* WB = (bf16_t*)(ws + WS_WB); bf16_t* WO = (bf16_t*)(ws + WS_WO); bf16_t* W1T = (bf16_t*)(ws + WS_W1T);
;     const float* win = a.in[2] + (size_t)l * 1024 * NIN; const float* g1 = a.in[1] + l * 1024;
;     constexpr int I_WIN = 16 * (NWIN / 32), I_PF = 2048, I_WB = 4 * 8 * 32, I_WO = 16 * 32, I_W1 = 2 * 32 * 2;
;     for (int it = gw; it < I_WIN + I_PF + I_WB + I_WO + I_W1; it += ngw) {
.LBB0_856:
	v_readlane_b32 s42, v254, 14
	s_mul_i32 s1, s0, 0x2100
	s_add_i32 s6, s42, 1
	s_add_i32 s1, s1, 0
	v_readlane_b32 s14, v254, 3
	v_readlane_b32 s15, v254, 4
	s_add_u32 s8, s14, 0x400000
	s_addc_u32 s9, s15, 0
	s_add_u32 s23, s14, 0x1500000
	s_addc_u32 s24, s15, 0
	v_bfe_u32 v48, v0, 5, 1
	s_add_u32 s25, s14, 0x300000
	s_mul_i32 s38, s42, 0x2118000
	v_readlane_b32 s44, v253, 35
	v_mul_u32_u24_e32 v2, 33, v48
	s_addc_u32 s26, s15, 0
	s_ashr_i32 s7, s6, 31
	s_add_i32 s10, s38, 0x2118000
	v_readlane_b32 s48, v253, 39
	v_and_b32_e32 v51, 31, v0
	v_lshlrev_b32_e32 v2, 2, v2
	s_mul_hi_i32 s11, s6, 0x2118000
	v_readlane_b32 s49, v253, 40
	s_add_u32 s10, s48, s10
	v_add_u32_e32 v3, s1, v2
	v_lshlrev_b32_e32 v4, 2, v51
	s_addc_u32 s11, s49, s11
	s_lshl_b32 s12, s6, 10
	v_add_u32_e32 v59, v3, v4
	v_add_u32_e32 v4, s1, v4
	s_ashr_i32 s13, s12, 31
	v_and_b32_e32 v1, 63, v0
	v_add_u32_e32 v64, v4, v2
	v_mov_b32_e32 v2, 0x1080
	v_readlane_b32 s46, v253, 37
	s_lshl_b64 s[12:13], s[12:13], 2
	v_lshl_or_b32 v1, v1, 2, v2
	v_readlane_b32 s47, v253, 38
	s_add_u32 s12, s46, s12
	v_add_u32_e32 v65, v3, v1
	v_lshlrev_b32_e32 v1, 3, v0
	s_addc_u32 s13, s47, s13
	s_lshl_b64 s[16:17], s[6:7], 20
	v_bfe_u32 v66, v0, 3, 3
	v_and_b32_e32 v50, 56, v1
	s_lshl_b64 s[18:19], s[6:7], 22
	s_lshl_b64 s[20:21], s[6:7], 23
	s_lshl_b32 s6, s6, 9
	v_mul_u32_u24_e32 v1, 0x84, v50
	v_lshlrev_b32_e32 v2, 2, v66
	v_lshlrev_b32_e32 v160, 1, v50
	s_ashr_i32 s7, s6, 31
	v_readlane_b32 s56, v253, 47
	v_add3_u32 v67, s1, v1, v2
	v_lshl_add_u64 v[2:3], s[14:15], 0, v[160:161]
	s_mov_b64 s[14:15], 0x1900000
	s_cmp_lg_u64 s[46:47], 0
	v_readlane_b32 s52, v253, 43
	v_readlane_b32 s53, v253, 44
	v_readlane_b32 s54, v253, 45
	v_readlane_b32 s55, v253, 46
	v_readlane_b32 s57, v253, 48
	v_readlane_b32 s58, v253, 49
	v_readlane_b32 s59, v253, 50
	v_lshl_add_u64 v[52:53], v[2:3], 0, s[14:15]
	s_cselect_b64 s[14:15], -1, 0
	s_add_u32 s27, s56, s16
	s_addc_u32 s44, s57, s17
	v_readlane_b32 s52, v253, 51
	v_readlane_b32 s64, v253, 63
	v_readlane_b32 s65, v254, 0
	s_add_u32 s16, s64, s18
	v_readlane_b32 s62, v253, 61
	s_addc_u32 s17, s65, s19
	v_readlane_b32 s63, v253, 62
	s_add_u32 s29, s62, s20
	v_readlane_b32 s54, v253, 53
	s_addc_u32 s30, s63, s21
	s_lshl_b64 s[6:7], s[6:7], 2
	v_readlane_b32 s43, v254, 15
	v_readlane_b32 s55, v253, 54
	s_add_u32 s18, s54, s6
	v_mov_b32_e32 v1, 0x1118
	s_addc_u32 s19, s55, s7
	s_ashr_i32 s43, s42, 31
	v_bfe_u32 v72, v0, 2, 1
	v_and_or_b32 v73, v0, 3, v1
	v_or_b32_e32 v0, 2, v48
	s_movk_i32 s1, 0x84
	s_lshl_b64 s[6:7], s[42:43], 18
	v_mad_u32_u24 v74, v0, s1, v4
	v_readlane_b32 s53, v253, 52
	s_add_u32 s1, s52, s6
	s_addc_u32 s6, s53, s7
	s_add_u32 s31, s1, 0x41e00
	v_readlane_b32 s1, v253, 20
	s_addc_u32 s33, s6, 0
	s_add_i32 s0, s1, s0
	v_readlane_b32 s1, v254, 17
	s_lshl_b32 s34, s0, 12
	s_lshl_b32 s35, s1, 15
	s_lshl_b32 s36, s0, 5
	s_lshl_b32 s37, s1, 8
	s_mul_hi_i32 s0, s42, 0x2118000
	s_add_u32 s38, s48, s38
	v_or_b32_e32 v68, 8, v66
	v_or_b32_e32 v69, 16, v66
	v_or_b32_e32 v70, 24, v66
	v_and_b32_e32 v71, 4, v66
	v_add_u32_e32 v75, 0x108, v74
	v_add_u32_e32 v76, 0x210, v74
	v_add_u32_e32 v77, 0x318, v74
	v_add_u32_e32 v78, 0x420, v74
	v_add_u32_e32 v79, 0x528, v74
	v_add_u32_e32 v80, 0x630, v74
	v_add_u32_e32 v81, 0x738, v74
	v_add_u32_e32 v82, 0x840, v74
	v_add_u32_e32 v83, 0x948, v74
	v_add_u32_e32 v84, 0xa50, v74
	v_add_u32_e32 v85, 0xb58, v74
	v_add_u32_e32 v86, 0xc60, v74
	v_add_u32_e32 v87, 0xd68, v74
	v_add_u32_e32 v88, 0xe70, v74
	v_add_u32_e32 v89, 0xf78, v74
	v_add_u32_e32 v90, 0x1080, v74
	v_add_u32_e32 v91, 0x1188, v74
	v_add_u32_e32 v92, 0x1290, v74
	v_add_u32_e32 v93, 0x1398, v74
	v_add_u32_e32 v94, 0x14a0, v74
	v_add_u32_e32 v95, 0x15a8, v74
	v_add_u32_e32 v96, 0x16b0, v74
	v_add_u32_e32 v97, 0x17b8, v74
	v_add_u32_e32 v98, 0x18c0, v74
	v_add_u32_e32 v99, 0x19c8, v74
	v_add_u32_e32 v100, 0x1ad0, v74
	v_add_u32_e32 v101, 0x1bd8, v74
	v_add_u32_e32 v102, 0x1ce0, v74
	v_add_u32_e32 v103, 0x1de8, v74
	v_add_u32_e32 v104, 0x1ef0, v74
	s_waitcnt lgkmcnt(0)
	v_lshl_add_u64 v[54:55], s[8:9], 0, v[160:161]
	v_mov_b32_e32 v49, v161
	s_addc_u32 s39, s49, s0
	v_readlane_b32 s45, v253, 36
	v_readlane_b32 s50, v253, 41
	v_readlane_b32 s51, v253, 42
	v_readlane_b32 s56, v253, 55
	v_readlane_b32 s57, v253, 56
	v_readlane_b32 s58, v253, 57
	v_readlane_b32 s59, v253, 58
	v_readlane_b32 s60, v253, 59
	v_readlane_b32 s61, v253, 60
	v_readlane_b32 s66, v254, 1
	v_readlane_b32 s67, v254, 2
	s_branch .LBB0_859
	.p2align	6

; DI void pool_fold_item(const float* __restrict__ win, const float* __restrict__ pw, const float* __restrict__ psc, const float* __restrict__ g1, bf16_t* WIN, int item, int lane) {
;     const int kt = item >> 4, nt = item & 15, np = nt * 32 + (lane & 31), gi = np >> 7, d = np & 127, kb = kt * 8 + (lane >> 5) * 4;
;     const float* wp = pw + (size_t)gi * 128 * 128 + d; const float sc = psc[np];
;     const float* wr = win + (size_t)kb * NIN + C_PL + gi * 128;
;     float acc[4] = {0.f, 0.f, 0.f, 0.f};
; DI void convert_first(const Args& a, int l, float* scr, int gw, int ngw, int lane) {
;     ...
;         if (r < I_PF) { pool_fold_item(win, a.in[8] + (size_t)l * 4 * 128 * 128, a.in[9] + l * 512, g1, WIN, r, lane); continue; } r -= I_PF;
.LBB0_870:
	s_andn2_b64 vcc, exec, s[0:1]
	s_cbranch_vccnz .LBB0_874
	s_lshl_b32 s0, s34, 2
	s_and_b32 s0, s0, 0x30000
	s_and_b32 s1, s36, 0x60
	v_or_b32_e32 v0, s1, v51
	s_add_u32 s0, s31, s0
	v_lshlrev_b32_sdwa v160, v224, v0 dst_sel:DWORD dst_unused:UNUSED_PAD src0_sel:DWORD src1_sel:WORD_0
	s_addc_u32 s1, s33, 0
	v_lshl_add_u64 v[56:57], s[0:1], 0, v[160:161]
	s_add_i32 s1, s22, 0xffffef00
	s_lshl_b32 s6, s1, 5
	s_and_b32 s6, s6, 0x1e0
	v_or_b32_e32 v106, s6, v51
	v_lshlrev_b32_e32 v0, 2, v106
	global_load_dword v58, v0, s[18:19]
	s_lshl_b32 s0, s36, 2
	s_lshr_b32 s1, s1, 1
	s_and_b32 s0, s0, 0x600
	s_and_b32 s1, s1, 0x3f8
	s_add_u32 s0, s38, s0
	v_or_b32_e32 v105, s1, v71
	s_addc_u32 s1, s39, 0
	v_mov_b64_e32 v[0:1], s[0:1]
	v_mov_b32_e32 v8, 0
	v_mad_u64_u32 v[60:61], s[0:1], v105, s41, v[0:1]
	s_mov_b64 s[6:7], 0
	v_mov_b32_e32 v9, v8
	v_mov_b32_e32 v62, v8
	v_mov_b32_e32 v63, v8
	s_mov_b64 s[20:21], 0x2000
	.p2align	6

; DI void tr_tile(const float* __restrict__ src, int srcN, int k0, int n0, int mode, const float* __restrict__ gk, bf16_t* dst, size_t dpitch, int ncopies, float* scr, int lane) {
;     ...
;     for (int i = 0; i < 32; ++i) { const int kk = 2 * i + (lane >> 5); v32[i] = valid ? src[(size_t)(k0 + kk) * srcN + sc] : 0.f; }
; #pragma unroll
;     for (int i = 0; i < 32; ++i) { const int kk = 2 * i + (lane >> 5); float v = v32[i]; if (gk) v *= gk[k0 + kk]; scr[kk * 33 + nn] = v; }
.LBB0_944:
	s_or_b64 exec, exec, s[20:21]
	v_cndmask_b32_e64 v17, 0, 1, s[14:15]
	v_cmp_ne_u32_e64 s[6:7], 1, v17
	s_andn2_b64 vcc, exec, s[14:15]
	s_cbranch_vccnz .LBB0_964
	v_ashrrev_i32_e32 v17, 31, v16
	v_lshl_add_u64 v[16:17], v[16:17], 2, s[12:13]
	global_load_dword v16, v[16:17], off
	s_ashr_i32 s1, s0, 31
	s_waitcnt vmcnt(0)
	v_mul_f32_e32 v36, v33, v16
	v_lshl_add_u64 v[16:17], s[0:1], 0, v[48:49]
	v_lshl_add_u64 v[18:19], v[16:17], 2, s[12:13]
	global_load_dword v16, v[18:19], off offset:8
	global_load_dword v17, v[18:19], off offset:16
	global_load_dword v37, v[18:19], off offset:24
	s_waitcnt vmcnt(2)
	v_mul_f32_e32 v16, v32, v16
	s_waitcnt vmcnt(1)
	v_mul_f32_e32 v17, v35, v17
	s_waitcnt vmcnt(0)
	v_mul_f32_e32 v37, v34, v37
	ds_write_b32 v59, v36
	ds_write_b32 v74, v16
	ds_write_b32 v75, v17
	ds_write_b32 v76, v37
	global_load_dword v16, v[18:19], off offset:32
	global_load_dword v17, v[18:19], off offset:40
	global_load_dword v36, v[18:19], off offset:48
	global_load_dword v37, v[18:19], off offset:56
	s_waitcnt vmcnt(2)
	v_pk_mul_f32 v[16:17], v[12:13], v[16:17]
	s_waitcnt vmcnt(0)
	v_pk_mul_f32 v[18:19], v[14:15], v[36:37]
	s_cbranch_execnz .LBB0_947
	.p2align	6

; DI void tr_tile(const float* __restrict__ src, int srcN, int k0, int n0, int mode, const float* __restrict__ gk, bf16_t* dst, size_t dpitch, int ncopies, float* scr, int lane) {
;     ...
;     for (int i = 0; i < 32; ++i) { const int kk = 2 * i + (lane >> 5); v32[i] = valid ? src[(size_t)(k0 + kk) * srcN + sc] : 0.f; }
; #pragma unroll
;     for (int i = 0; i < 32; ++i) { const int kk = 2 * i + (lane >> 5); float v = v32[i]; if (gk) v *= gk[k0 + kk]; scr[kk * 33 + nn] = v; }
.LBB0_947:
	s_and_b64 vcc, exec, s[6:7]
	ds_write_b32 v77, v16
	ds_write_b32 v78, v17
	ds_write_b32 v79, v18
	ds_write_b32 v80, v19
	s_cbranch_vccnz .LBB0_965
	s_ashr_i32 s1, s0, 31
	s_waitcnt vmcnt(0)
	v_lshl_add_u64 v[12:13], s[0:1], 0, v[48:49]
	v_lshl_add_u64 v[14:15], v[12:13], 2, s[12:13]
	global_load_dword v12, v[14:15], off offset:64
	global_load_dword v13, v[14:15], off offset:72
	global_load_dword v16, v[14:15], off offset:80
	global_load_dword v17, v[14:15], off offset:88
	s_waitcnt vmcnt(3)
	v_mul_f32_e32 v12, v29, v12
	s_waitcnt vmcnt(2)
	v_mul_f32_e32 v13, v28, v13
	s_waitcnt vmcnt(1)
	v_mul_f32_e32 v16, v31, v16
	s_waitcnt vmcnt(0)
	v_mul_f32_e32 v17, v30, v17
	ds_write_b32 v81, v12
	ds_write_b32 v82, v13
	ds_write_b32 v83, v16
	ds_write_b32 v84, v17
	global_load_dword v12, v[14:15], off offset:96
	global_load_dword v13, v[14:15], off offset:104
	global_load_dword v16, v[14:15], off offset:112
	global_load_dword v17, v[14:15], off offset:120
	s_waitcnt vmcnt(2)
	v_pk_mul_f32 v[12:13], v[8:9], v[12:13]
	s_waitcnt vmcnt(0)
	v_pk_mul_f32 v[14:15], v[10:11], v[16:17]
	s_cbranch_execnz .LBB0_950
	.p2align	6

; DI void tr_tile(const float* __restrict__ src, int srcN, int k0, int n0, int mode, const float* __restrict__ gk, bf16_t* dst, size_t dpitch, int ncopies, float* scr, int lane) {
;     ...
;     for (int i = 0; i < 32; ++i) { const int kk = 2 * i + (lane >> 5); v32[i] = valid ? src[(size_t)(k0 + kk) * srcN + sc] : 0.f; }
; #pragma unroll
;     for (int i = 0; i < 32; ++i) { const int kk = 2 * i + (lane >> 5); float v = v32[i]; if (gk) v *= gk[k0 + kk]; scr[kk * 33 + nn] = v; }
.LBB0_950:
	s_and_b64 vcc, exec, s[6:7]
	s_waitcnt vmcnt(0)
	ds_write_b32 v85, v12
	ds_write_b32 v86, v13
	ds_write_b32 v87, v14
	ds_write_b32 v88, v15
	s_cbranch_vccnz .LBB0_966
	s_ashr_i32 s1, s0, 31
	v_lshl_add_u64 v[8:9], s[0:1], 0, v[48:49]
	v_lshl_add_u64 v[10:11], v[8:9], 2, s[12:13]
	global_load_dword v8, v[10:11], off offset:128
	global_load_dword v9, v[10:11], off offset:136
	global_load_dword v12, v[10:11], off offset:144
	global_load_dword v13, v[10:11], off offset:152
	s_waitcnt vmcnt(3)
	v_mul_f32_e32 v8, v25, v8
	s_waitcnt vmcnt(2)
	v_mul_f32_e32 v9, v24, v9
	s_waitcnt vmcnt(1)
	v_mul_f32_e32 v12, v27, v12
	s_waitcnt vmcnt(0)
	v_mul_f32_e32 v13, v26, v13
	ds_write_b32 v89, v8
	ds_write_b32 v90, v9
	ds_write_b32 v91, v12
	ds_write_b32 v92, v13
	global_load_dword v8, v[10:11], off offset:160
	global_load_dword v9, v[10:11], off offset:168
	global_load_dword v12, v[10:11], off offset:176
	global_load_dword v13, v[10:11], off offset:184
	s_waitcnt vmcnt(2)
	v_pk_mul_f32 v[8:9], v[4:5], v[8:9]
	s_waitcnt vmcnt(0)
	v_pk_mul_f32 v[10:11], v[6:7], v[12:13]
	s_cbranch_execnz .LBB0_953
	.p2align	6

; DI void tr_tile(const float* __restrict__ src, int srcN, int k0, int n0, int mode, const float* __restrict__ gk, bf16_t* dst, size_t dpitch, int ncopies, float* scr, int lane) {
;     ...
;     for (int i = 0; i < 32; ++i) { const int kk = 2 * i + (lane >> 5); v32[i] = valid ? src[(size_t)(k0 + kk) * srcN + sc] : 0.f; }
; #pragma unroll
;     for (int i = 0; i < 32; ++i) { const int kk = 2 * i + (lane >> 5); float v = v32[i]; if (gk) v *= gk[k0 + kk]; scr[kk * 33 + nn] = v; }
.LBB0_953:
	s_and_b64 vcc, exec, s[6:7]
	ds_write_b32 v93, v8
	ds_write_b32 v94, v9
	ds_write_b32 v95, v10
	ds_write_b32 v96, v11
	s_cbranch_vccnz .LBB0_967
	s_ashr_i32 s1, s0, 31
	v_lshl_add_u64 v[4:5], s[0:1], 0, v[48:49]
	v_lshl_add_u64 v[6:7], v[4:5], 2, s[12:13]
	global_load_dword v4, v[6:7], off offset:192
	global_load_dword v5, v[6:7], off offset:200
	global_load_dword v8, v[6:7], off offset:208
	global_load_dword v9, v[6:7], off offset:216
	s_waitcnt vmcnt(3)
	v_mul_f32_e32 v4, v21, v4
	s_waitcnt vmcnt(2)
	v_mul_f32_e32 v5, v20, v5
	s_waitcnt vmcnt(1)
	v_mul_f32_e32 v8, v23, v8
	s_waitcnt vmcnt(0)
	v_mul_f32_e32 v9, v22, v9
	ds_write_b32 v97, v4
	ds_write_b32 v98, v5
	ds_write_b32 v99, v8
	ds_write_b32 v100, v9
	global_load_dword v4, v[6:7], off offset:224
	global_load_dword v5, v[6:7], off offset:232
	global_load_dword v8, v[6:7], off offset:240
	global_load_dword v9, v[6:7], off offset:248
	s_waitcnt vmcnt(2)
	v_pk_mul_f32 v[4:5], v[0:1], v[4:5]
	s_waitcnt vmcnt(0)
	v_pk_mul_f32 v[6:7], v[2:3], v[8:9]
	s_cbranch_execnz .LBB0_956
	.p2align	6
